# fast row routine also for context rows and the layer-0 prologue modulate
# speedup vs baseline: 1.0591x; 1.0041x over previous
; DI const float* modp(const Frame& F, int l, int mr, int which) { return (const float*)(F.ws + WS_MOD) + ((size_t)(l * 9 + mr) * 6 + which) * 1024; }
; DI void ln_row_v(const Frame& F, f32x4 (&v)[4], float* xout, const float* g, const float* b, const float* sh, const float* sc, bf16_t* hout, const float* slab, const float* gres, float* stat = nullptr) {
;     ...
;         float s = 0.f, s2 = 0.f;
; #pragma unroll
;         for (int j = 0; j < 4; ++j) { s += (v[j][0] + v[j][1]) + (v[j][2] + v[j][3]); s2 += (v[j][0] * v[j][0] + v[j][1] * v[j][1]) + (v[j][2] * v[j][2] + v[j][3] * v[j][3]); }
;         wave_sum2(s, s2, F.lane);
;         const float mean = s * (1.f / D); const float rstd = 1.f / sqrtf(fmaxf(s2 * (1.f / D) - mean * mean, 0.f) + EPS);
; DI void ln_phase(const Frame& F, int which) {
;     const int gw = F.vcu * 8 + F.wave, NGW = F.G * 8; const int l = F.l;
;     const int nrows = (l == NL - 1) ? ML : MT;
;     bf16_t* H = (bf16_t*)(F.ws + WS_HB);
;     const float* g = pin(F, which == 0 ? I_LN1G : I_LN2G) + l * 1024; const float* b = pin(F, which == 0 ? I_LN1B : I_LN2B) + l * 1024;
;     const bool wh = !(which == 1 && l == NL - 1);
;     f32x4 vc[4], vn[4];
;     if (gw < nrows) ln_load(F, xrow_ptr(F, gw), vc);
;     for (int row = gw; row < nrows; row += NGW) {
;         if (row + NGW < nrows) ln_load(F, xrow_ptr(F, row + NGW), vn);
;         const int mr = row < ML ? (row >> 11) : 8;
;         const float* sh = which == 0 ? modp(F, l, mr, 3) : modp(F, l + 1 < NL ? l + 1 : l, mr, 0);
;         const float* sc = which == 0 ? modp(F, l, mr, 4) : modp(F, l + 1 < NL ? l + 1 : l, mr, 1);
;         const bool sl = (which == 1 && row >= ML);
;         const bool st_only = row < ML && !(which == 1 && l == NL - 1);
;         float* stp = st_only ? (float*)(F.ws + (which == 0 ? WS_ST1 : WS_ST2)) + 2 * (size_t)row : nullptr;
;         ln_row_v(F, vc, st_only ? nullptr : xrow_ptr(F, row), g, b, sh, sc, wh ? H + (size_t)row * D : nullptr, sl ? (const float*)(F.ws + WS_KN) + (size_t)(row - ML) * 1024 : nullptr, modp(F, l, mr, 5), stp);
.LBB0_107:
	s_cmp_gt_i32 s28, 4
	s_mov_b64 s[2:3], -1
	s_cbranch_scc0 .LBB0_125
	v_readlane_b32 s2, v255, 29
	s_lshl_b32 s2, s2, 3
	v_readlane_b32 s3, v255, 31
	s_add_i32 s16, s3, s2
	v_lshlrev_b32_e32 v0, 4, v186
	v_lshlrev_b32_e32 v1, 3, v186
	v_lshlrev_b32_e32 v96, 2, v186
	v_xor_b32_e32 v3, 4, v96
	v_xor_b32_e32 v4, 8, v96
	v_xor_b32_e32 v5, 16, v96
	v_xor_b32_e32 v6, 32, v96
	v_xor_b32_e32 v7, 64, v96
	v_xor_b32_e32 v8, 128, v96
	s_load_dwordx4 s[4:7], s[62:63], 0x98
	v_readlane_b32 s22, v255, 35
	v_readlane_b32 s8, v255, 17
	v_readlane_b32 s9, v255, 18
	s_add_u32 s20, s94, 0x3600000
	s_addc_u32 s21, s95, 0
	s_lshl_b32 s2, s16, 12
	s_add_u32 s8, s8, s2
	s_addc_u32 s9, s9, 0
	s_add_u32 s20, s20, s2
	s_addc_u32 s21, s21, 0
	s_lshl_b32 s2, s16, 11
	s_add_u32 s10, s94, s2
	s_addc_u32 s11, s95, 0
	s_add_u32 s10, s10, 0x3e00000
	s_addc_u32 s11, s11, 0
	s_lshl_b32 s2, s16, 3
	s_add_u32 s12, s94, s2
	s_addc_u32 s13, s95, 0
	s_add_u32 s12, s12, 0x480000
	s_addc_u32 s13, s13, 0
	s_mov_b32 s3, s22
	s_mul_i32 s3, s3, 0x36000
	s_add_u32 s14, s94, s3
	s_addc_u32 s15, s95, 0
	s_add_u32 s14, s14, 0x103000
	s_addc_u32 s15, s15, 0
	s_add_u32 s18, s14, 0x1000
	s_addc_u32 s19, s15, 0
	s_lshl_b32 s2, s22, 12
	s_waitcnt lgkmcnt(0)
	s_add_u32 s4, s4, s2
	s_addc_u32 s5, s5, 0
	s_add_u32 s6, s6, s2
	s_addc_u32 s7, s7, 0
	global_load_dwordx4 v[10:13], v0, s[4:5]
	global_load_dwordx4 v[14:17], v0, s[4:5] offset:1024
	global_load_dwordx4 v[18:21], v0, s[4:5] offset:2048
	global_load_dwordx4 v[22:25], v0, s[4:5] offset:3072
	global_load_dwordx4 v[26:29], v0, s[6:7]
	global_load_dwordx4 v[30:33], v0, s[6:7] offset:1024
	global_load_dwordx4 v[34:37], v0, s[6:7] offset:2048
	global_load_dwordx4 v[38:41], v0, s[6:7] offset:3072
	s_add_u32 s2, s8, 0x0
	s_addc_u32 s3, s9, 0
	global_load_dwordx4 v[42:45], v0, s[2:3]
	global_load_dwordx4 v[46:49], v0, s[2:3] offset:1024
	global_load_dwordx4 v[50:53], v0, s[2:3] offset:2048
	global_load_dwordx4 v[54:57], v0, s[2:3] offset:3072
	s_add_u32 s2, s14, 0x0
	s_addc_u32 s3, s15, 0
	global_load_dwordx4 v[114:117], v0, s[2:3]
	global_load_dwordx4 v[118:121], v0, s[2:3] offset:1024
	global_load_dwordx4 v[122:125], v0, s[2:3] offset:2048
	global_load_dwordx4 v[126:129], v0, s[2:3] offset:3072
	s_add_u32 s2, s18, 0x0
	s_addc_u32 s3, s19, 0
	global_load_dwordx4 v[130:133], v0, s[2:3]
	global_load_dwordx4 v[134:137], v0, s[2:3] offset:1024
	global_load_dwordx4 v[138:141], v0, s[2:3] offset:2048
	global_load_dwordx4 v[142:145], v0, s[2:3] offset:3072
	s_add_u32 s2, s8, 0x800000
	s_addc_u32 s3, s9, 0
	global_load_dwordx4 v[58:61], v0, s[2:3]
	global_load_dwordx4 v[62:65], v0, s[2:3] offset:1024
	global_load_dwordx4 v[66:69], v0, s[2:3] offset:2048
	global_load_dwordx4 v[70:73], v0, s[2:3] offset:3072
	s_add_u32 s2, s14, 0x6000
	s_addc_u32 s3, s15, 0
	global_load_dwordx4 v[146:149], v0, s[2:3]
	global_load_dwordx4 v[150:153], v0, s[2:3] offset:1024
	global_load_dwordx4 v[154:157], v0, s[2:3] offset:2048
	global_load_dwordx4 v[158:161], v0, s[2:3] offset:3072
	s_add_u32 s2, s18, 0x6000
	s_addc_u32 s3, s19, 0
	global_load_dwordx4 v[162:165], v0, s[2:3]
	global_load_dwordx4 v[166:169], v0, s[2:3] offset:1024
	global_load_dwordx4 v[170:173], v0, s[2:3] offset:2048
	global_load_dwordx4 v[174:177], v0, s[2:3] offset:3072
	s_add_u32 s2, s8, 0x1000000
	s_addc_u32 s3, s9, 0
	global_load_dwordx4 v[74:77], v0, s[2:3]
	global_load_dwordx4 v[78:81], v0, s[2:3] offset:1024
	global_load_dwordx4 v[82:85], v0, s[2:3] offset:2048
	global_load_dwordx4 v[86:89], v0, s[2:3] offset:3072
	s_add_u32 s2, s8, 0x1800000
	s_addc_u32 s3, s9, 0
	global_load_dwordx4 v[98:101], v0, s[2:3]
	global_load_dwordx4 v[102:105], v0, s[2:3] offset:1024
	global_load_dwordx4 v[106:109], v0, s[2:3] offset:2048
	global_load_dwordx4 v[110:113], v0, s[2:3] offset:3072
	s_waitcnt vmcnt(28)
	v_add_f32_e32 v9, v42, v43
	v_add_f32_e32 v91, v44, v45
	v_mul_f32_e32 v90, v42, v42
	v_mul_f32_e32 v92, v43, v43
	v_add_f32_e32 v9, v9, v46
	v_add_f32_e32 v91, v91, v47
	v_add_f32_e32 v9, v9, v48
	v_add_f32_e32 v91, v91, v49
	v_add_f32_e32 v9, v9, v50
	v_add_f32_e32 v91, v91, v51
	v_add_f32_e32 v9, v9, v52
	v_add_f32_e32 v91, v91, v53
	v_add_f32_e32 v9, v9, v54
	v_add_f32_e32 v91, v91, v55
	v_add_f32_e32 v9, v9, v56
	v_add_f32_e32 v91, v91, v57
	v_fmac_f32_e32 v90, v44, v44
	v_fmac_f32_e32 v92, v45, v45
	v_fmac_f32_e32 v90, v46, v46
	v_fmac_f32_e32 v92, v47, v47
	v_fmac_f32_e32 v90, v48, v48
	v_fmac_f32_e32 v92, v49, v49
	v_fmac_f32_e32 v90, v50, v50
	v_fmac_f32_e32 v92, v51, v51
	v_fmac_f32_e32 v90, v52, v52
	v_fmac_f32_e32 v92, v53, v53
	v_fmac_f32_e32 v90, v54, v54
	v_fmac_f32_e32 v92, v55, v55
	v_fmac_f32_e32 v90, v56, v56
	v_fmac_f32_e32 v92, v57, v57
	v_add_f32_e32 v9, v9, v91
	v_add_f32_e32 v90, v90, v92
	ds_bpermute_b32 v91, v3, v9
	ds_bpermute_b32 v92, v3, v90
	s_waitcnt lgkmcnt(0)
	v_add_f32_e32 v9, v9, v91
	v_add_f32_e32 v90, v90, v92
	ds_bpermute_b32 v91, v4, v9
	ds_bpermute_b32 v92, v4, v90
	s_waitcnt lgkmcnt(0)
	v_add_f32_e32 v9, v9, v91
	v_add_f32_e32 v90, v90, v92
	ds_bpermute_b32 v91, v5, v9
	ds_bpermute_b32 v92, v5, v90
	s_waitcnt lgkmcnt(0)
	v_add_f32_e32 v9, v9, v91
	v_add_f32_e32 v90, v90, v92
	ds_bpermute_b32 v91, v6, v9
	ds_bpermute_b32 v92, v6, v90
	s_waitcnt lgkmcnt(0)
	v_add_f32_e32 v9, v9, v91
	v_add_f32_e32 v90, v90, v92
	ds_bpermute_b32 v91, v7, v9
	ds_bpermute_b32 v92, v7, v90
	s_waitcnt lgkmcnt(0)
	v_add_f32_e32 v9, v9, v91
	v_add_f32_e32 v90, v90, v92
	ds_bpermute_b32 v91, v8, v9
	ds_bpermute_b32 v92, v8, v90
	s_waitcnt lgkmcnt(0)
; DI unsigned pk2(float lo, float hi) { f32x2 v = {lo, hi}; bf16x2_t b = __builtin_convertvector(v, bf16x2_t); return __builtin_bit_cast(unsigned, b); }
; DI void ln_row_v(const Frame& F, f32x4 (&v)[4], float* xout, const float* g, const float* b, const float* sh, const float* sc, bf16_t* hout, const float* slab, const float* gres, float* stat = nullptr) {
;     ...
;         float s = 0.f, s2 = 0.f;
; #pragma unroll
;         for (int j = 0; j < 4; ++j) { s += (v[j][0] + v[j][1]) + (v[j][2] + v[j][3]); s2 += (v[j][0] * v[j][0] + v[j][1] * v[j][1]) + (v[j][2] * v[j][2] + v[j][3] * v[j][3]); }
;         wave_sum2(s, s2, F.lane);
;         const float mean = s * (1.f / D); const float rstd = 1.f / sqrtf(fmaxf(s2 * (1.f / D) - mean * mean, 0.f) + EPS);
;         if (stat && F.lane == 0) { f32x2 sv = {mean, rstd}; *(f32x2*)stat = sv; }
; #pragma unroll
;         for (int j = 0; j < 4; ++j) { const f32x4 gg = ((const f32x4*)g)[F.lane + 64 * j], bb = ((const f32x4*)b)[F.lane + 64 * j];
;             v[j] = (v[j] - mean) * rstd * gg + bb; if (xout) ((f32x4*)xout)[F.lane + 64 * j] = v[j]; }
;     }
;     if (hout) {
;         float s = 0.f, s2 = 0.f;
; #pragma unroll
;         for (int j = 0; j < 4; ++j) { s += (v[j][0] + v[j][1]) + (v[j][2] + v[j][3]); s2 += (v[j][0] * v[j][0] + v[j][1] * v[j][1]) + (v[j][2] * v[j][2] + v[j][3] * v[j][3]); }
;         wave_sum2(s, s2, F.lane);
;         const float mean = s * (1.f / D); const float rstd = 1.f / sqrtf(fmaxf(s2 * (1.f / D) - mean * mean, 0.f) + EPS);
; #pragma unroll
;         for (int j = 0; j < 4; ++j) { const f32x4 hh = ((const f32x4*)sh)[F.lane + 64 * j], cc = ((const f32x4*)sc)[F.lane + 64 * j];
;             const f32x4 o = (v[j] - mean) * rstd * (cc + 1.f) + hh; u32x2 wv; wv.x = pk2(o[0], o[1]); wv.y = pk2(o[2], o[3]);
;             ((u32x2*)hout)[F.lane + 64 * j] = wv; }
;     }
	v_add_f32_e32 v9, v9, v91
	v_add_f32_e32 v90, v90, v92
	v_mul_f32_e32 v93, 0x3a800000, v9
	v_mul_f32_e32 v91, 0x3a800000, v90
	v_fma_f32 v91, -v93, v93, v91
	v_max_f32_e32 v91, 0, v91
	v_add_f32_e32 v91, 0x358637bd, v91
	v_rsq_f32_e32 v94, v91
	v_mul_f32_e32 v91, 0.5, v91
	v_mul_f32_e32 v92, v94, v94
	v_fma_f32 v92, -v91, v92, 0.5
	v_fma_f32 v94, v94, v92, v94
	s_add_u32 s2, s12, 0x0
	s_addc_u32 s3, s13, 0
	v_mov_b32_e32 v188, v93
	v_mov_b32_e32 v189, v94
	s_mov_b64 exec, 1
	global_store_dwordx2 v97, v[188:189], s[2:3]
	s_mov_b64 exec, -1
	v_sub_f32_e32 v42, v42, v93
	v_sub_f32_e32 v43, v43, v93
	v_sub_f32_e32 v44, v44, v93
	v_sub_f32_e32 v45, v45, v93
	v_sub_f32_e32 v46, v46, v93
	v_sub_f32_e32 v47, v47, v93
	v_sub_f32_e32 v48, v48, v93
	v_sub_f32_e32 v49, v49, v93
	v_sub_f32_e32 v50, v50, v93
	v_sub_f32_e32 v51, v51, v93
	v_sub_f32_e32 v52, v52, v93
	v_sub_f32_e32 v53, v53, v93
	v_sub_f32_e32 v54, v54, v93
	v_sub_f32_e32 v55, v55, v93
	v_sub_f32_e32 v56, v56, v93
	v_sub_f32_e32 v57, v57, v93
	v_mul_f32_e32 v42, v94, v42
	v_mul_f32_e32 v43, v94, v43
	v_mul_f32_e32 v44, v94, v44
	v_mul_f32_e32 v45, v94, v45
	v_mul_f32_e32 v46, v94, v46
	v_mul_f32_e32 v47, v94, v47
	v_mul_f32_e32 v48, v94, v48
	v_mul_f32_e32 v49, v94, v49
	v_mul_f32_e32 v50, v94, v50
	v_mul_f32_e32 v51, v94, v51
	v_mul_f32_e32 v52, v94, v52
	v_mul_f32_e32 v53, v94, v53
	v_mul_f32_e32 v54, v94, v54
	v_mul_f32_e32 v55, v94, v55
	v_mul_f32_e32 v56, v94, v56
	v_mul_f32_e32 v57, v94, v57
	v_fma_f32 v42, v42, v10, v26
	v_fma_f32 v43, v43, v11, v27
	v_fma_f32 v44, v44, v12, v28
	v_fma_f32 v45, v45, v13, v29
	v_fma_f32 v46, v46, v14, v30
	v_fma_f32 v47, v47, v15, v31
	v_fma_f32 v48, v48, v16, v32
	v_fma_f32 v49, v49, v17, v33
	v_fma_f32 v50, v50, v18, v34
	v_fma_f32 v51, v51, v19, v35
	v_fma_f32 v52, v52, v20, v36
	v_fma_f32 v53, v53, v21, v37
	v_fma_f32 v54, v54, v22, v38
	v_fma_f32 v55, v55, v23, v39
	v_fma_f32 v56, v56, v24, v40
	v_fma_f32 v57, v57, v25, v41
	v_add_f32_e32 v9, v42, v43
	v_add_f32_e32 v91, v44, v45
	v_mul_f32_e32 v90, v42, v42
	v_mul_f32_e32 v92, v43, v43
	v_add_f32_e32 v9, v9, v46
	v_add_f32_e32 v91, v91, v47
	v_add_f32_e32 v9, v9, v48
	v_add_f32_e32 v91, v91, v49
	v_add_f32_e32 v9, v9, v50
	v_add_f32_e32 v91, v91, v51
	v_add_f32_e32 v9, v9, v52
	v_add_f32_e32 v91, v91, v53
	v_add_f32_e32 v9, v9, v54
	v_add_f32_e32 v91, v91, v55
	v_add_f32_e32 v9, v9, v56
	v_add_f32_e32 v91, v91, v57
	v_fmac_f32_e32 v90, v44, v44
	v_fmac_f32_e32 v92, v45, v45
	v_fmac_f32_e32 v90, v46, v46
	v_fmac_f32_e32 v92, v47, v47
	v_fmac_f32_e32 v90, v48, v48
	v_fmac_f32_e32 v92, v49, v49
	v_fmac_f32_e32 v90, v50, v50
	v_fmac_f32_e32 v92, v51, v51
	v_fmac_f32_e32 v90, v52, v52
	v_fmac_f32_e32 v92, v53, v53
	v_fmac_f32_e32 v90, v54, v54
	v_fmac_f32_e32 v92, v55, v55
	v_fmac_f32_e32 v90, v56, v56
	v_fmac_f32_e32 v92, v57, v57
	v_add_f32_e32 v9, v9, v91
	v_add_f32_e32 v90, v90, v92
	ds_bpermute_b32 v91, v3, v9
	ds_bpermute_b32 v92, v3, v90
	s_waitcnt lgkmcnt(0)
	v_add_f32_e32 v9, v9, v91
	v_add_f32_e32 v90, v90, v92
	ds_bpermute_b32 v91, v4, v9
	ds_bpermute_b32 v92, v4, v90
	s_waitcnt lgkmcnt(0)
	v_add_f32_e32 v9, v9, v91
	v_add_f32_e32 v90, v90, v92
	ds_bpermute_b32 v91, v5, v9
	ds_bpermute_b32 v92, v5, v90
	s_waitcnt lgkmcnt(0)
	v_add_f32_e32 v9, v9, v91
	v_add_f32_e32 v90, v90, v92
	ds_bpermute_b32 v91, v6, v9
	ds_bpermute_b32 v92, v6, v90
	s_waitcnt lgkmcnt(0)
	v_add_f32_e32 v9, v9, v91
	v_add_f32_e32 v90, v90, v92
	ds_bpermute_b32 v91, v7, v9
	ds_bpermute_b32 v92, v7, v90
	s_waitcnt lgkmcnt(0)
	v_add_f32_e32 v9, v9, v91
	v_add_f32_e32 v90, v90, v92
	ds_bpermute_b32 v91, v8, v9
	ds_bpermute_b32 v92, v8, v90
	s_waitcnt lgkmcnt(0)
	v_add_f32_e32 v9, v9, v91
	v_add_f32_e32 v90, v90, v92
	v_mul_f32_e32 v93, 0x3a800000, v9
	v_mul_f32_e32 v91, 0x3a800000, v90
	v_fma_f32 v91, -v93, v93, v91
	v_max_f32_e32 v91, 0, v91
	v_add_f32_e32 v91, 0x358637bd, v91
	v_rsq_f32_e32 v94, v91
	v_mul_f32_e32 v91, 0.5, v91
	v_mul_f32_e32 v92, v94, v94
	v_fma_f32 v92, -v91, v92, 0.5
	v_fma_f32 v94, v94, v92, v94
	s_waitcnt vmcnt(21)
	v_sub_f32_e32 v42, v42, v93
	v_sub_f32_e32 v43, v43, v93
	v_sub_f32_e32 v44, v44, v93
	v_sub_f32_e32 v45, v45, v93
	v_sub_f32_e32 v46, v46, v93
	v_sub_f32_e32 v47, v47, v93
	v_sub_f32_e32 v48, v48, v93
	v_sub_f32_e32 v49, v49, v93
	v_sub_f32_e32 v50, v50, v93
	v_sub_f32_e32 v51, v51, v93
	v_sub_f32_e32 v52, v52, v93
	v_sub_f32_e32 v53, v53, v93
	v_sub_f32_e32 v54, v54, v93
	v_sub_f32_e32 v55, v55, v93
	v_sub_f32_e32 v56, v56, v93
	v_sub_f32_e32 v57, v57, v93
	v_add_f32_e32 v130, 1.0, v130
	v_add_f32_e32 v131, 1.0, v131
	v_add_f32_e32 v132, 1.0, v132
	v_add_f32_e32 v133, 1.0, v133
	v_add_f32_e32 v134, 1.0, v134
	v_add_f32_e32 v135, 1.0, v135
	v_add_f32_e32 v136, 1.0, v136
	v_add_f32_e32 v137, 1.0, v137
	v_add_f32_e32 v138, 1.0, v138
	v_add_f32_e32 v139, 1.0, v139
	v_add_f32_e32 v140, 1.0, v140
	v_add_f32_e32 v141, 1.0, v141
	v_add_f32_e32 v142, 1.0, v142
	v_add_f32_e32 v143, 1.0, v143
	v_add_f32_e32 v144, 1.0, v144
	v_add_f32_e32 v145, 1.0, v145
	v_mul_f32_e32 v42, v94, v42
	v_mul_f32_e32 v43, v94, v43
	v_mul_f32_e32 v44, v94, v44
	v_mul_f32_e32 v45, v94, v45
	v_mul_f32_e32 v46, v94, v46
	v_mul_f32_e32 v47, v94, v47
	v_mul_f32_e32 v48, v94, v48
	v_mul_f32_e32 v49, v94, v49
	v_mul_f32_e32 v50, v94, v50
	v_mul_f32_e32 v51, v94, v51
	v_mul_f32_e32 v52, v94, v52
	v_mul_f32_e32 v53, v94, v53
	v_mul_f32_e32 v54, v94, v54
	v_mul_f32_e32 v55, v94, v55
	v_mul_f32_e32 v56, v94, v56
	v_mul_f32_e32 v57, v94, v57
	v_fma_f32 v42, v42, v130, v114
	v_fma_f32 v43, v43, v131, v115
	v_fma_f32 v44, v44, v132, v116
	v_fma_f32 v45, v45, v133, v117
	v_fma_f32 v46, v46, v134, v118
	v_fma_f32 v47, v47, v135, v119
; DI unsigned pk2(float lo, float hi) { f32x2 v = {lo, hi}; bf16x2_t b = __builtin_convertvector(v, bf16x2_t); return __builtin_bit_cast(unsigned, b); }
; DI void ln_row_v(const Frame& F, f32x4 (&v)[4], float* xout, const float* g, const float* b, const float* sh, const float* sc, bf16_t* hout, const float* slab, const float* gres, float* stat = nullptr) {
;     ...
;         float s = 0.f, s2 = 0.f;
; #pragma unroll
;         for (int j = 0; j < 4; ++j) { s += (v[j][0] + v[j][1]) + (v[j][2] + v[j][3]); s2 += (v[j][0] * v[j][0] + v[j][1] * v[j][1]) + (v[j][2] * v[j][2] + v[j][3] * v[j][3]); }
;         wave_sum2(s, s2, F.lane);
;         const float mean = s * (1.f / D); const float rstd = 1.f / sqrtf(fmaxf(s2 * (1.f / D) - mean * mean, 0.f) + EPS);
;         if (stat && F.lane == 0) { f32x2 sv = {mean, rstd}; *(f32x2*)stat = sv; }
; #pragma unroll
;         for (int j = 0; j < 4; ++j) { const f32x4 gg = ((const f32x4*)g)[F.lane + 64 * j], bb = ((const f32x4*)b)[F.lane + 64 * j];
;             v[j] = (v[j] - mean) * rstd * gg + bb; if (xout) ((f32x4*)xout)[F.lane + 64 * j] = v[j]; }
;     }
;     if (hout) {
;         float s = 0.f, s2 = 0.f;
; #pragma unroll
;         for (int j = 0; j < 4; ++j) { s += (v[j][0] + v[j][1]) + (v[j][2] + v[j][3]); s2 += (v[j][0] * v[j][0] + v[j][1] * v[j][1]) + (v[j][2] * v[j][2] + v[j][3] * v[j][3]); }
;         wave_sum2(s, s2, F.lane);
;         const float mean = s * (1.f / D); const float rstd = 1.f / sqrtf(fmaxf(s2 * (1.f / D) - mean * mean, 0.f) + EPS);
; #pragma unroll
;         for (int j = 0; j < 4; ++j) { const f32x4 hh = ((const f32x4*)sh)[F.lane + 64 * j], cc = ((const f32x4*)sc)[F.lane + 64 * j];
;             const f32x4 o = (v[j] - mean) * rstd * (cc + 1.f) + hh; u32x2 wv; wv.x = pk2(o[0], o[1]); wv.y = pk2(o[2], o[3]);
;             ((u32x2*)hout)[F.lane + 64 * j] = wv; }
;     }
	v_fma_f32 v48, v48, v136, v120
	v_fma_f32 v49, v49, v137, v121
	v_fma_f32 v50, v50, v138, v122
	v_fma_f32 v51, v51, v139, v123
	v_fma_f32 v52, v52, v140, v124
	v_fma_f32 v53, v53, v141, v125
	v_fma_f32 v54, v54, v142, v126
	v_fma_f32 v55, v55, v143, v127
	v_fma_f32 v56, v56, v144, v128
	v_fma_f32 v57, v57, v145, v129
	v_cvt_pk_bf16_f32 v190, v42, v43
	v_cvt_pk_bf16_f32 v191, v44, v45
	v_cvt_pk_bf16_f32 v192, v46, v47
	v_cvt_pk_bf16_f32 v193, v48, v49
	v_cvt_pk_bf16_f32 v194, v50, v51
	v_cvt_pk_bf16_f32 v195, v52, v53
	v_cvt_pk_bf16_f32 v196, v54, v55
	v_cvt_pk_bf16_f32 v197, v56, v57
	s_add_u32 s2, s10, 0x0
	s_addc_u32 s3, s11, 0
	global_store_dwordx2 v1, v[190:191], s[2:3]
	global_store_dwordx2 v1, v[192:193], s[2:3] offset:512
	global_store_dwordx2 v1, v[194:195], s[2:3] offset:1024
	global_store_dwordx2 v1, v[196:197], s[2:3] offset:1536
	s_add_u32 s2, s8, 0x2000000
	s_addc_u32 s3, s9, 0
	global_load_dwordx4 v[42:45], v0, s[2:3]
	global_load_dwordx4 v[46:49], v0, s[2:3] offset:1024
	global_load_dwordx4 v[50:53], v0, s[2:3] offset:2048
	global_load_dwordx4 v[54:57], v0, s[2:3] offset:3072
	s_add_u32 s2, s14, 0xc000
	s_addc_u32 s3, s15, 0
	global_load_dwordx4 v[114:117], v0, s[2:3]
	global_load_dwordx4 v[118:121], v0, s[2:3] offset:1024
	global_load_dwordx4 v[122:125], v0, s[2:3] offset:2048
	global_load_dwordx4 v[126:129], v0, s[2:3] offset:3072
	s_add_u32 s2, s18, 0xc000
	s_addc_u32 s3, s19, 0
	global_load_dwordx4 v[130:133], v0, s[2:3]
	global_load_dwordx4 v[134:137], v0, s[2:3] offset:1024
	global_load_dwordx4 v[138:141], v0, s[2:3] offset:2048
	global_load_dwordx4 v[142:145], v0, s[2:3] offset:3072
	s_waitcnt vmcnt(33)
	v_add_f32_e32 v9, v58, v59
	v_add_f32_e32 v91, v60, v61
	v_mul_f32_e32 v90, v58, v58
	v_mul_f32_e32 v92, v59, v59
	v_add_f32_e32 v9, v9, v62
	v_add_f32_e32 v91, v91, v63
	v_add_f32_e32 v9, v9, v64
	v_add_f32_e32 v91, v91, v65
	v_add_f32_e32 v9, v9, v66
	v_add_f32_e32 v91, v91, v67
	v_add_f32_e32 v9, v9, v68
	v_add_f32_e32 v91, v91, v69
	v_add_f32_e32 v9, v9, v70
	v_add_f32_e32 v91, v91, v71
	v_add_f32_e32 v9, v9, v72
	v_add_f32_e32 v91, v91, v73
	v_fmac_f32_e32 v90, v60, v60
	v_fmac_f32_e32 v92, v61, v61
	v_fmac_f32_e32 v90, v62, v62
	v_fmac_f32_e32 v92, v63, v63
	v_fmac_f32_e32 v90, v64, v64
	v_fmac_f32_e32 v92, v65, v65
	v_fmac_f32_e32 v90, v66, v66
	v_fmac_f32_e32 v92, v67, v67
	v_fmac_f32_e32 v90, v68, v68
	v_fmac_f32_e32 v92, v69, v69
	v_fmac_f32_e32 v90, v70, v70
	v_fmac_f32_e32 v92, v71, v71
	v_fmac_f32_e32 v90, v72, v72
	v_fmac_f32_e32 v92, v73, v73
	v_add_f32_e32 v9, v9, v91
	v_add_f32_e32 v90, v90, v92
	ds_bpermute_b32 v91, v3, v9
	ds_bpermute_b32 v92, v3, v90
	s_waitcnt lgkmcnt(0)
	v_add_f32_e32 v9, v9, v91
	v_add_f32_e32 v90, v90, v92
	ds_bpermute_b32 v91, v4, v9
	ds_bpermute_b32 v92, v4, v90
	s_waitcnt lgkmcnt(0)
	v_add_f32_e32 v9, v9, v91
	v_add_f32_e32 v90, v90, v92
	ds_bpermute_b32 v91, v5, v9
	ds_bpermute_b32 v92, v5, v90
	s_waitcnt lgkmcnt(0)
	v_add_f32_e32 v9, v9, v91
	v_add_f32_e32 v90, v90, v92
	ds_bpermute_b32 v91, v6, v9
	ds_bpermute_b32 v92, v6, v90
	s_waitcnt lgkmcnt(0)
	v_add_f32_e32 v9, v9, v91
	v_add_f32_e32 v90, v90, v92
	ds_bpermute_b32 v91, v7, v9
	ds_bpermute_b32 v92, v7, v90
	s_waitcnt lgkmcnt(0)
	v_add_f32_e32 v9, v9, v91
	v_add_f32_e32 v90, v90, v92
	ds_bpermute_b32 v91, v8, v9
	ds_bpermute_b32 v92, v8, v90
	s_waitcnt lgkmcnt(0)
	v_add_f32_e32 v9, v9, v91
	v_add_f32_e32 v90, v90, v92
	v_mul_f32_e32 v93, 0x3a800000, v9
	v_mul_f32_e32 v91, 0x3a800000, v90
	v_fma_f32 v91, -v93, v93, v91
	v_max_f32_e32 v91, 0, v91
	v_add_f32_e32 v91, 0x358637bd, v91
	v_rsq_f32_e32 v94, v91
	v_mul_f32_e32 v91, 0.5, v91
	v_mul_f32_e32 v92, v94, v94
	v_fma_f32 v92, -v91, v92, 0.5
	v_fma_f32 v94, v94, v92, v94
	s_add_u32 s2, s12, 0x4000
	s_addc_u32 s3, s13, 0
	v_mov_b32_e32 v188, v93
	v_mov_b32_e32 v189, v94
	s_mov_b64 exec, 1
	global_store_dwordx2 v97, v[188:189], s[2:3]
	s_mov_b64 exec, -1
	v_sub_f32_e32 v58, v58, v93
	v_sub_f32_e32 v59, v59, v93
	v_sub_f32_e32 v60, v60, v93
	v_sub_f32_e32 v61, v61, v93
	v_sub_f32_e32 v62, v62, v93
	v_sub_f32_e32 v63, v63, v93
	v_sub_f32_e32 v64, v64, v93
	v_sub_f32_e32 v65, v65, v93
	v_sub_f32_e32 v66, v66, v93
	v_sub_f32_e32 v67, v67, v93
	v_sub_f32_e32 v68, v68, v93
	v_sub_f32_e32 v69, v69, v93
	v_sub_f32_e32 v70, v70, v93
	v_sub_f32_e32 v71, v71, v93
	v_sub_f32_e32 v72, v72, v93
	v_sub_f32_e32 v73, v73, v93
	v_mul_f32_e32 v58, v94, v58
	v_mul_f32_e32 v59, v94, v59
	v_mul_f32_e32 v60, v94, v60
	v_mul_f32_e32 v61, v94, v61
	v_mul_f32_e32 v62, v94, v62
	v_mul_f32_e32 v63, v94, v63
	v_mul_f32_e32 v64, v94, v64
	v_mul_f32_e32 v65, v94, v65
	v_mul_f32_e32 v66, v94, v66
	v_mul_f32_e32 v67, v94, v67
	v_mul_f32_e32 v68, v94, v68
	v_mul_f32_e32 v69, v94, v69
	v_mul_f32_e32 v70, v94, v70
	v_mul_f32_e32 v71, v94, v71
	v_mul_f32_e32 v72, v94, v72
	v_mul_f32_e32 v73, v94, v73
	v_fma_f32 v58, v58, v10, v26
	v_fma_f32 v59, v59, v11, v27
	v_fma_f32 v60, v60, v12, v28
	v_fma_f32 v61, v61, v13, v29
	v_fma_f32 v62, v62, v14, v30
	v_fma_f32 v63, v63, v15, v31
	v_fma_f32 v64, v64, v16, v32
	v_fma_f32 v65, v65, v17, v33
	v_fma_f32 v66, v66, v18, v34
	v_fma_f32 v67, v67, v19, v35
	v_fma_f32 v68, v68, v20, v36
	v_fma_f32 v69, v69, v21, v37
	v_fma_f32 v70, v70, v22, v38
	v_fma_f32 v71, v71, v23, v39
	v_fma_f32 v72, v72, v24, v40
	v_fma_f32 v73, v73, v25, v41
	v_add_f32_e32 v9, v58, v59
	v_add_f32_e32 v91, v60, v61
	v_mul_f32_e32 v90, v58, v58
	v_mul_f32_e32 v92, v59, v59
	v_add_f32_e32 v9, v9, v62
	v_add_f32_e32 v91, v91, v63
	v_add_f32_e32 v9, v9, v64
	v_add_f32_e32 v91, v91, v65
	v_add_f32_e32 v9, v9, v66
	v_add_f32_e32 v91, v91, v67
	v_add_f32_e32 v9, v9, v68
	v_add_f32_e32 v91, v91, v69
	v_add_f32_e32 v9, v9, v70
	v_add_f32_e32 v91, v91, v71
	v_add_f32_e32 v9, v9, v72
	v_add_f32_e32 v91, v91, v73
	v_fmac_f32_e32 v90, v60, v60
	v_fmac_f32_e32 v92, v61, v61
	v_fmac_f32_e32 v90, v62, v62
	v_fmac_f32_e32 v92, v63, v63
	v_fmac_f32_e32 v90, v64, v64
	v_fmac_f32_e32 v92, v65, v65
	v_fmac_f32_e32 v90, v66, v66
	v_fmac_f32_e32 v92, v67, v67
	v_fmac_f32_e32 v90, v68, v68
	v_fmac_f32_e32 v92, v69, v69
	v_fmac_f32_e32 v90, v70, v70
	v_fmac_f32_e32 v92, v71, v71
	v_fmac_f32_e32 v90, v72, v72
	v_fmac_f32_e32 v92, v73, v73
	v_add_f32_e32 v9, v9, v91
	v_add_f32_e32 v90, v90, v92
	ds_bpermute_b32 v91, v3, v9
	ds_bpermute_b32 v92, v3, v90
	s_waitcnt lgkmcnt(0)
; DI unsigned pk2(float lo, float hi) { f32x2 v = {lo, hi}; bf16x2_t b = __builtin_convertvector(v, bf16x2_t); return __builtin_bit_cast(unsigned, b); }
; DI void ln_row_v(const Frame& F, f32x4 (&v)[4], float* xout, const float* g, const float* b, const float* sh, const float* sc, bf16_t* hout, const float* slab, const float* gres, float* stat = nullptr) {
;     ...
;         float s = 0.f, s2 = 0.f;
; #pragma unroll
;         for (int j = 0; j < 4; ++j) { s += (v[j][0] + v[j][1]) + (v[j][2] + v[j][3]); s2 += (v[j][0] * v[j][0] + v[j][1] * v[j][1]) + (v[j][2] * v[j][2] + v[j][3] * v[j][3]); }
;         wave_sum2(s, s2, F.lane);
;         const float mean = s * (1.f / D); const float rstd = 1.f / sqrtf(fmaxf(s2 * (1.f / D) - mean * mean, 0.f) + EPS);
;         if (stat && F.lane == 0) { f32x2 sv = {mean, rstd}; *(f32x2*)stat = sv; }
; #pragma unroll
;         for (int j = 0; j < 4; ++j) { const f32x4 gg = ((const f32x4*)g)[F.lane + 64 * j], bb = ((const f32x4*)b)[F.lane + 64 * j];
;             v[j] = (v[j] - mean) * rstd * gg + bb; if (xout) ((f32x4*)xout)[F.lane + 64 * j] = v[j]; }
;     }
;     if (hout) {
;         float s = 0.f, s2 = 0.f;
; #pragma unroll
;         for (int j = 0; j < 4; ++j) { s += (v[j][0] + v[j][1]) + (v[j][2] + v[j][3]); s2 += (v[j][0] * v[j][0] + v[j][1] * v[j][1]) + (v[j][2] * v[j][2] + v[j][3] * v[j][3]); }
;         wave_sum2(s, s2, F.lane);
;         const float mean = s * (1.f / D); const float rstd = 1.f / sqrtf(fmaxf(s2 * (1.f / D) - mean * mean, 0.f) + EPS);
; #pragma unroll
;         for (int j = 0; j < 4; ++j) { const f32x4 hh = ((const f32x4*)sh)[F.lane + 64 * j], cc = ((const f32x4*)sc)[F.lane + 64 * j];
;             const f32x4 o = (v[j] - mean) * rstd * (cc + 1.f) + hh; u32x2 wv; wv.x = pk2(o[0], o[1]); wv.y = pk2(o[2], o[3]);
;             ((u32x2*)hout)[F.lane + 64 * j] = wv; }
;     }
	v_add_f32_e32 v9, v9, v91
	v_add_f32_e32 v90, v90, v92
	ds_bpermute_b32 v91, v4, v9
	ds_bpermute_b32 v92, v4, v90
	s_waitcnt lgkmcnt(0)
	v_add_f32_e32 v9, v9, v91
	v_add_f32_e32 v90, v90, v92
	ds_bpermute_b32 v91, v5, v9
	ds_bpermute_b32 v92, v5, v90
	s_waitcnt lgkmcnt(0)
	v_add_f32_e32 v9, v9, v91
	v_add_f32_e32 v90, v90, v92
	ds_bpermute_b32 v91, v6, v9
	ds_bpermute_b32 v92, v6, v90
	s_waitcnt lgkmcnt(0)
	v_add_f32_e32 v9, v9, v91
	v_add_f32_e32 v90, v90, v92
	ds_bpermute_b32 v91, v7, v9
	ds_bpermute_b32 v92, v7, v90
	s_waitcnt lgkmcnt(0)
	v_add_f32_e32 v9, v9, v91
	v_add_f32_e32 v90, v90, v92
	ds_bpermute_b32 v91, v8, v9
	ds_bpermute_b32 v92, v8, v90
	s_waitcnt lgkmcnt(0)
	v_add_f32_e32 v9, v9, v91
	v_add_f32_e32 v90, v90, v92
	v_mul_f32_e32 v93, 0x3a800000, v9
	v_mul_f32_e32 v91, 0x3a800000, v90
	v_fma_f32 v91, -v93, v93, v91
	v_max_f32_e32 v91, 0, v91
	v_add_f32_e32 v91, 0x358637bd, v91
	v_rsq_f32_e32 v94, v91
	v_mul_f32_e32 v91, 0.5, v91
	v_mul_f32_e32 v92, v94, v94
	v_fma_f32 v92, -v91, v92, 0.5
	v_fma_f32 v94, v94, v92, v94
	s_waitcnt vmcnt(26)
	v_sub_f32_e32 v58, v58, v93
	v_sub_f32_e32 v59, v59, v93
	v_sub_f32_e32 v60, v60, v93
	v_sub_f32_e32 v61, v61, v93
	v_sub_f32_e32 v62, v62, v93
	v_sub_f32_e32 v63, v63, v93
	v_sub_f32_e32 v64, v64, v93
	v_sub_f32_e32 v65, v65, v93
	v_sub_f32_e32 v66, v66, v93
	v_sub_f32_e32 v67, v67, v93
	v_sub_f32_e32 v68, v68, v93
	v_sub_f32_e32 v69, v69, v93
	v_sub_f32_e32 v70, v70, v93
	v_sub_f32_e32 v71, v71, v93
	v_sub_f32_e32 v72, v72, v93
	v_sub_f32_e32 v73, v73, v93
	v_add_f32_e32 v162, 1.0, v162
	v_add_f32_e32 v163, 1.0, v163
	v_add_f32_e32 v164, 1.0, v164
	v_add_f32_e32 v165, 1.0, v165
	v_add_f32_e32 v166, 1.0, v166
	v_add_f32_e32 v167, 1.0, v167
	v_add_f32_e32 v168, 1.0, v168
	v_add_f32_e32 v169, 1.0, v169
	v_add_f32_e32 v170, 1.0, v170
	v_add_f32_e32 v171, 1.0, v171
	v_add_f32_e32 v172, 1.0, v172
	v_add_f32_e32 v173, 1.0, v173
	v_add_f32_e32 v174, 1.0, v174
	v_add_f32_e32 v175, 1.0, v175
	v_add_f32_e32 v176, 1.0, v176
	v_add_f32_e32 v177, 1.0, v177
	v_mul_f32_e32 v58, v94, v58
	v_mul_f32_e32 v59, v94, v59
	v_mul_f32_e32 v60, v94, v60
	v_mul_f32_e32 v61, v94, v61
	v_mul_f32_e32 v62, v94, v62
	v_mul_f32_e32 v63, v94, v63
	v_mul_f32_e32 v64, v94, v64
	v_mul_f32_e32 v65, v94, v65
	v_mul_f32_e32 v66, v94, v66
	v_mul_f32_e32 v67, v94, v67
	v_mul_f32_e32 v68, v94, v68
	v_mul_f32_e32 v69, v94, v69
	v_mul_f32_e32 v70, v94, v70
	v_mul_f32_e32 v71, v94, v71
	v_mul_f32_e32 v72, v94, v72
	v_mul_f32_e32 v73, v94, v73
	v_fma_f32 v58, v58, v162, v146
	v_fma_f32 v59, v59, v163, v147
	v_fma_f32 v60, v60, v164, v148
	v_fma_f32 v61, v61, v165, v149
	v_fma_f32 v62, v62, v166, v150
	v_fma_f32 v63, v63, v167, v151
	v_fma_f32 v64, v64, v168, v152
	v_fma_f32 v65, v65, v169, v153
	v_fma_f32 v66, v66, v170, v154
	v_fma_f32 v67, v67, v171, v155
	v_fma_f32 v68, v68, v172, v156
	v_fma_f32 v69, v69, v173, v157
	v_fma_f32 v70, v70, v174, v158
	v_fma_f32 v71, v71, v175, v159
	v_fma_f32 v72, v72, v176, v160
	v_fma_f32 v73, v73, v177, v161
	v_cvt_pk_bf16_f32 v190, v58, v59
	v_cvt_pk_bf16_f32 v191, v60, v61
	v_cvt_pk_bf16_f32 v192, v62, v63
	v_cvt_pk_bf16_f32 v193, v64, v65
	v_cvt_pk_bf16_f32 v194, v66, v67
	v_cvt_pk_bf16_f32 v195, v68, v69
	v_cvt_pk_bf16_f32 v196, v70, v71
	v_cvt_pk_bf16_f32 v197, v72, v73
	s_add_u32 s2, s10, 0x400000
	s_addc_u32 s3, s11, 0
	global_store_dwordx2 v1, v[190:191], s[2:3]
	global_store_dwordx2 v1, v[192:193], s[2:3] offset:512
	global_store_dwordx2 v1, v[194:195], s[2:3] offset:1024
	global_store_dwordx2 v1, v[196:197], s[2:3] offset:1536
	s_add_u32 s2, s8, 0x2800000
	s_addc_u32 s3, s9, 0
	global_load_dwordx4 v[58:61], v0, s[2:3]
	global_load_dwordx4 v[62:65], v0, s[2:3] offset:1024
	global_load_dwordx4 v[66:69], v0, s[2:3] offset:2048
	global_load_dwordx4 v[70:73], v0, s[2:3] offset:3072
	s_add_u32 s2, s14, 0x12000
	s_addc_u32 s3, s15, 0
	global_load_dwordx4 v[146:149], v0, s[2:3]
	global_load_dwordx4 v[150:153], v0, s[2:3] offset:1024
	global_load_dwordx4 v[154:157], v0, s[2:3] offset:2048
	global_load_dwordx4 v[158:161], v0, s[2:3] offset:3072
	s_add_u32 s2, s18, 0x12000
	s_addc_u32 s3, s19, 0
	global_load_dwordx4 v[162:165], v0, s[2:3]
	global_load_dwordx4 v[166:169], v0, s[2:3] offset:1024
	global_load_dwordx4 v[170:173], v0, s[2:3] offset:2048
	global_load_dwordx4 v[174:177], v0, s[2:3] offset:3072
	s_waitcnt vmcnt(38)
	v_add_f32_e32 v9, v74, v75
	v_add_f32_e32 v91, v76, v77
	v_mul_f32_e32 v90, v74, v74
	v_mul_f32_e32 v92, v75, v75
	v_add_f32_e32 v9, v9, v78
	v_add_f32_e32 v91, v91, v79
	v_add_f32_e32 v9, v9, v80
	v_add_f32_e32 v91, v91, v81
	v_add_f32_e32 v9, v9, v82
	v_add_f32_e32 v91, v91, v83
	v_add_f32_e32 v9, v9, v84
	v_add_f32_e32 v91, v91, v85
	v_add_f32_e32 v9, v9, v86
	v_add_f32_e32 v91, v91, v87
	v_add_f32_e32 v9, v9, v88
	v_add_f32_e32 v91, v91, v89
	v_fmac_f32_e32 v90, v76, v76
	v_fmac_f32_e32 v92, v77, v77
	v_fmac_f32_e32 v90, v78, v78
	v_fmac_f32_e32 v92, v79, v79
	v_fmac_f32_e32 v90, v80, v80
	v_fmac_f32_e32 v92, v81, v81
	v_fmac_f32_e32 v90, v82, v82
	v_fmac_f32_e32 v92, v83, v83
	v_fmac_f32_e32 v90, v84, v84
	v_fmac_f32_e32 v92, v85, v85
	v_fmac_f32_e32 v90, v86, v86
	v_fmac_f32_e32 v92, v87, v87
	v_fmac_f32_e32 v90, v88, v88
	v_fmac_f32_e32 v92, v89, v89
	v_add_f32_e32 v9, v9, v91
	v_add_f32_e32 v90, v90, v92
	ds_bpermute_b32 v91, v3, v9
	ds_bpermute_b32 v92, v3, v90
	s_waitcnt lgkmcnt(0)
	v_add_f32_e32 v9, v9, v91
	v_add_f32_e32 v90, v90, v92
	ds_bpermute_b32 v91, v4, v9
	ds_bpermute_b32 v92, v4, v90
	s_waitcnt lgkmcnt(0)
	v_add_f32_e32 v9, v9, v91
	v_add_f32_e32 v90, v90, v92
	ds_bpermute_b32 v91, v5, v9
	ds_bpermute_b32 v92, v5, v90
	s_waitcnt lgkmcnt(0)
; DI void ln_row_v(const Frame& F, f32x4 (&v)[4], float* xout, const float* g, const float* b, const float* sh, const float* sc, bf16_t* hout, const float* slab, const float* gres, float* stat = nullptr) {
;     ...
;         float s = 0.f, s2 = 0.f;
; #pragma unroll
;         for (int j = 0; j < 4; ++j) { s += (v[j][0] + v[j][1]) + (v[j][2] + v[j][3]); s2 += (v[j][0] * v[j][0] + v[j][1] * v[j][1]) + (v[j][2] * v[j][2] + v[j][3] * v[j][3]); }
;         wave_sum2(s, s2, F.lane);
;         const float mean = s * (1.f / D); const float rstd = 1.f / sqrtf(fmaxf(s2 * (1.f / D) - mean * mean, 0.f) + EPS);
;         if (stat && F.lane == 0) { f32x2 sv = {mean, rstd}; *(f32x2*)stat = sv; }
; #pragma unroll
;         for (int j = 0; j < 4; ++j) { const f32x4 gg = ((const f32x4*)g)[F.lane + 64 * j], bb = ((const f32x4*)b)[F.lane + 64 * j];
;             v[j] = (v[j] - mean) * rstd * gg + bb; if (xout) ((f32x4*)xout)[F.lane + 64 * j] = v[j]; }
	v_add_f32_e32 v9, v9, v91
	v_add_f32_e32 v90, v90, v92
	ds_bpermute_b32 v91, v6, v9
	ds_bpermute_b32 v92, v6, v90
	s_waitcnt lgkmcnt(0)
	v_add_f32_e32 v9, v9, v91
	v_add_f32_e32 v90, v90, v92
	ds_bpermute_b32 v91, v7, v9
	ds_bpermute_b32 v92, v7, v90
	s_waitcnt lgkmcnt(0)
	v_add_f32_e32 v9, v9, v91
	v_add_f32_e32 v90, v90, v92
	ds_bpermute_b32 v91, v8, v9
	ds_bpermute_b32 v92, v8, v90
	s_waitcnt lgkmcnt(0)
	v_add_f32_e32 v9, v9, v91
	v_add_f32_e32 v90, v90, v92
	v_mul_f32_e32 v93, 0x3a800000, v9
	v_mul_f32_e32 v91, 0x3a800000, v90
	v_fma_f32 v91, -v93, v93, v91
	v_max_f32_e32 v91, 0, v91
	v_add_f32_e32 v91, 0x358637bd, v91
	v_rsq_f32_e32 v94, v91
	v_mul_f32_e32 v91, 0.5, v91
	v_mul_f32_e32 v92, v94, v94
	v_fma_f32 v92, -v91, v92, 0.5
	v_fma_f32 v94, v94, v92, v94
	s_add_u32 s2, s12, 0x8000
	s_addc_u32 s3, s13, 0
	v_mov_b32_e32 v188, v93
	v_mov_b32_e32 v189, v94
	s_mov_b64 exec, 1
	global_store_dwordx2 v97, v[188:189], s[2:3]
	s_mov_b64 exec, -1
	v_sub_f32_e32 v74, v74, v93
	v_sub_f32_e32 v75, v75, v93
	v_sub_f32_e32 v76, v76, v93
	v_sub_f32_e32 v77, v77, v93
	v_sub_f32_e32 v78, v78, v93
	v_sub_f32_e32 v79, v79, v93
	v_sub_f32_e32 v80, v80, v93
	v_sub_f32_e32 v81, v81, v93
	v_sub_f32_e32 v82, v82, v93
	v_sub_f32_e32 v83, v83, v93
	v_sub_f32_e32 v84, v84, v93
	v_sub_f32_e32 v85, v85, v93
	v_sub_f32_e32 v86, v86, v93
	v_sub_f32_e32 v87, v87, v93
	v_sub_f32_e32 v88, v88, v93
	v_sub_f32_e32 v89, v89, v93
	v_mul_f32_e32 v74, v94, v74
	v_mul_f32_e32 v75, v94, v75
	v_mul_f32_e32 v76, v94, v76
	v_mul_f32_e32 v77, v94, v77
	v_mul_f32_e32 v78, v94, v78
	v_mul_f32_e32 v79, v94, v79
	v_mul_f32_e32 v80, v94, v80
	v_mul_f32_e32 v81, v94, v81
	v_mul_f32_e32 v82, v94, v82
	v_mul_f32_e32 v83, v94, v83
	v_mul_f32_e32 v84, v94, v84
	v_mul_f32_e32 v85, v94, v85
	v_mul_f32_e32 v86, v94, v86
	v_mul_f32_e32 v87, v94, v87
	v_mul_f32_e32 v88, v94, v88
	v_mul_f32_e32 v89, v94, v89
	v_fma_f32 v74, v74, v10, v26
	v_fma_f32 v75, v75, v11, v27
	v_fma_f32 v76, v76, v12, v28
	v_fma_f32 v77, v77, v13, v29
	v_fma_f32 v78, v78, v14, v30
	v_fma_f32 v79, v79, v15, v31
	v_fma_f32 v80, v80, v16, v32
	v_fma_f32 v81, v81, v17, v33
	v_fma_f32 v82, v82, v18, v34
	v_fma_f32 v83, v83, v19, v35
	v_fma_f32 v84, v84, v20, v36
	v_fma_f32 v85, v85, v21, v37
	v_fma_f32 v86, v86, v22, v38
	v_fma_f32 v87, v87, v23, v39
	v_fma_f32 v88, v88, v24, v40
	v_fma_f32 v89, v89, v25, v41
	v_add_f32_e32 v9, v74, v75
	v_add_f32_e32 v91, v76, v77
	v_mul_f32_e32 v90, v74, v74
	v_mul_f32_e32 v92, v75, v75
	v_add_f32_e32 v9, v9, v78
	v_add_f32_e32 v91, v91, v79
	v_add_f32_e32 v9, v9, v80
	v_add_f32_e32 v91, v91, v81
	v_add_f32_e32 v9, v9, v82
	v_add_f32_e32 v91, v91, v83
	v_add_f32_e32 v9, v9, v84
	v_add_f32_e32 v91, v91, v85
	v_add_f32_e32 v9, v9, v86
	v_add_f32_e32 v91, v91, v87
	v_add_f32_e32 v9, v9, v88
	v_add_f32_e32 v91, v91, v89
	v_fmac_f32_e32 v90, v76, v76
	v_fmac_f32_e32 v92, v77, v77
	v_fmac_f32_e32 v90, v78, v78
	v_fmac_f32_e32 v92, v79, v79
	v_fmac_f32_e32 v90, v80, v80
	v_fmac_f32_e32 v92, v81, v81
	v_fmac_f32_e32 v90, v82, v82
	v_fmac_f32_e32 v92, v83, v83
	v_fmac_f32_e32 v90, v84, v84
	v_fmac_f32_e32 v92, v85, v85
	v_fmac_f32_e32 v90, v86, v86
	v_fmac_f32_e32 v92, v87, v87
	v_fmac_f32_e32 v90, v88, v88
	v_fmac_f32_e32 v92, v89, v89
	v_add_f32_e32 v9, v9, v91
	v_add_f32_e32 v90, v90, v92
	ds_bpermute_b32 v91, v3, v9
	ds_bpermute_b32 v92, v3, v90
	s_waitcnt lgkmcnt(0)
	v_add_f32_e32 v9, v9, v91
	v_add_f32_e32 v90, v90, v92
	ds_bpermute_b32 v91, v4, v9
	ds_bpermute_b32 v92, v4, v90
	s_waitcnt lgkmcnt(0)
	v_add_f32_e32 v9, v9, v91
	v_add_f32_e32 v90, v90, v92
	ds_bpermute_b32 v91, v5, v9
	ds_bpermute_b32 v92, v5, v90
	s_waitcnt lgkmcnt(0)
	v_add_f32_e32 v9, v9, v91
	v_add_f32_e32 v90, v90, v92
	ds_bpermute_b32 v91, v6, v9
	ds_bpermute_b32 v92, v6, v90
	s_waitcnt lgkmcnt(0)
	v_add_f32_e32 v9, v9, v91
	v_add_f32_e32 v90, v90, v92
	ds_bpermute_b32 v91, v7, v9
	ds_bpermute_b32 v92, v7, v90
	s_waitcnt lgkmcnt(0)
	v_add_f32_e32 v9, v9, v91
	v_add_f32_e32 v90, v90, v92
	ds_bpermute_b32 v91, v8, v9
	ds_bpermute_b32 v92, v8, v90
	s_waitcnt lgkmcnt(0)
	v_add_f32_e32 v9, v9, v91
	v_add_f32_e32 v90, v90, v92
	v_mul_f32_e32 v93, 0x3a800000, v9
	v_mul_f32_e32 v91, 0x3a800000, v90
	v_fma_f32 v91, -v93, v93, v91
	v_max_f32_e32 v91, 0, v91
	v_add_f32_e32 v91, 0x358637bd, v91
	v_rsq_f32_e32 v94, v91
	v_mul_f32_e32 v91, 0.5, v91
	v_mul_f32_e32 v92, v94, v94
	v_fma_f32 v92, -v91, v92, 0.5
	v_fma_f32 v94, v94, v92, v94
	s_waitcnt vmcnt(18)
; DI unsigned pk2(float lo, float hi) { f32x2 v = {lo, hi}; bf16x2_t b = __builtin_convertvector(v, bf16x2_t); return __builtin_bit_cast(unsigned, b); }
; DI void ln_row_v(const Frame& F, f32x4 (&v)[4], float* xout, const float* g, const float* b, const float* sh, const float* sc, bf16_t* hout, const float* slab, const float* gres, float* stat = nullptr) {
;     ...
;         float s = 0.f, s2 = 0.f;
; #pragma unroll
;         for (int j = 0; j < 4; ++j) { s += (v[j][0] + v[j][1]) + (v[j][2] + v[j][3]); s2 += (v[j][0] * v[j][0] + v[j][1] * v[j][1]) + (v[j][2] * v[j][2] + v[j][3] * v[j][3]); }
;         wave_sum2(s, s2, F.lane);
;         const float mean = s * (1.f / D); const float rstd = 1.f / sqrtf(fmaxf(s2 * (1.f / D) - mean * mean, 0.f) + EPS);
;         if (stat && F.lane == 0) { f32x2 sv = {mean, rstd}; *(f32x2*)stat = sv; }
; #pragma unroll
;         for (int j = 0; j < 4; ++j) { const f32x4 gg = ((const f32x4*)g)[F.lane + 64 * j], bb = ((const f32x4*)b)[F.lane + 64 * j];
;             v[j] = (v[j] - mean) * rstd * gg + bb; if (xout) ((f32x4*)xout)[F.lane + 64 * j] = v[j]; }
;     }
;     if (hout) {
;         float s = 0.f, s2 = 0.f;
; #pragma unroll
;         for (int j = 0; j < 4; ++j) { s += (v[j][0] + v[j][1]) + (v[j][2] + v[j][3]); s2 += (v[j][0] * v[j][0] + v[j][1] * v[j][1]) + (v[j][2] * v[j][2] + v[j][3] * v[j][3]); }
;         wave_sum2(s, s2, F.lane);
;         const float mean = s * (1.f / D); const float rstd = 1.f / sqrtf(fmaxf(s2 * (1.f / D) - mean * mean, 0.f) + EPS);
; #pragma unroll
;         for (int j = 0; j < 4; ++j) { const f32x4 hh = ((const f32x4*)sh)[F.lane + 64 * j], cc = ((const f32x4*)sc)[F.lane + 64 * j];
;             const f32x4 o = (v[j] - mean) * rstd * (cc + 1.f) + hh; u32x2 wv; wv.x = pk2(o[0], o[1]); wv.y = pk2(o[2], o[3]);
;             ((u32x2*)hout)[F.lane + 64 * j] = wv; }
;     }
	v_sub_f32_e32 v74, v74, v93
	v_sub_f32_e32 v75, v75, v93
	v_sub_f32_e32 v76, v76, v93
	v_sub_f32_e32 v77, v77, v93
	v_sub_f32_e32 v78, v78, v93
	v_sub_f32_e32 v79, v79, v93
	v_sub_f32_e32 v80, v80, v93
	v_sub_f32_e32 v81, v81, v93
	v_sub_f32_e32 v82, v82, v93
	v_sub_f32_e32 v83, v83, v93
	v_sub_f32_e32 v84, v84, v93
	v_sub_f32_e32 v85, v85, v93
	v_sub_f32_e32 v86, v86, v93
	v_sub_f32_e32 v87, v87, v93
	v_sub_f32_e32 v88, v88, v93
	v_sub_f32_e32 v89, v89, v93
	v_add_f32_e32 v130, 1.0, v130
	v_add_f32_e32 v131, 1.0, v131
	v_add_f32_e32 v132, 1.0, v132
	v_add_f32_e32 v133, 1.0, v133
	v_add_f32_e32 v134, 1.0, v134
	v_add_f32_e32 v135, 1.0, v135
	v_add_f32_e32 v136, 1.0, v136
	v_add_f32_e32 v137, 1.0, v137
	v_add_f32_e32 v138, 1.0, v138
	v_add_f32_e32 v139, 1.0, v139
	v_add_f32_e32 v140, 1.0, v140
	v_add_f32_e32 v141, 1.0, v141
	v_add_f32_e32 v142, 1.0, v142
	v_add_f32_e32 v143, 1.0, v143
	v_add_f32_e32 v144, 1.0, v144
	v_add_f32_e32 v145, 1.0, v145
	v_mul_f32_e32 v74, v94, v74
	v_mul_f32_e32 v75, v94, v75
	v_mul_f32_e32 v76, v94, v76
	v_mul_f32_e32 v77, v94, v77
	v_mul_f32_e32 v78, v94, v78
	v_mul_f32_e32 v79, v94, v79
	v_mul_f32_e32 v80, v94, v80
	v_mul_f32_e32 v81, v94, v81
	v_mul_f32_e32 v82, v94, v82
	v_mul_f32_e32 v83, v94, v83
	v_mul_f32_e32 v84, v94, v84
	v_mul_f32_e32 v85, v94, v85
	v_mul_f32_e32 v86, v94, v86
	v_mul_f32_e32 v87, v94, v87
	v_mul_f32_e32 v88, v94, v88
	v_mul_f32_e32 v89, v94, v89
	v_fma_f32 v74, v74, v130, v114
	v_fma_f32 v75, v75, v131, v115
	v_fma_f32 v76, v76, v132, v116
	v_fma_f32 v77, v77, v133, v117
	v_fma_f32 v78, v78, v134, v118
	v_fma_f32 v79, v79, v135, v119
	v_fma_f32 v80, v80, v136, v120
	v_fma_f32 v81, v81, v137, v121
	v_fma_f32 v82, v82, v138, v122
	v_fma_f32 v83, v83, v139, v123
	v_fma_f32 v84, v84, v140, v124
	v_fma_f32 v85, v85, v141, v125
	v_fma_f32 v86, v86, v142, v126
	v_fma_f32 v87, v87, v143, v127
	v_fma_f32 v88, v88, v144, v128
	v_fma_f32 v89, v89, v145, v129
	v_cvt_pk_bf16_f32 v190, v74, v75
	v_cvt_pk_bf16_f32 v191, v76, v77
	v_cvt_pk_bf16_f32 v192, v78, v79
	v_cvt_pk_bf16_f32 v193, v80, v81
	v_cvt_pk_bf16_f32 v194, v82, v83
	v_cvt_pk_bf16_f32 v195, v84, v85
	v_cvt_pk_bf16_f32 v196, v86, v87
	v_cvt_pk_bf16_f32 v197, v88, v89
	s_add_u32 s2, s10, 0x800000
	s_addc_u32 s3, s11, 0
	global_store_dwordx2 v1, v[190:191], s[2:3]
	global_store_dwordx2 v1, v[192:193], s[2:3] offset:512
	global_store_dwordx2 v1, v[194:195], s[2:3] offset:1024
	global_store_dwordx2 v1, v[196:197], s[2:3] offset:1536
	s_add_u32 s2, s8, 0x3000000
	s_addc_u32 s3, s9, 0
	global_load_dwordx4 v[74:77], v0, s[2:3]
	global_load_dwordx4 v[78:81], v0, s[2:3] offset:1024
	global_load_dwordx4 v[82:85], v0, s[2:3] offset:2048
	global_load_dwordx4 v[86:89], v0, s[2:3] offset:3072
	s_add_u32 s2, s14, 0x18000
	s_addc_u32 s3, s15, 0
	global_load_dwordx4 v[114:117], v0, s[2:3]
	global_load_dwordx4 v[118:121], v0, s[2:3] offset:1024
	global_load_dwordx4 v[122:125], v0, s[2:3] offset:2048
	global_load_dwordx4 v[126:129], v0, s[2:3] offset:3072
	s_add_u32 s2, s18, 0x18000
	s_addc_u32 s3, s19, 0
	global_load_dwordx4 v[130:133], v0, s[2:3]
	global_load_dwordx4 v[134:137], v0, s[2:3] offset:1024
	global_load_dwordx4 v[138:141], v0, s[2:3] offset:2048
	global_load_dwordx4 v[142:145], v0, s[2:3] offset:3072
	v_add_f32_e32 v9, v98, v99
	v_add_f32_e32 v91, v100, v101
	v_mul_f32_e32 v90, v98, v98
	v_mul_f32_e32 v92, v99, v99
	v_add_f32_e32 v9, v9, v102
	v_add_f32_e32 v91, v91, v103
	v_add_f32_e32 v9, v9, v104
	v_add_f32_e32 v91, v91, v105
	v_add_f32_e32 v9, v9, v106
	v_add_f32_e32 v91, v91, v107
	v_add_f32_e32 v9, v9, v108
	v_add_f32_e32 v91, v91, v109
	v_add_f32_e32 v9, v9, v110
	v_add_f32_e32 v91, v91, v111
	v_add_f32_e32 v9, v9, v112
	v_add_f32_e32 v91, v91, v113
	v_fmac_f32_e32 v90, v100, v100
	v_fmac_f32_e32 v92, v101, v101
	v_fmac_f32_e32 v90, v102, v102
	v_fmac_f32_e32 v92, v103, v103
	v_fmac_f32_e32 v90, v104, v104
	v_fmac_f32_e32 v92, v105, v105
	v_fmac_f32_e32 v90, v106, v106
	v_fmac_f32_e32 v92, v107, v107
	v_fmac_f32_e32 v90, v108, v108
	v_fmac_f32_e32 v92, v109, v109
	v_fmac_f32_e32 v90, v110, v110
	v_fmac_f32_e32 v92, v111, v111
	v_fmac_f32_e32 v90, v112, v112
	v_fmac_f32_e32 v92, v113, v113
	v_add_f32_e32 v9, v9, v91
	v_add_f32_e32 v90, v90, v92
	ds_bpermute_b32 v91, v3, v9
	ds_bpermute_b32 v92, v3, v90
	s_waitcnt lgkmcnt(0)
	v_add_f32_e32 v9, v9, v91
	v_add_f32_e32 v90, v90, v92
	ds_bpermute_b32 v91, v4, v9
	ds_bpermute_b32 v92, v4, v90
	s_waitcnt lgkmcnt(0)
	v_add_f32_e32 v9, v9, v91
	v_add_f32_e32 v90, v90, v92
	ds_bpermute_b32 v91, v5, v9
	ds_bpermute_b32 v92, v5, v90
	s_waitcnt lgkmcnt(0)
	v_add_f32_e32 v9, v9, v91
	v_add_f32_e32 v90, v90, v92
	ds_bpermute_b32 v91, v6, v9
	ds_bpermute_b32 v92, v6, v90
	s_waitcnt lgkmcnt(0)
	v_add_f32_e32 v9, v9, v91
	v_add_f32_e32 v90, v90, v92
	ds_bpermute_b32 v91, v7, v9
	ds_bpermute_b32 v92, v7, v90
	s_waitcnt lgkmcnt(0)
	v_add_f32_e32 v9, v9, v91
	v_add_f32_e32 v90, v90, v92
	ds_bpermute_b32 v91, v8, v9
	ds_bpermute_b32 v92, v8, v90
	s_waitcnt lgkmcnt(0)
; DI unsigned pk2(float lo, float hi) { f32x2 v = {lo, hi}; bf16x2_t b = __builtin_convertvector(v, bf16x2_t); return __builtin_bit_cast(unsigned, b); }
; DI void ln_row_v(const Frame& F, f32x4 (&v)[4], float* xout, const float* g, const float* b, const float* sh, const float* sc, bf16_t* hout, const float* slab, const float* gres, float* stat = nullptr) {
;     ...
;         float s = 0.f, s2 = 0.f;
; #pragma unroll
;         for (int j = 0; j < 4; ++j) { s += (v[j][0] + v[j][1]) + (v[j][2] + v[j][3]); s2 += (v[j][0] * v[j][0] + v[j][1] * v[j][1]) + (v[j][2] * v[j][2] + v[j][3] * v[j][3]); }
;         wave_sum2(s, s2, F.lane);
;         const float mean = s * (1.f / D); const float rstd = 1.f / sqrtf(fmaxf(s2 * (1.f / D) - mean * mean, 0.f) + EPS);
;         if (stat && F.lane == 0) { f32x2 sv = {mean, rstd}; *(f32x2*)stat = sv; }
; #pragma unroll
;         for (int j = 0; j < 4; ++j) { const f32x4 gg = ((const f32x4*)g)[F.lane + 64 * j], bb = ((const f32x4*)b)[F.lane + 64 * j];
;             v[j] = (v[j] - mean) * rstd * gg + bb; if (xout) ((f32x4*)xout)[F.lane + 64 * j] = v[j]; }
;     }
;     if (hout) {
;         float s = 0.f, s2 = 0.f;
; #pragma unroll
;         for (int j = 0; j < 4; ++j) { s += (v[j][0] + v[j][1]) + (v[j][2] + v[j][3]); s2 += (v[j][0] * v[j][0] + v[j][1] * v[j][1]) + (v[j][2] * v[j][2] + v[j][3] * v[j][3]); }
;         wave_sum2(s, s2, F.lane);
;         const float mean = s * (1.f / D); const float rstd = 1.f / sqrtf(fmaxf(s2 * (1.f / D) - mean * mean, 0.f) + EPS);
; #pragma unroll
;         for (int j = 0; j < 4; ++j) { const f32x4 hh = ((const f32x4*)sh)[F.lane + 64 * j], cc = ((const f32x4*)sc)[F.lane + 64 * j];
;             const f32x4 o = (v[j] - mean) * rstd * (cc + 1.f) + hh; u32x2 wv; wv.x = pk2(o[0], o[1]); wv.y = pk2(o[2], o[3]);
;             ((u32x2*)hout)[F.lane + 64 * j] = wv; }
;     }
	v_add_f32_e32 v9, v9, v91
	v_add_f32_e32 v90, v90, v92
	v_mul_f32_e32 v93, 0x3a800000, v9
	v_mul_f32_e32 v91, 0x3a800000, v90
	v_fma_f32 v91, -v93, v93, v91
	v_max_f32_e32 v91, 0, v91
	v_add_f32_e32 v91, 0x358637bd, v91
	v_rsq_f32_e32 v94, v91
	v_mul_f32_e32 v91, 0.5, v91
	v_mul_f32_e32 v92, v94, v94
	v_fma_f32 v92, -v91, v92, 0.5
	v_fma_f32 v94, v94, v92, v94
	s_add_u32 s2, s12, 0xc000
	s_addc_u32 s3, s13, 0
	v_mov_b32_e32 v188, v93
	v_mov_b32_e32 v189, v94
	s_mov_b64 exec, 1
	global_store_dwordx2 v97, v[188:189], s[2:3]
	s_mov_b64 exec, -1
	v_sub_f32_e32 v98, v98, v93
	v_sub_f32_e32 v99, v99, v93
	v_sub_f32_e32 v100, v100, v93
	v_sub_f32_e32 v101, v101, v93
	v_sub_f32_e32 v102, v102, v93
	v_sub_f32_e32 v103, v103, v93
	v_sub_f32_e32 v104, v104, v93
	v_sub_f32_e32 v105, v105, v93
	v_sub_f32_e32 v106, v106, v93
	v_sub_f32_e32 v107, v107, v93
	v_sub_f32_e32 v108, v108, v93
	v_sub_f32_e32 v109, v109, v93
	v_sub_f32_e32 v110, v110, v93
	v_sub_f32_e32 v111, v111, v93
	v_sub_f32_e32 v112, v112, v93
	v_sub_f32_e32 v113, v113, v93
	v_mul_f32_e32 v98, v94, v98
	v_mul_f32_e32 v99, v94, v99
	v_mul_f32_e32 v100, v94, v100
	v_mul_f32_e32 v101, v94, v101
	v_mul_f32_e32 v102, v94, v102
	v_mul_f32_e32 v103, v94, v103
	v_mul_f32_e32 v104, v94, v104
	v_mul_f32_e32 v105, v94, v105
	v_mul_f32_e32 v106, v94, v106
	v_mul_f32_e32 v107, v94, v107
	v_mul_f32_e32 v108, v94, v108
	v_mul_f32_e32 v109, v94, v109
	v_mul_f32_e32 v110, v94, v110
	v_mul_f32_e32 v111, v94, v111
	v_mul_f32_e32 v112, v94, v112
	v_mul_f32_e32 v113, v94, v113
	v_fma_f32 v98, v98, v10, v26
	v_fma_f32 v99, v99, v11, v27
	v_fma_f32 v100, v100, v12, v28
	v_fma_f32 v101, v101, v13, v29
	v_fma_f32 v102, v102, v14, v30
	v_fma_f32 v103, v103, v15, v31
	v_fma_f32 v104, v104, v16, v32
	v_fma_f32 v105, v105, v17, v33
	v_fma_f32 v106, v106, v18, v34
	v_fma_f32 v107, v107, v19, v35
	v_fma_f32 v108, v108, v20, v36
	v_fma_f32 v109, v109, v21, v37
	v_fma_f32 v110, v110, v22, v38
	v_fma_f32 v111, v111, v23, v39
	v_fma_f32 v112, v112, v24, v40
	v_fma_f32 v113, v113, v25, v41
	v_add_f32_e32 v9, v98, v99
	v_add_f32_e32 v91, v100, v101
	v_mul_f32_e32 v90, v98, v98
	v_mul_f32_e32 v92, v99, v99
	v_add_f32_e32 v9, v9, v102
	v_add_f32_e32 v91, v91, v103
	v_add_f32_e32 v9, v9, v104
	v_add_f32_e32 v91, v91, v105
	v_add_f32_e32 v9, v9, v106
	v_add_f32_e32 v91, v91, v107
	v_add_f32_e32 v9, v9, v108
	v_add_f32_e32 v91, v91, v109
	v_add_f32_e32 v9, v9, v110
	v_add_f32_e32 v91, v91, v111
	v_add_f32_e32 v9, v9, v112
	v_add_f32_e32 v91, v91, v113
	v_fmac_f32_e32 v90, v100, v100
	v_fmac_f32_e32 v92, v101, v101
	v_fmac_f32_e32 v90, v102, v102
	v_fmac_f32_e32 v92, v103, v103
	v_fmac_f32_e32 v90, v104, v104
	v_fmac_f32_e32 v92, v105, v105
	v_fmac_f32_e32 v90, v106, v106
	v_fmac_f32_e32 v92, v107, v107
	v_fmac_f32_e32 v90, v108, v108
	v_fmac_f32_e32 v92, v109, v109
	v_fmac_f32_e32 v90, v110, v110
	v_fmac_f32_e32 v92, v111, v111
	v_fmac_f32_e32 v90, v112, v112
	v_fmac_f32_e32 v92, v113, v113
	v_add_f32_e32 v9, v9, v91
	v_add_f32_e32 v90, v90, v92
	ds_bpermute_b32 v91, v3, v9
	ds_bpermute_b32 v92, v3, v90
	s_waitcnt lgkmcnt(0)
	v_add_f32_e32 v9, v9, v91
	v_add_f32_e32 v90, v90, v92
	ds_bpermute_b32 v91, v4, v9
	ds_bpermute_b32 v92, v4, v90
	s_waitcnt lgkmcnt(0)
	v_add_f32_e32 v9, v9, v91
	v_add_f32_e32 v90, v90, v92
	ds_bpermute_b32 v91, v5, v9
	ds_bpermute_b32 v92, v5, v90
	s_waitcnt lgkmcnt(0)
	v_add_f32_e32 v9, v9, v91
	v_add_f32_e32 v90, v90, v92
	ds_bpermute_b32 v91, v6, v9
	ds_bpermute_b32 v92, v6, v90
	s_waitcnt lgkmcnt(0)
	v_add_f32_e32 v9, v9, v91
	v_add_f32_e32 v90, v90, v92
	ds_bpermute_b32 v91, v7, v9
	ds_bpermute_b32 v92, v7, v90
	s_waitcnt lgkmcnt(0)
	v_add_f32_e32 v9, v9, v91
	v_add_f32_e32 v90, v90, v92
	ds_bpermute_b32 v91, v8, v9
	ds_bpermute_b32 v92, v8, v90
	s_waitcnt lgkmcnt(0)
	v_add_f32_e32 v9, v9, v91
	v_add_f32_e32 v90, v90, v92
	v_mul_f32_e32 v93, 0x3a800000, v9
	v_mul_f32_e32 v91, 0x3a800000, v90
	v_fma_f32 v91, -v93, v93, v91
	v_max_f32_e32 v91, 0, v91
	v_add_f32_e32 v91, 0x358637bd, v91
	v_rsq_f32_e32 v94, v91
	v_mul_f32_e32 v91, 0.5, v91
	v_mul_f32_e32 v92, v94, v94
	v_fma_f32 v92, -v91, v92, 0.5
	v_fma_f32 v94, v94, v92, v94
	s_waitcnt vmcnt(18)
	v_sub_f32_e32 v98, v98, v93
	v_sub_f32_e32 v99, v99, v93
	v_sub_f32_e32 v100, v100, v93
	v_sub_f32_e32 v101, v101, v93
	v_sub_f32_e32 v102, v102, v93
	v_sub_f32_e32 v103, v103, v93
	v_sub_f32_e32 v104, v104, v93
	v_sub_f32_e32 v105, v105, v93
	v_sub_f32_e32 v106, v106, v93
	v_sub_f32_e32 v107, v107, v93
	v_sub_f32_e32 v108, v108, v93
	v_sub_f32_e32 v109, v109, v93
	v_sub_f32_e32 v110, v110, v93
	v_sub_f32_e32 v111, v111, v93
	v_sub_f32_e32 v112, v112, v93
	v_sub_f32_e32 v113, v113, v93
	v_add_f32_e32 v162, 1.0, v162
	v_add_f32_e32 v163, 1.0, v163
	v_add_f32_e32 v164, 1.0, v164
	v_add_f32_e32 v165, 1.0, v165
	v_add_f32_e32 v166, 1.0, v166
	v_add_f32_e32 v167, 1.0, v167
	v_add_f32_e32 v168, 1.0, v168
	v_add_f32_e32 v169, 1.0, v169
	v_add_f32_e32 v170, 1.0, v170
	v_add_f32_e32 v171, 1.0, v171
	v_add_f32_e32 v172, 1.0, v172
	v_add_f32_e32 v173, 1.0, v173
	v_add_f32_e32 v174, 1.0, v174
	v_add_f32_e32 v175, 1.0, v175
	v_add_f32_e32 v176, 1.0, v176
	v_add_f32_e32 v177, 1.0, v177
	v_mul_f32_e32 v98, v94, v98
	v_mul_f32_e32 v99, v94, v99
	v_mul_f32_e32 v100, v94, v100
	v_mul_f32_e32 v101, v94, v101
	v_mul_f32_e32 v102, v94, v102
	v_mul_f32_e32 v103, v94, v103
	v_mul_f32_e32 v104, v94, v104
	v_mul_f32_e32 v105, v94, v105
	v_mul_f32_e32 v106, v94, v106
	v_mul_f32_e32 v107, v94, v107
	v_mul_f32_e32 v108, v94, v108
	v_mul_f32_e32 v109, v94, v109
	v_mul_f32_e32 v110, v94, v110
	v_mul_f32_e32 v111, v94, v111
	v_mul_f32_e32 v112, v94, v112
	v_mul_f32_e32 v113, v94, v113
; DI unsigned pk2(float lo, float hi) { f32x2 v = {lo, hi}; bf16x2_t b = __builtin_convertvector(v, bf16x2_t); return __builtin_bit_cast(unsigned, b); }
; DI void ln_row_v(const Frame& F, f32x4 (&v)[4], float* xout, const float* g, const float* b, const float* sh, const float* sc, bf16_t* hout, const float* slab, const float* gres, float* stat = nullptr) {
;     ...
;         float s = 0.f, s2 = 0.f;
; #pragma unroll
;         for (int j = 0; j < 4; ++j) { s += (v[j][0] + v[j][1]) + (v[j][2] + v[j][3]); s2 += (v[j][0] * v[j][0] + v[j][1] * v[j][1]) + (v[j][2] * v[j][2] + v[j][3] * v[j][3]); }
;         wave_sum2(s, s2, F.lane);
;         const float mean = s * (1.f / D); const float rstd = 1.f / sqrtf(fmaxf(s2 * (1.f / D) - mean * mean, 0.f) + EPS);
;         if (stat && F.lane == 0) { f32x2 sv = {mean, rstd}; *(f32x2*)stat = sv; }
; #pragma unroll
;         for (int j = 0; j < 4; ++j) { const f32x4 gg = ((const f32x4*)g)[F.lane + 64 * j], bb = ((const f32x4*)b)[F.lane + 64 * j];
;             v[j] = (v[j] - mean) * rstd * gg + bb; if (xout) ((f32x4*)xout)[F.lane + 64 * j] = v[j]; }
;     }
;     if (hout) {
;         float s = 0.f, s2 = 0.f;
; #pragma unroll
;         for (int j = 0; j < 4; ++j) { s += (v[j][0] + v[j][1]) + (v[j][2] + v[j][3]); s2 += (v[j][0] * v[j][0] + v[j][1] * v[j][1]) + (v[j][2] * v[j][2] + v[j][3] * v[j][3]); }
;         wave_sum2(s, s2, F.lane);
;         const float mean = s * (1.f / D); const float rstd = 1.f / sqrtf(fmaxf(s2 * (1.f / D) - mean * mean, 0.f) + EPS);
; #pragma unroll
;         for (int j = 0; j < 4; ++j) { const f32x4 hh = ((const f32x4*)sh)[F.lane + 64 * j], cc = ((const f32x4*)sc)[F.lane + 64 * j];
;             const f32x4 o = (v[j] - mean) * rstd * (cc + 1.f) + hh; u32x2 wv; wv.x = pk2(o[0], o[1]); wv.y = pk2(o[2], o[3]);
;             ((u32x2*)hout)[F.lane + 64 * j] = wv; }
;     }
	v_fma_f32 v98, v98, v162, v146
	v_fma_f32 v99, v99, v163, v147
	v_fma_f32 v100, v100, v164, v148
	v_fma_f32 v101, v101, v165, v149
	v_fma_f32 v102, v102, v166, v150
	v_fma_f32 v103, v103, v167, v151
	v_fma_f32 v104, v104, v168, v152
	v_fma_f32 v105, v105, v169, v153
	v_fma_f32 v106, v106, v170, v154
	v_fma_f32 v107, v107, v171, v155
	v_fma_f32 v108, v108, v172, v156
	v_fma_f32 v109, v109, v173, v157
	v_fma_f32 v110, v110, v174, v158
	v_fma_f32 v111, v111, v175, v159
	v_fma_f32 v112, v112, v176, v160
	v_fma_f32 v113, v113, v177, v161
	v_cvt_pk_bf16_f32 v190, v98, v99
	v_cvt_pk_bf16_f32 v191, v100, v101
	v_cvt_pk_bf16_f32 v192, v102, v103
	v_cvt_pk_bf16_f32 v193, v104, v105
	v_cvt_pk_bf16_f32 v194, v106, v107
	v_cvt_pk_bf16_f32 v195, v108, v109
	v_cvt_pk_bf16_f32 v196, v110, v111
	v_cvt_pk_bf16_f32 v197, v112, v113
	s_add_u32 s2, s10, 0xc00000
	s_addc_u32 s3, s11, 0
	global_store_dwordx2 v1, v[190:191], s[2:3]
	global_store_dwordx2 v1, v[192:193], s[2:3] offset:512
	global_store_dwordx2 v1, v[194:195], s[2:3] offset:1024
	global_store_dwordx2 v1, v[196:197], s[2:3] offset:1536
	s_add_u32 s2, s8, 0x3800000
	s_addc_u32 s3, s9, 0
	global_load_dwordx4 v[98:101], v0, s[2:3]
	global_load_dwordx4 v[102:105], v0, s[2:3] offset:1024
	global_load_dwordx4 v[106:109], v0, s[2:3] offset:2048
	global_load_dwordx4 v[110:113], v0, s[2:3] offset:3072
	s_add_u32 s2, s14, 0x1e000
	s_addc_u32 s3, s15, 0
	global_load_dwordx4 v[146:149], v0, s[2:3]
	global_load_dwordx4 v[150:153], v0, s[2:3] offset:1024
	global_load_dwordx4 v[154:157], v0, s[2:3] offset:2048
	global_load_dwordx4 v[158:161], v0, s[2:3] offset:3072
	s_add_u32 s2, s18, 0x1e000
	s_addc_u32 s3, s19, 0
	global_load_dwordx4 v[162:165], v0, s[2:3]
	global_load_dwordx4 v[166:169], v0, s[2:3] offset:1024
	global_load_dwordx4 v[170:173], v0, s[2:3] offset:2048
	global_load_dwordx4 v[174:177], v0, s[2:3] offset:3072
	v_add_f32_e32 v9, v42, v43
	v_add_f32_e32 v91, v44, v45
	v_mul_f32_e32 v90, v42, v42
	v_mul_f32_e32 v92, v43, v43
	v_add_f32_e32 v9, v9, v46
	v_add_f32_e32 v91, v91, v47
	v_add_f32_e32 v9, v9, v48
	v_add_f32_e32 v91, v91, v49
	v_add_f32_e32 v9, v9, v50
	v_add_f32_e32 v91, v91, v51
	v_add_f32_e32 v9, v9, v52
	v_add_f32_e32 v91, v91, v53
	v_add_f32_e32 v9, v9, v54
	v_add_f32_e32 v91, v91, v55
	v_add_f32_e32 v9, v9, v56
	v_add_f32_e32 v91, v91, v57
	v_fmac_f32_e32 v90, v44, v44
	v_fmac_f32_e32 v92, v45, v45
	v_fmac_f32_e32 v90, v46, v46
	v_fmac_f32_e32 v92, v47, v47
	v_fmac_f32_e32 v90, v48, v48
	v_fmac_f32_e32 v92, v49, v49
	v_fmac_f32_e32 v90, v50, v50
	v_fmac_f32_e32 v92, v51, v51
	v_fmac_f32_e32 v90, v52, v52
	v_fmac_f32_e32 v92, v53, v53
	v_fmac_f32_e32 v90, v54, v54
	v_fmac_f32_e32 v92, v55, v55
	v_fmac_f32_e32 v90, v56, v56
	v_fmac_f32_e32 v92, v57, v57
	v_add_f32_e32 v9, v9, v91
	v_add_f32_e32 v90, v90, v92
	ds_bpermute_b32 v91, v3, v9
	ds_bpermute_b32 v92, v3, v90
	s_waitcnt lgkmcnt(0)
	v_add_f32_e32 v9, v9, v91
	v_add_f32_e32 v90, v90, v92
	ds_bpermute_b32 v91, v4, v9
	ds_bpermute_b32 v92, v4, v90
	s_waitcnt lgkmcnt(0)
	v_add_f32_e32 v9, v9, v91
	v_add_f32_e32 v90, v90, v92
	ds_bpermute_b32 v91, v5, v9
	ds_bpermute_b32 v92, v5, v90
	s_waitcnt lgkmcnt(0)
	v_add_f32_e32 v9, v9, v91
	v_add_f32_e32 v90, v90, v92
	ds_bpermute_b32 v91, v6, v9
	ds_bpermute_b32 v92, v6, v90
	s_waitcnt lgkmcnt(0)
	v_add_f32_e32 v9, v9, v91
	v_add_f32_e32 v90, v90, v92
	ds_bpermute_b32 v91, v7, v9
	ds_bpermute_b32 v92, v7, v90
	s_waitcnt lgkmcnt(0)
	v_add_f32_e32 v9, v9, v91
	v_add_f32_e32 v90, v90, v92
	ds_bpermute_b32 v91, v8, v9
	ds_bpermute_b32 v92, v8, v90
	s_waitcnt lgkmcnt(0)
	v_add_f32_e32 v9, v9, v91
	v_add_f32_e32 v90, v90, v92
	v_mul_f32_e32 v93, 0x3a800000, v9
	v_mul_f32_e32 v91, 0x3a800000, v90
	v_fma_f32 v91, -v93, v93, v91
	v_max_f32_e32 v91, 0, v91
	v_add_f32_e32 v91, 0x358637bd, v91
	v_rsq_f32_e32 v94, v91
	v_mul_f32_e32 v91, 0.5, v91
	v_mul_f32_e32 v92, v94, v94
	v_fma_f32 v92, -v91, v92, 0.5
	v_fma_f32 v94, v94, v92, v94
	s_add_u32 s2, s12, 0x10000
	s_addc_u32 s3, s13, 0
	v_mov_b32_e32 v188, v93
	v_mov_b32_e32 v189, v94
	s_mov_b64 exec, 1
	global_store_dwordx2 v97, v[188:189], s[2:3]
	s_mov_b64 exec, -1
	v_sub_f32_e32 v42, v42, v93
	v_sub_f32_e32 v43, v43, v93
	v_sub_f32_e32 v44, v44, v93
	v_sub_f32_e32 v45, v45, v93
	v_sub_f32_e32 v46, v46, v93
	v_sub_f32_e32 v47, v47, v93
	v_sub_f32_e32 v48, v48, v93
	v_sub_f32_e32 v49, v49, v93
	v_sub_f32_e32 v50, v50, v93
	v_sub_f32_e32 v51, v51, v93
	v_sub_f32_e32 v52, v52, v93
	v_sub_f32_e32 v53, v53, v93
	v_sub_f32_e32 v54, v54, v93
	v_sub_f32_e32 v55, v55, v93
	v_sub_f32_e32 v56, v56, v93
	v_sub_f32_e32 v57, v57, v93
	v_mul_f32_e32 v42, v94, v42
	v_mul_f32_e32 v43, v94, v43
	v_mul_f32_e32 v44, v94, v44
	v_mul_f32_e32 v45, v94, v45
	v_mul_f32_e32 v46, v94, v46
	v_mul_f32_e32 v47, v94, v47
	v_mul_f32_e32 v48, v94, v48
	v_mul_f32_e32 v49, v94, v49
	v_mul_f32_e32 v50, v94, v50
	v_mul_f32_e32 v51, v94, v51
	v_mul_f32_e32 v52, v94, v52
	v_mul_f32_e32 v53, v94, v53
	v_mul_f32_e32 v54, v94, v54
	v_mul_f32_e32 v55, v94, v55
	v_mul_f32_e32 v56, v94, v56
	v_mul_f32_e32 v57, v94, v57
	v_fma_f32 v42, v42, v10, v26
	v_fma_f32 v43, v43, v11, v27
	v_fma_f32 v44, v44, v12, v28
	v_fma_f32 v45, v45, v13, v29
	v_fma_f32 v46, v46, v14, v30
	v_fma_f32 v47, v47, v15, v31
	v_fma_f32 v48, v48, v16, v32
	v_fma_f32 v49, v49, v17, v33
	v_fma_f32 v50, v50, v18, v34
	v_fma_f32 v51, v51, v19, v35
	v_fma_f32 v52, v52, v20, v36
	v_fma_f32 v53, v53, v21, v37
	v_fma_f32 v54, v54, v22, v38
	v_fma_f32 v55, v55, v23, v39
	v_fma_f32 v56, v56, v24, v40
	v_fma_f32 v57, v57, v25, v41
	v_add_f32_e32 v9, v42, v43
	v_add_f32_e32 v91, v44, v45
	v_mul_f32_e32 v90, v42, v42
	v_mul_f32_e32 v92, v43, v43
	v_add_f32_e32 v9, v9, v46
	v_add_f32_e32 v91, v91, v47
	v_add_f32_e32 v9, v9, v48
	v_add_f32_e32 v91, v91, v49
	v_add_f32_e32 v9, v9, v50
	v_add_f32_e32 v91, v91, v51
	v_add_f32_e32 v9, v9, v52
	v_add_f32_e32 v91, v91, v53
	v_add_f32_e32 v9, v9, v54
	v_add_f32_e32 v91, v91, v55
	v_add_f32_e32 v9, v9, v56
	v_add_f32_e32 v91, v91, v57
	v_fmac_f32_e32 v90, v44, v44
	v_fmac_f32_e32 v92, v45, v45
	v_fmac_f32_e32 v90, v46, v46
	v_fmac_f32_e32 v92, v47, v47
	v_fmac_f32_e32 v90, v48, v48
	v_fmac_f32_e32 v92, v49, v49
	v_fmac_f32_e32 v90, v50, v50
	v_fmac_f32_e32 v92, v51, v51
	v_fmac_f32_e32 v90, v52, v52
	v_fmac_f32_e32 v92, v53, v53
	v_fmac_f32_e32 v90, v54, v54
	v_fmac_f32_e32 v92, v55, v55
	v_fmac_f32_e32 v90, v56, v56
	v_fmac_f32_e32 v92, v57, v57
	v_add_f32_e32 v9, v9, v91
	v_add_f32_e32 v90, v90, v92
	ds_bpermute_b32 v91, v3, v9
	ds_bpermute_b32 v92, v3, v90
	s_waitcnt lgkmcnt(0)
; DI unsigned pk2(float lo, float hi) { f32x2 v = {lo, hi}; bf16x2_t b = __builtin_convertvector(v, bf16x2_t); return __builtin_bit_cast(unsigned, b); }
; DI void ln_row_v(const Frame& F, f32x4 (&v)[4], float* xout, const float* g, const float* b, const float* sh, const float* sc, bf16_t* hout, const float* slab, const float* gres, float* stat = nullptr) {
;     ...
;         float s = 0.f, s2 = 0.f;
; #pragma unroll
;         for (int j = 0; j < 4; ++j) { s += (v[j][0] + v[j][1]) + (v[j][2] + v[j][3]); s2 += (v[j][0] * v[j][0] + v[j][1] * v[j][1]) + (v[j][2] * v[j][2] + v[j][3] * v[j][3]); }
;         wave_sum2(s, s2, F.lane);
;         const float mean = s * (1.f / D); const float rstd = 1.f / sqrtf(fmaxf(s2 * (1.f / D) - mean * mean, 0.f) + EPS);
;         if (stat && F.lane == 0) { f32x2 sv = {mean, rstd}; *(f32x2*)stat = sv; }
; #pragma unroll
;         for (int j = 0; j < 4; ++j) { const f32x4 gg = ((const f32x4*)g)[F.lane + 64 * j], bb = ((const f32x4*)b)[F.lane + 64 * j];
;             v[j] = (v[j] - mean) * rstd * gg + bb; if (xout) ((f32x4*)xout)[F.lane + 64 * j] = v[j]; }
;     }
;     if (hout) {
;         float s = 0.f, s2 = 0.f;
; #pragma unroll
;         for (int j = 0; j < 4; ++j) { s += (v[j][0] + v[j][1]) + (v[j][2] + v[j][3]); s2 += (v[j][0] * v[j][0] + v[j][1] * v[j][1]) + (v[j][2] * v[j][2] + v[j][3] * v[j][3]); }
;         wave_sum2(s, s2, F.lane);
;         const float mean = s * (1.f / D); const float rstd = 1.f / sqrtf(fmaxf(s2 * (1.f / D) - mean * mean, 0.f) + EPS);
; #pragma unroll
;         for (int j = 0; j < 4; ++j) { const f32x4 hh = ((const f32x4*)sh)[F.lane + 64 * j], cc = ((const f32x4*)sc)[F.lane + 64 * j];
;             const f32x4 o = (v[j] - mean) * rstd * (cc + 1.f) + hh; u32x2 wv; wv.x = pk2(o[0], o[1]); wv.y = pk2(o[2], o[3]);
;             ((u32x2*)hout)[F.lane + 64 * j] = wv; }
;     }
	v_add_f32_e32 v9, v9, v91
	v_add_f32_e32 v90, v90, v92
	ds_bpermute_b32 v91, v4, v9
	ds_bpermute_b32 v92, v4, v90
	s_waitcnt lgkmcnt(0)
	v_add_f32_e32 v9, v9, v91
	v_add_f32_e32 v90, v90, v92
	ds_bpermute_b32 v91, v5, v9
	ds_bpermute_b32 v92, v5, v90
	s_waitcnt lgkmcnt(0)
	v_add_f32_e32 v9, v9, v91
	v_add_f32_e32 v90, v90, v92
	ds_bpermute_b32 v91, v6, v9
	ds_bpermute_b32 v92, v6, v90
	s_waitcnt lgkmcnt(0)
	v_add_f32_e32 v9, v9, v91
	v_add_f32_e32 v90, v90, v92
	ds_bpermute_b32 v91, v7, v9
	ds_bpermute_b32 v92, v7, v90
	s_waitcnt lgkmcnt(0)
	v_add_f32_e32 v9, v9, v91
	v_add_f32_e32 v90, v90, v92
	ds_bpermute_b32 v91, v8, v9
	ds_bpermute_b32 v92, v8, v90
	s_waitcnt lgkmcnt(0)
	v_add_f32_e32 v9, v9, v91
	v_add_f32_e32 v90, v90, v92
	v_mul_f32_e32 v93, 0x3a800000, v9
	v_mul_f32_e32 v91, 0x3a800000, v90
	v_fma_f32 v91, -v93, v93, v91
	v_max_f32_e32 v91, 0, v91
	v_add_f32_e32 v91, 0x358637bd, v91
	v_rsq_f32_e32 v94, v91
	v_mul_f32_e32 v91, 0.5, v91
	v_mul_f32_e32 v92, v94, v94
	v_fma_f32 v92, -v91, v92, 0.5
	v_fma_f32 v94, v94, v92, v94
	s_waitcnt vmcnt(18)
	v_sub_f32_e32 v42, v42, v93
	v_sub_f32_e32 v43, v43, v93
	v_sub_f32_e32 v44, v44, v93
	v_sub_f32_e32 v45, v45, v93
	v_sub_f32_e32 v46, v46, v93
	v_sub_f32_e32 v47, v47, v93
	v_sub_f32_e32 v48, v48, v93
	v_sub_f32_e32 v49, v49, v93
	v_sub_f32_e32 v50, v50, v93
	v_sub_f32_e32 v51, v51, v93
	v_sub_f32_e32 v52, v52, v93
	v_sub_f32_e32 v53, v53, v93
	v_sub_f32_e32 v54, v54, v93
	v_sub_f32_e32 v55, v55, v93
	v_sub_f32_e32 v56, v56, v93
	v_sub_f32_e32 v57, v57, v93
	v_add_f32_e32 v130, 1.0, v130
	v_add_f32_e32 v131, 1.0, v131
	v_add_f32_e32 v132, 1.0, v132
	v_add_f32_e32 v133, 1.0, v133
	v_add_f32_e32 v134, 1.0, v134
	v_add_f32_e32 v135, 1.0, v135
	v_add_f32_e32 v136, 1.0, v136
	v_add_f32_e32 v137, 1.0, v137
	v_add_f32_e32 v138, 1.0, v138
	v_add_f32_e32 v139, 1.0, v139
	v_add_f32_e32 v140, 1.0, v140
	v_add_f32_e32 v141, 1.0, v141
	v_add_f32_e32 v142, 1.0, v142
	v_add_f32_e32 v143, 1.0, v143
	v_add_f32_e32 v144, 1.0, v144
	v_add_f32_e32 v145, 1.0, v145
	v_mul_f32_e32 v42, v94, v42
	v_mul_f32_e32 v43, v94, v43
	v_mul_f32_e32 v44, v94, v44
	v_mul_f32_e32 v45, v94, v45
	v_mul_f32_e32 v46, v94, v46
	v_mul_f32_e32 v47, v94, v47
	v_mul_f32_e32 v48, v94, v48
	v_mul_f32_e32 v49, v94, v49
	v_mul_f32_e32 v50, v94, v50
	v_mul_f32_e32 v51, v94, v51
	v_mul_f32_e32 v52, v94, v52
	v_mul_f32_e32 v53, v94, v53
	v_mul_f32_e32 v54, v94, v54
	v_mul_f32_e32 v55, v94, v55
	v_mul_f32_e32 v56, v94, v56
	v_mul_f32_e32 v57, v94, v57
	v_fma_f32 v42, v42, v130, v114
	v_fma_f32 v43, v43, v131, v115
	v_fma_f32 v44, v44, v132, v116
	v_fma_f32 v45, v45, v133, v117
	v_fma_f32 v46, v46, v134, v118
	v_fma_f32 v47, v47, v135, v119
	v_fma_f32 v48, v48, v136, v120
	v_fma_f32 v49, v49, v137, v121
	v_fma_f32 v50, v50, v138, v122
	v_fma_f32 v51, v51, v139, v123
	v_fma_f32 v52, v52, v140, v124
	v_fma_f32 v53, v53, v141, v125
	v_fma_f32 v54, v54, v142, v126
	v_fma_f32 v55, v55, v143, v127
	v_fma_f32 v56, v56, v144, v128
	v_fma_f32 v57, v57, v145, v129
	v_cvt_pk_bf16_f32 v190, v42, v43
	v_cvt_pk_bf16_f32 v191, v44, v45
	v_cvt_pk_bf16_f32 v192, v46, v47
	v_cvt_pk_bf16_f32 v193, v48, v49
	v_cvt_pk_bf16_f32 v194, v50, v51
	v_cvt_pk_bf16_f32 v195, v52, v53
	v_cvt_pk_bf16_f32 v196, v54, v55
	v_cvt_pk_bf16_f32 v197, v56, v57
	s_add_u32 s2, s10, 0x1000000
	s_addc_u32 s3, s11, 0
	global_store_dwordx2 v1, v[190:191], s[2:3]
	global_store_dwordx2 v1, v[192:193], s[2:3] offset:512
	global_store_dwordx2 v1, v[194:195], s[2:3] offset:1024
	global_store_dwordx2 v1, v[196:197], s[2:3] offset:1536
	s_mov_b64 s[2:3], s[20:21]
	global_load_dwordx4 v[42:45], v0, s[2:3]
	global_load_dwordx4 v[46:49], v0, s[2:3] offset:1024
	global_load_dwordx4 v[50:53], v0, s[2:3] offset:2048
	global_load_dwordx4 v[54:57], v0, s[2:3] offset:3072
	s_add_u32 s2, s14, 0x24000
	s_addc_u32 s3, s15, 0
	global_load_dwordx4 v[114:117], v0, s[2:3]
	global_load_dwordx4 v[118:121], v0, s[2:3] offset:1024
	global_load_dwordx4 v[122:125], v0, s[2:3] offset:2048
	global_load_dwordx4 v[126:129], v0, s[2:3] offset:3072
	s_add_u32 s2, s18, 0x24000
	s_addc_u32 s3, s19, 0
	global_load_dwordx4 v[130:133], v0, s[2:3]
	global_load_dwordx4 v[134:137], v0, s[2:3] offset:1024
	global_load_dwordx4 v[138:141], v0, s[2:3] offset:2048
	global_load_dwordx4 v[142:145], v0, s[2:3] offset:3072
	v_add_f32_e32 v9, v58, v59
	v_add_f32_e32 v91, v60, v61
	v_mul_f32_e32 v90, v58, v58
	v_mul_f32_e32 v92, v59, v59
	v_add_f32_e32 v9, v9, v62
	v_add_f32_e32 v91, v91, v63
	v_add_f32_e32 v9, v9, v64
	v_add_f32_e32 v91, v91, v65
	v_add_f32_e32 v9, v9, v66
	v_add_f32_e32 v91, v91, v67
	v_add_f32_e32 v9, v9, v68
	v_add_f32_e32 v91, v91, v69
	v_add_f32_e32 v9, v9, v70
	v_add_f32_e32 v91, v91, v71
	v_add_f32_e32 v9, v9, v72
	v_add_f32_e32 v91, v91, v73
	v_fmac_f32_e32 v90, v60, v60
	v_fmac_f32_e32 v92, v61, v61
	v_fmac_f32_e32 v90, v62, v62
	v_fmac_f32_e32 v92, v63, v63
	v_fmac_f32_e32 v90, v64, v64
	v_fmac_f32_e32 v92, v65, v65
	v_fmac_f32_e32 v90, v66, v66
	v_fmac_f32_e32 v92, v67, v67
	v_fmac_f32_e32 v90, v68, v68
	v_fmac_f32_e32 v92, v69, v69
	v_fmac_f32_e32 v90, v70, v70
	v_fmac_f32_e32 v92, v71, v71
	v_fmac_f32_e32 v90, v72, v72
	v_fmac_f32_e32 v92, v73, v73
	v_add_f32_e32 v9, v9, v91
	v_add_f32_e32 v90, v90, v92
	ds_bpermute_b32 v91, v3, v9
	ds_bpermute_b32 v92, v3, v90
	s_waitcnt lgkmcnt(0)
	v_add_f32_e32 v9, v9, v91
	v_add_f32_e32 v90, v90, v92
	ds_bpermute_b32 v91, v4, v9
	ds_bpermute_b32 v92, v4, v90
	s_waitcnt lgkmcnt(0)
	v_add_f32_e32 v9, v9, v91
	v_add_f32_e32 v90, v90, v92
	ds_bpermute_b32 v91, v5, v9
	ds_bpermute_b32 v92, v5, v90
	s_waitcnt lgkmcnt(0)
; DI void ln_row_v(const Frame& F, f32x4 (&v)[4], float* xout, const float* g, const float* b, const float* sh, const float* sc, bf16_t* hout, const float* slab, const float* gres, float* stat = nullptr) {
;     ...
;         float s = 0.f, s2 = 0.f;
; #pragma unroll
;         for (int j = 0; j < 4; ++j) { s += (v[j][0] + v[j][1]) + (v[j][2] + v[j][3]); s2 += (v[j][0] * v[j][0] + v[j][1] * v[j][1]) + (v[j][2] * v[j][2] + v[j][3] * v[j][3]); }
;         wave_sum2(s, s2, F.lane);
;         const float mean = s * (1.f / D); const float rstd = 1.f / sqrtf(fmaxf(s2 * (1.f / D) - mean * mean, 0.f) + EPS);
;         if (stat && F.lane == 0) { f32x2 sv = {mean, rstd}; *(f32x2*)stat = sv; }
; #pragma unroll
;         for (int j = 0; j < 4; ++j) { const f32x4 gg = ((const f32x4*)g)[F.lane + 64 * j], bb = ((const f32x4*)b)[F.lane + 64 * j];
;             v[j] = (v[j] - mean) * rstd * gg + bb; if (xout) ((f32x4*)xout)[F.lane + 64 * j] = v[j]; }
	v_add_f32_e32 v9, v9, v91
	v_add_f32_e32 v90, v90, v92
	ds_bpermute_b32 v91, v6, v9
	ds_bpermute_b32 v92, v6, v90
	s_waitcnt lgkmcnt(0)
	v_add_f32_e32 v9, v9, v91
	v_add_f32_e32 v90, v90, v92
	ds_bpermute_b32 v91, v7, v9
	ds_bpermute_b32 v92, v7, v90
	s_waitcnt lgkmcnt(0)
	v_add_f32_e32 v9, v9, v91
	v_add_f32_e32 v90, v90, v92
	ds_bpermute_b32 v91, v8, v9
	ds_bpermute_b32 v92, v8, v90
	s_waitcnt lgkmcnt(0)
	v_add_f32_e32 v9, v9, v91
	v_add_f32_e32 v90, v90, v92
	v_mul_f32_e32 v93, 0x3a800000, v9
	v_mul_f32_e32 v91, 0x3a800000, v90
	v_fma_f32 v91, -v93, v93, v91
	v_max_f32_e32 v91, 0, v91
	v_add_f32_e32 v91, 0x358637bd, v91
	v_rsq_f32_e32 v94, v91
	v_mul_f32_e32 v91, 0.5, v91
	v_mul_f32_e32 v92, v94, v94
	v_fma_f32 v92, -v91, v92, 0.5
	v_fma_f32 v94, v94, v92, v94
	s_add_u32 s2, s12, 0x14000
	s_addc_u32 s3, s13, 0
	v_mov_b32_e32 v188, v93
	v_mov_b32_e32 v189, v94
	s_mov_b64 exec, 1
	global_store_dwordx2 v97, v[188:189], s[2:3]
	s_mov_b64 exec, -1
	v_sub_f32_e32 v58, v58, v93
	v_sub_f32_e32 v59, v59, v93
	v_sub_f32_e32 v60, v60, v93
	v_sub_f32_e32 v61, v61, v93
	v_sub_f32_e32 v62, v62, v93
	v_sub_f32_e32 v63, v63, v93
	v_sub_f32_e32 v64, v64, v93
	v_sub_f32_e32 v65, v65, v93
	v_sub_f32_e32 v66, v66, v93
	v_sub_f32_e32 v67, v67, v93
	v_sub_f32_e32 v68, v68, v93
	v_sub_f32_e32 v69, v69, v93
	v_sub_f32_e32 v70, v70, v93
	v_sub_f32_e32 v71, v71, v93
	v_sub_f32_e32 v72, v72, v93
	v_sub_f32_e32 v73, v73, v93
	v_mul_f32_e32 v58, v94, v58
	v_mul_f32_e32 v59, v94, v59
	v_mul_f32_e32 v60, v94, v60
	v_mul_f32_e32 v61, v94, v61
	v_mul_f32_e32 v62, v94, v62
	v_mul_f32_e32 v63, v94, v63
	v_mul_f32_e32 v64, v94, v64
	v_mul_f32_e32 v65, v94, v65
	v_mul_f32_e32 v66, v94, v66
	v_mul_f32_e32 v67, v94, v67
	v_mul_f32_e32 v68, v94, v68
	v_mul_f32_e32 v69, v94, v69
	v_mul_f32_e32 v70, v94, v70
	v_mul_f32_e32 v71, v94, v71
	v_mul_f32_e32 v72, v94, v72
	v_mul_f32_e32 v73, v94, v73
	v_fma_f32 v58, v58, v10, v26
	v_fma_f32 v59, v59, v11, v27
	v_fma_f32 v60, v60, v12, v28
	v_fma_f32 v61, v61, v13, v29
	v_fma_f32 v62, v62, v14, v30
	v_fma_f32 v63, v63, v15, v31
	v_fma_f32 v64, v64, v16, v32
	v_fma_f32 v65, v65, v17, v33
	v_fma_f32 v66, v66, v18, v34
	v_fma_f32 v67, v67, v19, v35
	v_fma_f32 v68, v68, v20, v36
	v_fma_f32 v69, v69, v21, v37
	v_fma_f32 v70, v70, v22, v38
	v_fma_f32 v71, v71, v23, v39
	v_fma_f32 v72, v72, v24, v40
	v_fma_f32 v73, v73, v25, v41
	v_add_f32_e32 v9, v58, v59
	v_add_f32_e32 v91, v60, v61
	v_mul_f32_e32 v90, v58, v58
	v_mul_f32_e32 v92, v59, v59
	v_add_f32_e32 v9, v9, v62
	v_add_f32_e32 v91, v91, v63
	v_add_f32_e32 v9, v9, v64
	v_add_f32_e32 v91, v91, v65
	v_add_f32_e32 v9, v9, v66
	v_add_f32_e32 v91, v91, v67
	v_add_f32_e32 v9, v9, v68
	v_add_f32_e32 v91, v91, v69
	v_add_f32_e32 v9, v9, v70
	v_add_f32_e32 v91, v91, v71
	v_add_f32_e32 v9, v9, v72
	v_add_f32_e32 v91, v91, v73
	v_fmac_f32_e32 v90, v60, v60
	v_fmac_f32_e32 v92, v61, v61
	v_fmac_f32_e32 v90, v62, v62
	v_fmac_f32_e32 v92, v63, v63
	v_fmac_f32_e32 v90, v64, v64
	v_fmac_f32_e32 v92, v65, v65
	v_fmac_f32_e32 v90, v66, v66
	v_fmac_f32_e32 v92, v67, v67
	v_fmac_f32_e32 v90, v68, v68
	v_fmac_f32_e32 v92, v69, v69
	v_fmac_f32_e32 v90, v70, v70
	v_fmac_f32_e32 v92, v71, v71
	v_fmac_f32_e32 v90, v72, v72
	v_fmac_f32_e32 v92, v73, v73
	v_add_f32_e32 v9, v9, v91
	v_add_f32_e32 v90, v90, v92
	ds_bpermute_b32 v91, v3, v9
	ds_bpermute_b32 v92, v3, v90
	s_waitcnt lgkmcnt(0)
	v_add_f32_e32 v9, v9, v91
	v_add_f32_e32 v90, v90, v92
	ds_bpermute_b32 v91, v4, v9
	ds_bpermute_b32 v92, v4, v90
	s_waitcnt lgkmcnt(0)
	v_add_f32_e32 v9, v9, v91
	v_add_f32_e32 v90, v90, v92
	ds_bpermute_b32 v91, v5, v9
	ds_bpermute_b32 v92, v5, v90
	s_waitcnt lgkmcnt(0)
	v_add_f32_e32 v9, v9, v91
	v_add_f32_e32 v90, v90, v92
	ds_bpermute_b32 v91, v6, v9
	ds_bpermute_b32 v92, v6, v90
	s_waitcnt lgkmcnt(0)
	v_add_f32_e32 v9, v9, v91
	v_add_f32_e32 v90, v90, v92
	ds_bpermute_b32 v91, v7, v9
	ds_bpermute_b32 v92, v7, v90
	s_waitcnt lgkmcnt(0)
	v_add_f32_e32 v9, v9, v91
	v_add_f32_e32 v90, v90, v92
	ds_bpermute_b32 v91, v8, v9
	ds_bpermute_b32 v92, v8, v90
	s_waitcnt lgkmcnt(0)
	v_add_f32_e32 v9, v9, v91
	v_add_f32_e32 v90, v90, v92
	v_mul_f32_e32 v93, 0x3a800000, v9
	v_mul_f32_e32 v91, 0x3a800000, v90
	v_fma_f32 v91, -v93, v93, v91
	v_max_f32_e32 v91, 0, v91
	v_add_f32_e32 v91, 0x358637bd, v91
	v_rsq_f32_e32 v94, v91
	v_mul_f32_e32 v91, 0.5, v91
	v_mul_f32_e32 v92, v94, v94
	v_fma_f32 v92, -v91, v92, 0.5
	v_fma_f32 v94, v94, v92, v94
	s_waitcnt vmcnt(18)
; DI unsigned pk2(float lo, float hi) { f32x2 v = {lo, hi}; bf16x2_t b = __builtin_convertvector(v, bf16x2_t); return __builtin_bit_cast(unsigned, b); }
; DI void ln_row_v(const Frame& F, f32x4 (&v)[4], float* xout, const float* g, const float* b, const float* sh, const float* sc, bf16_t* hout, const float* slab, const float* gres, float* stat = nullptr) {
;     ...
;         float s = 0.f, s2 = 0.f;
; #pragma unroll
;         for (int j = 0; j < 4; ++j) { s += (v[j][0] + v[j][1]) + (v[j][2] + v[j][3]); s2 += (v[j][0] * v[j][0] + v[j][1] * v[j][1]) + (v[j][2] * v[j][2] + v[j][3] * v[j][3]); }
;         wave_sum2(s, s2, F.lane);
;         const float mean = s * (1.f / D); const float rstd = 1.f / sqrtf(fmaxf(s2 * (1.f / D) - mean * mean, 0.f) + EPS);
;         if (stat && F.lane == 0) { f32x2 sv = {mean, rstd}; *(f32x2*)stat = sv; }
; #pragma unroll
;         for (int j = 0; j < 4; ++j) { const f32x4 gg = ((const f32x4*)g)[F.lane + 64 * j], bb = ((const f32x4*)b)[F.lane + 64 * j];
;             v[j] = (v[j] - mean) * rstd * gg + bb; if (xout) ((f32x4*)xout)[F.lane + 64 * j] = v[j]; }
;     }
;     if (hout) {
;         float s = 0.f, s2 = 0.f;
; #pragma unroll
;         for (int j = 0; j < 4; ++j) { s += (v[j][0] + v[j][1]) + (v[j][2] + v[j][3]); s2 += (v[j][0] * v[j][0] + v[j][1] * v[j][1]) + (v[j][2] * v[j][2] + v[j][3] * v[j][3]); }
;         wave_sum2(s, s2, F.lane);
;         const float mean = s * (1.f / D); const float rstd = 1.f / sqrtf(fmaxf(s2 * (1.f / D) - mean * mean, 0.f) + EPS);
; #pragma unroll
;         for (int j = 0; j < 4; ++j) { const f32x4 hh = ((const f32x4*)sh)[F.lane + 64 * j], cc = ((const f32x4*)sc)[F.lane + 64 * j];
;             const f32x4 o = (v[j] - mean) * rstd * (cc + 1.f) + hh; u32x2 wv; wv.x = pk2(o[0], o[1]); wv.y = pk2(o[2], o[3]);
;             ((u32x2*)hout)[F.lane + 64 * j] = wv; }
;     }
	v_sub_f32_e32 v58, v58, v93
	v_sub_f32_e32 v59, v59, v93
	v_sub_f32_e32 v60, v60, v93
	v_sub_f32_e32 v61, v61, v93
	v_sub_f32_e32 v62, v62, v93
	v_sub_f32_e32 v63, v63, v93
	v_sub_f32_e32 v64, v64, v93
	v_sub_f32_e32 v65, v65, v93
	v_sub_f32_e32 v66, v66, v93
	v_sub_f32_e32 v67, v67, v93
	v_sub_f32_e32 v68, v68, v93
	v_sub_f32_e32 v69, v69, v93
	v_sub_f32_e32 v70, v70, v93
	v_sub_f32_e32 v71, v71, v93
	v_sub_f32_e32 v72, v72, v93
	v_sub_f32_e32 v73, v73, v93
	v_add_f32_e32 v162, 1.0, v162
	v_add_f32_e32 v163, 1.0, v163
	v_add_f32_e32 v164, 1.0, v164
	v_add_f32_e32 v165, 1.0, v165
	v_add_f32_e32 v166, 1.0, v166
	v_add_f32_e32 v167, 1.0, v167
	v_add_f32_e32 v168, 1.0, v168
	v_add_f32_e32 v169, 1.0, v169
	v_add_f32_e32 v170, 1.0, v170
	v_add_f32_e32 v171, 1.0, v171
	v_add_f32_e32 v172, 1.0, v172
	v_add_f32_e32 v173, 1.0, v173
	v_add_f32_e32 v174, 1.0, v174
	v_add_f32_e32 v175, 1.0, v175
	v_add_f32_e32 v176, 1.0, v176
	v_add_f32_e32 v177, 1.0, v177
	v_mul_f32_e32 v58, v94, v58
	v_mul_f32_e32 v59, v94, v59
	v_mul_f32_e32 v60, v94, v60
	v_mul_f32_e32 v61, v94, v61
	v_mul_f32_e32 v62, v94, v62
	v_mul_f32_e32 v63, v94, v63
	v_mul_f32_e32 v64, v94, v64
	v_mul_f32_e32 v65, v94, v65
	v_mul_f32_e32 v66, v94, v66
	v_mul_f32_e32 v67, v94, v67
	v_mul_f32_e32 v68, v94, v68
	v_mul_f32_e32 v69, v94, v69
	v_mul_f32_e32 v70, v94, v70
	v_mul_f32_e32 v71, v94, v71
	v_mul_f32_e32 v72, v94, v72
	v_mul_f32_e32 v73, v94, v73
	v_fma_f32 v58, v58, v162, v146
	v_fma_f32 v59, v59, v163, v147
	v_fma_f32 v60, v60, v164, v148
	v_fma_f32 v61, v61, v165, v149
	v_fma_f32 v62, v62, v166, v150
	v_fma_f32 v63, v63, v167, v151
	v_fma_f32 v64, v64, v168, v152
	v_fma_f32 v65, v65, v169, v153
	v_fma_f32 v66, v66, v170, v154
	v_fma_f32 v67, v67, v171, v155
	v_fma_f32 v68, v68, v172, v156
	v_fma_f32 v69, v69, v173, v157
	v_fma_f32 v70, v70, v174, v158
	v_fma_f32 v71, v71, v175, v159
	v_fma_f32 v72, v72, v176, v160
	v_fma_f32 v73, v73, v177, v161
	v_cvt_pk_bf16_f32 v190, v58, v59
	v_cvt_pk_bf16_f32 v191, v60, v61
	v_cvt_pk_bf16_f32 v192, v62, v63
	v_cvt_pk_bf16_f32 v193, v64, v65
	v_cvt_pk_bf16_f32 v194, v66, v67
	v_cvt_pk_bf16_f32 v195, v68, v69
	v_cvt_pk_bf16_f32 v196, v70, v71
	v_cvt_pk_bf16_f32 v197, v72, v73
	s_add_u32 s2, s10, 0x1400000
	s_addc_u32 s3, s11, 0
	global_store_dwordx2 v1, v[190:191], s[2:3]
	global_store_dwordx2 v1, v[192:193], s[2:3] offset:512
	global_store_dwordx2 v1, v[194:195], s[2:3] offset:1024
	global_store_dwordx2 v1, v[196:197], s[2:3] offset:1536
	s_add_u32 s2, s14, 0x2a000
	s_addc_u32 s3, s15, 0
	global_load_dwordx4 v[146:149], v0, s[2:3]
	global_load_dwordx4 v[150:153], v0, s[2:3] offset:1024
	global_load_dwordx4 v[154:157], v0, s[2:3] offset:2048
	global_load_dwordx4 v[158:161], v0, s[2:3] offset:3072
	s_add_u32 s2, s18, 0x2a000
	s_addc_u32 s3, s19, 0
	global_load_dwordx4 v[162:165], v0, s[2:3]
	global_load_dwordx4 v[166:169], v0, s[2:3] offset:1024
	global_load_dwordx4 v[170:173], v0, s[2:3] offset:2048
	global_load_dwordx4 v[174:177], v0, s[2:3] offset:3072
	v_add_f32_e32 v9, v74, v75
	v_add_f32_e32 v91, v76, v77
	v_mul_f32_e32 v90, v74, v74
	v_mul_f32_e32 v92, v75, v75
	v_add_f32_e32 v9, v9, v78
	v_add_f32_e32 v91, v91, v79
	v_add_f32_e32 v9, v9, v80
	v_add_f32_e32 v91, v91, v81
	v_add_f32_e32 v9, v9, v82
	v_add_f32_e32 v91, v91, v83
	v_add_f32_e32 v9, v9, v84
	v_add_f32_e32 v91, v91, v85
	v_add_f32_e32 v9, v9, v86
	v_add_f32_e32 v91, v91, v87
	v_add_f32_e32 v9, v9, v88
	v_add_f32_e32 v91, v91, v89
	v_fmac_f32_e32 v90, v76, v76
	v_fmac_f32_e32 v92, v77, v77
	v_fmac_f32_e32 v90, v78, v78
	v_fmac_f32_e32 v92, v79, v79
	v_fmac_f32_e32 v90, v80, v80
	v_fmac_f32_e32 v92, v81, v81
	v_fmac_f32_e32 v90, v82, v82
	v_fmac_f32_e32 v92, v83, v83
	v_fmac_f32_e32 v90, v84, v84
	v_fmac_f32_e32 v92, v85, v85
	v_fmac_f32_e32 v90, v86, v86
	v_fmac_f32_e32 v92, v87, v87
	v_fmac_f32_e32 v90, v88, v88
	v_fmac_f32_e32 v92, v89, v89
	v_add_f32_e32 v9, v9, v91
	v_add_f32_e32 v90, v90, v92
	ds_bpermute_b32 v91, v3, v9
	ds_bpermute_b32 v92, v3, v90
	s_waitcnt lgkmcnt(0)
	v_add_f32_e32 v9, v9, v91
	v_add_f32_e32 v90, v90, v92
	ds_bpermute_b32 v91, v4, v9
	ds_bpermute_b32 v92, v4, v90
	s_waitcnt lgkmcnt(0)
	v_add_f32_e32 v9, v9, v91
	v_add_f32_e32 v90, v90, v92
	ds_bpermute_b32 v91, v5, v9
	ds_bpermute_b32 v92, v5, v90
	s_waitcnt lgkmcnt(0)
	v_add_f32_e32 v9, v9, v91
	v_add_f32_e32 v90, v90, v92
	ds_bpermute_b32 v91, v6, v9
	ds_bpermute_b32 v92, v6, v90
	s_waitcnt lgkmcnt(0)
	v_add_f32_e32 v9, v9, v91
	v_add_f32_e32 v90, v90, v92
	ds_bpermute_b32 v91, v7, v9
	ds_bpermute_b32 v92, v7, v90
	s_waitcnt lgkmcnt(0)
	v_add_f32_e32 v9, v9, v91
	v_add_f32_e32 v90, v90, v92
	ds_bpermute_b32 v91, v8, v9
	ds_bpermute_b32 v92, v8, v90
	s_waitcnt lgkmcnt(0)
; DI unsigned pk2(float lo, float hi) { f32x2 v = {lo, hi}; bf16x2_t b = __builtin_convertvector(v, bf16x2_t); return __builtin_bit_cast(unsigned, b); }
; DI void ln_row_v(const Frame& F, f32x4 (&v)[4], float* xout, const float* g, const float* b, const float* sh, const float* sc, bf16_t* hout, const float* slab, const float* gres, float* stat = nullptr) {
;     ...
;         float s = 0.f, s2 = 0.f;
; #pragma unroll
;         for (int j = 0; j < 4; ++j) { s += (v[j][0] + v[j][1]) + (v[j][2] + v[j][3]); s2 += (v[j][0] * v[j][0] + v[j][1] * v[j][1]) + (v[j][2] * v[j][2] + v[j][3] * v[j][3]); }
;         wave_sum2(s, s2, F.lane);
;         const float mean = s * (1.f / D); const float rstd = 1.f / sqrtf(fmaxf(s2 * (1.f / D) - mean * mean, 0.f) + EPS);
;         if (stat && F.lane == 0) { f32x2 sv = {mean, rstd}; *(f32x2*)stat = sv; }
; #pragma unroll
;         for (int j = 0; j < 4; ++j) { const f32x4 gg = ((const f32x4*)g)[F.lane + 64 * j], bb = ((const f32x4*)b)[F.lane + 64 * j];
;             v[j] = (v[j] - mean) * rstd * gg + bb; if (xout) ((f32x4*)xout)[F.lane + 64 * j] = v[j]; }
;     }
;     if (hout) {
;         float s = 0.f, s2 = 0.f;
; #pragma unroll
;         for (int j = 0; j < 4; ++j) { s += (v[j][0] + v[j][1]) + (v[j][2] + v[j][3]); s2 += (v[j][0] * v[j][0] + v[j][1] * v[j][1]) + (v[j][2] * v[j][2] + v[j][3] * v[j][3]); }
;         wave_sum2(s, s2, F.lane);
;         const float mean = s * (1.f / D); const float rstd = 1.f / sqrtf(fmaxf(s2 * (1.f / D) - mean * mean, 0.f) + EPS);
; #pragma unroll
;         for (int j = 0; j < 4; ++j) { const f32x4 hh = ((const f32x4*)sh)[F.lane + 64 * j], cc = ((const f32x4*)sc)[F.lane + 64 * j];
;             const f32x4 o = (v[j] - mean) * rstd * (cc + 1.f) + hh; u32x2 wv; wv.x = pk2(o[0], o[1]); wv.y = pk2(o[2], o[3]);
;             ((u32x2*)hout)[F.lane + 64 * j] = wv; }
;     }
	v_add_f32_e32 v9, v9, v91
	v_add_f32_e32 v90, v90, v92
	v_mul_f32_e32 v93, 0x3a800000, v9
	v_mul_f32_e32 v91, 0x3a800000, v90
	v_fma_f32 v91, -v93, v93, v91
	v_max_f32_e32 v91, 0, v91
	v_add_f32_e32 v91, 0x358637bd, v91
	v_rsq_f32_e32 v94, v91
	v_mul_f32_e32 v91, 0.5, v91
	v_mul_f32_e32 v92, v94, v94
	v_fma_f32 v92, -v91, v92, 0.5
	v_fma_f32 v94, v94, v92, v94
	s_add_u32 s2, s12, 0x18000
	s_addc_u32 s3, s13, 0
	v_mov_b32_e32 v188, v93
	v_mov_b32_e32 v189, v94
	s_mov_b64 exec, 1
	global_store_dwordx2 v97, v[188:189], s[2:3]
	s_mov_b64 exec, -1
	v_sub_f32_e32 v74, v74, v93
	v_sub_f32_e32 v75, v75, v93
	v_sub_f32_e32 v76, v76, v93
	v_sub_f32_e32 v77, v77, v93
	v_sub_f32_e32 v78, v78, v93
	v_sub_f32_e32 v79, v79, v93
	v_sub_f32_e32 v80, v80, v93
	v_sub_f32_e32 v81, v81, v93
	v_sub_f32_e32 v82, v82, v93
	v_sub_f32_e32 v83, v83, v93
	v_sub_f32_e32 v84, v84, v93
	v_sub_f32_e32 v85, v85, v93
	v_sub_f32_e32 v86, v86, v93
	v_sub_f32_e32 v87, v87, v93
	v_sub_f32_e32 v88, v88, v93
	v_sub_f32_e32 v89, v89, v93
	v_mul_f32_e32 v74, v94, v74
	v_mul_f32_e32 v75, v94, v75
	v_mul_f32_e32 v76, v94, v76
	v_mul_f32_e32 v77, v94, v77
	v_mul_f32_e32 v78, v94, v78
	v_mul_f32_e32 v79, v94, v79
	v_mul_f32_e32 v80, v94, v80
	v_mul_f32_e32 v81, v94, v81
	v_mul_f32_e32 v82, v94, v82
	v_mul_f32_e32 v83, v94, v83
	v_mul_f32_e32 v84, v94, v84
	v_mul_f32_e32 v85, v94, v85
	v_mul_f32_e32 v86, v94, v86
	v_mul_f32_e32 v87, v94, v87
	v_mul_f32_e32 v88, v94, v88
	v_mul_f32_e32 v89, v94, v89
	v_fma_f32 v74, v74, v10, v26
	v_fma_f32 v75, v75, v11, v27
	v_fma_f32 v76, v76, v12, v28
	v_fma_f32 v77, v77, v13, v29
	v_fma_f32 v78, v78, v14, v30
	v_fma_f32 v79, v79, v15, v31
	v_fma_f32 v80, v80, v16, v32
	v_fma_f32 v81, v81, v17, v33
	v_fma_f32 v82, v82, v18, v34
	v_fma_f32 v83, v83, v19, v35
	v_fma_f32 v84, v84, v20, v36
	v_fma_f32 v85, v85, v21, v37
	v_fma_f32 v86, v86, v22, v38
	v_fma_f32 v87, v87, v23, v39
	v_fma_f32 v88, v88, v24, v40
	v_fma_f32 v89, v89, v25, v41
	v_add_f32_e32 v9, v74, v75
	v_add_f32_e32 v91, v76, v77
	v_mul_f32_e32 v90, v74, v74
	v_mul_f32_e32 v92, v75, v75
	v_add_f32_e32 v9, v9, v78
	v_add_f32_e32 v91, v91, v79
	v_add_f32_e32 v9, v9, v80
	v_add_f32_e32 v91, v91, v81
	v_add_f32_e32 v9, v9, v82
	v_add_f32_e32 v91, v91, v83
	v_add_f32_e32 v9, v9, v84
	v_add_f32_e32 v91, v91, v85
	v_add_f32_e32 v9, v9, v86
	v_add_f32_e32 v91, v91, v87
	v_add_f32_e32 v9, v9, v88
	v_add_f32_e32 v91, v91, v89
	v_fmac_f32_e32 v90, v76, v76
	v_fmac_f32_e32 v92, v77, v77
	v_fmac_f32_e32 v90, v78, v78
	v_fmac_f32_e32 v92, v79, v79
	v_fmac_f32_e32 v90, v80, v80
	v_fmac_f32_e32 v92, v81, v81
	v_fmac_f32_e32 v90, v82, v82
	v_fmac_f32_e32 v92, v83, v83
	v_fmac_f32_e32 v90, v84, v84
	v_fmac_f32_e32 v92, v85, v85
	v_fmac_f32_e32 v90, v86, v86
	v_fmac_f32_e32 v92, v87, v87
	v_fmac_f32_e32 v90, v88, v88
	v_fmac_f32_e32 v92, v89, v89
	v_add_f32_e32 v9, v9, v91
	v_add_f32_e32 v90, v90, v92
	ds_bpermute_b32 v91, v3, v9
	ds_bpermute_b32 v92, v3, v90
	s_waitcnt lgkmcnt(0)
	v_add_f32_e32 v9, v9, v91
	v_add_f32_e32 v90, v90, v92
	ds_bpermute_b32 v91, v4, v9
	ds_bpermute_b32 v92, v4, v90
	s_waitcnt lgkmcnt(0)
	v_add_f32_e32 v9, v9, v91
	v_add_f32_e32 v90, v90, v92
	ds_bpermute_b32 v91, v5, v9
	ds_bpermute_b32 v92, v5, v90
	s_waitcnt lgkmcnt(0)
	v_add_f32_e32 v9, v9, v91
	v_add_f32_e32 v90, v90, v92
	ds_bpermute_b32 v91, v6, v9
	ds_bpermute_b32 v92, v6, v90
	s_waitcnt lgkmcnt(0)
	v_add_f32_e32 v9, v9, v91
	v_add_f32_e32 v90, v90, v92
	ds_bpermute_b32 v91, v7, v9
	ds_bpermute_b32 v92, v7, v90
	s_waitcnt lgkmcnt(0)
	v_add_f32_e32 v9, v9, v91
	v_add_f32_e32 v90, v90, v92
	ds_bpermute_b32 v91, v8, v9
	ds_bpermute_b32 v92, v8, v90
	s_waitcnt lgkmcnt(0)
	v_add_f32_e32 v9, v9, v91
	v_add_f32_e32 v90, v90, v92
	v_mul_f32_e32 v93, 0x3a800000, v9
	v_mul_f32_e32 v91, 0x3a800000, v90
	v_fma_f32 v91, -v93, v93, v91
	v_max_f32_e32 v91, 0, v91
	v_add_f32_e32 v91, 0x358637bd, v91
	v_rsq_f32_e32 v94, v91
	v_mul_f32_e32 v91, 0.5, v91
	v_mul_f32_e32 v92, v94, v94
	v_fma_f32 v92, -v91, v92, 0.5
	v_fma_f32 v94, v94, v92, v94
	s_waitcnt vmcnt(14)
	v_sub_f32_e32 v74, v74, v93
	v_sub_f32_e32 v75, v75, v93
	v_sub_f32_e32 v76, v76, v93
	v_sub_f32_e32 v77, v77, v93
	v_sub_f32_e32 v78, v78, v93
	v_sub_f32_e32 v79, v79, v93
	v_sub_f32_e32 v80, v80, v93
	v_sub_f32_e32 v81, v81, v93
	v_sub_f32_e32 v82, v82, v93
	v_sub_f32_e32 v83, v83, v93
	v_sub_f32_e32 v84, v84, v93
	v_sub_f32_e32 v85, v85, v93
	v_sub_f32_e32 v86, v86, v93
	v_sub_f32_e32 v87, v87, v93
	v_sub_f32_e32 v88, v88, v93
	v_sub_f32_e32 v89, v89, v93
	v_add_f32_e32 v130, 1.0, v130
	v_add_f32_e32 v131, 1.0, v131
	v_add_f32_e32 v132, 1.0, v132
	v_add_f32_e32 v133, 1.0, v133
	v_add_f32_e32 v134, 1.0, v134
	v_add_f32_e32 v135, 1.0, v135
	v_add_f32_e32 v136, 1.0, v136
	v_add_f32_e32 v137, 1.0, v137
	v_add_f32_e32 v138, 1.0, v138
	v_add_f32_e32 v139, 1.0, v139
	v_add_f32_e32 v140, 1.0, v140
	v_add_f32_e32 v141, 1.0, v141
	v_add_f32_e32 v142, 1.0, v142
	v_add_f32_e32 v143, 1.0, v143
	v_add_f32_e32 v144, 1.0, v144
	v_add_f32_e32 v145, 1.0, v145
	v_mul_f32_e32 v74, v94, v74
	v_mul_f32_e32 v75, v94, v75
	v_mul_f32_e32 v76, v94, v76
	v_mul_f32_e32 v77, v94, v77
	v_mul_f32_e32 v78, v94, v78
	v_mul_f32_e32 v79, v94, v79
	v_mul_f32_e32 v80, v94, v80
	v_mul_f32_e32 v81, v94, v81
	v_mul_f32_e32 v82, v94, v82
	v_mul_f32_e32 v83, v94, v83
	v_mul_f32_e32 v84, v94, v84
	v_mul_f32_e32 v85, v94, v85
	v_mul_f32_e32 v86, v94, v86
	v_mul_f32_e32 v87, v94, v87
	v_mul_f32_e32 v88, v94, v88
	v_mul_f32_e32 v89, v94, v89
	v_fma_f32 v74, v74, v130, v114
	v_fma_f32 v75, v75, v131, v115
	v_fma_f32 v76, v76, v132, v116
	v_fma_f32 v77, v77, v133, v117
	v_fma_f32 v78, v78, v134, v118
	v_fma_f32 v79, v79, v135, v119
; DI unsigned pk2(float lo, float hi) { f32x2 v = {lo, hi}; bf16x2_t b = __builtin_convertvector(v, bf16x2_t); return __builtin_bit_cast(unsigned, b); }
; DI void ln_row_v(const Frame& F, f32x4 (&v)[4], float* xout, const float* g, const float* b, const float* sh, const float* sc, bf16_t* hout, const float* slab, const float* gres, float* stat = nullptr) {
;     ...
;         float s = 0.f, s2 = 0.f;
; #pragma unroll
;         for (int j = 0; j < 4; ++j) { s += (v[j][0] + v[j][1]) + (v[j][2] + v[j][3]); s2 += (v[j][0] * v[j][0] + v[j][1] * v[j][1]) + (v[j][2] * v[j][2] + v[j][3] * v[j][3]); }
;         wave_sum2(s, s2, F.lane);
;         const float mean = s * (1.f / D); const float rstd = 1.f / sqrtf(fmaxf(s2 * (1.f / D) - mean * mean, 0.f) + EPS);
;         if (stat && F.lane == 0) { f32x2 sv = {mean, rstd}; *(f32x2*)stat = sv; }
; #pragma unroll
;         for (int j = 0; j < 4; ++j) { const f32x4 gg = ((const f32x4*)g)[F.lane + 64 * j], bb = ((const f32x4*)b)[F.lane + 64 * j];
;             v[j] = (v[j] - mean) * rstd * gg + bb; if (xout) ((f32x4*)xout)[F.lane + 64 * j] = v[j]; }
;     }
;     if (hout) {
;         float s = 0.f, s2 = 0.f;
; #pragma unroll
;         for (int j = 0; j < 4; ++j) { s += (v[j][0] + v[j][1]) + (v[j][2] + v[j][3]); s2 += (v[j][0] * v[j][0] + v[j][1] * v[j][1]) + (v[j][2] * v[j][2] + v[j][3] * v[j][3]); }
;         wave_sum2(s, s2, F.lane);
;         const float mean = s * (1.f / D); const float rstd = 1.f / sqrtf(fmaxf(s2 * (1.f / D) - mean * mean, 0.f) + EPS);
; #pragma unroll
;         for (int j = 0; j < 4; ++j) { const f32x4 hh = ((const f32x4*)sh)[F.lane + 64 * j], cc = ((const f32x4*)sc)[F.lane + 64 * j];
;             const f32x4 o = (v[j] - mean) * rstd * (cc + 1.f) + hh; u32x2 wv; wv.x = pk2(o[0], o[1]); wv.y = pk2(o[2], o[3]);
;             ((u32x2*)hout)[F.lane + 64 * j] = wv; }
;     }
	v_fma_f32 v80, v80, v136, v120
	v_fma_f32 v81, v81, v137, v121
	v_fma_f32 v82, v82, v138, v122
	v_fma_f32 v83, v83, v139, v123
	v_fma_f32 v84, v84, v140, v124
	v_fma_f32 v85, v85, v141, v125
	v_fma_f32 v86, v86, v142, v126
	v_fma_f32 v87, v87, v143, v127
	v_fma_f32 v88, v88, v144, v128
	v_fma_f32 v89, v89, v145, v129
	v_cvt_pk_bf16_f32 v190, v74, v75
	v_cvt_pk_bf16_f32 v191, v76, v77
	v_cvt_pk_bf16_f32 v192, v78, v79
	v_cvt_pk_bf16_f32 v193, v80, v81
	v_cvt_pk_bf16_f32 v194, v82, v83
	v_cvt_pk_bf16_f32 v195, v84, v85
	v_cvt_pk_bf16_f32 v196, v86, v87
	v_cvt_pk_bf16_f32 v197, v88, v89
	s_add_u32 s2, s10, 0x1800000
	s_addc_u32 s3, s11, 0
	global_store_dwordx2 v1, v[190:191], s[2:3]
	global_store_dwordx2 v1, v[192:193], s[2:3] offset:512
	global_store_dwordx2 v1, v[194:195], s[2:3] offset:1024
	global_store_dwordx2 v1, v[196:197], s[2:3] offset:1536
	s_add_u32 s2, s14, 0x30000
	s_addc_u32 s3, s15, 0
	global_load_dwordx4 v[114:117], v0, s[2:3]
	global_load_dwordx4 v[118:121], v0, s[2:3] offset:1024
	global_load_dwordx4 v[122:125], v0, s[2:3] offset:2048
	global_load_dwordx4 v[126:129], v0, s[2:3] offset:3072
	s_add_u32 s2, s18, 0x30000
	s_addc_u32 s3, s19, 0
	global_load_dwordx4 v[130:133], v0, s[2:3]
	global_load_dwordx4 v[134:137], v0, s[2:3] offset:1024
	global_load_dwordx4 v[138:141], v0, s[2:3] offset:2048
	global_load_dwordx4 v[142:145], v0, s[2:3] offset:3072
	v_add_f32_e32 v9, v98, v99
	v_add_f32_e32 v91, v100, v101
	v_mul_f32_e32 v90, v98, v98
	v_mul_f32_e32 v92, v99, v99
	v_add_f32_e32 v9, v9, v102
	v_add_f32_e32 v91, v91, v103
	v_add_f32_e32 v9, v9, v104
	v_add_f32_e32 v91, v91, v105
	v_add_f32_e32 v9, v9, v106
	v_add_f32_e32 v91, v91, v107
	v_add_f32_e32 v9, v9, v108
	v_add_f32_e32 v91, v91, v109
	v_add_f32_e32 v9, v9, v110
	v_add_f32_e32 v91, v91, v111
	v_add_f32_e32 v9, v9, v112
	v_add_f32_e32 v91, v91, v113
	v_fmac_f32_e32 v90, v100, v100
	v_fmac_f32_e32 v92, v101, v101
	v_fmac_f32_e32 v90, v102, v102
	v_fmac_f32_e32 v92, v103, v103
	v_fmac_f32_e32 v90, v104, v104
	v_fmac_f32_e32 v92, v105, v105
	v_fmac_f32_e32 v90, v106, v106
	v_fmac_f32_e32 v92, v107, v107
	v_fmac_f32_e32 v90, v108, v108
	v_fmac_f32_e32 v92, v109, v109
	v_fmac_f32_e32 v90, v110, v110
	v_fmac_f32_e32 v92, v111, v111
	v_fmac_f32_e32 v90, v112, v112
	v_fmac_f32_e32 v92, v113, v113
	v_add_f32_e32 v9, v9, v91
	v_add_f32_e32 v90, v90, v92
	ds_bpermute_b32 v91, v3, v9
	ds_bpermute_b32 v92, v3, v90
	s_waitcnt lgkmcnt(0)
	v_add_f32_e32 v9, v9, v91
	v_add_f32_e32 v90, v90, v92
	ds_bpermute_b32 v91, v4, v9
	ds_bpermute_b32 v92, v4, v90
	s_waitcnt lgkmcnt(0)
	v_add_f32_e32 v9, v9, v91
	v_add_f32_e32 v90, v90, v92
	ds_bpermute_b32 v91, v5, v9
	ds_bpermute_b32 v92, v5, v90
	s_waitcnt lgkmcnt(0)
	v_add_f32_e32 v9, v9, v91
	v_add_f32_e32 v90, v90, v92
	ds_bpermute_b32 v91, v6, v9
	ds_bpermute_b32 v92, v6, v90
	s_waitcnt lgkmcnt(0)
	v_add_f32_e32 v9, v9, v91
	v_add_f32_e32 v90, v90, v92
	ds_bpermute_b32 v91, v7, v9
	ds_bpermute_b32 v92, v7, v90
	s_waitcnt lgkmcnt(0)
	v_add_f32_e32 v9, v9, v91
	v_add_f32_e32 v90, v90, v92
	ds_bpermute_b32 v91, v8, v9
	ds_bpermute_b32 v92, v8, v90
	s_waitcnt lgkmcnt(0)
	v_add_f32_e32 v9, v9, v91
	v_add_f32_e32 v90, v90, v92
	v_mul_f32_e32 v93, 0x3a800000, v9
	v_mul_f32_e32 v91, 0x3a800000, v90
	v_fma_f32 v91, -v93, v93, v91
	v_max_f32_e32 v91, 0, v91
	v_add_f32_e32 v91, 0x358637bd, v91
	v_rsq_f32_e32 v94, v91
	v_mul_f32_e32 v91, 0.5, v91
	v_mul_f32_e32 v92, v94, v94
	v_fma_f32 v92, -v91, v92, 0.5
	v_fma_f32 v94, v94, v92, v94
	s_add_u32 s2, s12, 0x1c000
	s_addc_u32 s3, s13, 0
	v_mov_b32_e32 v188, v93
	v_mov_b32_e32 v189, v94
	s_mov_b64 exec, 1
	global_store_dwordx2 v97, v[188:189], s[2:3]
	s_mov_b64 exec, -1
	v_sub_f32_e32 v98, v98, v93
	v_sub_f32_e32 v99, v99, v93
	v_sub_f32_e32 v100, v100, v93
	v_sub_f32_e32 v101, v101, v93
	v_sub_f32_e32 v102, v102, v93
	v_sub_f32_e32 v103, v103, v93
	v_sub_f32_e32 v104, v104, v93
	v_sub_f32_e32 v105, v105, v93
	v_sub_f32_e32 v106, v106, v93
	v_sub_f32_e32 v107, v107, v93
	v_sub_f32_e32 v108, v108, v93
	v_sub_f32_e32 v109, v109, v93
	v_sub_f32_e32 v110, v110, v93
	v_sub_f32_e32 v111, v111, v93
	v_sub_f32_e32 v112, v112, v93
	v_sub_f32_e32 v113, v113, v93
	v_mul_f32_e32 v98, v94, v98
	v_mul_f32_e32 v99, v94, v99
	v_mul_f32_e32 v100, v94, v100
	v_mul_f32_e32 v101, v94, v101
	v_mul_f32_e32 v102, v94, v102
	v_mul_f32_e32 v103, v94, v103
	v_mul_f32_e32 v104, v94, v104
	v_mul_f32_e32 v105, v94, v105
	v_mul_f32_e32 v106, v94, v106
	v_mul_f32_e32 v107, v94, v107
	v_mul_f32_e32 v108, v94, v108
	v_mul_f32_e32 v109, v94, v109
	v_mul_f32_e32 v110, v94, v110
	v_mul_f32_e32 v111, v94, v111
	v_mul_f32_e32 v112, v94, v112
	v_mul_f32_e32 v113, v94, v113
	v_fma_f32 v98, v98, v10, v26
	v_fma_f32 v99, v99, v11, v27
	v_fma_f32 v100, v100, v12, v28
	v_fma_f32 v101, v101, v13, v29
	v_fma_f32 v102, v102, v14, v30
	v_fma_f32 v103, v103, v15, v31
	v_fma_f32 v104, v104, v16, v32
	v_fma_f32 v105, v105, v17, v33
	v_fma_f32 v106, v106, v18, v34
	v_fma_f32 v107, v107, v19, v35
	v_fma_f32 v108, v108, v20, v36
	v_fma_f32 v109, v109, v21, v37
	v_fma_f32 v110, v110, v22, v38
	v_fma_f32 v111, v111, v23, v39
	v_fma_f32 v112, v112, v24, v40
	v_fma_f32 v113, v113, v25, v41
	v_add_f32_e32 v9, v98, v99
	v_add_f32_e32 v91, v100, v101
	v_mul_f32_e32 v90, v98, v98
	v_mul_f32_e32 v92, v99, v99
	v_add_f32_e32 v9, v9, v102
	v_add_f32_e32 v91, v91, v103
	v_add_f32_e32 v9, v9, v104
	v_add_f32_e32 v91, v91, v105
	v_add_f32_e32 v9, v9, v106
	v_add_f32_e32 v91, v91, v107
	v_add_f32_e32 v9, v9, v108
	v_add_f32_e32 v91, v91, v109
	v_add_f32_e32 v9, v9, v110
	v_add_f32_e32 v91, v91, v111
	v_add_f32_e32 v9, v9, v112
	v_add_f32_e32 v91, v91, v113
	v_fmac_f32_e32 v90, v100, v100
	v_fmac_f32_e32 v92, v101, v101
	v_fmac_f32_e32 v90, v102, v102
	v_fmac_f32_e32 v92, v103, v103
	v_fmac_f32_e32 v90, v104, v104
	v_fmac_f32_e32 v92, v105, v105
	v_fmac_f32_e32 v90, v106, v106
	v_fmac_f32_e32 v92, v107, v107
	v_fmac_f32_e32 v90, v108, v108
	v_fmac_f32_e32 v92, v109, v109
	v_fmac_f32_e32 v90, v110, v110
	v_fmac_f32_e32 v92, v111, v111
	v_fmac_f32_e32 v90, v112, v112
	v_fmac_f32_e32 v92, v113, v113
	v_add_f32_e32 v9, v9, v91
	v_add_f32_e32 v90, v90, v92
	ds_bpermute_b32 v91, v3, v9
	ds_bpermute_b32 v92, v3, v90
	s_waitcnt lgkmcnt(0)
; DI unsigned pk2(float lo, float hi) { f32x2 v = {lo, hi}; bf16x2_t b = __builtin_convertvector(v, bf16x2_t); return __builtin_bit_cast(unsigned, b); }
; DI void ln_row_v(const Frame& F, f32x4 (&v)[4], float* xout, const float* g, const float* b, const float* sh, const float* sc, bf16_t* hout, const float* slab, const float* gres, float* stat = nullptr) {
;     ...
;         float s = 0.f, s2 = 0.f;
; #pragma unroll
;         for (int j = 0; j < 4; ++j) { s += (v[j][0] + v[j][1]) + (v[j][2] + v[j][3]); s2 += (v[j][0] * v[j][0] + v[j][1] * v[j][1]) + (v[j][2] * v[j][2] + v[j][3] * v[j][3]); }
;         wave_sum2(s, s2, F.lane);
;         const float mean = s * (1.f / D); const float rstd = 1.f / sqrtf(fmaxf(s2 * (1.f / D) - mean * mean, 0.f) + EPS);
;         if (stat && F.lane == 0) { f32x2 sv = {mean, rstd}; *(f32x2*)stat = sv; }
; #pragma unroll
;         for (int j = 0; j < 4; ++j) { const f32x4 gg = ((const f32x4*)g)[F.lane + 64 * j], bb = ((const f32x4*)b)[F.lane + 64 * j];
;             v[j] = (v[j] - mean) * rstd * gg + bb; if (xout) ((f32x4*)xout)[F.lane + 64 * j] = v[j]; }
;     }
;     if (hout) {
;         float s = 0.f, s2 = 0.f;
; #pragma unroll
;         for (int j = 0; j < 4; ++j) { s += (v[j][0] + v[j][1]) + (v[j][2] + v[j][3]); s2 += (v[j][0] * v[j][0] + v[j][1] * v[j][1]) + (v[j][2] * v[j][2] + v[j][3] * v[j][3]); }
;         wave_sum2(s, s2, F.lane);
;         const float mean = s * (1.f / D); const float rstd = 1.f / sqrtf(fmaxf(s2 * (1.f / D) - mean * mean, 0.f) + EPS);
; #pragma unroll
;         for (int j = 0; j < 4; ++j) { const f32x4 hh = ((const f32x4*)sh)[F.lane + 64 * j], cc = ((const f32x4*)sc)[F.lane + 64 * j];
;             const f32x4 o = (v[j] - mean) * rstd * (cc + 1.f) + hh; u32x2 wv; wv.x = pk2(o[0], o[1]); wv.y = pk2(o[2], o[3]);
;             ((u32x2*)hout)[F.lane + 64 * j] = wv; }
;     }
; DI void ln_phase(const Frame& F, int which) {
;     ...
;         const bool sl = (which == 1 && row >= ML);
;         const bool st_only = row < ML && !(which == 1 && l == NL - 1);
;         float* stp = st_only ? (float*)(F.ws + (which == 0 ? WS_ST1 : WS_ST2)) + 2 * (size_t)row : nullptr;
;         ln_row_v(F, vc, st_only ? nullptr : xrow_ptr(F, row), g, b, sh, sc, wh ? H + (size_t)row * D : nullptr, sl ? (const float*)(F.ws + WS_KN) + (size_t)(row - ML) * 1024 : nullptr, modp(F, l, mr, 5), stp);
	v_add_f32_e32 v9, v9, v91
	v_add_f32_e32 v90, v90, v92
	ds_bpermute_b32 v91, v4, v9
	ds_bpermute_b32 v92, v4, v90
	s_waitcnt lgkmcnt(0)
	v_add_f32_e32 v9, v9, v91
	v_add_f32_e32 v90, v90, v92
	ds_bpermute_b32 v91, v5, v9
	ds_bpermute_b32 v92, v5, v90
	s_waitcnt lgkmcnt(0)
	v_add_f32_e32 v9, v9, v91
	v_add_f32_e32 v90, v90, v92
	ds_bpermute_b32 v91, v6, v9
	ds_bpermute_b32 v92, v6, v90
	s_waitcnt lgkmcnt(0)
	v_add_f32_e32 v9, v9, v91
	v_add_f32_e32 v90, v90, v92
	ds_bpermute_b32 v91, v7, v9
	ds_bpermute_b32 v92, v7, v90
	s_waitcnt lgkmcnt(0)
	v_add_f32_e32 v9, v9, v91
	v_add_f32_e32 v90, v90, v92
	ds_bpermute_b32 v91, v8, v9
	ds_bpermute_b32 v92, v8, v90
	s_waitcnt lgkmcnt(0)
	v_add_f32_e32 v9, v9, v91
	v_add_f32_e32 v90, v90, v92
	v_mul_f32_e32 v93, 0x3a800000, v9
	v_mul_f32_e32 v91, 0x3a800000, v90
	v_fma_f32 v91, -v93, v93, v91
	v_max_f32_e32 v91, 0, v91
	v_add_f32_e32 v91, 0x358637bd, v91
	v_rsq_f32_e32 v94, v91
	v_mul_f32_e32 v91, 0.5, v91
	v_mul_f32_e32 v92, v94, v94
	v_fma_f32 v92, -v91, v92, 0.5
	v_fma_f32 v94, v94, v92, v94
	s_waitcnt vmcnt(14)
	v_sub_f32_e32 v98, v98, v93
	v_sub_f32_e32 v99, v99, v93
	v_sub_f32_e32 v100, v100, v93
	v_sub_f32_e32 v101, v101, v93
	v_sub_f32_e32 v102, v102, v93
	v_sub_f32_e32 v103, v103, v93
	v_sub_f32_e32 v104, v104, v93
	v_sub_f32_e32 v105, v105, v93
	v_sub_f32_e32 v106, v106, v93
	v_sub_f32_e32 v107, v107, v93
	v_sub_f32_e32 v108, v108, v93
	v_sub_f32_e32 v109, v109, v93
	v_sub_f32_e32 v110, v110, v93
	v_sub_f32_e32 v111, v111, v93
	v_sub_f32_e32 v112, v112, v93
	v_sub_f32_e32 v113, v113, v93
	v_add_f32_e32 v162, 1.0, v162
	v_add_f32_e32 v163, 1.0, v163
	v_add_f32_e32 v164, 1.0, v164
	v_add_f32_e32 v165, 1.0, v165
	v_add_f32_e32 v166, 1.0, v166
	v_add_f32_e32 v167, 1.0, v167
	v_add_f32_e32 v168, 1.0, v168
	v_add_f32_e32 v169, 1.0, v169
	v_add_f32_e32 v170, 1.0, v170
	v_add_f32_e32 v171, 1.0, v171
	v_add_f32_e32 v172, 1.0, v172
	v_add_f32_e32 v173, 1.0, v173
	v_add_f32_e32 v174, 1.0, v174
	v_add_f32_e32 v175, 1.0, v175
	v_add_f32_e32 v176, 1.0, v176
	v_add_f32_e32 v177, 1.0, v177
	v_mul_f32_e32 v98, v94, v98
	v_mul_f32_e32 v99, v94, v99
	v_mul_f32_e32 v100, v94, v100
	v_mul_f32_e32 v101, v94, v101
	v_mul_f32_e32 v102, v94, v102
	v_mul_f32_e32 v103, v94, v103
	v_mul_f32_e32 v104, v94, v104
	v_mul_f32_e32 v105, v94, v105
	v_mul_f32_e32 v106, v94, v106
	v_mul_f32_e32 v107, v94, v107
	v_mul_f32_e32 v108, v94, v108
	v_mul_f32_e32 v109, v94, v109
	v_mul_f32_e32 v110, v94, v110
	v_mul_f32_e32 v111, v94, v111
	v_mul_f32_e32 v112, v94, v112
	v_mul_f32_e32 v113, v94, v113
	v_fma_f32 v98, v98, v162, v146
	v_fma_f32 v99, v99, v163, v147
	v_fma_f32 v100, v100, v164, v148
	v_fma_f32 v101, v101, v165, v149
	v_fma_f32 v102, v102, v166, v150
	v_fma_f32 v103, v103, v167, v151
	v_fma_f32 v104, v104, v168, v152
	v_fma_f32 v105, v105, v169, v153
	v_fma_f32 v106, v106, v170, v154
	v_fma_f32 v107, v107, v171, v155
	v_fma_f32 v108, v108, v172, v156
	v_fma_f32 v109, v109, v173, v157
	v_fma_f32 v110, v110, v174, v158
	v_fma_f32 v111, v111, v175, v159
	v_fma_f32 v112, v112, v176, v160
	v_fma_f32 v113, v113, v177, v161
	v_cvt_pk_bf16_f32 v190, v98, v99
	v_cvt_pk_bf16_f32 v191, v100, v101
	v_cvt_pk_bf16_f32 v192, v102, v103
	v_cvt_pk_bf16_f32 v193, v104, v105
	v_cvt_pk_bf16_f32 v194, v106, v107
	v_cvt_pk_bf16_f32 v195, v108, v109
	v_cvt_pk_bf16_f32 v196, v110, v111
	v_cvt_pk_bf16_f32 v197, v112, v113
	s_add_u32 s2, s10, 0x1c00000
	s_addc_u32 s3, s11, 0
	global_store_dwordx2 v1, v[190:191], s[2:3]
	global_store_dwordx2 v1, v[192:193], s[2:3] offset:512
	global_store_dwordx2 v1, v[194:195], s[2:3] offset:1024
	global_store_dwordx2 v1, v[196:197], s[2:3] offset:1536
	s_cmp_eq_u32 s22, 3
	s_cbranch_scc1 .Lln_a_noctx
	v_add_f32_e32 v9, v42, v43
	v_add_f32_e32 v91, v44, v45
	v_mul_f32_e32 v90, v42, v42
	v_mul_f32_e32 v92, v43, v43
	v_add_f32_e32 v9, v9, v46
	v_add_f32_e32 v91, v91, v47
	v_add_f32_e32 v9, v9, v48
	v_add_f32_e32 v91, v91, v49
	v_add_f32_e32 v9, v9, v50
	v_add_f32_e32 v91, v91, v51
	v_add_f32_e32 v9, v9, v52
	v_add_f32_e32 v91, v91, v53
	v_add_f32_e32 v9, v9, v54
	v_add_f32_e32 v91, v91, v55
	v_add_f32_e32 v9, v9, v56
	v_add_f32_e32 v91, v91, v57
	v_fmac_f32_e32 v90, v44, v44
	v_fmac_f32_e32 v92, v45, v45
	v_fmac_f32_e32 v90, v46, v46
	v_fmac_f32_e32 v92, v47, v47
	v_fmac_f32_e32 v90, v48, v48
	v_fmac_f32_e32 v92, v49, v49
	v_fmac_f32_e32 v90, v50, v50
	v_fmac_f32_e32 v92, v51, v51
	v_fmac_f32_e32 v90, v52, v52
	v_fmac_f32_e32 v92, v53, v53
	v_fmac_f32_e32 v90, v54, v54
	v_fmac_f32_e32 v92, v55, v55
	v_fmac_f32_e32 v90, v56, v56
	v_fmac_f32_e32 v92, v57, v57
	v_add_f32_e32 v9, v9, v91
	v_add_f32_e32 v90, v90, v92
	ds_bpermute_b32 v91, v3, v9
	ds_bpermute_b32 v92, v3, v90
	s_waitcnt lgkmcnt(0)
	v_add_f32_e32 v9, v9, v91
	v_add_f32_e32 v90, v90, v92
	ds_bpermute_b32 v91, v4, v9
	ds_bpermute_b32 v92, v4, v90
	s_waitcnt lgkmcnt(0)
	v_add_f32_e32 v9, v9, v91
	v_add_f32_e32 v90, v90, v92
	ds_bpermute_b32 v91, v5, v9
	ds_bpermute_b32 v92, v5, v90
	s_waitcnt lgkmcnt(0)
	v_add_f32_e32 v9, v9, v91
	v_add_f32_e32 v90, v90, v92
	ds_bpermute_b32 v91, v6, v9
	ds_bpermute_b32 v92, v6, v90
	s_waitcnt lgkmcnt(0)
	v_add_f32_e32 v9, v9, v91
	v_add_f32_e32 v90, v90, v92
	ds_bpermute_b32 v91, v7, v9
	ds_bpermute_b32 v92, v7, v90
	s_waitcnt lgkmcnt(0)
	v_add_f32_e32 v9, v9, v91
	v_add_f32_e32 v90, v90, v92
	ds_bpermute_b32 v91, v8, v9
	ds_bpermute_b32 v92, v8, v90
	s_waitcnt lgkmcnt(0)
; DI unsigned pk2(float lo, float hi) { f32x2 v = {lo, hi}; bf16x2_t b = __builtin_convertvector(v, bf16x2_t); return __builtin_bit_cast(unsigned, b); }
; DI void ln_row_v(const Frame& F, f32x4 (&v)[4], float* xout, const float* g, const float* b, const float* sh, const float* sc, bf16_t* hout, const float* slab, const float* gres, float* stat = nullptr) {
;     ...
;         float s = 0.f, s2 = 0.f;
; #pragma unroll
;         for (int j = 0; j < 4; ++j) { s += (v[j][0] + v[j][1]) + (v[j][2] + v[j][3]); s2 += (v[j][0] * v[j][0] + v[j][1] * v[j][1]) + (v[j][2] * v[j][2] + v[j][3] * v[j][3]); }
;         wave_sum2(s, s2, F.lane);
;         const float mean = s * (1.f / D); const float rstd = 1.f / sqrtf(fmaxf(s2 * (1.f / D) - mean * mean, 0.f) + EPS);
;         if (stat && F.lane == 0) { f32x2 sv = {mean, rstd}; *(f32x2*)stat = sv; }
; #pragma unroll
;         for (int j = 0; j < 4; ++j) { const f32x4 gg = ((const f32x4*)g)[F.lane + 64 * j], bb = ((const f32x4*)b)[F.lane + 64 * j];
;             v[j] = (v[j] - mean) * rstd * gg + bb; if (xout) ((f32x4*)xout)[F.lane + 64 * j] = v[j]; }
;     }
;     if (hout) {
;         float s = 0.f, s2 = 0.f;
; #pragma unroll
;         for (int j = 0; j < 4; ++j) { s += (v[j][0] + v[j][1]) + (v[j][2] + v[j][3]); s2 += (v[j][0] * v[j][0] + v[j][1] * v[j][1]) + (v[j][2] * v[j][2] + v[j][3] * v[j][3]); }
;         wave_sum2(s, s2, F.lane);
;         const float mean = s * (1.f / D); const float rstd = 1.f / sqrtf(fmaxf(s2 * (1.f / D) - mean * mean, 0.f) + EPS);
; #pragma unroll
;         for (int j = 0; j < 4; ++j) { const f32x4 hh = ((const f32x4*)sh)[F.lane + 64 * j], cc = ((const f32x4*)sc)[F.lane + 64 * j];
;             const f32x4 o = (v[j] - mean) * rstd * (cc + 1.f) + hh; u32x2 wv; wv.x = pk2(o[0], o[1]); wv.y = pk2(o[2], o[3]);
;             ((u32x2*)hout)[F.lane + 64 * j] = wv; }
;     }
; DI void ln_phase(const Frame& F, int which) {
;     ...
;         const bool sl = (which == 1 && row >= ML);
;         const bool st_only = row < ML && !(which == 1 && l == NL - 1);
;         float* stp = st_only ? (float*)(F.ws + (which == 0 ? WS_ST1 : WS_ST2)) + 2 * (size_t)row : nullptr;
;         ln_row_v(F, vc, st_only ? nullptr : xrow_ptr(F, row), g, b, sh, sc, wh ? H + (size_t)row * D : nullptr, sl ? (const float*)(F.ws + WS_KN) + (size_t)(row - ML) * 1024 : nullptr, modp(F, l, mr, 5), stp);
	v_add_f32_e32 v9, v9, v91
	v_add_f32_e32 v90, v90, v92
	v_mul_f32_e32 v93, 0x3a800000, v9
	v_mul_f32_e32 v91, 0x3a800000, v90
	v_fma_f32 v91, -v93, v93, v91
	v_max_f32_e32 v91, 0, v91
	v_add_f32_e32 v91, 0x358637bd, v91
	v_rsq_f32_e32 v94, v91
	v_mul_f32_e32 v91, 0.5, v91
	v_mul_f32_e32 v92, v94, v94
	v_fma_f32 v92, -v91, v92, 0.5
	v_fma_f32 v94, v94, v92, v94
	v_sub_f32_e32 v42, v42, v93
	v_sub_f32_e32 v43, v43, v93
	v_sub_f32_e32 v44, v44, v93
	v_sub_f32_e32 v45, v45, v93
	v_sub_f32_e32 v46, v46, v93
	v_sub_f32_e32 v47, v47, v93
	v_sub_f32_e32 v48, v48, v93
	v_sub_f32_e32 v49, v49, v93
	v_sub_f32_e32 v50, v50, v93
	v_sub_f32_e32 v51, v51, v93
	v_sub_f32_e32 v52, v52, v93
	v_sub_f32_e32 v53, v53, v93
	v_sub_f32_e32 v54, v54, v93
	v_sub_f32_e32 v55, v55, v93
	v_sub_f32_e32 v56, v56, v93
	v_sub_f32_e32 v57, v57, v93
	v_mul_f32_e32 v42, v94, v42
	v_mul_f32_e32 v43, v94, v43
	v_mul_f32_e32 v44, v94, v44
	v_mul_f32_e32 v45, v94, v45
	v_mul_f32_e32 v46, v94, v46
	v_mul_f32_e32 v47, v94, v47
	v_mul_f32_e32 v48, v94, v48
	v_mul_f32_e32 v49, v94, v49
	v_mul_f32_e32 v50, v94, v50
	v_mul_f32_e32 v51, v94, v51
	v_mul_f32_e32 v52, v94, v52
	v_mul_f32_e32 v53, v94, v53
	v_mul_f32_e32 v54, v94, v54
	v_mul_f32_e32 v55, v94, v55
	v_mul_f32_e32 v56, v94, v56
	v_mul_f32_e32 v57, v94, v57
	v_fma_f32 v42, v42, v10, v26
	v_fma_f32 v43, v43, v11, v27
	v_fma_f32 v44, v44, v12, v28
	v_fma_f32 v45, v45, v13, v29
	v_fma_f32 v46, v46, v14, v30
	v_fma_f32 v47, v47, v15, v31
	v_fma_f32 v48, v48, v16, v32
	v_fma_f32 v49, v49, v17, v33
	v_fma_f32 v50, v50, v18, v34
	v_fma_f32 v51, v51, v19, v35
	v_fma_f32 v52, v52, v20, v36
	v_fma_f32 v53, v53, v21, v37
	v_fma_f32 v54, v54, v22, v38
	v_fma_f32 v55, v55, v23, v39
	v_fma_f32 v56, v56, v24, v40
	v_fma_f32 v57, v57, v25, v41
	s_mov_b64 s[2:3], s[20:21]
	global_store_dwordx4 v0, v[42:45], s[2:3]
	global_store_dwordx4 v0, v[46:49], s[2:3] offset:1024
	global_store_dwordx4 v0, v[50:53], s[2:3] offset:2048
	global_store_dwordx4 v0, v[54:57], s[2:3] offset:3072
	v_add_f32_e32 v9, v42, v43
	v_add_f32_e32 v91, v44, v45
	v_mul_f32_e32 v90, v42, v42
	v_mul_f32_e32 v92, v43, v43
	v_add_f32_e32 v9, v9, v46
	v_add_f32_e32 v91, v91, v47
	v_add_f32_e32 v9, v9, v48
	v_add_f32_e32 v91, v91, v49
	v_add_f32_e32 v9, v9, v50
	v_add_f32_e32 v91, v91, v51
	v_add_f32_e32 v9, v9, v52
	v_add_f32_e32 v91, v91, v53
	v_add_f32_e32 v9, v9, v54
	v_add_f32_e32 v91, v91, v55
	v_add_f32_e32 v9, v9, v56
	v_add_f32_e32 v91, v91, v57
	v_fmac_f32_e32 v90, v44, v44
	v_fmac_f32_e32 v92, v45, v45
	v_fmac_f32_e32 v90, v46, v46
	v_fmac_f32_e32 v92, v47, v47
	v_fmac_f32_e32 v90, v48, v48
	v_fmac_f32_e32 v92, v49, v49
	v_fmac_f32_e32 v90, v50, v50
	v_fmac_f32_e32 v92, v51, v51
	v_fmac_f32_e32 v90, v52, v52
	v_fmac_f32_e32 v92, v53, v53
	v_fmac_f32_e32 v90, v54, v54
	v_fmac_f32_e32 v92, v55, v55
	v_fmac_f32_e32 v90, v56, v56
	v_fmac_f32_e32 v92, v57, v57
	v_add_f32_e32 v9, v9, v91
	v_add_f32_e32 v90, v90, v92
	ds_bpermute_b32 v91, v3, v9
	ds_bpermute_b32 v92, v3, v90
	s_waitcnt lgkmcnt(0)
	v_add_f32_e32 v9, v9, v91
	v_add_f32_e32 v90, v90, v92
	ds_bpermute_b32 v91, v4, v9
	ds_bpermute_b32 v92, v4, v90
	s_waitcnt lgkmcnt(0)
	v_add_f32_e32 v9, v9, v91
	v_add_f32_e32 v90, v90, v92
	ds_bpermute_b32 v91, v5, v9
	ds_bpermute_b32 v92, v5, v90
	s_waitcnt lgkmcnt(0)
	v_add_f32_e32 v9, v9, v91
	v_add_f32_e32 v90, v90, v92
	ds_bpermute_b32 v91, v6, v9
	ds_bpermute_b32 v92, v6, v90
	s_waitcnt lgkmcnt(0)
	v_add_f32_e32 v9, v9, v91
	v_add_f32_e32 v90, v90, v92
	ds_bpermute_b32 v91, v7, v9
	ds_bpermute_b32 v92, v7, v90
	s_waitcnt lgkmcnt(0)
	v_add_f32_e32 v9, v9, v91
	v_add_f32_e32 v90, v90, v92
	ds_bpermute_b32 v91, v8, v9
	ds_bpermute_b32 v92, v8, v90
	s_waitcnt lgkmcnt(0)
	v_add_f32_e32 v9, v9, v91
	v_add_f32_e32 v90, v90, v92
	v_mul_f32_e32 v93, 0x3a800000, v9
	v_mul_f32_e32 v91, 0x3a800000, v90
	v_fma_f32 v91, -v93, v93, v91
	v_max_f32_e32 v91, 0, v91
	v_add_f32_e32 v91, 0x358637bd, v91
	v_rsq_f32_e32 v94, v91
	v_mul_f32_e32 v91, 0.5, v91
	v_mul_f32_e32 v92, v94, v94
	v_fma_f32 v92, -v91, v92, 0.5
	v_fma_f32 v94, v94, v92, v94
	s_waitcnt vmcnt(9)
	v_sub_f32_e32 v42, v42, v93
	v_sub_f32_e32 v43, v43, v93
	v_sub_f32_e32 v44, v44, v93
	v_sub_f32_e32 v45, v45, v93
	v_sub_f32_e32 v46, v46, v93
	v_sub_f32_e32 v47, v47, v93
	v_sub_f32_e32 v48, v48, v93
	v_sub_f32_e32 v49, v49, v93
	v_sub_f32_e32 v50, v50, v93
	v_sub_f32_e32 v51, v51, v93
	v_sub_f32_e32 v52, v52, v93
	v_sub_f32_e32 v53, v53, v93
	v_sub_f32_e32 v54, v54, v93
	v_sub_f32_e32 v55, v55, v93
	v_sub_f32_e32 v56, v56, v93
	v_sub_f32_e32 v57, v57, v93
	v_add_f32_e32 v130, 1.0, v130
	v_add_f32_e32 v131, 1.0, v131
	v_add_f32_e32 v132, 1.0, v132
	v_add_f32_e32 v133, 1.0, v133
	v_add_f32_e32 v134, 1.0, v134
	v_add_f32_e32 v135, 1.0, v135
	v_add_f32_e32 v136, 1.0, v136
	v_add_f32_e32 v137, 1.0, v137
	v_add_f32_e32 v138, 1.0, v138
	v_add_f32_e32 v139, 1.0, v139
	v_add_f32_e32 v140, 1.0, v140
	v_add_f32_e32 v141, 1.0, v141
	v_add_f32_e32 v142, 1.0, v142
	v_add_f32_e32 v143, 1.0, v143
	v_add_f32_e32 v144, 1.0, v144
	v_add_f32_e32 v145, 1.0, v145
	v_mul_f32_e32 v42, v94, v42
	v_mul_f32_e32 v43, v94, v43
	v_mul_f32_e32 v44, v94, v44
	v_mul_f32_e32 v45, v94, v45
	v_mul_f32_e32 v46, v94, v46
	v_mul_f32_e32 v47, v94, v47
	v_mul_f32_e32 v48, v94, v48
	v_mul_f32_e32 v49, v94, v49
	v_mul_f32_e32 v50, v94, v50
	v_mul_f32_e32 v51, v94, v51
	v_mul_f32_e32 v52, v94, v52
	v_mul_f32_e32 v53, v94, v53
	v_mul_f32_e32 v54, v94, v54
	v_mul_f32_e32 v55, v94, v55
	v_mul_f32_e32 v56, v94, v56
	v_mul_f32_e32 v57, v94, v57
	v_fma_f32 v42, v42, v130, v114
	v_fma_f32 v43, v43, v131, v115
	v_fma_f32 v44, v44, v132, v116
	v_fma_f32 v45, v45, v133, v117
	v_fma_f32 v46, v46, v134, v118
	v_fma_f32 v47, v47, v135, v119
	v_fma_f32 v48, v48, v136, v120
	v_fma_f32 v49, v49, v137, v121
	v_fma_f32 v50, v50, v138, v122
	v_fma_f32 v51, v51, v139, v123
	v_fma_f32 v52, v52, v140, v124
	v_fma_f32 v53, v53, v141, v125
	v_fma_f32 v54, v54, v142, v126
	v_fma_f32 v55, v55, v143, v127
	v_fma_f32 v56, v56, v144, v128
	v_fma_f32 v57, v57, v145, v129
	v_cvt_pk_bf16_f32 v190, v42, v43
	v_cvt_pk_bf16_f32 v191, v44, v45
	v_cvt_pk_bf16_f32 v192, v46, v47
	v_cvt_pk_bf16_f32 v193, v48, v49
	v_cvt_pk_bf16_f32 v194, v50, v51
	v_cvt_pk_bf16_f32 v195, v52, v53
	v_cvt_pk_bf16_f32 v196, v54, v55
	v_cvt_pk_bf16_f32 v197, v56, v57
	s_add_u32 s2, s10, 0x2000000
	s_addc_u32 s3, s11, 0
	global_store_dwordx2 v1, v[190:191], s[2:3]
	global_store_dwordx2 v1, v[192:193], s[2:3] offset:512
	global_store_dwordx2 v1, v[194:195], s[2:3] offset:1024
	global_store_dwordx2 v1, v[196:197], s[2:3] offset:1536
; DI void ln_phase(const Frame& F, int which) {
;     const int gw = F.vcu * 8 + F.wave, NGW = F.G * 8; const int l = F.l;
;     const int nrows = (l == NL - 1) ? ML : MT;
;     bf16_t* H = (bf16_t*)(F.ws + WS_HB);
;     const float* g = pin(F, which == 0 ? I_LN1G : I_LN2G) + l * 1024; const float* b = pin(F, which == 0 ? I_LN1B : I_LN2B) + l * 1024;
;     const bool wh = !(which == 1 && l == NL - 1);
;     f32x4 vc[4], vn[4];
;     if (gw < nrows) ln_load(F, xrow_ptr(F, gw), vc);
;     for (int row = gw; row < nrows; row += NGW) {
;         if (row + NGW < nrows) ln_load(F, xrow_ptr(F, row + NGW), vn);
.Lln_a_noctx:
	s_waitcnt vmcnt(0)
	s_add_i32 s16, s16, 0x4800
	s_add_i32 s2, s70, 0xffe5
	s_and_b32 s2, s2, 0xff
	s_cmp_lt_u32 s2, 9
	s_movk_i32 s2, 0x4800
	s_cselect_b32 s8, 0x4000, s2
	s_cmp_ge_u32 s16, s8
	s_cbranch_scc1 .LBB0_124
	s_lshl_b32 s9, s93, 3
	s_lshl_b64 s[2:3], s[44:45], 3
	s_add_u32 s2, s62, s2
	s_addc_u32 s3, s63, s3
	s_load_dwordx4 s[4:7], s[2:3], 0x98
	v_readlane_b32 s2, v255, 35
	s_lshl_b32 s2, s2, 12
	v_mov_b32_e32 v0, s16
	v_sub_co_u32_e32 v1, vcc, s16, v217
	s_waitcnt lgkmcnt(0)
	s_add_u32 s10, s6, s2
	s_addc_u32 s11, s7, 0
	s_add_u32 s12, s4, s2
	s_addc_u32 s13, s5, 0
	s_add_u32 s18, s94, 0x3600000
	s_addc_u32 s19, s95, 0
	v_readlane_b32 s20, v255, 17
	v_cndmask_b32_e32 v0, v1, v0, vcc
	v_mov_b32_e32 v1, v97
	s_and_b64 s[2:3], vcc, exec
	v_readlane_b32 s21, v255, 18
	s_cselect_b32 s3, s21, s19
	s_cselect_b32 s2, s20, s18
	v_lshlrev_b64 v[0:1], 12, v[0:1]
	v_lshl_add_u64 v[0:1], s[2:3], 0, v[0:1]
	v_lshlrev_b32_e32 v8, 4, v186
	v_readfirstlane_b32 s2, v0
	v_readfirstlane_b32 s3, v1
	s_nop 4
	global_load_dwordx4 v[16:19], v8, s[2:3]
	global_load_dwordx4 v[12:15], v8, s[2:3] offset:1024
	global_load_dwordx4 v[4:7], v8, s[2:3] offset:2048
	global_load_dwordx4 v[0:3], v8, s[2:3] offset:3072
	v_mov_b32_e32 v9, v97
	s_cmp_lg_u64 s[4:5], 0
	v_lshl_add_u64 v[32:33], s[12:13], 0, v[8:9]
	v_lshl_add_u64 v[34:35], s[10:11], 0, v[8:9]
	v_lshl_add_u64 v[8:9], s[94:95], 0, v[8:9]
	s_mov_b64 s[4:5], 0x103000
	v_lshl_add_u64 v[36:37], v[8:9], 0, s[4:5]
	s_mov_b64 s[4:5], 0x104000
	s_cselect_b64 s[6:7], -1, 0
	v_lshl_add_u64 v[38:39], v[8:9], 0, s[4:5]
	s_lshl_b32 s4, s16, 3
	s_add_u32 s4, s4, s44
	s_addc_u32 s5, 0, s45
	v_readlane_b32 s10, v255, 4
	s_add_u32 s12, s10, s4
	v_readlane_b32 s4, v255, 5
	s_addc_u32 s13, s4, s5
	s_lshl_b32 s24, s93, 6
	s_add_i32 s10, s16, 0xffffc000
	s_lshl_b64 s[4:5], s[16:17], 11
	v_readlane_b32 s11, v255, 6
	s_add_u32 s11, s11, s44
	v_readlane_b32 s14, v255, 7
	s_addc_u32 s14, s14, s45
	s_add_u32 s4, s11, s4
	v_lshlrev_b32_e32 v8, 3, v186
	v_mov_b32_e32 v9, v97
	s_addc_u32 s5, s14, s5
	v_lshlrev_b32_e32 v10, 2, v186
	v_lshl_add_u64 v[40:41], s[4:5], 0, v[8:9]
	v_mov_b32_e32 v8, 0
	v_xor_b32_e32 v48, 4, v10
	v_xor_b32_e32 v49, 8, v10
	v_xor_b32_e32 v50, 16, v10
	v_xor_b32_e32 v51, 32, v10
	v_xor_b32_e32 v52, 64, v10
	v_xor_b32_e32 v53, 0x80, v10
	v_cmp_ne_u32_e64 s[2:3], 0, v186
	s_lshl_b32 s14, s93, 14
	s_mov_b32 s15, s17
	s_mov_b32 s16, s10
	v_mov_b32_e32 v9, v8
	v_mov_b32_e32 v10, v8
	v_mov_b32_e32 v11, v8
	v_mov_b32_e32 v20, v8
	v_mov_b32_e32 v21, v8
	v_mov_b32_e32 v22, v8
	v_mov_b32_e32 v23, v8
	v_mov_b32_e32 v24, v8
	v_mov_b32_e32 v25, v8
	v_mov_b32_e32 v26, v8
	v_mov_b32_e32 v27, v8
	v_mov_b32_e32 v28, v8
	v_mov_b32_e32 v29, v8
	v_mov_b32_e32 v30, v8
	v_mov_b32_e32 v31, v8
	v_readlane_b32 s22, v255, 19
	v_readlane_b32 s23, v255, 20
	s_branch .LBB0_111

; DI const float* modp(const Frame& F, int l, int mr, int which) { return (const float*)(F.ws + WS_MOD) + ((size_t)(l * 9 + mr) * 6 + which) * 1024; }
; DI void ln_row_v(const Frame& F, f32x4 (&v)[4], float* xout, const float* g, const float* b, const float* sh, const float* sc, bf16_t* hout, const float* slab, const float* gres, float* stat = nullptr) {
;     if (slab) {
; #pragma unroll
;         for (int j = 0; j < 4; ++j) { f32x4 a = ((const f32x4*)slab)[F.lane + 64 * j];
; #pragma unroll
;             for (int z = 1; z < 8; ++z) a += ((const f32x4*)(slab + (size_t)z * MC * 1024))[F.lane + 64 * j];
;             v[j] = v[j] * ALPHA + ((const f32x4*)gres)[F.lane + 64 * j] * a; }
; DI void ln_phase(const Frame& F, int which) {
;     const int gw = F.vcu * 8 + F.wave, NGW = F.G * 8; const int l = F.l;
;     const int nrows = (l == NL - 1) ? ML : MT;
;     bf16_t* H = (bf16_t*)(F.ws + WS_HB);
;     const float* g = pin(F, which == 0 ? I_LN1G : I_LN2G) + l * 1024; const float* b = pin(F, which == 0 ? I_LN1B : I_LN2B) + l * 1024;
;     const bool wh = !(which == 1 && l == NL - 1);
;     f32x4 vc[4], vn[4];
;     if (gw < nrows) ln_load(F, xrow_ptr(F, gw), vc);
;     for (int row = gw; row < nrows; row += NGW) {
;         if (row + NGW < nrows) ln_load(F, xrow_ptr(F, row + NGW), vn);
;         const int mr = row < ML ? (row >> 11) : 8;
;         const float* sh = which == 0 ? modp(F, l, mr, 3) : modp(F, l + 1 < NL ? l + 1 : l, mr, 0);
;         const float* sc = which == 0 ? modp(F, l, mr, 4) : modp(F, l + 1 < NL ? l + 1 : l, mr, 1);
;         const bool sl = (which == 1 && row >= ML);
;         const bool st_only = row < ML && !(which == 1 && l == NL - 1);
;         float* stp = st_only ? (float*)(F.ws + (which == 0 ? WS_ST1 : WS_ST2)) + 2 * (size_t)row : nullptr;
;         ln_row_v(F, vc, st_only ? nullptr : xrow_ptr(F, row), g, b, sh, sc, wh ? H + (size_t)row * D : nullptr, sl ? (const float*)(F.ws + WS_KN) + (size_t)(row - ML) * 1024 : nullptr, modp(F, l, mr, 5), stp);
.LBB0_513:
	s_and_b64 vcc, exec, s[2:3]
	s_cbranch_vccz .LBB0_537
	v_readlane_b32 s2, v255, 29
	s_lshl_b32 s2, s2, 3
	v_readlane_b32 s3, v255, 31
	s_add_i32 s16, s3, s2
	v_lshlrev_b32_e32 v0, 4, v186
	v_lshlrev_b32_e32 v1, 3, v186
	v_lshlrev_b32_e32 v96, 2, v186
	v_xor_b32_e32 v3, 4, v96
	v_xor_b32_e32 v4, 8, v96
	v_xor_b32_e32 v5, 16, v96
	v_xor_b32_e32 v6, 32, v96
	v_xor_b32_e32 v7, 64, v96
	v_xor_b32_e32 v8, 128, v96
	s_load_dwordx4 s[4:7], s[62:63], 0xb8
	v_readlane_b32 s22, v255, 35
	v_readlane_b32 s8, v255, 17
	v_readlane_b32 s9, v255, 18
	s_add_u32 s20, s94, 0x3600000
	s_addc_u32 s21, s95, 0
	s_lshl_b32 s2, s16, 12
	s_add_u32 s8, s8, s2
	s_addc_u32 s9, s9, 0
	s_add_u32 s20, s20, s2
	s_addc_u32 s21, s21, 0
	s_lshl_b32 s2, s16, 11
	s_add_u32 s10, s94, s2
	s_addc_u32 s11, s95, 0
	s_add_u32 s10, s10, 0x3e00000
	s_addc_u32 s11, s11, 0
	s_lshl_b32 s2, s16, 3
	s_add_u32 s12, s94, s2
	s_addc_u32 s13, s95, 0
	s_add_u32 s12, s12, 0x4c0000
	s_addc_u32 s13, s13, 0
	s_add_i32 s3, s22, 1
	s_min_u32 s3, s3, 3
	s_mul_i32 s3, s3, 0x36000
	s_add_u32 s14, s94, s3
	s_addc_u32 s15, s95, 0
	s_add_u32 s14, s14, 0x100000
	s_addc_u32 s15, s15, 0
	s_add_u32 s18, s14, 0x1000
	s_addc_u32 s19, s15, 0
	s_lshl_b32 s2, s22, 12
	s_waitcnt lgkmcnt(0)
	s_add_u32 s4, s4, s2
	s_addc_u32 s5, s5, 0
	s_add_u32 s6, s6, s2
	s_addc_u32 s7, s7, 0
	s_lshl_b32 s2, s16, 12
	s_add_u32 s24, s94, s2
	s_addc_u32 s25, s95, 0
	s_add_u32 s24, s24, 0x9100000
	s_addc_u32 s25, s25, 0
	s_mul_i32 s2, s22, 0x36000
	s_add_u32 s26, s94, s2
	s_addc_u32 s27, s95, 0
	s_add_u32 s26, s26, 0x135000
	s_addc_u32 s27, s27, 0
	s_cmp_eq_u32 s22, 3
	s_cbranch_scc1 .Lln_b_final
	global_load_dwordx4 v[10:13], v0, s[4:5]
	global_load_dwordx4 v[14:17], v0, s[4:5] offset:1024
	global_load_dwordx4 v[18:21], v0, s[4:5] offset:2048
	global_load_dwordx4 v[22:25], v0, s[4:5] offset:3072
	global_load_dwordx4 v[26:29], v0, s[6:7]
	global_load_dwordx4 v[30:33], v0, s[6:7] offset:1024
	global_load_dwordx4 v[34:37], v0, s[6:7] offset:2048
	global_load_dwordx4 v[38:41], v0, s[6:7] offset:3072
	s_add_u32 s2, s8, 0x0
	s_addc_u32 s3, s9, 0
	global_load_dwordx4 v[42:45], v0, s[2:3]
	global_load_dwordx4 v[46:49], v0, s[2:3] offset:1024
	global_load_dwordx4 v[50:53], v0, s[2:3] offset:2048
	global_load_dwordx4 v[54:57], v0, s[2:3] offset:3072
	s_add_u32 s2, s14, 0x0
	s_addc_u32 s3, s15, 0
	global_load_dwordx4 v[114:117], v0, s[2:3]
	global_load_dwordx4 v[118:121], v0, s[2:3] offset:1024
	global_load_dwordx4 v[122:125], v0, s[2:3] offset:2048
	global_load_dwordx4 v[126:129], v0, s[2:3] offset:3072
	s_add_u32 s2, s18, 0x0
	s_addc_u32 s3, s19, 0
	global_load_dwordx4 v[130:133], v0, s[2:3]
	global_load_dwordx4 v[134:137], v0, s[2:3] offset:1024
	global_load_dwordx4 v[138:141], v0, s[2:3] offset:2048
	global_load_dwordx4 v[142:145], v0, s[2:3] offset:3072
	s_add_u32 s2, s8, 0x800000
	s_addc_u32 s3, s9, 0
	global_load_dwordx4 v[58:61], v0, s[2:3]
	global_load_dwordx4 v[62:65], v0, s[2:3] offset:1024
	global_load_dwordx4 v[66:69], v0, s[2:3] offset:2048
	global_load_dwordx4 v[70:73], v0, s[2:3] offset:3072
	s_add_u32 s2, s14, 0x6000
	s_addc_u32 s3, s15, 0
	global_load_dwordx4 v[146:149], v0, s[2:3]
	global_load_dwordx4 v[150:153], v0, s[2:3] offset:1024
	global_load_dwordx4 v[154:157], v0, s[2:3] offset:2048
	global_load_dwordx4 v[158:161], v0, s[2:3] offset:3072
	s_add_u32 s2, s18, 0x6000
	s_addc_u32 s3, s19, 0
	global_load_dwordx4 v[162:165], v0, s[2:3]
	global_load_dwordx4 v[166:169], v0, s[2:3] offset:1024
	global_load_dwordx4 v[170:173], v0, s[2:3] offset:2048
	global_load_dwordx4 v[174:177], v0, s[2:3] offset:3072
	s_add_u32 s2, s8, 0x1000000
	s_addc_u32 s3, s9, 0
	global_load_dwordx4 v[74:77], v0, s[2:3]
	global_load_dwordx4 v[78:81], v0, s[2:3] offset:1024
	global_load_dwordx4 v[82:85], v0, s[2:3] offset:2048
	global_load_dwordx4 v[86:89], v0, s[2:3] offset:3072
	s_add_u32 s2, s8, 0x1800000
	s_addc_u32 s3, s9, 0
	global_load_dwordx4 v[98:101], v0, s[2:3]
	global_load_dwordx4 v[102:105], v0, s[2:3] offset:1024
	global_load_dwordx4 v[106:109], v0, s[2:3] offset:2048
	global_load_dwordx4 v[110:113], v0, s[2:3] offset:3072
	s_waitcnt vmcnt(28)
	v_add_f32_e32 v9, v42, v43
	v_add_f32_e32 v91, v44, v45
	v_mul_f32_e32 v90, v42, v42
	v_mul_f32_e32 v92, v43, v43
	v_add_f32_e32 v9, v9, v46
	v_add_f32_e32 v91, v91, v47
	v_add_f32_e32 v9, v9, v48
	v_add_f32_e32 v91, v91, v49
	v_add_f32_e32 v9, v9, v50
	v_add_f32_e32 v91, v91, v51
	v_add_f32_e32 v9, v9, v52
	v_add_f32_e32 v91, v91, v53
	v_add_f32_e32 v9, v9, v54
	v_add_f32_e32 v91, v91, v55
	v_add_f32_e32 v9, v9, v56
	v_add_f32_e32 v91, v91, v57
	v_fmac_f32_e32 v90, v44, v44
	v_fmac_f32_e32 v92, v45, v45
	v_fmac_f32_e32 v90, v46, v46
	v_fmac_f32_e32 v92, v47, v47
	v_fmac_f32_e32 v90, v48, v48
	v_fmac_f32_e32 v92, v49, v49
	v_fmac_f32_e32 v90, v50, v50
	v_fmac_f32_e32 v92, v51, v51
	v_fmac_f32_e32 v90, v52, v52
	v_fmac_f32_e32 v92, v53, v53
	v_fmac_f32_e32 v90, v54, v54
	v_fmac_f32_e32 v92, v55, v55
	v_fmac_f32_e32 v90, v56, v56
	v_fmac_f32_e32 v92, v57, v57
	v_add_f32_e32 v9, v9, v91
	v_add_f32_e32 v90, v90, v92
	ds_bpermute_b32 v91, v3, v9
	ds_bpermute_b32 v92, v3, v90
	s_waitcnt lgkmcnt(0)
	v_add_f32_e32 v9, v9, v91
	v_add_f32_e32 v90, v90, v92
	ds_bpermute_b32 v91, v4, v9
	ds_bpermute_b32 v92, v4, v90
	s_waitcnt lgkmcnt(0)
	v_add_f32_e32 v9, v9, v91
	v_add_f32_e32 v90, v90, v92
	ds_bpermute_b32 v91, v5, v9
	ds_bpermute_b32 v92, v5, v90
	s_waitcnt lgkmcnt(0)
	v_add_f32_e32 v9, v9, v91
	v_add_f32_e32 v90, v90, v92
	ds_bpermute_b32 v91, v6, v9
	ds_bpermute_b32 v92, v6, v90
	s_waitcnt lgkmcnt(0)
	v_add_f32_e32 v9, v9, v91
	v_add_f32_e32 v90, v90, v92
	ds_bpermute_b32 v91, v7, v9
	ds_bpermute_b32 v92, v7, v90
	s_waitcnt lgkmcnt(0)
; DI unsigned pk2(float lo, float hi) { f32x2 v = {lo, hi}; bf16x2_t b = __builtin_convertvector(v, bf16x2_t); return __builtin_bit_cast(unsigned, b); }
; DI void ln_row_v(const Frame& F, f32x4 (&v)[4], float* xout, const float* g, const float* b, const float* sh, const float* sc, bf16_t* hout, const float* slab, const float* gres, float* stat = nullptr) {
;     ...
;         float s = 0.f, s2 = 0.f;
; #pragma unroll
;         for (int j = 0; j < 4; ++j) { s += (v[j][0] + v[j][1]) + (v[j][2] + v[j][3]); s2 += (v[j][0] * v[j][0] + v[j][1] * v[j][1]) + (v[j][2] * v[j][2] + v[j][3] * v[j][3]); }
;         wave_sum2(s, s2, F.lane);
;         const float mean = s * (1.f / D); const float rstd = 1.f / sqrtf(fmaxf(s2 * (1.f / D) - mean * mean, 0.f) + EPS);
;         if (stat && F.lane == 0) { f32x2 sv = {mean, rstd}; *(f32x2*)stat = sv; }
; #pragma unroll
;         for (int j = 0; j < 4; ++j) { const f32x4 gg = ((const f32x4*)g)[F.lane + 64 * j], bb = ((const f32x4*)b)[F.lane + 64 * j];
;             v[j] = (v[j] - mean) * rstd * gg + bb; if (xout) ((f32x4*)xout)[F.lane + 64 * j] = v[j]; }
;     }
;     if (hout) {
;         float s = 0.f, s2 = 0.f;
; #pragma unroll
;         for (int j = 0; j < 4; ++j) { s += (v[j][0] + v[j][1]) + (v[j][2] + v[j][3]); s2 += (v[j][0] * v[j][0] + v[j][1] * v[j][1]) + (v[j][2] * v[j][2] + v[j][3] * v[j][3]); }
;         wave_sum2(s, s2, F.lane);
;         const float mean = s * (1.f / D); const float rstd = 1.f / sqrtf(fmaxf(s2 * (1.f / D) - mean * mean, 0.f) + EPS);
; #pragma unroll
;         for (int j = 0; j < 4; ++j) { const f32x4 hh = ((const f32x4*)sh)[F.lane + 64 * j], cc = ((const f32x4*)sc)[F.lane + 64 * j];
;             const f32x4 o = (v[j] - mean) * rstd * (cc + 1.f) + hh; u32x2 wv; wv.x = pk2(o[0], o[1]); wv.y = pk2(o[2], o[3]);
;             ((u32x2*)hout)[F.lane + 64 * j] = wv; }
;     }
	v_add_f32_e32 v9, v9, v91
	v_add_f32_e32 v90, v90, v92
	ds_bpermute_b32 v91, v8, v9
	ds_bpermute_b32 v92, v8, v90
	s_waitcnt lgkmcnt(0)
	v_add_f32_e32 v9, v9, v91
	v_add_f32_e32 v90, v90, v92
	v_mul_f32_e32 v93, 0x3a800000, v9
	v_mul_f32_e32 v91, 0x3a800000, v90
	v_fma_f32 v91, -v93, v93, v91
	v_max_f32_e32 v91, 0, v91
	v_add_f32_e32 v91, 0x358637bd, v91
	v_rsq_f32_e32 v94, v91
	v_mul_f32_e32 v91, 0.5, v91
	v_mul_f32_e32 v92, v94, v94
	v_fma_f32 v92, -v91, v92, 0.5
	v_fma_f32 v94, v94, v92, v94
	s_add_u32 s2, s12, 0x0
	s_addc_u32 s3, s13, 0
	v_mov_b32_e32 v188, v93
	v_mov_b32_e32 v189, v94
	s_mov_b64 exec, 1
	global_store_dwordx2 v97, v[188:189], s[2:3]
	s_mov_b64 exec, -1
	v_sub_f32_e32 v42, v42, v93
	v_sub_f32_e32 v43, v43, v93
	v_sub_f32_e32 v44, v44, v93
	v_sub_f32_e32 v45, v45, v93
	v_sub_f32_e32 v46, v46, v93
	v_sub_f32_e32 v47, v47, v93
	v_sub_f32_e32 v48, v48, v93
	v_sub_f32_e32 v49, v49, v93
	v_sub_f32_e32 v50, v50, v93
	v_sub_f32_e32 v51, v51, v93
	v_sub_f32_e32 v52, v52, v93
	v_sub_f32_e32 v53, v53, v93
	v_sub_f32_e32 v54, v54, v93
	v_sub_f32_e32 v55, v55, v93
	v_sub_f32_e32 v56, v56, v93
	v_sub_f32_e32 v57, v57, v93
	v_mul_f32_e32 v42, v94, v42
	v_mul_f32_e32 v43, v94, v43
	v_mul_f32_e32 v44, v94, v44
	v_mul_f32_e32 v45, v94, v45
	v_mul_f32_e32 v46, v94, v46
	v_mul_f32_e32 v47, v94, v47
	v_mul_f32_e32 v48, v94, v48
	v_mul_f32_e32 v49, v94, v49
	v_mul_f32_e32 v50, v94, v50
	v_mul_f32_e32 v51, v94, v51
	v_mul_f32_e32 v52, v94, v52
	v_mul_f32_e32 v53, v94, v53
	v_mul_f32_e32 v54, v94, v54
	v_mul_f32_e32 v55, v94, v55
	v_mul_f32_e32 v56, v94, v56
	v_mul_f32_e32 v57, v94, v57
	v_fma_f32 v42, v42, v10, v26
	v_fma_f32 v43, v43, v11, v27
	v_fma_f32 v44, v44, v12, v28
	v_fma_f32 v45, v45, v13, v29
	v_fma_f32 v46, v46, v14, v30
	v_fma_f32 v47, v47, v15, v31
	v_fma_f32 v48, v48, v16, v32
	v_fma_f32 v49, v49, v17, v33
	v_fma_f32 v50, v50, v18, v34
	v_fma_f32 v51, v51, v19, v35
	v_fma_f32 v52, v52, v20, v36
	v_fma_f32 v53, v53, v21, v37
	v_fma_f32 v54, v54, v22, v38
	v_fma_f32 v55, v55, v23, v39
	v_fma_f32 v56, v56, v24, v40
	v_fma_f32 v57, v57, v25, v41
	v_add_f32_e32 v9, v42, v43
	v_add_f32_e32 v91, v44, v45
	v_mul_f32_e32 v90, v42, v42
	v_mul_f32_e32 v92, v43, v43
	v_add_f32_e32 v9, v9, v46
	v_add_f32_e32 v91, v91, v47
	v_add_f32_e32 v9, v9, v48
	v_add_f32_e32 v91, v91, v49
	v_add_f32_e32 v9, v9, v50
	v_add_f32_e32 v91, v91, v51
	v_add_f32_e32 v9, v9, v52
	v_add_f32_e32 v91, v91, v53
	v_add_f32_e32 v9, v9, v54
	v_add_f32_e32 v91, v91, v55
	v_add_f32_e32 v9, v9, v56
	v_add_f32_e32 v91, v91, v57
	v_fmac_f32_e32 v90, v44, v44
	v_fmac_f32_e32 v92, v45, v45
	v_fmac_f32_e32 v90, v46, v46
	v_fmac_f32_e32 v92, v47, v47
	v_fmac_f32_e32 v90, v48, v48
	v_fmac_f32_e32 v92, v49, v49
	v_fmac_f32_e32 v90, v50, v50
	v_fmac_f32_e32 v92, v51, v51
	v_fmac_f32_e32 v90, v52, v52
	v_fmac_f32_e32 v92, v53, v53
	v_fmac_f32_e32 v90, v54, v54
	v_fmac_f32_e32 v92, v55, v55
	v_fmac_f32_e32 v90, v56, v56
	v_fmac_f32_e32 v92, v57, v57
	v_add_f32_e32 v9, v9, v91
	v_add_f32_e32 v90, v90, v92
	ds_bpermute_b32 v91, v3, v9
	ds_bpermute_b32 v92, v3, v90
	s_waitcnt lgkmcnt(0)
	v_add_f32_e32 v9, v9, v91
	v_add_f32_e32 v90, v90, v92
	ds_bpermute_b32 v91, v4, v9
	ds_bpermute_b32 v92, v4, v90
	s_waitcnt lgkmcnt(0)
	v_add_f32_e32 v9, v9, v91
	v_add_f32_e32 v90, v90, v92
	ds_bpermute_b32 v91, v5, v9
	ds_bpermute_b32 v92, v5, v90
	s_waitcnt lgkmcnt(0)
	v_add_f32_e32 v9, v9, v91
	v_add_f32_e32 v90, v90, v92
	ds_bpermute_b32 v91, v6, v9
	ds_bpermute_b32 v92, v6, v90
	s_waitcnt lgkmcnt(0)
	v_add_f32_e32 v9, v9, v91
	v_add_f32_e32 v90, v90, v92
	ds_bpermute_b32 v91, v7, v9
	ds_bpermute_b32 v92, v7, v90
	s_waitcnt lgkmcnt(0)
	v_add_f32_e32 v9, v9, v91
	v_add_f32_e32 v90, v90, v92
	ds_bpermute_b32 v91, v8, v9
	ds_bpermute_b32 v92, v8, v90
	s_waitcnt lgkmcnt(0)
	v_add_f32_e32 v9, v9, v91
	v_add_f32_e32 v90, v90, v92
	v_mul_f32_e32 v93, 0x3a800000, v9
	v_mul_f32_e32 v91, 0x3a800000, v90
	v_fma_f32 v91, -v93, v93, v91
	v_max_f32_e32 v91, 0, v91
	v_add_f32_e32 v91, 0x358637bd, v91
	v_rsq_f32_e32 v94, v91
	v_mul_f32_e32 v91, 0.5, v91
	v_mul_f32_e32 v92, v94, v94
	v_fma_f32 v92, -v91, v92, 0.5
	v_fma_f32 v94, v94, v92, v94
	s_waitcnt vmcnt(21)
	v_sub_f32_e32 v42, v42, v93
	v_sub_f32_e32 v43, v43, v93
	v_sub_f32_e32 v44, v44, v93
	v_sub_f32_e32 v45, v45, v93
	v_sub_f32_e32 v46, v46, v93
	v_sub_f32_e32 v47, v47, v93
	v_sub_f32_e32 v48, v48, v93
	v_sub_f32_e32 v49, v49, v93
	v_sub_f32_e32 v50, v50, v93
	v_sub_f32_e32 v51, v51, v93
	v_sub_f32_e32 v52, v52, v93
	v_sub_f32_e32 v53, v53, v93
	v_sub_f32_e32 v54, v54, v93
	v_sub_f32_e32 v55, v55, v93
	v_sub_f32_e32 v56, v56, v93
	v_sub_f32_e32 v57, v57, v93
	v_add_f32_e32 v130, 1.0, v130
	v_add_f32_e32 v131, 1.0, v131
	v_add_f32_e32 v132, 1.0, v132
	v_add_f32_e32 v133, 1.0, v133
	v_add_f32_e32 v134, 1.0, v134
	v_add_f32_e32 v135, 1.0, v135
	v_add_f32_e32 v136, 1.0, v136
	v_add_f32_e32 v137, 1.0, v137
	v_add_f32_e32 v138, 1.0, v138
	v_add_f32_e32 v139, 1.0, v139
	v_add_f32_e32 v140, 1.0, v140
	v_add_f32_e32 v141, 1.0, v141
	v_add_f32_e32 v142, 1.0, v142
	v_add_f32_e32 v143, 1.0, v143
	v_add_f32_e32 v144, 1.0, v144
	v_add_f32_e32 v145, 1.0, v145
	v_mul_f32_e32 v42, v94, v42
	v_mul_f32_e32 v43, v94, v43
	v_mul_f32_e32 v44, v94, v44
	v_mul_f32_e32 v45, v94, v45
	v_mul_f32_e32 v46, v94, v46
	v_mul_f32_e32 v47, v94, v47
	v_mul_f32_e32 v48, v94, v48
	v_mul_f32_e32 v49, v94, v49
	v_mul_f32_e32 v50, v94, v50
	v_mul_f32_e32 v51, v94, v51
	v_mul_f32_e32 v52, v94, v52
	v_mul_f32_e32 v53, v94, v53
	v_mul_f32_e32 v54, v94, v54
	v_mul_f32_e32 v55, v94, v55
	v_mul_f32_e32 v56, v94, v56
	v_mul_f32_e32 v57, v94, v57
	v_fma_f32 v42, v42, v130, v114
; DI unsigned pk2(float lo, float hi) { f32x2 v = {lo, hi}; bf16x2_t b = __builtin_convertvector(v, bf16x2_t); return __builtin_bit_cast(unsigned, b); }
; DI void ln_row_v(const Frame& F, f32x4 (&v)[4], float* xout, const float* g, const float* b, const float* sh, const float* sc, bf16_t* hout, const float* slab, const float* gres, float* stat = nullptr) {
;     ...
;     if (g) {
;         float s = 0.f, s2 = 0.f;
; #pragma unroll
;         for (int j = 0; j < 4; ++j) { s += (v[j][0] + v[j][1]) + (v[j][2] + v[j][3]); s2 += (v[j][0] * v[j][0] + v[j][1] * v[j][1]) + (v[j][2] * v[j][2] + v[j][3] * v[j][3]); }
;         wave_sum2(s, s2, F.lane);
;         const float mean = s * (1.f / D); const float rstd = 1.f / sqrtf(fmaxf(s2 * (1.f / D) - mean * mean, 0.f) + EPS);
;         if (stat && F.lane == 0) { f32x2 sv = {mean, rstd}; *(f32x2*)stat = sv; }
; #pragma unroll
;         for (int j = 0; j < 4; ++j) { const f32x4 gg = ((const f32x4*)g)[F.lane + 64 * j], bb = ((const f32x4*)b)[F.lane + 64 * j];
;             v[j] = (v[j] - mean) * rstd * gg + bb; if (xout) ((f32x4*)xout)[F.lane + 64 * j] = v[j]; }
;     }
;     if (hout) {
;         float s = 0.f, s2 = 0.f;
; #pragma unroll
;         for (int j = 0; j < 4; ++j) { s += (v[j][0] + v[j][1]) + (v[j][2] + v[j][3]); s2 += (v[j][0] * v[j][0] + v[j][1] * v[j][1]) + (v[j][2] * v[j][2] + v[j][3] * v[j][3]); }
;         wave_sum2(s, s2, F.lane);
;         const float mean = s * (1.f / D); const float rstd = 1.f / sqrtf(fmaxf(s2 * (1.f / D) - mean * mean, 0.f) + EPS);
; #pragma unroll
;         for (int j = 0; j < 4; ++j) { const f32x4 hh = ((const f32x4*)sh)[F.lane + 64 * j], cc = ((const f32x4*)sc)[F.lane + 64 * j];
;             const f32x4 o = (v[j] - mean) * rstd * (cc + 1.f) + hh; u32x2 wv; wv.x = pk2(o[0], o[1]); wv.y = pk2(o[2], o[3]);
;             ((u32x2*)hout)[F.lane + 64 * j] = wv; }
;     }
	v_fma_f32 v43, v43, v131, v115
	v_fma_f32 v44, v44, v132, v116
	v_fma_f32 v45, v45, v133, v117
	v_fma_f32 v46, v46, v134, v118
	v_fma_f32 v47, v47, v135, v119
	v_fma_f32 v48, v48, v136, v120
	v_fma_f32 v49, v49, v137, v121
	v_fma_f32 v50, v50, v138, v122
	v_fma_f32 v51, v51, v139, v123
	v_fma_f32 v52, v52, v140, v124
	v_fma_f32 v53, v53, v141, v125
	v_fma_f32 v54, v54, v142, v126
	v_fma_f32 v55, v55, v143, v127
	v_fma_f32 v56, v56, v144, v128
	v_fma_f32 v57, v57, v145, v129
	v_cvt_pk_bf16_f32 v190, v42, v43
	v_cvt_pk_bf16_f32 v191, v44, v45
	v_cvt_pk_bf16_f32 v192, v46, v47
	v_cvt_pk_bf16_f32 v193, v48, v49
	v_cvt_pk_bf16_f32 v194, v50, v51
	v_cvt_pk_bf16_f32 v195, v52, v53
	v_cvt_pk_bf16_f32 v196, v54, v55
	v_cvt_pk_bf16_f32 v197, v56, v57
	s_add_u32 s2, s10, 0x0
	s_addc_u32 s3, s11, 0
	global_store_dwordx2 v1, v[190:191], s[2:3]
	global_store_dwordx2 v1, v[192:193], s[2:3] offset:512
	global_store_dwordx2 v1, v[194:195], s[2:3] offset:1024
	global_store_dwordx2 v1, v[196:197], s[2:3] offset:1536
	s_add_u32 s2, s8, 0x2000000
	s_addc_u32 s3, s9, 0
	global_load_dwordx4 v[42:45], v0, s[2:3]
	global_load_dwordx4 v[46:49], v0, s[2:3] offset:1024
	global_load_dwordx4 v[50:53], v0, s[2:3] offset:2048
	global_load_dwordx4 v[54:57], v0, s[2:3] offset:3072
	s_add_u32 s2, s14, 0xc000
	s_addc_u32 s3, s15, 0
	global_load_dwordx4 v[114:117], v0, s[2:3]
	global_load_dwordx4 v[118:121], v0, s[2:3] offset:1024
	global_load_dwordx4 v[122:125], v0, s[2:3] offset:2048
	global_load_dwordx4 v[126:129], v0, s[2:3] offset:3072
	s_add_u32 s2, s18, 0xc000
	s_addc_u32 s3, s19, 0
	global_load_dwordx4 v[130:133], v0, s[2:3]
	global_load_dwordx4 v[134:137], v0, s[2:3] offset:1024
	global_load_dwordx4 v[138:141], v0, s[2:3] offset:2048
	global_load_dwordx4 v[142:145], v0, s[2:3] offset:3072
	s_waitcnt vmcnt(33)
	v_add_f32_e32 v9, v58, v59
	v_add_f32_e32 v91, v60, v61
	v_mul_f32_e32 v90, v58, v58
	v_mul_f32_e32 v92, v59, v59
	v_add_f32_e32 v9, v9, v62
	v_add_f32_e32 v91, v91, v63
	v_add_f32_e32 v9, v9, v64
	v_add_f32_e32 v91, v91, v65
	v_add_f32_e32 v9, v9, v66
	v_add_f32_e32 v91, v91, v67
	v_add_f32_e32 v9, v9, v68
	v_add_f32_e32 v91, v91, v69
	v_add_f32_e32 v9, v9, v70
	v_add_f32_e32 v91, v91, v71
	v_add_f32_e32 v9, v9, v72
	v_add_f32_e32 v91, v91, v73
	v_fmac_f32_e32 v90, v60, v60
	v_fmac_f32_e32 v92, v61, v61
	v_fmac_f32_e32 v90, v62, v62
	v_fmac_f32_e32 v92, v63, v63
	v_fmac_f32_e32 v90, v64, v64
	v_fmac_f32_e32 v92, v65, v65
	v_fmac_f32_e32 v90, v66, v66
	v_fmac_f32_e32 v92, v67, v67
	v_fmac_f32_e32 v90, v68, v68
	v_fmac_f32_e32 v92, v69, v69
	v_fmac_f32_e32 v90, v70, v70
	v_fmac_f32_e32 v92, v71, v71
	v_fmac_f32_e32 v90, v72, v72
	v_fmac_f32_e32 v92, v73, v73
	v_add_f32_e32 v9, v9, v91
	v_add_f32_e32 v90, v90, v92
	ds_bpermute_b32 v91, v3, v9
	ds_bpermute_b32 v92, v3, v90
	s_waitcnt lgkmcnt(0)
	v_add_f32_e32 v9, v9, v91
	v_add_f32_e32 v90, v90, v92
	ds_bpermute_b32 v91, v4, v9
	ds_bpermute_b32 v92, v4, v90
	s_waitcnt lgkmcnt(0)
	v_add_f32_e32 v9, v9, v91
	v_add_f32_e32 v90, v90, v92
	ds_bpermute_b32 v91, v5, v9
	ds_bpermute_b32 v92, v5, v90
	s_waitcnt lgkmcnt(0)
	v_add_f32_e32 v9, v9, v91
	v_add_f32_e32 v90, v90, v92
	ds_bpermute_b32 v91, v6, v9
	ds_bpermute_b32 v92, v6, v90
	s_waitcnt lgkmcnt(0)
	v_add_f32_e32 v9, v9, v91
	v_add_f32_e32 v90, v90, v92
	ds_bpermute_b32 v91, v7, v9
	ds_bpermute_b32 v92, v7, v90
	s_waitcnt lgkmcnt(0)
	v_add_f32_e32 v9, v9, v91
	v_add_f32_e32 v90, v90, v92
	ds_bpermute_b32 v91, v8, v9
	ds_bpermute_b32 v92, v8, v90
	s_waitcnt lgkmcnt(0)
	v_add_f32_e32 v9, v9, v91
	v_add_f32_e32 v90, v90, v92
	v_mul_f32_e32 v93, 0x3a800000, v9
	v_mul_f32_e32 v91, 0x3a800000, v90
	v_fma_f32 v91, -v93, v93, v91
	v_max_f32_e32 v91, 0, v91
	v_add_f32_e32 v91, 0x358637bd, v91
	v_rsq_f32_e32 v94, v91
	v_mul_f32_e32 v91, 0.5, v91
	v_mul_f32_e32 v92, v94, v94
	v_fma_f32 v92, -v91, v92, 0.5
	v_fma_f32 v94, v94, v92, v94
	s_add_u32 s2, s12, 0x4000
	s_addc_u32 s3, s13, 0
	v_mov_b32_e32 v188, v93
	v_mov_b32_e32 v189, v94
	s_mov_b64 exec, 1
	global_store_dwordx2 v97, v[188:189], s[2:3]
	s_mov_b64 exec, -1
	v_sub_f32_e32 v58, v58, v93
	v_sub_f32_e32 v59, v59, v93
	v_sub_f32_e32 v60, v60, v93
	v_sub_f32_e32 v61, v61, v93
	v_sub_f32_e32 v62, v62, v93
	v_sub_f32_e32 v63, v63, v93
	v_sub_f32_e32 v64, v64, v93
	v_sub_f32_e32 v65, v65, v93
	v_sub_f32_e32 v66, v66, v93
	v_sub_f32_e32 v67, v67, v93
	v_sub_f32_e32 v68, v68, v93
	v_sub_f32_e32 v69, v69, v93
	v_sub_f32_e32 v70, v70, v93
	v_sub_f32_e32 v71, v71, v93
	v_sub_f32_e32 v72, v72, v93
	v_sub_f32_e32 v73, v73, v93
	v_mul_f32_e32 v58, v94, v58
	v_mul_f32_e32 v59, v94, v59
	v_mul_f32_e32 v60, v94, v60
	v_mul_f32_e32 v61, v94, v61
	v_mul_f32_e32 v62, v94, v62
	v_mul_f32_e32 v63, v94, v63
	v_mul_f32_e32 v64, v94, v64
	v_mul_f32_e32 v65, v94, v65
	v_mul_f32_e32 v66, v94, v66
	v_mul_f32_e32 v67, v94, v67
	v_mul_f32_e32 v68, v94, v68
	v_mul_f32_e32 v69, v94, v69
	v_mul_f32_e32 v70, v94, v70
	v_mul_f32_e32 v71, v94, v71
	v_mul_f32_e32 v72, v94, v72
	v_mul_f32_e32 v73, v94, v73
	v_fma_f32 v58, v58, v10, v26
	v_fma_f32 v59, v59, v11, v27
	v_fma_f32 v60, v60, v12, v28
	v_fma_f32 v61, v61, v13, v29
	v_fma_f32 v62, v62, v14, v30
	v_fma_f32 v63, v63, v15, v31
	v_fma_f32 v64, v64, v16, v32
	v_fma_f32 v65, v65, v17, v33
	v_fma_f32 v66, v66, v18, v34
	v_fma_f32 v67, v67, v19, v35
	v_fma_f32 v68, v68, v20, v36
	v_fma_f32 v69, v69, v21, v37
	v_fma_f32 v70, v70, v22, v38
	v_fma_f32 v71, v71, v23, v39
	v_fma_f32 v72, v72, v24, v40
	v_fma_f32 v73, v73, v25, v41
	v_add_f32_e32 v9, v58, v59
	v_add_f32_e32 v91, v60, v61
	v_mul_f32_e32 v90, v58, v58
	v_mul_f32_e32 v92, v59, v59
	v_add_f32_e32 v9, v9, v62
	v_add_f32_e32 v91, v91, v63
	v_add_f32_e32 v9, v9, v64
	v_add_f32_e32 v91, v91, v65
	v_add_f32_e32 v9, v9, v66
	v_add_f32_e32 v91, v91, v67
	v_add_f32_e32 v9, v9, v68
	v_add_f32_e32 v91, v91, v69
	v_add_f32_e32 v9, v9, v70
	v_add_f32_e32 v91, v91, v71
	v_add_f32_e32 v9, v9, v72
	v_add_f32_e32 v91, v91, v73
	v_fmac_f32_e32 v90, v60, v60
	v_fmac_f32_e32 v92, v61, v61
	v_fmac_f32_e32 v90, v62, v62
	v_fmac_f32_e32 v92, v63, v63
	v_fmac_f32_e32 v90, v64, v64
	v_fmac_f32_e32 v92, v65, v65
	v_fmac_f32_e32 v90, v66, v66
	v_fmac_f32_e32 v92, v67, v67
	v_fmac_f32_e32 v90, v68, v68
	v_fmac_f32_e32 v92, v69, v69
	v_fmac_f32_e32 v90, v70, v70
	v_fmac_f32_e32 v92, v71, v71
	v_fmac_f32_e32 v90, v72, v72
	v_fmac_f32_e32 v92, v73, v73
	v_add_f32_e32 v9, v9, v91
	v_add_f32_e32 v90, v90, v92
	ds_bpermute_b32 v91, v3, v9
	ds_bpermute_b32 v92, v3, v90
	s_waitcnt lgkmcnt(0)
; DI unsigned pk2(float lo, float hi) { f32x2 v = {lo, hi}; bf16x2_t b = __builtin_convertvector(v, bf16x2_t); return __builtin_bit_cast(unsigned, b); }
; DI void ln_row_v(const Frame& F, f32x4 (&v)[4], float* xout, const float* g, const float* b, const float* sh, const float* sc, bf16_t* hout, const float* slab, const float* gres, float* stat = nullptr) {
;     ...
;     if (hout) {
;         float s = 0.f, s2 = 0.f;
; #pragma unroll
;         for (int j = 0; j < 4; ++j) { s += (v[j][0] + v[j][1]) + (v[j][2] + v[j][3]); s2 += (v[j][0] * v[j][0] + v[j][1] * v[j][1]) + (v[j][2] * v[j][2] + v[j][3] * v[j][3]); }
;         wave_sum2(s, s2, F.lane);
;         const float mean = s * (1.f / D); const float rstd = 1.f / sqrtf(fmaxf(s2 * (1.f / D) - mean * mean, 0.f) + EPS);
; #pragma unroll
;         for (int j = 0; j < 4; ++j) { const f32x4 hh = ((const f32x4*)sh)[F.lane + 64 * j], cc = ((const f32x4*)sc)[F.lane + 64 * j];
;             const f32x4 o = (v[j] - mean) * rstd * (cc + 1.f) + hh; u32x2 wv; wv.x = pk2(o[0], o[1]); wv.y = pk2(o[2], o[3]);
;             ((u32x2*)hout)[F.lane + 64 * j] = wv; }
;     }
	v_add_f32_e32 v9, v9, v91
	v_add_f32_e32 v90, v90, v92
	ds_bpermute_b32 v91, v4, v9
	ds_bpermute_b32 v92, v4, v90
	s_waitcnt lgkmcnt(0)
	v_add_f32_e32 v9, v9, v91
	v_add_f32_e32 v90, v90, v92
	ds_bpermute_b32 v91, v5, v9
	ds_bpermute_b32 v92, v5, v90
	s_waitcnt lgkmcnt(0)
	v_add_f32_e32 v9, v9, v91
	v_add_f32_e32 v90, v90, v92
	ds_bpermute_b32 v91, v6, v9
	ds_bpermute_b32 v92, v6, v90
	s_waitcnt lgkmcnt(0)
	v_add_f32_e32 v9, v9, v91
	v_add_f32_e32 v90, v90, v92
	ds_bpermute_b32 v91, v7, v9
	ds_bpermute_b32 v92, v7, v90
	s_waitcnt lgkmcnt(0)
	v_add_f32_e32 v9, v9, v91
	v_add_f32_e32 v90, v90, v92
	ds_bpermute_b32 v91, v8, v9
	ds_bpermute_b32 v92, v8, v90
	s_waitcnt lgkmcnt(0)
	v_add_f32_e32 v9, v9, v91
	v_add_f32_e32 v90, v90, v92
	v_mul_f32_e32 v93, 0x3a800000, v9
	v_mul_f32_e32 v91, 0x3a800000, v90
	v_fma_f32 v91, -v93, v93, v91
	v_max_f32_e32 v91, 0, v91
	v_add_f32_e32 v91, 0x358637bd, v91
	v_rsq_f32_e32 v94, v91
	v_mul_f32_e32 v91, 0.5, v91
	v_mul_f32_e32 v92, v94, v94
	v_fma_f32 v92, -v91, v92, 0.5
	v_fma_f32 v94, v94, v92, v94
	s_waitcnt vmcnt(26)
	v_sub_f32_e32 v58, v58, v93
	v_sub_f32_e32 v59, v59, v93
	v_sub_f32_e32 v60, v60, v93
	v_sub_f32_e32 v61, v61, v93
	v_sub_f32_e32 v62, v62, v93
	v_sub_f32_e32 v63, v63, v93
	v_sub_f32_e32 v64, v64, v93
	v_sub_f32_e32 v65, v65, v93
	v_sub_f32_e32 v66, v66, v93
	v_sub_f32_e32 v67, v67, v93
	v_sub_f32_e32 v68, v68, v93
	v_sub_f32_e32 v69, v69, v93
	v_sub_f32_e32 v70, v70, v93
	v_sub_f32_e32 v71, v71, v93
	v_sub_f32_e32 v72, v72, v93
	v_sub_f32_e32 v73, v73, v93
	v_add_f32_e32 v162, 1.0, v162
	v_add_f32_e32 v163, 1.0, v163
	v_add_f32_e32 v164, 1.0, v164
	v_add_f32_e32 v165, 1.0, v165
	v_add_f32_e32 v166, 1.0, v166
	v_add_f32_e32 v167, 1.0, v167
	v_add_f32_e32 v168, 1.0, v168
	v_add_f32_e32 v169, 1.0, v169
	v_add_f32_e32 v170, 1.0, v170
	v_add_f32_e32 v171, 1.0, v171
	v_add_f32_e32 v172, 1.0, v172
	v_add_f32_e32 v173, 1.0, v173
	v_add_f32_e32 v174, 1.0, v174
	v_add_f32_e32 v175, 1.0, v175
	v_add_f32_e32 v176, 1.0, v176
	v_add_f32_e32 v177, 1.0, v177
	v_mul_f32_e32 v58, v94, v58
	v_mul_f32_e32 v59, v94, v59
	v_mul_f32_e32 v60, v94, v60
	v_mul_f32_e32 v61, v94, v61
	v_mul_f32_e32 v62, v94, v62
	v_mul_f32_e32 v63, v94, v63
	v_mul_f32_e32 v64, v94, v64
	v_mul_f32_e32 v65, v94, v65
	v_mul_f32_e32 v66, v94, v66
	v_mul_f32_e32 v67, v94, v67
	v_mul_f32_e32 v68, v94, v68
	v_mul_f32_e32 v69, v94, v69
	v_mul_f32_e32 v70, v94, v70
	v_mul_f32_e32 v71, v94, v71
	v_mul_f32_e32 v72, v94, v72
	v_mul_f32_e32 v73, v94, v73
	v_fma_f32 v58, v58, v162, v146
	v_fma_f32 v59, v59, v163, v147
	v_fma_f32 v60, v60, v164, v148
	v_fma_f32 v61, v61, v165, v149
	v_fma_f32 v62, v62, v166, v150
	v_fma_f32 v63, v63, v167, v151
	v_fma_f32 v64, v64, v168, v152
	v_fma_f32 v65, v65, v169, v153
	v_fma_f32 v66, v66, v170, v154
	v_fma_f32 v67, v67, v171, v155
	v_fma_f32 v68, v68, v172, v156
	v_fma_f32 v69, v69, v173, v157
	v_fma_f32 v70, v70, v174, v158
	v_fma_f32 v71, v71, v175, v159
	v_fma_f32 v72, v72, v176, v160
	v_fma_f32 v73, v73, v177, v161
	v_cvt_pk_bf16_f32 v190, v58, v59
	v_cvt_pk_bf16_f32 v191, v60, v61
	v_cvt_pk_bf16_f32 v192, v62, v63
	v_cvt_pk_bf16_f32 v193, v64, v65
	v_cvt_pk_bf16_f32 v194, v66, v67
	v_cvt_pk_bf16_f32 v195, v68, v69
	v_cvt_pk_bf16_f32 v196, v70, v71
	v_cvt_pk_bf16_f32 v197, v72, v73
	s_add_u32 s2, s10, 0x400000
	s_addc_u32 s3, s11, 0
	global_store_dwordx2 v1, v[190:191], s[2:3]
	global_store_dwordx2 v1, v[192:193], s[2:3] offset:512
	global_store_dwordx2 v1, v[194:195], s[2:3] offset:1024
	global_store_dwordx2 v1, v[196:197], s[2:3] offset:1536
	s_add_u32 s2, s8, 0x2800000
	s_addc_u32 s3, s9, 0
	global_load_dwordx4 v[58:61], v0, s[2:3]
	global_load_dwordx4 v[62:65], v0, s[2:3] offset:1024
	global_load_dwordx4 v[66:69], v0, s[2:3] offset:2048
	global_load_dwordx4 v[70:73], v0, s[2:3] offset:3072
	s_add_u32 s2, s14, 0x12000
	s_addc_u32 s3, s15, 0
	global_load_dwordx4 v[146:149], v0, s[2:3]
	global_load_dwordx4 v[150:153], v0, s[2:3] offset:1024
	global_load_dwordx4 v[154:157], v0, s[2:3] offset:2048
	global_load_dwordx4 v[158:161], v0, s[2:3] offset:3072
	s_add_u32 s2, s18, 0x12000
	s_addc_u32 s3, s19, 0
	global_load_dwordx4 v[162:165], v0, s[2:3]
	global_load_dwordx4 v[166:169], v0, s[2:3] offset:1024
	global_load_dwordx4 v[170:173], v0, s[2:3] offset:2048
	global_load_dwordx4 v[174:177], v0, s[2:3] offset:3072
	s_waitcnt vmcnt(38)
	v_add_f32_e32 v9, v74, v75
	v_add_f32_e32 v91, v76, v77
	v_mul_f32_e32 v90, v74, v74
	v_mul_f32_e32 v92, v75, v75
	v_add_f32_e32 v9, v9, v78
	v_add_f32_e32 v91, v91, v79
	v_add_f32_e32 v9, v9, v80
	v_add_f32_e32 v91, v91, v81
	v_add_f32_e32 v9, v9, v82
	v_add_f32_e32 v91, v91, v83
	v_add_f32_e32 v9, v9, v84
	v_add_f32_e32 v91, v91, v85
	v_add_f32_e32 v9, v9, v86
	v_add_f32_e32 v91, v91, v87
	v_add_f32_e32 v9, v9, v88
	v_add_f32_e32 v91, v91, v89
	v_fmac_f32_e32 v90, v76, v76
	v_fmac_f32_e32 v92, v77, v77
	v_fmac_f32_e32 v90, v78, v78
	v_fmac_f32_e32 v92, v79, v79
	v_fmac_f32_e32 v90, v80, v80
	v_fmac_f32_e32 v92, v81, v81
	v_fmac_f32_e32 v90, v82, v82
	v_fmac_f32_e32 v92, v83, v83
	v_fmac_f32_e32 v90, v84, v84
	v_fmac_f32_e32 v92, v85, v85
	v_fmac_f32_e32 v90, v86, v86
	v_fmac_f32_e32 v92, v87, v87
	v_fmac_f32_e32 v90, v88, v88
	v_fmac_f32_e32 v92, v89, v89
	v_add_f32_e32 v9, v9, v91
	v_add_f32_e32 v90, v90, v92
	ds_bpermute_b32 v91, v3, v9
	ds_bpermute_b32 v92, v3, v90
	s_waitcnt lgkmcnt(0)
	v_add_f32_e32 v9, v9, v91
	v_add_f32_e32 v90, v90, v92
	ds_bpermute_b32 v91, v4, v9
	ds_bpermute_b32 v92, v4, v90
	s_waitcnt lgkmcnt(0)
	v_add_f32_e32 v9, v9, v91
	v_add_f32_e32 v90, v90, v92
	ds_bpermute_b32 v91, v5, v9
	ds_bpermute_b32 v92, v5, v90
	s_waitcnt lgkmcnt(0)
; DI void ln_row_v(const Frame& F, f32x4 (&v)[4], float* xout, const float* g, const float* b, const float* sh, const float* sc, bf16_t* hout, const float* slab, const float* gres, float* stat = nullptr) {
;     ...
;     if (g) {
;         float s = 0.f, s2 = 0.f;
; #pragma unroll
;         for (int j = 0; j < 4; ++j) { s += (v[j][0] + v[j][1]) + (v[j][2] + v[j][3]); s2 += (v[j][0] * v[j][0] + v[j][1] * v[j][1]) + (v[j][2] * v[j][2] + v[j][3] * v[j][3]); }
;         wave_sum2(s, s2, F.lane);
;         const float mean = s * (1.f / D); const float rstd = 1.f / sqrtf(fmaxf(s2 * (1.f / D) - mean * mean, 0.f) + EPS);
;         if (stat && F.lane == 0) { f32x2 sv = {mean, rstd}; *(f32x2*)stat = sv; }
; #pragma unroll
;         for (int j = 0; j < 4; ++j) { const f32x4 gg = ((const f32x4*)g)[F.lane + 64 * j], bb = ((const f32x4*)b)[F.lane + 64 * j];
;             v[j] = (v[j] - mean) * rstd * gg + bb; if (xout) ((f32x4*)xout)[F.lane + 64 * j] = v[j]; }
;     }
;     if (hout) {
;         float s = 0.f, s2 = 0.f;
; #pragma unroll
;         for (int j = 0; j < 4; ++j) { s += (v[j][0] + v[j][1]) + (v[j][2] + v[j][3]); s2 += (v[j][0] * v[j][0] + v[j][1] * v[j][1]) + (v[j][2] * v[j][2] + v[j][3] * v[j][3]); }
;         wave_sum2(s, s2, F.lane);
;         const float mean = s * (1.f / D); const float rstd = 1.f / sqrtf(fmaxf(s2 * (1.f / D) - mean * mean, 0.f) + EPS);
	v_add_f32_e32 v9, v9, v91
	v_add_f32_e32 v90, v90, v92
	ds_bpermute_b32 v91, v6, v9
	ds_bpermute_b32 v92, v6, v90
	s_waitcnt lgkmcnt(0)
	v_add_f32_e32 v9, v9, v91
	v_add_f32_e32 v90, v90, v92
	ds_bpermute_b32 v91, v7, v9
	ds_bpermute_b32 v92, v7, v90
	s_waitcnt lgkmcnt(0)
	v_add_f32_e32 v9, v9, v91
	v_add_f32_e32 v90, v90, v92
	ds_bpermute_b32 v91, v8, v9
	ds_bpermute_b32 v92, v8, v90
	s_waitcnt lgkmcnt(0)
	v_add_f32_e32 v9, v9, v91
	v_add_f32_e32 v90, v90, v92
	v_mul_f32_e32 v93, 0x3a800000, v9
	v_mul_f32_e32 v91, 0x3a800000, v90
	v_fma_f32 v91, -v93, v93, v91
	v_max_f32_e32 v91, 0, v91
	v_add_f32_e32 v91, 0x358637bd, v91
	v_rsq_f32_e32 v94, v91
	v_mul_f32_e32 v91, 0.5, v91
	v_mul_f32_e32 v92, v94, v94
	v_fma_f32 v92, -v91, v92, 0.5
	v_fma_f32 v94, v94, v92, v94
	s_add_u32 s2, s12, 0x8000
	s_addc_u32 s3, s13, 0
	v_mov_b32_e32 v188, v93
	v_mov_b32_e32 v189, v94
	s_mov_b64 exec, 1
	global_store_dwordx2 v97, v[188:189], s[2:3]
	s_mov_b64 exec, -1
	v_sub_f32_e32 v74, v74, v93
	v_sub_f32_e32 v75, v75, v93
	v_sub_f32_e32 v76, v76, v93
	v_sub_f32_e32 v77, v77, v93
	v_sub_f32_e32 v78, v78, v93
	v_sub_f32_e32 v79, v79, v93
	v_sub_f32_e32 v80, v80, v93
	v_sub_f32_e32 v81, v81, v93
	v_sub_f32_e32 v82, v82, v93
	v_sub_f32_e32 v83, v83, v93
	v_sub_f32_e32 v84, v84, v93
	v_sub_f32_e32 v85, v85, v93
	v_sub_f32_e32 v86, v86, v93
	v_sub_f32_e32 v87, v87, v93
	v_sub_f32_e32 v88, v88, v93
	v_sub_f32_e32 v89, v89, v93
	v_mul_f32_e32 v74, v94, v74
	v_mul_f32_e32 v75, v94, v75
	v_mul_f32_e32 v76, v94, v76
	v_mul_f32_e32 v77, v94, v77
	v_mul_f32_e32 v78, v94, v78
	v_mul_f32_e32 v79, v94, v79
	v_mul_f32_e32 v80, v94, v80
	v_mul_f32_e32 v81, v94, v81
	v_mul_f32_e32 v82, v94, v82
	v_mul_f32_e32 v83, v94, v83
	v_mul_f32_e32 v84, v94, v84
	v_mul_f32_e32 v85, v94, v85
	v_mul_f32_e32 v86, v94, v86
	v_mul_f32_e32 v87, v94, v87
	v_mul_f32_e32 v88, v94, v88
	v_mul_f32_e32 v89, v94, v89
	v_fma_f32 v74, v74, v10, v26
	v_fma_f32 v75, v75, v11, v27
	v_fma_f32 v76, v76, v12, v28
	v_fma_f32 v77, v77, v13, v29
	v_fma_f32 v78, v78, v14, v30
	v_fma_f32 v79, v79, v15, v31
	v_fma_f32 v80, v80, v16, v32
	v_fma_f32 v81, v81, v17, v33
	v_fma_f32 v82, v82, v18, v34
	v_fma_f32 v83, v83, v19, v35
	v_fma_f32 v84, v84, v20, v36
	v_fma_f32 v85, v85, v21, v37
	v_fma_f32 v86, v86, v22, v38
	v_fma_f32 v87, v87, v23, v39
	v_fma_f32 v88, v88, v24, v40
	v_fma_f32 v89, v89, v25, v41
	v_add_f32_e32 v9, v74, v75
	v_add_f32_e32 v91, v76, v77
	v_mul_f32_e32 v90, v74, v74
	v_mul_f32_e32 v92, v75, v75
	v_add_f32_e32 v9, v9, v78
	v_add_f32_e32 v91, v91, v79
	v_add_f32_e32 v9, v9, v80
	v_add_f32_e32 v91, v91, v81
	v_add_f32_e32 v9, v9, v82
	v_add_f32_e32 v91, v91, v83
	v_add_f32_e32 v9, v9, v84
	v_add_f32_e32 v91, v91, v85
	v_add_f32_e32 v9, v9, v86
	v_add_f32_e32 v91, v91, v87
	v_add_f32_e32 v9, v9, v88
	v_add_f32_e32 v91, v91, v89
	v_fmac_f32_e32 v90, v76, v76
	v_fmac_f32_e32 v92, v77, v77
	v_fmac_f32_e32 v90, v78, v78
	v_fmac_f32_e32 v92, v79, v79
	v_fmac_f32_e32 v90, v80, v80
	v_fmac_f32_e32 v92, v81, v81
	v_fmac_f32_e32 v90, v82, v82
	v_fmac_f32_e32 v92, v83, v83
	v_fmac_f32_e32 v90, v84, v84
	v_fmac_f32_e32 v92, v85, v85
	v_fmac_f32_e32 v90, v86, v86
	v_fmac_f32_e32 v92, v87, v87
	v_fmac_f32_e32 v90, v88, v88
	v_fmac_f32_e32 v92, v89, v89
	v_add_f32_e32 v9, v9, v91
	v_add_f32_e32 v90, v90, v92
	ds_bpermute_b32 v91, v3, v9
	ds_bpermute_b32 v92, v3, v90
	s_waitcnt lgkmcnt(0)
	v_add_f32_e32 v9, v9, v91
	v_add_f32_e32 v90, v90, v92
	ds_bpermute_b32 v91, v4, v9
	ds_bpermute_b32 v92, v4, v90
	s_waitcnt lgkmcnt(0)
	v_add_f32_e32 v9, v9, v91
	v_add_f32_e32 v90, v90, v92
	ds_bpermute_b32 v91, v5, v9
	ds_bpermute_b32 v92, v5, v90
	s_waitcnt lgkmcnt(0)
	v_add_f32_e32 v9, v9, v91
	v_add_f32_e32 v90, v90, v92
	ds_bpermute_b32 v91, v6, v9
	ds_bpermute_b32 v92, v6, v90
	s_waitcnt lgkmcnt(0)
	v_add_f32_e32 v9, v9, v91
	v_add_f32_e32 v90, v90, v92
	ds_bpermute_b32 v91, v7, v9
	ds_bpermute_b32 v92, v7, v90
	s_waitcnt lgkmcnt(0)
	v_add_f32_e32 v9, v9, v91
	v_add_f32_e32 v90, v90, v92
	ds_bpermute_b32 v91, v8, v9
	ds_bpermute_b32 v92, v8, v90
	s_waitcnt lgkmcnt(0)
	v_add_f32_e32 v9, v9, v91
	v_add_f32_e32 v90, v90, v92
	v_mul_f32_e32 v93, 0x3a800000, v9
	v_mul_f32_e32 v91, 0x3a800000, v90
	v_fma_f32 v91, -v93, v93, v91
	v_max_f32_e32 v91, 0, v91
	v_add_f32_e32 v91, 0x358637bd, v91
	v_rsq_f32_e32 v94, v91
	v_mul_f32_e32 v91, 0.5, v91
	v_mul_f32_e32 v92, v94, v94
	v_fma_f32 v92, -v91, v92, 0.5
	v_fma_f32 v94, v94, v92, v94
	s_waitcnt vmcnt(18)
; DI unsigned pk2(float lo, float hi) { f32x2 v = {lo, hi}; bf16x2_t b = __builtin_convertvector(v, bf16x2_t); return __builtin_bit_cast(unsigned, b); }
; DI void ln_row_v(const Frame& F, f32x4 (&v)[4], float* xout, const float* g, const float* b, const float* sh, const float* sc, bf16_t* hout, const float* slab, const float* gres, float* stat = nullptr) {
;     ...
;     if (hout) {
;         float s = 0.f, s2 = 0.f;
; #pragma unroll
;         for (int j = 0; j < 4; ++j) { s += (v[j][0] + v[j][1]) + (v[j][2] + v[j][3]); s2 += (v[j][0] * v[j][0] + v[j][1] * v[j][1]) + (v[j][2] * v[j][2] + v[j][3] * v[j][3]); }
;         wave_sum2(s, s2, F.lane);
;         const float mean = s * (1.f / D); const float rstd = 1.f / sqrtf(fmaxf(s2 * (1.f / D) - mean * mean, 0.f) + EPS);
; #pragma unroll
;         for (int j = 0; j < 4; ++j) { const f32x4 hh = ((const f32x4*)sh)[F.lane + 64 * j], cc = ((const f32x4*)sc)[F.lane + 64 * j];
;             const f32x4 o = (v[j] - mean) * rstd * (cc + 1.f) + hh; u32x2 wv; wv.x = pk2(o[0], o[1]); wv.y = pk2(o[2], o[3]);
;             ((u32x2*)hout)[F.lane + 64 * j] = wv; }
;     }
	v_sub_f32_e32 v74, v74, v93
	v_sub_f32_e32 v75, v75, v93
	v_sub_f32_e32 v76, v76, v93
	v_sub_f32_e32 v77, v77, v93
	v_sub_f32_e32 v78, v78, v93
	v_sub_f32_e32 v79, v79, v93
	v_sub_f32_e32 v80, v80, v93
	v_sub_f32_e32 v81, v81, v93
	v_sub_f32_e32 v82, v82, v93
	v_sub_f32_e32 v83, v83, v93
	v_sub_f32_e32 v84, v84, v93
	v_sub_f32_e32 v85, v85, v93
	v_sub_f32_e32 v86, v86, v93
	v_sub_f32_e32 v87, v87, v93
	v_sub_f32_e32 v88, v88, v93
	v_sub_f32_e32 v89, v89, v93
	v_add_f32_e32 v130, 1.0, v130
	v_add_f32_e32 v131, 1.0, v131
	v_add_f32_e32 v132, 1.0, v132
	v_add_f32_e32 v133, 1.0, v133
	v_add_f32_e32 v134, 1.0, v134
	v_add_f32_e32 v135, 1.0, v135
	v_add_f32_e32 v136, 1.0, v136
	v_add_f32_e32 v137, 1.0, v137
	v_add_f32_e32 v138, 1.0, v138
	v_add_f32_e32 v139, 1.0, v139
	v_add_f32_e32 v140, 1.0, v140
	v_add_f32_e32 v141, 1.0, v141
	v_add_f32_e32 v142, 1.0, v142
	v_add_f32_e32 v143, 1.0, v143
	v_add_f32_e32 v144, 1.0, v144
	v_add_f32_e32 v145, 1.0, v145
	v_mul_f32_e32 v74, v94, v74
	v_mul_f32_e32 v75, v94, v75
	v_mul_f32_e32 v76, v94, v76
	v_mul_f32_e32 v77, v94, v77
	v_mul_f32_e32 v78, v94, v78
	v_mul_f32_e32 v79, v94, v79
	v_mul_f32_e32 v80, v94, v80
	v_mul_f32_e32 v81, v94, v81
	v_mul_f32_e32 v82, v94, v82
	v_mul_f32_e32 v83, v94, v83
	v_mul_f32_e32 v84, v94, v84
	v_mul_f32_e32 v85, v94, v85
	v_mul_f32_e32 v86, v94, v86
	v_mul_f32_e32 v87, v94, v87
	v_mul_f32_e32 v88, v94, v88
	v_mul_f32_e32 v89, v94, v89
	v_fma_f32 v74, v74, v130, v114
	v_fma_f32 v75, v75, v131, v115
	v_fma_f32 v76, v76, v132, v116
	v_fma_f32 v77, v77, v133, v117
	v_fma_f32 v78, v78, v134, v118
	v_fma_f32 v79, v79, v135, v119
	v_fma_f32 v80, v80, v136, v120
	v_fma_f32 v81, v81, v137, v121
	v_fma_f32 v82, v82, v138, v122
	v_fma_f32 v83, v83, v139, v123
	v_fma_f32 v84, v84, v140, v124
	v_fma_f32 v85, v85, v141, v125
	v_fma_f32 v86, v86, v142, v126
	v_fma_f32 v87, v87, v143, v127
	v_fma_f32 v88, v88, v144, v128
	v_fma_f32 v89, v89, v145, v129
	v_cvt_pk_bf16_f32 v190, v74, v75
	v_cvt_pk_bf16_f32 v191, v76, v77
	v_cvt_pk_bf16_f32 v192, v78, v79
	v_cvt_pk_bf16_f32 v193, v80, v81
	v_cvt_pk_bf16_f32 v194, v82, v83
	v_cvt_pk_bf16_f32 v195, v84, v85
	v_cvt_pk_bf16_f32 v196, v86, v87
	v_cvt_pk_bf16_f32 v197, v88, v89
	s_add_u32 s2, s10, 0x800000
	s_addc_u32 s3, s11, 0
	global_store_dwordx2 v1, v[190:191], s[2:3]
	global_store_dwordx2 v1, v[192:193], s[2:3] offset:512
	global_store_dwordx2 v1, v[194:195], s[2:3] offset:1024
	global_store_dwordx2 v1, v[196:197], s[2:3] offset:1536
	s_add_u32 s2, s8, 0x3000000
	s_addc_u32 s3, s9, 0
	global_load_dwordx4 v[74:77], v0, s[2:3]
	global_load_dwordx4 v[78:81], v0, s[2:3] offset:1024
	global_load_dwordx4 v[82:85], v0, s[2:3] offset:2048
	global_load_dwordx4 v[86:89], v0, s[2:3] offset:3072
	s_add_u32 s2, s14, 0x18000
	s_addc_u32 s3, s15, 0
	global_load_dwordx4 v[114:117], v0, s[2:3]
	global_load_dwordx4 v[118:121], v0, s[2:3] offset:1024
	global_load_dwordx4 v[122:125], v0, s[2:3] offset:2048
	global_load_dwordx4 v[126:129], v0, s[2:3] offset:3072
	s_add_u32 s2, s18, 0x18000
	s_addc_u32 s3, s19, 0
	global_load_dwordx4 v[130:133], v0, s[2:3]
	global_load_dwordx4 v[134:137], v0, s[2:3] offset:1024
	global_load_dwordx4 v[138:141], v0, s[2:3] offset:2048
	global_load_dwordx4 v[142:145], v0, s[2:3] offset:3072
	v_add_f32_e32 v9, v98, v99
	v_add_f32_e32 v91, v100, v101
	v_mul_f32_e32 v90, v98, v98
	v_mul_f32_e32 v92, v99, v99
	v_add_f32_e32 v9, v9, v102
	v_add_f32_e32 v91, v91, v103
	v_add_f32_e32 v9, v9, v104
	v_add_f32_e32 v91, v91, v105
	v_add_f32_e32 v9, v9, v106
	v_add_f32_e32 v91, v91, v107
	v_add_f32_e32 v9, v9, v108
	v_add_f32_e32 v91, v91, v109
	v_add_f32_e32 v9, v9, v110
	v_add_f32_e32 v91, v91, v111
	v_add_f32_e32 v9, v9, v112
	v_add_f32_e32 v91, v91, v113
	v_fmac_f32_e32 v90, v100, v100
	v_fmac_f32_e32 v92, v101, v101
	v_fmac_f32_e32 v90, v102, v102
	v_fmac_f32_e32 v92, v103, v103
	v_fmac_f32_e32 v90, v104, v104
	v_fmac_f32_e32 v92, v105, v105
	v_fmac_f32_e32 v90, v106, v106
	v_fmac_f32_e32 v92, v107, v107
	v_fmac_f32_e32 v90, v108, v108
	v_fmac_f32_e32 v92, v109, v109
	v_fmac_f32_e32 v90, v110, v110
	v_fmac_f32_e32 v92, v111, v111
	v_fmac_f32_e32 v90, v112, v112
	v_fmac_f32_e32 v92, v113, v113
	v_add_f32_e32 v9, v9, v91
	v_add_f32_e32 v90, v90, v92
	ds_bpermute_b32 v91, v3, v9
	ds_bpermute_b32 v92, v3, v90
	s_waitcnt lgkmcnt(0)
	v_add_f32_e32 v9, v9, v91
	v_add_f32_e32 v90, v90, v92
	ds_bpermute_b32 v91, v4, v9
	ds_bpermute_b32 v92, v4, v90
	s_waitcnt lgkmcnt(0)
	v_add_f32_e32 v9, v9, v91
	v_add_f32_e32 v90, v90, v92
	ds_bpermute_b32 v91, v5, v9
	ds_bpermute_b32 v92, v5, v90
	s_waitcnt lgkmcnt(0)
	v_add_f32_e32 v9, v9, v91
	v_add_f32_e32 v90, v90, v92
	ds_bpermute_b32 v91, v6, v9
	ds_bpermute_b32 v92, v6, v90
	s_waitcnt lgkmcnt(0)
	v_add_f32_e32 v9, v9, v91
	v_add_f32_e32 v90, v90, v92
	ds_bpermute_b32 v91, v7, v9
	ds_bpermute_b32 v92, v7, v90
	s_waitcnt lgkmcnt(0)
	v_add_f32_e32 v9, v9, v91
	v_add_f32_e32 v90, v90, v92
	ds_bpermute_b32 v91, v8, v9
	ds_bpermute_b32 v92, v8, v90
	s_waitcnt lgkmcnt(0)
; DI unsigned pk2(float lo, float hi) { f32x2 v = {lo, hi}; bf16x2_t b = __builtin_convertvector(v, bf16x2_t); return __builtin_bit_cast(unsigned, b); }
; DI void ln_row_v(const Frame& F, f32x4 (&v)[4], float* xout, const float* g, const float* b, const float* sh, const float* sc, bf16_t* hout, const float* slab, const float* gres, float* stat = nullptr) {
;     ...
;     if (g) {
;         float s = 0.f, s2 = 0.f;
; #pragma unroll
;         for (int j = 0; j < 4; ++j) { s += (v[j][0] + v[j][1]) + (v[j][2] + v[j][3]); s2 += (v[j][0] * v[j][0] + v[j][1] * v[j][1]) + (v[j][2] * v[j][2] + v[j][3] * v[j][3]); }
;         wave_sum2(s, s2, F.lane);
;         const float mean = s * (1.f / D); const float rstd = 1.f / sqrtf(fmaxf(s2 * (1.f / D) - mean * mean, 0.f) + EPS);
;         if (stat && F.lane == 0) { f32x2 sv = {mean, rstd}; *(f32x2*)stat = sv; }
; #pragma unroll
;         for (int j = 0; j < 4; ++j) { const f32x4 gg = ((const f32x4*)g)[F.lane + 64 * j], bb = ((const f32x4*)b)[F.lane + 64 * j];
;             v[j] = (v[j] - mean) * rstd * gg + bb; if (xout) ((f32x4*)xout)[F.lane + 64 * j] = v[j]; }
;     }
;     if (hout) {
;         float s = 0.f, s2 = 0.f;
; #pragma unroll
;         for (int j = 0; j < 4; ++j) { s += (v[j][0] + v[j][1]) + (v[j][2] + v[j][3]); s2 += (v[j][0] * v[j][0] + v[j][1] * v[j][1]) + (v[j][2] * v[j][2] + v[j][3] * v[j][3]); }
;         wave_sum2(s, s2, F.lane);
;         const float mean = s * (1.f / D); const float rstd = 1.f / sqrtf(fmaxf(s2 * (1.f / D) - mean * mean, 0.f) + EPS);
; #pragma unroll
;         for (int j = 0; j < 4; ++j) { const f32x4 hh = ((const f32x4*)sh)[F.lane + 64 * j], cc = ((const f32x4*)sc)[F.lane + 64 * j];
;             const f32x4 o = (v[j] - mean) * rstd * (cc + 1.f) + hh; u32x2 wv; wv.x = pk2(o[0], o[1]); wv.y = pk2(o[2], o[3]);
;             ((u32x2*)hout)[F.lane + 64 * j] = wv; }
;     }
	v_add_f32_e32 v9, v9, v91
	v_add_f32_e32 v90, v90, v92
	v_mul_f32_e32 v93, 0x3a800000, v9
	v_mul_f32_e32 v91, 0x3a800000, v90
	v_fma_f32 v91, -v93, v93, v91
	v_max_f32_e32 v91, 0, v91
	v_add_f32_e32 v91, 0x358637bd, v91
	v_rsq_f32_e32 v94, v91
	v_mul_f32_e32 v91, 0.5, v91
	v_mul_f32_e32 v92, v94, v94
	v_fma_f32 v92, -v91, v92, 0.5
	v_fma_f32 v94, v94, v92, v94
	s_add_u32 s2, s12, 0xc000
	s_addc_u32 s3, s13, 0
	v_mov_b32_e32 v188, v93
	v_mov_b32_e32 v189, v94
	s_mov_b64 exec, 1
	global_store_dwordx2 v97, v[188:189], s[2:3]
	s_mov_b64 exec, -1
	v_sub_f32_e32 v98, v98, v93
	v_sub_f32_e32 v99, v99, v93
	v_sub_f32_e32 v100, v100, v93
	v_sub_f32_e32 v101, v101, v93
	v_sub_f32_e32 v102, v102, v93
	v_sub_f32_e32 v103, v103, v93
	v_sub_f32_e32 v104, v104, v93
	v_sub_f32_e32 v105, v105, v93
	v_sub_f32_e32 v106, v106, v93
	v_sub_f32_e32 v107, v107, v93
	v_sub_f32_e32 v108, v108, v93
	v_sub_f32_e32 v109, v109, v93
	v_sub_f32_e32 v110, v110, v93
	v_sub_f32_e32 v111, v111, v93
	v_sub_f32_e32 v112, v112, v93
	v_sub_f32_e32 v113, v113, v93
	v_mul_f32_e32 v98, v94, v98
	v_mul_f32_e32 v99, v94, v99
	v_mul_f32_e32 v100, v94, v100
	v_mul_f32_e32 v101, v94, v101
	v_mul_f32_e32 v102, v94, v102
	v_mul_f32_e32 v103, v94, v103
	v_mul_f32_e32 v104, v94, v104
	v_mul_f32_e32 v105, v94, v105
	v_mul_f32_e32 v106, v94, v106
	v_mul_f32_e32 v107, v94, v107
	v_mul_f32_e32 v108, v94, v108
	v_mul_f32_e32 v109, v94, v109
	v_mul_f32_e32 v110, v94, v110
	v_mul_f32_e32 v111, v94, v111
	v_mul_f32_e32 v112, v94, v112
	v_mul_f32_e32 v113, v94, v113
	v_fma_f32 v98, v98, v10, v26
	v_fma_f32 v99, v99, v11, v27
	v_fma_f32 v100, v100, v12, v28
	v_fma_f32 v101, v101, v13, v29
	v_fma_f32 v102, v102, v14, v30
	v_fma_f32 v103, v103, v15, v31
	v_fma_f32 v104, v104, v16, v32
	v_fma_f32 v105, v105, v17, v33
	v_fma_f32 v106, v106, v18, v34
	v_fma_f32 v107, v107, v19, v35
	v_fma_f32 v108, v108, v20, v36
	v_fma_f32 v109, v109, v21, v37
	v_fma_f32 v110, v110, v22, v38
	v_fma_f32 v111, v111, v23, v39
	v_fma_f32 v112, v112, v24, v40
	v_fma_f32 v113, v113, v25, v41
	v_add_f32_e32 v9, v98, v99
	v_add_f32_e32 v91, v100, v101
	v_mul_f32_e32 v90, v98, v98
	v_mul_f32_e32 v92, v99, v99
	v_add_f32_e32 v9, v9, v102
	v_add_f32_e32 v91, v91, v103
	v_add_f32_e32 v9, v9, v104
	v_add_f32_e32 v91, v91, v105
	v_add_f32_e32 v9, v9, v106
	v_add_f32_e32 v91, v91, v107
	v_add_f32_e32 v9, v9, v108
	v_add_f32_e32 v91, v91, v109
	v_add_f32_e32 v9, v9, v110
	v_add_f32_e32 v91, v91, v111
	v_add_f32_e32 v9, v9, v112
	v_add_f32_e32 v91, v91, v113
	v_fmac_f32_e32 v90, v100, v100
	v_fmac_f32_e32 v92, v101, v101
	v_fmac_f32_e32 v90, v102, v102
	v_fmac_f32_e32 v92, v103, v103
	v_fmac_f32_e32 v90, v104, v104
	v_fmac_f32_e32 v92, v105, v105
	v_fmac_f32_e32 v90, v106, v106
	v_fmac_f32_e32 v92, v107, v107
	v_fmac_f32_e32 v90, v108, v108
	v_fmac_f32_e32 v92, v109, v109
	v_fmac_f32_e32 v90, v110, v110
	v_fmac_f32_e32 v92, v111, v111
	v_fmac_f32_e32 v90, v112, v112
	v_fmac_f32_e32 v92, v113, v113
	v_add_f32_e32 v9, v9, v91
	v_add_f32_e32 v90, v90, v92
	ds_bpermute_b32 v91, v3, v9
	ds_bpermute_b32 v92, v3, v90
	s_waitcnt lgkmcnt(0)
	v_add_f32_e32 v9, v9, v91
	v_add_f32_e32 v90, v90, v92
	ds_bpermute_b32 v91, v4, v9
	ds_bpermute_b32 v92, v4, v90
	s_waitcnt lgkmcnt(0)
	v_add_f32_e32 v9, v9, v91
	v_add_f32_e32 v90, v90, v92
	ds_bpermute_b32 v91, v5, v9
	ds_bpermute_b32 v92, v5, v90
	s_waitcnt lgkmcnt(0)
	v_add_f32_e32 v9, v9, v91
	v_add_f32_e32 v90, v90, v92
	ds_bpermute_b32 v91, v6, v9
	ds_bpermute_b32 v92, v6, v90
	s_waitcnt lgkmcnt(0)
	v_add_f32_e32 v9, v9, v91
	v_add_f32_e32 v90, v90, v92
	ds_bpermute_b32 v91, v7, v9
	ds_bpermute_b32 v92, v7, v90
	s_waitcnt lgkmcnt(0)
	v_add_f32_e32 v9, v9, v91
	v_add_f32_e32 v90, v90, v92
	ds_bpermute_b32 v91, v8, v9
	ds_bpermute_b32 v92, v8, v90
	s_waitcnt lgkmcnt(0)
	v_add_f32_e32 v9, v9, v91
	v_add_f32_e32 v90, v90, v92
	v_mul_f32_e32 v93, 0x3a800000, v9
	v_mul_f32_e32 v91, 0x3a800000, v90
	v_fma_f32 v91, -v93, v93, v91
	v_max_f32_e32 v91, 0, v91
	v_add_f32_e32 v91, 0x358637bd, v91
	v_rsq_f32_e32 v94, v91
	v_mul_f32_e32 v91, 0.5, v91
	v_mul_f32_e32 v92, v94, v94
	v_fma_f32 v92, -v91, v92, 0.5
	v_fma_f32 v94, v94, v92, v94
	s_waitcnt vmcnt(18)
	v_sub_f32_e32 v98, v98, v93
	v_sub_f32_e32 v99, v99, v93
	v_sub_f32_e32 v100, v100, v93
	v_sub_f32_e32 v101, v101, v93
	v_sub_f32_e32 v102, v102, v93
	v_sub_f32_e32 v103, v103, v93
	v_sub_f32_e32 v104, v104, v93
	v_sub_f32_e32 v105, v105, v93
	v_sub_f32_e32 v106, v106, v93
	v_sub_f32_e32 v107, v107, v93
	v_sub_f32_e32 v108, v108, v93
	v_sub_f32_e32 v109, v109, v93
	v_sub_f32_e32 v110, v110, v93
	v_sub_f32_e32 v111, v111, v93
	v_sub_f32_e32 v112, v112, v93
	v_sub_f32_e32 v113, v113, v93
	v_add_f32_e32 v162, 1.0, v162
	v_add_f32_e32 v163, 1.0, v163
	v_add_f32_e32 v164, 1.0, v164
	v_add_f32_e32 v165, 1.0, v165
	v_add_f32_e32 v166, 1.0, v166
	v_add_f32_e32 v167, 1.0, v167
	v_add_f32_e32 v168, 1.0, v168
	v_add_f32_e32 v169, 1.0, v169
	v_add_f32_e32 v170, 1.0, v170
	v_add_f32_e32 v171, 1.0, v171
	v_add_f32_e32 v172, 1.0, v172
	v_add_f32_e32 v173, 1.0, v173
	v_add_f32_e32 v174, 1.0, v174
	v_add_f32_e32 v175, 1.0, v175
	v_add_f32_e32 v176, 1.0, v176
	v_add_f32_e32 v177, 1.0, v177
	v_mul_f32_e32 v98, v94, v98
	v_mul_f32_e32 v99, v94, v99
	v_mul_f32_e32 v100, v94, v100
	v_mul_f32_e32 v101, v94, v101
	v_mul_f32_e32 v102, v94, v102
	v_mul_f32_e32 v103, v94, v103
	v_mul_f32_e32 v104, v94, v104
	v_mul_f32_e32 v105, v94, v105
	v_mul_f32_e32 v106, v94, v106
	v_mul_f32_e32 v107, v94, v107
	v_mul_f32_e32 v108, v94, v108
	v_mul_f32_e32 v109, v94, v109
	v_mul_f32_e32 v110, v94, v110
	v_mul_f32_e32 v111, v94, v111
	v_mul_f32_e32 v112, v94, v112
	v_mul_f32_e32 v113, v94, v113
; DI unsigned pk2(float lo, float hi) { f32x2 v = {lo, hi}; bf16x2_t b = __builtin_convertvector(v, bf16x2_t); return __builtin_bit_cast(unsigned, b); }
; DI void ln_row_v(const Frame& F, f32x4 (&v)[4], float* xout, const float* g, const float* b, const float* sh, const float* sc, bf16_t* hout, const float* slab, const float* gres, float* stat = nullptr) {
;     ...
;     if (g) {
;         float s = 0.f, s2 = 0.f;
; #pragma unroll
;         for (int j = 0; j < 4; ++j) { s += (v[j][0] + v[j][1]) + (v[j][2] + v[j][3]); s2 += (v[j][0] * v[j][0] + v[j][1] * v[j][1]) + (v[j][2] * v[j][2] + v[j][3] * v[j][3]); }
;         wave_sum2(s, s2, F.lane);
;         const float mean = s * (1.f / D); const float rstd = 1.f / sqrtf(fmaxf(s2 * (1.f / D) - mean * mean, 0.f) + EPS);
;         if (stat && F.lane == 0) { f32x2 sv = {mean, rstd}; *(f32x2*)stat = sv; }
; #pragma unroll
;         for (int j = 0; j < 4; ++j) { const f32x4 gg = ((const f32x4*)g)[F.lane + 64 * j], bb = ((const f32x4*)b)[F.lane + 64 * j];
;             v[j] = (v[j] - mean) * rstd * gg + bb; if (xout) ((f32x4*)xout)[F.lane + 64 * j] = v[j]; }
;     }
;     if (hout) {
;         float s = 0.f, s2 = 0.f;
; #pragma unroll
;         for (int j = 0; j < 4; ++j) { s += (v[j][0] + v[j][1]) + (v[j][2] + v[j][3]); s2 += (v[j][0] * v[j][0] + v[j][1] * v[j][1]) + (v[j][2] * v[j][2] + v[j][3] * v[j][3]); }
;         wave_sum2(s, s2, F.lane);
;         const float mean = s * (1.f / D); const float rstd = 1.f / sqrtf(fmaxf(s2 * (1.f / D) - mean * mean, 0.f) + EPS);
; #pragma unroll
;         for (int j = 0; j < 4; ++j) { const f32x4 hh = ((const f32x4*)sh)[F.lane + 64 * j], cc = ((const f32x4*)sc)[F.lane + 64 * j];
;             const f32x4 o = (v[j] - mean) * rstd * (cc + 1.f) + hh; u32x2 wv; wv.x = pk2(o[0], o[1]); wv.y = pk2(o[2], o[3]);
;             ((u32x2*)hout)[F.lane + 64 * j] = wv; }
;     }
	v_fma_f32 v98, v98, v162, v146
	v_fma_f32 v99, v99, v163, v147
	v_fma_f32 v100, v100, v164, v148
	v_fma_f32 v101, v101, v165, v149
	v_fma_f32 v102, v102, v166, v150
	v_fma_f32 v103, v103, v167, v151
	v_fma_f32 v104, v104, v168, v152
	v_fma_f32 v105, v105, v169, v153
	v_fma_f32 v106, v106, v170, v154
	v_fma_f32 v107, v107, v171, v155
	v_fma_f32 v108, v108, v172, v156
	v_fma_f32 v109, v109, v173, v157
	v_fma_f32 v110, v110, v174, v158
	v_fma_f32 v111, v111, v175, v159
	v_fma_f32 v112, v112, v176, v160
	v_fma_f32 v113, v113, v177, v161
	v_cvt_pk_bf16_f32 v190, v98, v99
	v_cvt_pk_bf16_f32 v191, v100, v101
	v_cvt_pk_bf16_f32 v192, v102, v103
	v_cvt_pk_bf16_f32 v193, v104, v105
	v_cvt_pk_bf16_f32 v194, v106, v107
	v_cvt_pk_bf16_f32 v195, v108, v109
	v_cvt_pk_bf16_f32 v196, v110, v111
	v_cvt_pk_bf16_f32 v197, v112, v113
	s_add_u32 s2, s10, 0xc00000
	s_addc_u32 s3, s11, 0
	global_store_dwordx2 v1, v[190:191], s[2:3]
	global_store_dwordx2 v1, v[192:193], s[2:3] offset:512
	global_store_dwordx2 v1, v[194:195], s[2:3] offset:1024
	global_store_dwordx2 v1, v[196:197], s[2:3] offset:1536
	s_add_u32 s2, s8, 0x3800000
	s_addc_u32 s3, s9, 0
	global_load_dwordx4 v[98:101], v0, s[2:3]
	global_load_dwordx4 v[102:105], v0, s[2:3] offset:1024
	global_load_dwordx4 v[106:109], v0, s[2:3] offset:2048
	global_load_dwordx4 v[110:113], v0, s[2:3] offset:3072
	s_add_u32 s2, s14, 0x1e000
	s_addc_u32 s3, s15, 0
	global_load_dwordx4 v[146:149], v0, s[2:3]
	global_load_dwordx4 v[150:153], v0, s[2:3] offset:1024
	global_load_dwordx4 v[154:157], v0, s[2:3] offset:2048
	global_load_dwordx4 v[158:161], v0, s[2:3] offset:3072
	s_add_u32 s2, s18, 0x1e000
	s_addc_u32 s3, s19, 0
	global_load_dwordx4 v[162:165], v0, s[2:3]
	global_load_dwordx4 v[166:169], v0, s[2:3] offset:1024
	global_load_dwordx4 v[170:173], v0, s[2:3] offset:2048
	global_load_dwordx4 v[174:177], v0, s[2:3] offset:3072
	v_add_f32_e32 v9, v42, v43
	v_add_f32_e32 v91, v44, v45
	v_mul_f32_e32 v90, v42, v42
	v_mul_f32_e32 v92, v43, v43
	v_add_f32_e32 v9, v9, v46
	v_add_f32_e32 v91, v91, v47
	v_add_f32_e32 v9, v9, v48
	v_add_f32_e32 v91, v91, v49
	v_add_f32_e32 v9, v9, v50
	v_add_f32_e32 v91, v91, v51
	v_add_f32_e32 v9, v9, v52
	v_add_f32_e32 v91, v91, v53
	v_add_f32_e32 v9, v9, v54
	v_add_f32_e32 v91, v91, v55
	v_add_f32_e32 v9, v9, v56
	v_add_f32_e32 v91, v91, v57
	v_fmac_f32_e32 v90, v44, v44
	v_fmac_f32_e32 v92, v45, v45
	v_fmac_f32_e32 v90, v46, v46
	v_fmac_f32_e32 v92, v47, v47
	v_fmac_f32_e32 v90, v48, v48
	v_fmac_f32_e32 v92, v49, v49
	v_fmac_f32_e32 v90, v50, v50
	v_fmac_f32_e32 v92, v51, v51
	v_fmac_f32_e32 v90, v52, v52
	v_fmac_f32_e32 v92, v53, v53
	v_fmac_f32_e32 v90, v54, v54
	v_fmac_f32_e32 v92, v55, v55
	v_fmac_f32_e32 v90, v56, v56
	v_fmac_f32_e32 v92, v57, v57
	v_add_f32_e32 v9, v9, v91
	v_add_f32_e32 v90, v90, v92
	ds_bpermute_b32 v91, v3, v9
	ds_bpermute_b32 v92, v3, v90
	s_waitcnt lgkmcnt(0)
	v_add_f32_e32 v9, v9, v91
	v_add_f32_e32 v90, v90, v92
	ds_bpermute_b32 v91, v4, v9
	ds_bpermute_b32 v92, v4, v90
	s_waitcnt lgkmcnt(0)
	v_add_f32_e32 v9, v9, v91
	v_add_f32_e32 v90, v90, v92
	ds_bpermute_b32 v91, v5, v9
	ds_bpermute_b32 v92, v5, v90
	s_waitcnt lgkmcnt(0)
	v_add_f32_e32 v9, v9, v91
	v_add_f32_e32 v90, v90, v92
	ds_bpermute_b32 v91, v6, v9
	ds_bpermute_b32 v92, v6, v90
	s_waitcnt lgkmcnt(0)
	v_add_f32_e32 v9, v9, v91
	v_add_f32_e32 v90, v90, v92
	ds_bpermute_b32 v91, v7, v9
	ds_bpermute_b32 v92, v7, v90
	s_waitcnt lgkmcnt(0)
	v_add_f32_e32 v9, v9, v91
	v_add_f32_e32 v90, v90, v92
	ds_bpermute_b32 v91, v8, v9
	ds_bpermute_b32 v92, v8, v90
	s_waitcnt lgkmcnt(0)
	v_add_f32_e32 v9, v9, v91
	v_add_f32_e32 v90, v90, v92
	v_mul_f32_e32 v93, 0x3a800000, v9
	v_mul_f32_e32 v91, 0x3a800000, v90
	v_fma_f32 v91, -v93, v93, v91
	v_max_f32_e32 v91, 0, v91
	v_add_f32_e32 v91, 0x358637bd, v91
	v_rsq_f32_e32 v94, v91
	v_mul_f32_e32 v91, 0.5, v91
	v_mul_f32_e32 v92, v94, v94
	v_fma_f32 v92, -v91, v92, 0.5
	v_fma_f32 v94, v94, v92, v94
	s_add_u32 s2, s12, 0x10000
	s_addc_u32 s3, s13, 0
	v_mov_b32_e32 v188, v93
	v_mov_b32_e32 v189, v94
	s_mov_b64 exec, 1
	global_store_dwordx2 v97, v[188:189], s[2:3]
	s_mov_b64 exec, -1
	v_sub_f32_e32 v42, v42, v93
	v_sub_f32_e32 v43, v43, v93
	v_sub_f32_e32 v44, v44, v93
	v_sub_f32_e32 v45, v45, v93
	v_sub_f32_e32 v46, v46, v93
	v_sub_f32_e32 v47, v47, v93
	v_sub_f32_e32 v48, v48, v93
	v_sub_f32_e32 v49, v49, v93
	v_sub_f32_e32 v50, v50, v93
	v_sub_f32_e32 v51, v51, v93
	v_sub_f32_e32 v52, v52, v93
	v_sub_f32_e32 v53, v53, v93
	v_sub_f32_e32 v54, v54, v93
	v_sub_f32_e32 v55, v55, v93
	v_sub_f32_e32 v56, v56, v93
	v_sub_f32_e32 v57, v57, v93
	v_mul_f32_e32 v42, v94, v42
	v_mul_f32_e32 v43, v94, v43
	v_mul_f32_e32 v44, v94, v44
	v_mul_f32_e32 v45, v94, v45
	v_mul_f32_e32 v46, v94, v46
	v_mul_f32_e32 v47, v94, v47
	v_mul_f32_e32 v48, v94, v48
	v_mul_f32_e32 v49, v94, v49
	v_mul_f32_e32 v50, v94, v50
	v_mul_f32_e32 v51, v94, v51
	v_mul_f32_e32 v52, v94, v52
	v_mul_f32_e32 v53, v94, v53
	v_mul_f32_e32 v54, v94, v54
	v_mul_f32_e32 v55, v94, v55
	v_mul_f32_e32 v56, v94, v56
	v_mul_f32_e32 v57, v94, v57
	v_fma_f32 v42, v42, v10, v26
	v_fma_f32 v43, v43, v11, v27
	v_fma_f32 v44, v44, v12, v28
	v_fma_f32 v45, v45, v13, v29
	v_fma_f32 v46, v46, v14, v30
	v_fma_f32 v47, v47, v15, v31
	v_fma_f32 v48, v48, v16, v32
	v_fma_f32 v49, v49, v17, v33
	v_fma_f32 v50, v50, v18, v34
	v_fma_f32 v51, v51, v19, v35
	v_fma_f32 v52, v52, v20, v36
	v_fma_f32 v53, v53, v21, v37
	v_fma_f32 v54, v54, v22, v38
	v_fma_f32 v55, v55, v23, v39
	v_fma_f32 v56, v56, v24, v40
	v_fma_f32 v57, v57, v25, v41
	v_add_f32_e32 v9, v42, v43
	v_add_f32_e32 v91, v44, v45
	v_mul_f32_e32 v90, v42, v42
	v_mul_f32_e32 v92, v43, v43
	v_add_f32_e32 v9, v9, v46
	v_add_f32_e32 v91, v91, v47
	v_add_f32_e32 v9, v9, v48
	v_add_f32_e32 v91, v91, v49
	v_add_f32_e32 v9, v9, v50
	v_add_f32_e32 v91, v91, v51
	v_add_f32_e32 v9, v9, v52
	v_add_f32_e32 v91, v91, v53
	v_add_f32_e32 v9, v9, v54
	v_add_f32_e32 v91, v91, v55
	v_add_f32_e32 v9, v9, v56
	v_add_f32_e32 v91, v91, v57
	v_fmac_f32_e32 v90, v44, v44
	v_fmac_f32_e32 v92, v45, v45
	v_fmac_f32_e32 v90, v46, v46
	v_fmac_f32_e32 v92, v47, v47
	v_fmac_f32_e32 v90, v48, v48
	v_fmac_f32_e32 v92, v49, v49
	v_fmac_f32_e32 v90, v50, v50
	v_fmac_f32_e32 v92, v51, v51
	v_fmac_f32_e32 v90, v52, v52
	v_fmac_f32_e32 v92, v53, v53
	v_fmac_f32_e32 v90, v54, v54
	v_fmac_f32_e32 v92, v55, v55
	v_fmac_f32_e32 v90, v56, v56
	v_fmac_f32_e32 v92, v57, v57
	v_add_f32_e32 v9, v9, v91
	v_add_f32_e32 v90, v90, v92
	ds_bpermute_b32 v91, v3, v9
	ds_bpermute_b32 v92, v3, v90
	s_waitcnt lgkmcnt(0)
; DI unsigned pk2(float lo, float hi) { f32x2 v = {lo, hi}; bf16x2_t b = __builtin_convertvector(v, bf16x2_t); return __builtin_bit_cast(unsigned, b); }
; DI void ln_row_v(const Frame& F, f32x4 (&v)[4], float* xout, const float* g, const float* b, const float* sh, const float* sc, bf16_t* hout, const float* slab, const float* gres, float* stat = nullptr) {
;     ...
;     if (hout) {
;         float s = 0.f, s2 = 0.f;
; #pragma unroll
;         for (int j = 0; j < 4; ++j) { s += (v[j][0] + v[j][1]) + (v[j][2] + v[j][3]); s2 += (v[j][0] * v[j][0] + v[j][1] * v[j][1]) + (v[j][2] * v[j][2] + v[j][3] * v[j][3]); }
;         wave_sum2(s, s2, F.lane);
;         const float mean = s * (1.f / D); const float rstd = 1.f / sqrtf(fmaxf(s2 * (1.f / D) - mean * mean, 0.f) + EPS);
; #pragma unroll
;         for (int j = 0; j < 4; ++j) { const f32x4 hh = ((const f32x4*)sh)[F.lane + 64 * j], cc = ((const f32x4*)sc)[F.lane + 64 * j];
;             const f32x4 o = (v[j] - mean) * rstd * (cc + 1.f) + hh; u32x2 wv; wv.x = pk2(o[0], o[1]); wv.y = pk2(o[2], o[3]);
;             ((u32x2*)hout)[F.lane + 64 * j] = wv; }
;     }
; DI void ln_phase(const Frame& F, int which) {
;     ...
;     for (int row = gw; row < nrows; row += NGW) {
;         if (row + NGW < nrows) ln_load(F, xrow_ptr(F, row + NGW), vn);
	v_add_f32_e32 v9, v9, v91
	v_add_f32_e32 v90, v90, v92
	ds_bpermute_b32 v91, v4, v9
	ds_bpermute_b32 v92, v4, v90
	s_waitcnt lgkmcnt(0)
	v_add_f32_e32 v9, v9, v91
	v_add_f32_e32 v90, v90, v92
	ds_bpermute_b32 v91, v5, v9
	ds_bpermute_b32 v92, v5, v90
	s_waitcnt lgkmcnt(0)
	v_add_f32_e32 v9, v9, v91
	v_add_f32_e32 v90, v90, v92
	ds_bpermute_b32 v91, v6, v9
	ds_bpermute_b32 v92, v6, v90
	s_waitcnt lgkmcnt(0)
	v_add_f32_e32 v9, v9, v91
	v_add_f32_e32 v90, v90, v92
	ds_bpermute_b32 v91, v7, v9
	ds_bpermute_b32 v92, v7, v90
	s_waitcnt lgkmcnt(0)
	v_add_f32_e32 v9, v9, v91
	v_add_f32_e32 v90, v90, v92
	ds_bpermute_b32 v91, v8, v9
	ds_bpermute_b32 v92, v8, v90
	s_waitcnt lgkmcnt(0)
	v_add_f32_e32 v9, v9, v91
	v_add_f32_e32 v90, v90, v92
	v_mul_f32_e32 v93, 0x3a800000, v9
	v_mul_f32_e32 v91, 0x3a800000, v90
	v_fma_f32 v91, -v93, v93, v91
	v_max_f32_e32 v91, 0, v91
	v_add_f32_e32 v91, 0x358637bd, v91
	v_rsq_f32_e32 v94, v91
	v_mul_f32_e32 v91, 0.5, v91
	v_mul_f32_e32 v92, v94, v94
	v_fma_f32 v92, -v91, v92, 0.5
	v_fma_f32 v94, v94, v92, v94
	s_waitcnt vmcnt(18)
	v_sub_f32_e32 v42, v42, v93
	v_sub_f32_e32 v43, v43, v93
	v_sub_f32_e32 v44, v44, v93
	v_sub_f32_e32 v45, v45, v93
	v_sub_f32_e32 v46, v46, v93
	v_sub_f32_e32 v47, v47, v93
	v_sub_f32_e32 v48, v48, v93
	v_sub_f32_e32 v49, v49, v93
	v_sub_f32_e32 v50, v50, v93
	v_sub_f32_e32 v51, v51, v93
	v_sub_f32_e32 v52, v52, v93
	v_sub_f32_e32 v53, v53, v93
	v_sub_f32_e32 v54, v54, v93
	v_sub_f32_e32 v55, v55, v93
	v_sub_f32_e32 v56, v56, v93
	v_sub_f32_e32 v57, v57, v93
	v_add_f32_e32 v130, 1.0, v130
	v_add_f32_e32 v131, 1.0, v131
	v_add_f32_e32 v132, 1.0, v132
	v_add_f32_e32 v133, 1.0, v133
	v_add_f32_e32 v134, 1.0, v134
	v_add_f32_e32 v135, 1.0, v135
	v_add_f32_e32 v136, 1.0, v136
	v_add_f32_e32 v137, 1.0, v137
	v_add_f32_e32 v138, 1.0, v138
	v_add_f32_e32 v139, 1.0, v139
	v_add_f32_e32 v140, 1.0, v140
	v_add_f32_e32 v141, 1.0, v141
	v_add_f32_e32 v142, 1.0, v142
	v_add_f32_e32 v143, 1.0, v143
	v_add_f32_e32 v144, 1.0, v144
	v_add_f32_e32 v145, 1.0, v145
	v_mul_f32_e32 v42, v94, v42
	v_mul_f32_e32 v43, v94, v43
	v_mul_f32_e32 v44, v94, v44
	v_mul_f32_e32 v45, v94, v45
	v_mul_f32_e32 v46, v94, v46
	v_mul_f32_e32 v47, v94, v47
	v_mul_f32_e32 v48, v94, v48
	v_mul_f32_e32 v49, v94, v49
	v_mul_f32_e32 v50, v94, v50
	v_mul_f32_e32 v51, v94, v51
	v_mul_f32_e32 v52, v94, v52
	v_mul_f32_e32 v53, v94, v53
	v_mul_f32_e32 v54, v94, v54
	v_mul_f32_e32 v55, v94, v55
	v_mul_f32_e32 v56, v94, v56
	v_mul_f32_e32 v57, v94, v57
	v_fma_f32 v42, v42, v130, v114
	v_fma_f32 v43, v43, v131, v115
	v_fma_f32 v44, v44, v132, v116
	v_fma_f32 v45, v45, v133, v117
	v_fma_f32 v46, v46, v134, v118
	v_fma_f32 v47, v47, v135, v119
	v_fma_f32 v48, v48, v136, v120
	v_fma_f32 v49, v49, v137, v121
	v_fma_f32 v50, v50, v138, v122
	v_fma_f32 v51, v51, v139, v123
	v_fma_f32 v52, v52, v140, v124
	v_fma_f32 v53, v53, v141, v125
	v_fma_f32 v54, v54, v142, v126
	v_fma_f32 v55, v55, v143, v127
	v_fma_f32 v56, v56, v144, v128
	v_fma_f32 v57, v57, v145, v129
	v_cvt_pk_bf16_f32 v190, v42, v43
	v_cvt_pk_bf16_f32 v191, v44, v45
	v_cvt_pk_bf16_f32 v192, v46, v47
	v_cvt_pk_bf16_f32 v193, v48, v49
	v_cvt_pk_bf16_f32 v194, v50, v51
	v_cvt_pk_bf16_f32 v195, v52, v53
	v_cvt_pk_bf16_f32 v196, v54, v55
	v_cvt_pk_bf16_f32 v197, v56, v57
	s_add_u32 s2, s10, 0x1000000
	s_addc_u32 s3, s11, 0
	global_store_dwordx2 v1, v[190:191], s[2:3]
	global_store_dwordx2 v1, v[192:193], s[2:3] offset:512
	global_store_dwordx2 v1, v[194:195], s[2:3] offset:1024
	global_store_dwordx2 v1, v[196:197], s[2:3] offset:1536
	s_mov_b64 s[2:3], s[20:21]
	global_load_dwordx4 v[42:45], v0, s[2:3]
	global_load_dwordx4 v[46:49], v0, s[2:3] offset:1024
	global_load_dwordx4 v[50:53], v0, s[2:3] offset:2048
	global_load_dwordx4 v[54:57], v0, s[2:3] offset:3072
	s_add_u32 s2, s14, 0x24000
	s_addc_u32 s3, s15, 0
	global_load_dwordx4 v[114:117], v0, s[2:3]
	global_load_dwordx4 v[118:121], v0, s[2:3] offset:1024
	global_load_dwordx4 v[122:125], v0, s[2:3] offset:2048
	global_load_dwordx4 v[126:129], v0, s[2:3] offset:3072
	s_add_u32 s2, s18, 0x24000
	s_addc_u32 s3, s19, 0
	global_load_dwordx4 v[130:133], v0, s[2:3]
	global_load_dwordx4 v[134:137], v0, s[2:3] offset:1024
	global_load_dwordx4 v[138:141], v0, s[2:3] offset:2048
	global_load_dwordx4 v[142:145], v0, s[2:3] offset:3072
	v_add_f32_e32 v9, v58, v59
	v_add_f32_e32 v91, v60, v61
	v_mul_f32_e32 v90, v58, v58
	v_mul_f32_e32 v92, v59, v59
	v_add_f32_e32 v9, v9, v62
	v_add_f32_e32 v91, v91, v63
	v_add_f32_e32 v9, v9, v64
	v_add_f32_e32 v91, v91, v65
	v_add_f32_e32 v9, v9, v66
	v_add_f32_e32 v91, v91, v67
	v_add_f32_e32 v9, v9, v68
	v_add_f32_e32 v91, v91, v69
	v_add_f32_e32 v9, v9, v70
	v_add_f32_e32 v91, v91, v71
	v_add_f32_e32 v9, v9, v72
	v_add_f32_e32 v91, v91, v73
	v_fmac_f32_e32 v90, v60, v60
	v_fmac_f32_e32 v92, v61, v61
	v_fmac_f32_e32 v90, v62, v62
	v_fmac_f32_e32 v92, v63, v63
	v_fmac_f32_e32 v90, v64, v64
	v_fmac_f32_e32 v92, v65, v65
	v_fmac_f32_e32 v90, v66, v66
	v_fmac_f32_e32 v92, v67, v67
	v_fmac_f32_e32 v90, v68, v68
	v_fmac_f32_e32 v92, v69, v69
	v_fmac_f32_e32 v90, v70, v70
	v_fmac_f32_e32 v92, v71, v71
	v_fmac_f32_e32 v90, v72, v72
	v_fmac_f32_e32 v92, v73, v73
	v_add_f32_e32 v9, v9, v91
	v_add_f32_e32 v90, v90, v92
	ds_bpermute_b32 v91, v3, v9
	ds_bpermute_b32 v92, v3, v90
	s_waitcnt lgkmcnt(0)
	v_add_f32_e32 v9, v9, v91
	v_add_f32_e32 v90, v90, v92
	ds_bpermute_b32 v91, v4, v9
	ds_bpermute_b32 v92, v4, v90
	s_waitcnt lgkmcnt(0)
	v_add_f32_e32 v9, v9, v91
	v_add_f32_e32 v90, v90, v92
	ds_bpermute_b32 v91, v5, v9
	ds_bpermute_b32 v92, v5, v90
	s_waitcnt lgkmcnt(0)
; DI void ln_row_v(const Frame& F, f32x4 (&v)[4], float* xout, const float* g, const float* b, const float* sh, const float* sc, bf16_t* hout, const float* slab, const float* gres, float* stat = nullptr) {
;     ...
;     if (g) {
;         float s = 0.f, s2 = 0.f;
; #pragma unroll
;         for (int j = 0; j < 4; ++j) { s += (v[j][0] + v[j][1]) + (v[j][2] + v[j][3]); s2 += (v[j][0] * v[j][0] + v[j][1] * v[j][1]) + (v[j][2] * v[j][2] + v[j][3] * v[j][3]); }
;         wave_sum2(s, s2, F.lane);
;         const float mean = s * (1.f / D); const float rstd = 1.f / sqrtf(fmaxf(s2 * (1.f / D) - mean * mean, 0.f) + EPS);
;         if (stat && F.lane == 0) { f32x2 sv = {mean, rstd}; *(f32x2*)stat = sv; }
; #pragma unroll
;         for (int j = 0; j < 4; ++j) { const f32x4 gg = ((const f32x4*)g)[F.lane + 64 * j], bb = ((const f32x4*)b)[F.lane + 64 * j];
;             v[j] = (v[j] - mean) * rstd * gg + bb; if (xout) ((f32x4*)xout)[F.lane + 64 * j] = v[j]; }
;     }
;     if (hout) {
;         float s = 0.f, s2 = 0.f;
; #pragma unroll
;         for (int j = 0; j < 4; ++j) { s += (v[j][0] + v[j][1]) + (v[j][2] + v[j][3]); s2 += (v[j][0] * v[j][0] + v[j][1] * v[j][1]) + (v[j][2] * v[j][2] + v[j][3] * v[j][3]); }
;         wave_sum2(s, s2, F.lane);
;         const float mean = s * (1.f / D); const float rstd = 1.f / sqrtf(fmaxf(s2 * (1.f / D) - mean * mean, 0.f) + EPS);
	v_add_f32_e32 v9, v9, v91
	v_add_f32_e32 v90, v90, v92
	ds_bpermute_b32 v91, v6, v9
	ds_bpermute_b32 v92, v6, v90
	s_waitcnt lgkmcnt(0)
	v_add_f32_e32 v9, v9, v91
	v_add_f32_e32 v90, v90, v92
	ds_bpermute_b32 v91, v7, v9
	ds_bpermute_b32 v92, v7, v90
	s_waitcnt lgkmcnt(0)
	v_add_f32_e32 v9, v9, v91
	v_add_f32_e32 v90, v90, v92
	ds_bpermute_b32 v91, v8, v9
	ds_bpermute_b32 v92, v8, v90
	s_waitcnt lgkmcnt(0)
	v_add_f32_e32 v9, v9, v91
	v_add_f32_e32 v90, v90, v92
	v_mul_f32_e32 v93, 0x3a800000, v9
	v_mul_f32_e32 v91, 0x3a800000, v90
	v_fma_f32 v91, -v93, v93, v91
	v_max_f32_e32 v91, 0, v91
	v_add_f32_e32 v91, 0x358637bd, v91
	v_rsq_f32_e32 v94, v91
	v_mul_f32_e32 v91, 0.5, v91
	v_mul_f32_e32 v92, v94, v94
	v_fma_f32 v92, -v91, v92, 0.5
	v_fma_f32 v94, v94, v92, v94
	s_add_u32 s2, s12, 0x14000
	s_addc_u32 s3, s13, 0
	v_mov_b32_e32 v188, v93
	v_mov_b32_e32 v189, v94
	s_mov_b64 exec, 1
	global_store_dwordx2 v97, v[188:189], s[2:3]
	s_mov_b64 exec, -1
	v_sub_f32_e32 v58, v58, v93
	v_sub_f32_e32 v59, v59, v93
	v_sub_f32_e32 v60, v60, v93
	v_sub_f32_e32 v61, v61, v93
	v_sub_f32_e32 v62, v62, v93
	v_sub_f32_e32 v63, v63, v93
	v_sub_f32_e32 v64, v64, v93
	v_sub_f32_e32 v65, v65, v93
	v_sub_f32_e32 v66, v66, v93
	v_sub_f32_e32 v67, v67, v93
	v_sub_f32_e32 v68, v68, v93
	v_sub_f32_e32 v69, v69, v93
	v_sub_f32_e32 v70, v70, v93
	v_sub_f32_e32 v71, v71, v93
	v_sub_f32_e32 v72, v72, v93
	v_sub_f32_e32 v73, v73, v93
	v_mul_f32_e32 v58, v94, v58
	v_mul_f32_e32 v59, v94, v59
	v_mul_f32_e32 v60, v94, v60
	v_mul_f32_e32 v61, v94, v61
	v_mul_f32_e32 v62, v94, v62
	v_mul_f32_e32 v63, v94, v63
	v_mul_f32_e32 v64, v94, v64
	v_mul_f32_e32 v65, v94, v65
	v_mul_f32_e32 v66, v94, v66
	v_mul_f32_e32 v67, v94, v67
	v_mul_f32_e32 v68, v94, v68
	v_mul_f32_e32 v69, v94, v69
	v_mul_f32_e32 v70, v94, v70
	v_mul_f32_e32 v71, v94, v71
	v_mul_f32_e32 v72, v94, v72
	v_mul_f32_e32 v73, v94, v73
	v_fma_f32 v58, v58, v10, v26
	v_fma_f32 v59, v59, v11, v27
	v_fma_f32 v60, v60, v12, v28
	v_fma_f32 v61, v61, v13, v29
	v_fma_f32 v62, v62, v14, v30
	v_fma_f32 v63, v63, v15, v31
	v_fma_f32 v64, v64, v16, v32
	v_fma_f32 v65, v65, v17, v33
	v_fma_f32 v66, v66, v18, v34
	v_fma_f32 v67, v67, v19, v35
	v_fma_f32 v68, v68, v20, v36
	v_fma_f32 v69, v69, v21, v37
	v_fma_f32 v70, v70, v22, v38
	v_fma_f32 v71, v71, v23, v39
	v_fma_f32 v72, v72, v24, v40
	v_fma_f32 v73, v73, v25, v41
	v_add_f32_e32 v9, v58, v59
	v_add_f32_e32 v91, v60, v61
	v_mul_f32_e32 v90, v58, v58
	v_mul_f32_e32 v92, v59, v59
	v_add_f32_e32 v9, v9, v62
	v_add_f32_e32 v91, v91, v63
	v_add_f32_e32 v9, v9, v64
	v_add_f32_e32 v91, v91, v65
	v_add_f32_e32 v9, v9, v66
	v_add_f32_e32 v91, v91, v67
	v_add_f32_e32 v9, v9, v68
	v_add_f32_e32 v91, v91, v69
	v_add_f32_e32 v9, v9, v70
	v_add_f32_e32 v91, v91, v71
	v_add_f32_e32 v9, v9, v72
	v_add_f32_e32 v91, v91, v73
	v_fmac_f32_e32 v90, v60, v60
	v_fmac_f32_e32 v92, v61, v61
	v_fmac_f32_e32 v90, v62, v62
	v_fmac_f32_e32 v92, v63, v63
	v_fmac_f32_e32 v90, v64, v64
	v_fmac_f32_e32 v92, v65, v65
	v_fmac_f32_e32 v90, v66, v66
	v_fmac_f32_e32 v92, v67, v67
	v_fmac_f32_e32 v90, v68, v68
	v_fmac_f32_e32 v92, v69, v69
	v_fmac_f32_e32 v90, v70, v70
	v_fmac_f32_e32 v92, v71, v71
	v_fmac_f32_e32 v90, v72, v72
	v_fmac_f32_e32 v92, v73, v73
	v_add_f32_e32 v9, v9, v91
	v_add_f32_e32 v90, v90, v92
	ds_bpermute_b32 v91, v3, v9
	ds_bpermute_b32 v92, v3, v90
	s_waitcnt lgkmcnt(0)
	v_add_f32_e32 v9, v9, v91
	v_add_f32_e32 v90, v90, v92
	ds_bpermute_b32 v91, v4, v9
	ds_bpermute_b32 v92, v4, v90
	s_waitcnt lgkmcnt(0)
	v_add_f32_e32 v9, v9, v91
	v_add_f32_e32 v90, v90, v92
	ds_bpermute_b32 v91, v5, v9
	ds_bpermute_b32 v92, v5, v90
	s_waitcnt lgkmcnt(0)
	v_add_f32_e32 v9, v9, v91
	v_add_f32_e32 v90, v90, v92
	ds_bpermute_b32 v91, v6, v9
	ds_bpermute_b32 v92, v6, v90
	s_waitcnt lgkmcnt(0)
	v_add_f32_e32 v9, v9, v91
	v_add_f32_e32 v90, v90, v92
	ds_bpermute_b32 v91, v7, v9
	ds_bpermute_b32 v92, v7, v90
	s_waitcnt lgkmcnt(0)
	v_add_f32_e32 v9, v9, v91
	v_add_f32_e32 v90, v90, v92
	ds_bpermute_b32 v91, v8, v9
	ds_bpermute_b32 v92, v8, v90
	s_waitcnt lgkmcnt(0)
	v_add_f32_e32 v9, v9, v91
	v_add_f32_e32 v90, v90, v92
	v_mul_f32_e32 v93, 0x3a800000, v9
	v_mul_f32_e32 v91, 0x3a800000, v90
	v_fma_f32 v91, -v93, v93, v91
	v_max_f32_e32 v91, 0, v91
	v_add_f32_e32 v91, 0x358637bd, v91
	v_rsq_f32_e32 v94, v91
	v_mul_f32_e32 v91, 0.5, v91
	v_mul_f32_e32 v92, v94, v94
	v_fma_f32 v92, -v91, v92, 0.5
	v_fma_f32 v94, v94, v92, v94
	s_waitcnt vmcnt(18)
; DI unsigned pk2(float lo, float hi) { f32x2 v = {lo, hi}; bf16x2_t b = __builtin_convertvector(v, bf16x2_t); return __builtin_bit_cast(unsigned, b); }
; DI void ln_row_v(const Frame& F, f32x4 (&v)[4], float* xout, const float* g, const float* b, const float* sh, const float* sc, bf16_t* hout, const float* slab, const float* gres, float* stat = nullptr) {
;     ...
;     if (hout) {
;         float s = 0.f, s2 = 0.f;
; #pragma unroll
;         for (int j = 0; j < 4; ++j) { s += (v[j][0] + v[j][1]) + (v[j][2] + v[j][3]); s2 += (v[j][0] * v[j][0] + v[j][1] * v[j][1]) + (v[j][2] * v[j][2] + v[j][3] * v[j][3]); }
;         wave_sum2(s, s2, F.lane);
;         const float mean = s * (1.f / D); const float rstd = 1.f / sqrtf(fmaxf(s2 * (1.f / D) - mean * mean, 0.f) + EPS);
; #pragma unroll
;         for (int j = 0; j < 4; ++j) { const f32x4 hh = ((const f32x4*)sh)[F.lane + 64 * j], cc = ((const f32x4*)sc)[F.lane + 64 * j];
;             const f32x4 o = (v[j] - mean) * rstd * (cc + 1.f) + hh; u32x2 wv; wv.x = pk2(o[0], o[1]); wv.y = pk2(o[2], o[3]);
;             ((u32x2*)hout)[F.lane + 64 * j] = wv; }
;     }
	v_sub_f32_e32 v58, v58, v93
	v_sub_f32_e32 v59, v59, v93
	v_sub_f32_e32 v60, v60, v93
	v_sub_f32_e32 v61, v61, v93
	v_sub_f32_e32 v62, v62, v93
	v_sub_f32_e32 v63, v63, v93
	v_sub_f32_e32 v64, v64, v93
	v_sub_f32_e32 v65, v65, v93
	v_sub_f32_e32 v66, v66, v93
	v_sub_f32_e32 v67, v67, v93
	v_sub_f32_e32 v68, v68, v93
	v_sub_f32_e32 v69, v69, v93
	v_sub_f32_e32 v70, v70, v93
	v_sub_f32_e32 v71, v71, v93
	v_sub_f32_e32 v72, v72, v93
	v_sub_f32_e32 v73, v73, v93
	v_add_f32_e32 v162, 1.0, v162
	v_add_f32_e32 v163, 1.0, v163
	v_add_f32_e32 v164, 1.0, v164
	v_add_f32_e32 v165, 1.0, v165
	v_add_f32_e32 v166, 1.0, v166
	v_add_f32_e32 v167, 1.0, v167
	v_add_f32_e32 v168, 1.0, v168
	v_add_f32_e32 v169, 1.0, v169
	v_add_f32_e32 v170, 1.0, v170
	v_add_f32_e32 v171, 1.0, v171
	v_add_f32_e32 v172, 1.0, v172
	v_add_f32_e32 v173, 1.0, v173
	v_add_f32_e32 v174, 1.0, v174
	v_add_f32_e32 v175, 1.0, v175
	v_add_f32_e32 v176, 1.0, v176
	v_add_f32_e32 v177, 1.0, v177
	v_mul_f32_e32 v58, v94, v58
	v_mul_f32_e32 v59, v94, v59
	v_mul_f32_e32 v60, v94, v60
	v_mul_f32_e32 v61, v94, v61
	v_mul_f32_e32 v62, v94, v62
	v_mul_f32_e32 v63, v94, v63
	v_mul_f32_e32 v64, v94, v64
	v_mul_f32_e32 v65, v94, v65
	v_mul_f32_e32 v66, v94, v66
	v_mul_f32_e32 v67, v94, v67
	v_mul_f32_e32 v68, v94, v68
	v_mul_f32_e32 v69, v94, v69
	v_mul_f32_e32 v70, v94, v70
	v_mul_f32_e32 v71, v94, v71
	v_mul_f32_e32 v72, v94, v72
	v_mul_f32_e32 v73, v94, v73
	v_fma_f32 v58, v58, v162, v146
	v_fma_f32 v59, v59, v163, v147
	v_fma_f32 v60, v60, v164, v148
	v_fma_f32 v61, v61, v165, v149
	v_fma_f32 v62, v62, v166, v150
	v_fma_f32 v63, v63, v167, v151
	v_fma_f32 v64, v64, v168, v152
	v_fma_f32 v65, v65, v169, v153
	v_fma_f32 v66, v66, v170, v154
	v_fma_f32 v67, v67, v171, v155
	v_fma_f32 v68, v68, v172, v156
	v_fma_f32 v69, v69, v173, v157
	v_fma_f32 v70, v70, v174, v158
	v_fma_f32 v71, v71, v175, v159
	v_fma_f32 v72, v72, v176, v160
	v_fma_f32 v73, v73, v177, v161
	v_cvt_pk_bf16_f32 v190, v58, v59
	v_cvt_pk_bf16_f32 v191, v60, v61
	v_cvt_pk_bf16_f32 v192, v62, v63
	v_cvt_pk_bf16_f32 v193, v64, v65
	v_cvt_pk_bf16_f32 v194, v66, v67
	v_cvt_pk_bf16_f32 v195, v68, v69
	v_cvt_pk_bf16_f32 v196, v70, v71
	v_cvt_pk_bf16_f32 v197, v72, v73
	s_add_u32 s2, s10, 0x1400000
	s_addc_u32 s3, s11, 0
	global_store_dwordx2 v1, v[190:191], s[2:3]
	global_store_dwordx2 v1, v[192:193], s[2:3] offset:512
	global_store_dwordx2 v1, v[194:195], s[2:3] offset:1024
	global_store_dwordx2 v1, v[196:197], s[2:3] offset:1536
	s_add_u32 s2, s14, 0x2a000
	s_addc_u32 s3, s15, 0
	global_load_dwordx4 v[146:149], v0, s[2:3]
	global_load_dwordx4 v[150:153], v0, s[2:3] offset:1024
	global_load_dwordx4 v[154:157], v0, s[2:3] offset:2048
	global_load_dwordx4 v[158:161], v0, s[2:3] offset:3072
	s_add_u32 s2, s18, 0x2a000
	s_addc_u32 s3, s19, 0
	global_load_dwordx4 v[162:165], v0, s[2:3]
	global_load_dwordx4 v[166:169], v0, s[2:3] offset:1024
	global_load_dwordx4 v[170:173], v0, s[2:3] offset:2048
	global_load_dwordx4 v[174:177], v0, s[2:3] offset:3072
	v_add_f32_e32 v9, v74, v75
	v_add_f32_e32 v91, v76, v77
	v_mul_f32_e32 v90, v74, v74
	v_mul_f32_e32 v92, v75, v75
	v_add_f32_e32 v9, v9, v78
	v_add_f32_e32 v91, v91, v79
	v_add_f32_e32 v9, v9, v80
	v_add_f32_e32 v91, v91, v81
	v_add_f32_e32 v9, v9, v82
	v_add_f32_e32 v91, v91, v83
	v_add_f32_e32 v9, v9, v84
	v_add_f32_e32 v91, v91, v85
	v_add_f32_e32 v9, v9, v86
	v_add_f32_e32 v91, v91, v87
	v_add_f32_e32 v9, v9, v88
	v_add_f32_e32 v91, v91, v89
	v_fmac_f32_e32 v90, v76, v76
	v_fmac_f32_e32 v92, v77, v77
	v_fmac_f32_e32 v90, v78, v78
	v_fmac_f32_e32 v92, v79, v79
	v_fmac_f32_e32 v90, v80, v80
	v_fmac_f32_e32 v92, v81, v81
	v_fmac_f32_e32 v90, v82, v82
	v_fmac_f32_e32 v92, v83, v83
	v_fmac_f32_e32 v90, v84, v84
	v_fmac_f32_e32 v92, v85, v85
	v_fmac_f32_e32 v90, v86, v86
	v_fmac_f32_e32 v92, v87, v87
	v_fmac_f32_e32 v90, v88, v88
	v_fmac_f32_e32 v92, v89, v89
	v_add_f32_e32 v9, v9, v91
	v_add_f32_e32 v90, v90, v92
	ds_bpermute_b32 v91, v3, v9
	ds_bpermute_b32 v92, v3, v90
	s_waitcnt lgkmcnt(0)
	v_add_f32_e32 v9, v9, v91
	v_add_f32_e32 v90, v90, v92
	ds_bpermute_b32 v91, v4, v9
	ds_bpermute_b32 v92, v4, v90
	s_waitcnt lgkmcnt(0)
	v_add_f32_e32 v9, v9, v91
	v_add_f32_e32 v90, v90, v92
	ds_bpermute_b32 v91, v5, v9
	ds_bpermute_b32 v92, v5, v90
	s_waitcnt lgkmcnt(0)
	v_add_f32_e32 v9, v9, v91
	v_add_f32_e32 v90, v90, v92
	ds_bpermute_b32 v91, v6, v9
	ds_bpermute_b32 v92, v6, v90
	s_waitcnt lgkmcnt(0)
	v_add_f32_e32 v9, v9, v91
	v_add_f32_e32 v90, v90, v92
	ds_bpermute_b32 v91, v7, v9
	ds_bpermute_b32 v92, v7, v90
	s_waitcnt lgkmcnt(0)
	v_add_f32_e32 v9, v9, v91
	v_add_f32_e32 v90, v90, v92
	ds_bpermute_b32 v91, v8, v9
	ds_bpermute_b32 v92, v8, v90
	s_waitcnt lgkmcnt(0)
; DI unsigned pk2(float lo, float hi) { f32x2 v = {lo, hi}; bf16x2_t b = __builtin_convertvector(v, bf16x2_t); return __builtin_bit_cast(unsigned, b); }
; DI void ln_row_v(const Frame& F, f32x4 (&v)[4], float* xout, const float* g, const float* b, const float* sh, const float* sc, bf16_t* hout, const float* slab, const float* gres, float* stat = nullptr) {
;     ...
;     if (g) {
;         float s = 0.f, s2 = 0.f;
; #pragma unroll
;         for (int j = 0; j < 4; ++j) { s += (v[j][0] + v[j][1]) + (v[j][2] + v[j][3]); s2 += (v[j][0] * v[j][0] + v[j][1] * v[j][1]) + (v[j][2] * v[j][2] + v[j][3] * v[j][3]); }
;         wave_sum2(s, s2, F.lane);
;         const float mean = s * (1.f / D); const float rstd = 1.f / sqrtf(fmaxf(s2 * (1.f / D) - mean * mean, 0.f) + EPS);
;         if (stat && F.lane == 0) { f32x2 sv = {mean, rstd}; *(f32x2*)stat = sv; }
; #pragma unroll
;         for (int j = 0; j < 4; ++j) { const f32x4 gg = ((const f32x4*)g)[F.lane + 64 * j], bb = ((const f32x4*)b)[F.lane + 64 * j];
;             v[j] = (v[j] - mean) * rstd * gg + bb; if (xout) ((f32x4*)xout)[F.lane + 64 * j] = v[j]; }
;     }
;     if (hout) {
;         float s = 0.f, s2 = 0.f;
; #pragma unroll
;         for (int j = 0; j < 4; ++j) { s += (v[j][0] + v[j][1]) + (v[j][2] + v[j][3]); s2 += (v[j][0] * v[j][0] + v[j][1] * v[j][1]) + (v[j][2] * v[j][2] + v[j][3] * v[j][3]); }
;         wave_sum2(s, s2, F.lane);
;         const float mean = s * (1.f / D); const float rstd = 1.f / sqrtf(fmaxf(s2 * (1.f / D) - mean * mean, 0.f) + EPS);
; #pragma unroll
;         for (int j = 0; j < 4; ++j) { const f32x4 hh = ((const f32x4*)sh)[F.lane + 64 * j], cc = ((const f32x4*)sc)[F.lane + 64 * j];
;             const f32x4 o = (v[j] - mean) * rstd * (cc + 1.f) + hh; u32x2 wv; wv.x = pk2(o[0], o[1]); wv.y = pk2(o[2], o[3]);
;             ((u32x2*)hout)[F.lane + 64 * j] = wv; }
;     }
	v_add_f32_e32 v9, v9, v91
	v_add_f32_e32 v90, v90, v92
	v_mul_f32_e32 v93, 0x3a800000, v9
	v_mul_f32_e32 v91, 0x3a800000, v90
	v_fma_f32 v91, -v93, v93, v91
	v_max_f32_e32 v91, 0, v91
	v_add_f32_e32 v91, 0x358637bd, v91
	v_rsq_f32_e32 v94, v91
	v_mul_f32_e32 v91, 0.5, v91
	v_mul_f32_e32 v92, v94, v94
	v_fma_f32 v92, -v91, v92, 0.5
	v_fma_f32 v94, v94, v92, v94
	s_add_u32 s2, s12, 0x18000
	s_addc_u32 s3, s13, 0
	v_mov_b32_e32 v188, v93
	v_mov_b32_e32 v189, v94
	s_mov_b64 exec, 1
	global_store_dwordx2 v97, v[188:189], s[2:3]
	s_mov_b64 exec, -1
	v_sub_f32_e32 v74, v74, v93
	v_sub_f32_e32 v75, v75, v93
	v_sub_f32_e32 v76, v76, v93
	v_sub_f32_e32 v77, v77, v93
	v_sub_f32_e32 v78, v78, v93
	v_sub_f32_e32 v79, v79, v93
	v_sub_f32_e32 v80, v80, v93
	v_sub_f32_e32 v81, v81, v93
	v_sub_f32_e32 v82, v82, v93
	v_sub_f32_e32 v83, v83, v93
	v_sub_f32_e32 v84, v84, v93
	v_sub_f32_e32 v85, v85, v93
	v_sub_f32_e32 v86, v86, v93
	v_sub_f32_e32 v87, v87, v93
	v_sub_f32_e32 v88, v88, v93
	v_sub_f32_e32 v89, v89, v93
	v_mul_f32_e32 v74, v94, v74
	v_mul_f32_e32 v75, v94, v75
	v_mul_f32_e32 v76, v94, v76
	v_mul_f32_e32 v77, v94, v77
	v_mul_f32_e32 v78, v94, v78
	v_mul_f32_e32 v79, v94, v79
	v_mul_f32_e32 v80, v94, v80
	v_mul_f32_e32 v81, v94, v81
	v_mul_f32_e32 v82, v94, v82
	v_mul_f32_e32 v83, v94, v83
	v_mul_f32_e32 v84, v94, v84
	v_mul_f32_e32 v85, v94, v85
	v_mul_f32_e32 v86, v94, v86
	v_mul_f32_e32 v87, v94, v87
	v_mul_f32_e32 v88, v94, v88
	v_mul_f32_e32 v89, v94, v89
	v_fma_f32 v74, v74, v10, v26
	v_fma_f32 v75, v75, v11, v27
	v_fma_f32 v76, v76, v12, v28
	v_fma_f32 v77, v77, v13, v29
	v_fma_f32 v78, v78, v14, v30
	v_fma_f32 v79, v79, v15, v31
	v_fma_f32 v80, v80, v16, v32
	v_fma_f32 v81, v81, v17, v33
	v_fma_f32 v82, v82, v18, v34
	v_fma_f32 v83, v83, v19, v35
	v_fma_f32 v84, v84, v20, v36
	v_fma_f32 v85, v85, v21, v37
	v_fma_f32 v86, v86, v22, v38
	v_fma_f32 v87, v87, v23, v39
	v_fma_f32 v88, v88, v24, v40
	v_fma_f32 v89, v89, v25, v41
	v_add_f32_e32 v9, v74, v75
	v_add_f32_e32 v91, v76, v77
	v_mul_f32_e32 v90, v74, v74
	v_mul_f32_e32 v92, v75, v75
	v_add_f32_e32 v9, v9, v78
	v_add_f32_e32 v91, v91, v79
	v_add_f32_e32 v9, v9, v80
	v_add_f32_e32 v91, v91, v81
	v_add_f32_e32 v9, v9, v82
	v_add_f32_e32 v91, v91, v83
	v_add_f32_e32 v9, v9, v84
	v_add_f32_e32 v91, v91, v85
	v_add_f32_e32 v9, v9, v86
	v_add_f32_e32 v91, v91, v87
	v_add_f32_e32 v9, v9, v88
	v_add_f32_e32 v91, v91, v89
	v_fmac_f32_e32 v90, v76, v76
	v_fmac_f32_e32 v92, v77, v77
	v_fmac_f32_e32 v90, v78, v78
	v_fmac_f32_e32 v92, v79, v79
	v_fmac_f32_e32 v90, v80, v80
	v_fmac_f32_e32 v92, v81, v81
	v_fmac_f32_e32 v90, v82, v82
	v_fmac_f32_e32 v92, v83, v83
	v_fmac_f32_e32 v90, v84, v84
	v_fmac_f32_e32 v92, v85, v85
	v_fmac_f32_e32 v90, v86, v86
	v_fmac_f32_e32 v92, v87, v87
	v_fmac_f32_e32 v90, v88, v88
	v_fmac_f32_e32 v92, v89, v89
	v_add_f32_e32 v9, v9, v91
	v_add_f32_e32 v90, v90, v92
	ds_bpermute_b32 v91, v3, v9
	ds_bpermute_b32 v92, v3, v90
	s_waitcnt lgkmcnt(0)
	v_add_f32_e32 v9, v9, v91
	v_add_f32_e32 v90, v90, v92
	ds_bpermute_b32 v91, v4, v9
	ds_bpermute_b32 v92, v4, v90
	s_waitcnt lgkmcnt(0)
	v_add_f32_e32 v9, v9, v91
	v_add_f32_e32 v90, v90, v92
	ds_bpermute_b32 v91, v5, v9
	ds_bpermute_b32 v92, v5, v90
	s_waitcnt lgkmcnt(0)
	v_add_f32_e32 v9, v9, v91
	v_add_f32_e32 v90, v90, v92
	ds_bpermute_b32 v91, v6, v9
	ds_bpermute_b32 v92, v6, v90
	s_waitcnt lgkmcnt(0)
	v_add_f32_e32 v9, v9, v91
	v_add_f32_e32 v90, v90, v92
	ds_bpermute_b32 v91, v7, v9
	ds_bpermute_b32 v92, v7, v90
	s_waitcnt lgkmcnt(0)
	v_add_f32_e32 v9, v9, v91
	v_add_f32_e32 v90, v90, v92
	ds_bpermute_b32 v91, v8, v9
	ds_bpermute_b32 v92, v8, v90
	s_waitcnt lgkmcnt(0)
	v_add_f32_e32 v9, v9, v91
	v_add_f32_e32 v90, v90, v92
	v_mul_f32_e32 v93, 0x3a800000, v9
	v_mul_f32_e32 v91, 0x3a800000, v90
	v_fma_f32 v91, -v93, v93, v91
	v_max_f32_e32 v91, 0, v91
	v_add_f32_e32 v91, 0x358637bd, v91
	v_rsq_f32_e32 v94, v91
	v_mul_f32_e32 v91, 0.5, v91
	v_mul_f32_e32 v92, v94, v94
	v_fma_f32 v92, -v91, v92, 0.5
	v_fma_f32 v94, v94, v92, v94
	s_waitcnt vmcnt(14)
	v_sub_f32_e32 v74, v74, v93
	v_sub_f32_e32 v75, v75, v93
	v_sub_f32_e32 v76, v76, v93
	v_sub_f32_e32 v77, v77, v93
	v_sub_f32_e32 v78, v78, v93
	v_sub_f32_e32 v79, v79, v93
	v_sub_f32_e32 v80, v80, v93
	v_sub_f32_e32 v81, v81, v93
	v_sub_f32_e32 v82, v82, v93
	v_sub_f32_e32 v83, v83, v93
	v_sub_f32_e32 v84, v84, v93
	v_sub_f32_e32 v85, v85, v93
	v_sub_f32_e32 v86, v86, v93
	v_sub_f32_e32 v87, v87, v93
	v_sub_f32_e32 v88, v88, v93
	v_sub_f32_e32 v89, v89, v93
	v_add_f32_e32 v130, 1.0, v130
	v_add_f32_e32 v131, 1.0, v131
	v_add_f32_e32 v132, 1.0, v132
	v_add_f32_e32 v133, 1.0, v133
	v_add_f32_e32 v134, 1.0, v134
	v_add_f32_e32 v135, 1.0, v135
	v_add_f32_e32 v136, 1.0, v136
	v_add_f32_e32 v137, 1.0, v137
	v_add_f32_e32 v138, 1.0, v138
	v_add_f32_e32 v139, 1.0, v139
	v_add_f32_e32 v140, 1.0, v140
	v_add_f32_e32 v141, 1.0, v141
	v_add_f32_e32 v142, 1.0, v142
	v_add_f32_e32 v143, 1.0, v143
	v_add_f32_e32 v144, 1.0, v144
	v_add_f32_e32 v145, 1.0, v145
	v_mul_f32_e32 v74, v94, v74
	v_mul_f32_e32 v75, v94, v75
	v_mul_f32_e32 v76, v94, v76
	v_mul_f32_e32 v77, v94, v77
	v_mul_f32_e32 v78, v94, v78
	v_mul_f32_e32 v79, v94, v79
	v_mul_f32_e32 v80, v94, v80
	v_mul_f32_e32 v81, v94, v81
	v_mul_f32_e32 v82, v94, v82
	v_mul_f32_e32 v83, v94, v83
	v_mul_f32_e32 v84, v94, v84
	v_mul_f32_e32 v85, v94, v85
	v_mul_f32_e32 v86, v94, v86
	v_mul_f32_e32 v87, v94, v87
	v_mul_f32_e32 v88, v94, v88
	v_mul_f32_e32 v89, v94, v89
	v_fma_f32 v74, v74, v130, v114
	v_fma_f32 v75, v75, v131, v115
	v_fma_f32 v76, v76, v132, v116
	v_fma_f32 v77, v77, v133, v117
	v_fma_f32 v78, v78, v134, v118
	v_fma_f32 v79, v79, v135, v119
; DI unsigned pk2(float lo, float hi) { f32x2 v = {lo, hi}; bf16x2_t b = __builtin_convertvector(v, bf16x2_t); return __builtin_bit_cast(unsigned, b); }
; DI const float* modp(const Frame& F, int l, int mr, int which) { return (const float*)(F.ws + WS_MOD) + ((size_t)(l * 9 + mr) * 6 + which) * 1024; }
; DI void ln_row_v(const Frame& F, f32x4 (&v)[4], float* xout, const float* g, const float* b, const float* sh, const float* sc, bf16_t* hout, const float* slab, const float* gres, float* stat = nullptr) {
;     ...
;     if (hout) {
;         float s = 0.f, s2 = 0.f;
; #pragma unroll
;         for (int j = 0; j < 4; ++j) { s += (v[j][0] + v[j][1]) + (v[j][2] + v[j][3]); s2 += (v[j][0] * v[j][0] + v[j][1] * v[j][1]) + (v[j][2] * v[j][2] + v[j][3] * v[j][3]); }
;         wave_sum2(s, s2, F.lane);
;         const float mean = s * (1.f / D); const float rstd = 1.f / sqrtf(fmaxf(s2 * (1.f / D) - mean * mean, 0.f) + EPS);
; #pragma unroll
;         for (int j = 0; j < 4; ++j) { const f32x4 hh = ((const f32x4*)sh)[F.lane + 64 * j], cc = ((const f32x4*)sc)[F.lane + 64 * j];
;             const f32x4 o = (v[j] - mean) * rstd * (cc + 1.f) + hh; u32x2 wv; wv.x = pk2(o[0], o[1]); wv.y = pk2(o[2], o[3]);
;             ((u32x2*)hout)[F.lane + 64 * j] = wv; }
;     }
; DI void ln_phase(const Frame& F, int which) {
;     ...
;         const int mr = row < ML ? (row >> 11) : 8;
;         const float* sh = which == 0 ? modp(F, l, mr, 3) : modp(F, l + 1 < NL ? l + 1 : l, mr, 0);
;         const float* sc = which == 0 ? modp(F, l, mr, 4) : modp(F, l + 1 < NL ? l + 1 : l, mr, 1);
	v_fma_f32 v80, v80, v136, v120
	v_fma_f32 v81, v81, v137, v121
	v_fma_f32 v82, v82, v138, v122
	v_fma_f32 v83, v83, v139, v123
	v_fma_f32 v84, v84, v140, v124
	v_fma_f32 v85, v85, v141, v125
	v_fma_f32 v86, v86, v142, v126
	v_fma_f32 v87, v87, v143, v127
	v_fma_f32 v88, v88, v144, v128
	v_fma_f32 v89, v89, v145, v129
	v_cvt_pk_bf16_f32 v190, v74, v75
	v_cvt_pk_bf16_f32 v191, v76, v77
	v_cvt_pk_bf16_f32 v192, v78, v79
	v_cvt_pk_bf16_f32 v193, v80, v81
	v_cvt_pk_bf16_f32 v194, v82, v83
	v_cvt_pk_bf16_f32 v195, v84, v85
	v_cvt_pk_bf16_f32 v196, v86, v87
	v_cvt_pk_bf16_f32 v197, v88, v89
	s_add_u32 s2, s10, 0x1800000
	s_addc_u32 s3, s11, 0
	global_store_dwordx2 v1, v[190:191], s[2:3]
	global_store_dwordx2 v1, v[192:193], s[2:3] offset:512
	global_store_dwordx2 v1, v[194:195], s[2:3] offset:1024
	global_store_dwordx2 v1, v[196:197], s[2:3] offset:1536
	s_add_u32 s2, s14, 0x30000
	s_addc_u32 s3, s15, 0
	global_load_dwordx4 v[114:117], v0, s[2:3]
	global_load_dwordx4 v[118:121], v0, s[2:3] offset:1024
	global_load_dwordx4 v[122:125], v0, s[2:3] offset:2048
	global_load_dwordx4 v[126:129], v0, s[2:3] offset:3072
	s_add_u32 s2, s18, 0x30000
	s_addc_u32 s3, s19, 0
	global_load_dwordx4 v[130:133], v0, s[2:3]
	global_load_dwordx4 v[134:137], v0, s[2:3] offset:1024
	global_load_dwordx4 v[138:141], v0, s[2:3] offset:2048
	global_load_dwordx4 v[142:145], v0, s[2:3] offset:3072
	v_add_f32_e32 v9, v98, v99
	v_add_f32_e32 v91, v100, v101
	v_mul_f32_e32 v90, v98, v98
	v_mul_f32_e32 v92, v99, v99
	v_add_f32_e32 v9, v9, v102
	v_add_f32_e32 v91, v91, v103
	v_add_f32_e32 v9, v9, v104
	v_add_f32_e32 v91, v91, v105
	v_add_f32_e32 v9, v9, v106
	v_add_f32_e32 v91, v91, v107
	v_add_f32_e32 v9, v9, v108
	v_add_f32_e32 v91, v91, v109
	v_add_f32_e32 v9, v9, v110
	v_add_f32_e32 v91, v91, v111
	v_add_f32_e32 v9, v9, v112
	v_add_f32_e32 v91, v91, v113
	v_fmac_f32_e32 v90, v100, v100
	v_fmac_f32_e32 v92, v101, v101
	v_fmac_f32_e32 v90, v102, v102
	v_fmac_f32_e32 v92, v103, v103
	v_fmac_f32_e32 v90, v104, v104
	v_fmac_f32_e32 v92, v105, v105
	v_fmac_f32_e32 v90, v106, v106
	v_fmac_f32_e32 v92, v107, v107
	v_fmac_f32_e32 v90, v108, v108
	v_fmac_f32_e32 v92, v109, v109
	v_fmac_f32_e32 v90, v110, v110
	v_fmac_f32_e32 v92, v111, v111
	v_fmac_f32_e32 v90, v112, v112
	v_fmac_f32_e32 v92, v113, v113
	v_add_f32_e32 v9, v9, v91
	v_add_f32_e32 v90, v90, v92
	ds_bpermute_b32 v91, v3, v9
	ds_bpermute_b32 v92, v3, v90
	s_waitcnt lgkmcnt(0)
	v_add_f32_e32 v9, v9, v91
	v_add_f32_e32 v90, v90, v92
	ds_bpermute_b32 v91, v4, v9
	ds_bpermute_b32 v92, v4, v90
	s_waitcnt lgkmcnt(0)
	v_add_f32_e32 v9, v9, v91
	v_add_f32_e32 v90, v90, v92
	ds_bpermute_b32 v91, v5, v9
	ds_bpermute_b32 v92, v5, v90
	s_waitcnt lgkmcnt(0)
	v_add_f32_e32 v9, v9, v91
	v_add_f32_e32 v90, v90, v92
	ds_bpermute_b32 v91, v6, v9
	ds_bpermute_b32 v92, v6, v90
	s_waitcnt lgkmcnt(0)
	v_add_f32_e32 v9, v9, v91
	v_add_f32_e32 v90, v90, v92
	ds_bpermute_b32 v91, v7, v9
	ds_bpermute_b32 v92, v7, v90
	s_waitcnt lgkmcnt(0)
	v_add_f32_e32 v9, v9, v91
	v_add_f32_e32 v90, v90, v92
	ds_bpermute_b32 v91, v8, v9
	ds_bpermute_b32 v92, v8, v90
	s_waitcnt lgkmcnt(0)
	v_add_f32_e32 v9, v9, v91
	v_add_f32_e32 v90, v90, v92
	v_mul_f32_e32 v93, 0x3a800000, v9
	v_mul_f32_e32 v91, 0x3a800000, v90
	v_fma_f32 v91, -v93, v93, v91
	v_max_f32_e32 v91, 0, v91
	v_add_f32_e32 v91, 0x358637bd, v91
	v_rsq_f32_e32 v94, v91
	v_mul_f32_e32 v91, 0.5, v91
	v_mul_f32_e32 v92, v94, v94
	v_fma_f32 v92, -v91, v92, 0.5
	v_fma_f32 v94, v94, v92, v94
	s_add_u32 s2, s12, 0x1c000
	s_addc_u32 s3, s13, 0
	v_mov_b32_e32 v188, v93
	v_mov_b32_e32 v189, v94
	s_mov_b64 exec, 1
	global_store_dwordx2 v97, v[188:189], s[2:3]
	s_mov_b64 exec, -1
	v_sub_f32_e32 v98, v98, v93
	v_sub_f32_e32 v99, v99, v93
	v_sub_f32_e32 v100, v100, v93
	v_sub_f32_e32 v101, v101, v93
	v_sub_f32_e32 v102, v102, v93
	v_sub_f32_e32 v103, v103, v93
	v_sub_f32_e32 v104, v104, v93
	v_sub_f32_e32 v105, v105, v93
	v_sub_f32_e32 v106, v106, v93
	v_sub_f32_e32 v107, v107, v93
	v_sub_f32_e32 v108, v108, v93
	v_sub_f32_e32 v109, v109, v93
	v_sub_f32_e32 v110, v110, v93
	v_sub_f32_e32 v111, v111, v93
	v_sub_f32_e32 v112, v112, v93
	v_sub_f32_e32 v113, v113, v93
	v_mul_f32_e32 v98, v94, v98
	v_mul_f32_e32 v99, v94, v99
	v_mul_f32_e32 v100, v94, v100
	v_mul_f32_e32 v101, v94, v101
	v_mul_f32_e32 v102, v94, v102
	v_mul_f32_e32 v103, v94, v103
	v_mul_f32_e32 v104, v94, v104
	v_mul_f32_e32 v105, v94, v105
	v_mul_f32_e32 v106, v94, v106
	v_mul_f32_e32 v107, v94, v107
	v_mul_f32_e32 v108, v94, v108
	v_mul_f32_e32 v109, v94, v109
	v_mul_f32_e32 v110, v94, v110
	v_mul_f32_e32 v111, v94, v111
	v_mul_f32_e32 v112, v94, v112
	v_mul_f32_e32 v113, v94, v113
	v_fma_f32 v98, v98, v10, v26
	v_fma_f32 v99, v99, v11, v27
	v_fma_f32 v100, v100, v12, v28
	v_fma_f32 v101, v101, v13, v29
	v_fma_f32 v102, v102, v14, v30
	v_fma_f32 v103, v103, v15, v31
	v_fma_f32 v104, v104, v16, v32
	v_fma_f32 v105, v105, v17, v33
	v_fma_f32 v106, v106, v18, v34
	v_fma_f32 v107, v107, v19, v35
	v_fma_f32 v108, v108, v20, v36
	v_fma_f32 v109, v109, v21, v37
	v_fma_f32 v110, v110, v22, v38
	v_fma_f32 v111, v111, v23, v39
	v_fma_f32 v112, v112, v24, v40
	v_fma_f32 v113, v113, v25, v41
	v_add_f32_e32 v9, v98, v99
	v_add_f32_e32 v91, v100, v101
	v_mul_f32_e32 v90, v98, v98
	v_mul_f32_e32 v92, v99, v99
	v_add_f32_e32 v9, v9, v102
	v_add_f32_e32 v91, v91, v103
	v_add_f32_e32 v9, v9, v104
	v_add_f32_e32 v91, v91, v105
	v_add_f32_e32 v9, v9, v106
	v_add_f32_e32 v91, v91, v107
	v_add_f32_e32 v9, v9, v108
	v_add_f32_e32 v91, v91, v109
	v_add_f32_e32 v9, v9, v110
	v_add_f32_e32 v91, v91, v111
	v_add_f32_e32 v9, v9, v112
	v_add_f32_e32 v91, v91, v113
	v_fmac_f32_e32 v90, v100, v100
	v_fmac_f32_e32 v92, v101, v101
	v_fmac_f32_e32 v90, v102, v102
	v_fmac_f32_e32 v92, v103, v103
	v_fmac_f32_e32 v90, v104, v104
	v_fmac_f32_e32 v92, v105, v105
	v_fmac_f32_e32 v90, v106, v106
	v_fmac_f32_e32 v92, v107, v107
	v_fmac_f32_e32 v90, v108, v108
	v_fmac_f32_e32 v92, v109, v109
	v_fmac_f32_e32 v90, v110, v110
	v_fmac_f32_e32 v92, v111, v111
	v_fmac_f32_e32 v90, v112, v112
	v_fmac_f32_e32 v92, v113, v113
	v_add_f32_e32 v9, v9, v91
	v_add_f32_e32 v90, v90, v92
	ds_bpermute_b32 v91, v3, v9
	ds_bpermute_b32 v92, v3, v90
	s_waitcnt lgkmcnt(0)
; DI unsigned pk2(float lo, float hi) { f32x2 v = {lo, hi}; bf16x2_t b = __builtin_convertvector(v, bf16x2_t); return __builtin_bit_cast(unsigned, b); }
; DI void ln_row_v(const Frame& F, f32x4 (&v)[4], float* xout, const float* g, const float* b, const float* sh, const float* sc, bf16_t* hout, const float* slab, const float* gres, float* stat = nullptr) {
;     if (slab) {
; #pragma unroll
;         for (int j = 0; j < 4; ++j) { f32x4 a = ((const f32x4*)slab)[F.lane + 64 * j];
; #pragma unroll
;             for (int z = 1; z < 8; ++z) a += ((const f32x4*)(slab + (size_t)z * MC * 1024))[F.lane + 64 * j];
;             v[j] = v[j] * ALPHA + ((const f32x4*)gres)[F.lane + 64 * j] * a; }
;     ...
;     if (hout) {
;         float s = 0.f, s2 = 0.f;
; #pragma unroll
;         for (int j = 0; j < 4; ++j) { s += (v[j][0] + v[j][1]) + (v[j][2] + v[j][3]); s2 += (v[j][0] * v[j][0] + v[j][1] * v[j][1]) + (v[j][2] * v[j][2] + v[j][3] * v[j][3]); }
;         wave_sum2(s, s2, F.lane);
;         const float mean = s * (1.f / D); const float rstd = 1.f / sqrtf(fmaxf(s2 * (1.f / D) - mean * mean, 0.f) + EPS);
; #pragma unroll
;         for (int j = 0; j < 4; ++j) { const f32x4 hh = ((const f32x4*)sh)[F.lane + 64 * j], cc = ((const f32x4*)sc)[F.lane + 64 * j];
;             const f32x4 o = (v[j] - mean) * rstd * (cc + 1.f) + hh; u32x2 wv; wv.x = pk2(o[0], o[1]); wv.y = pk2(o[2], o[3]);
;             ((u32x2*)hout)[F.lane + 64 * j] = wv; }
;     }
	v_add_f32_e32 v9, v9, v91
	v_add_f32_e32 v90, v90, v92
	ds_bpermute_b32 v91, v4, v9
	ds_bpermute_b32 v92, v4, v90
	s_waitcnt lgkmcnt(0)
	v_add_f32_e32 v9, v9, v91
	v_add_f32_e32 v90, v90, v92
	ds_bpermute_b32 v91, v5, v9
	ds_bpermute_b32 v92, v5, v90
	s_waitcnt lgkmcnt(0)
	v_add_f32_e32 v9, v9, v91
	v_add_f32_e32 v90, v90, v92
	ds_bpermute_b32 v91, v6, v9
	ds_bpermute_b32 v92, v6, v90
	s_waitcnt lgkmcnt(0)
	v_add_f32_e32 v9, v9, v91
	v_add_f32_e32 v90, v90, v92
	ds_bpermute_b32 v91, v7, v9
	ds_bpermute_b32 v92, v7, v90
	s_waitcnt lgkmcnt(0)
	v_add_f32_e32 v9, v9, v91
	v_add_f32_e32 v90, v90, v92
	ds_bpermute_b32 v91, v8, v9
	ds_bpermute_b32 v92, v8, v90
	s_waitcnt lgkmcnt(0)
	v_add_f32_e32 v9, v9, v91
	v_add_f32_e32 v90, v90, v92
	v_mul_f32_e32 v93, 0x3a800000, v9
	v_mul_f32_e32 v91, 0x3a800000, v90
	v_fma_f32 v91, -v93, v93, v91
	v_max_f32_e32 v91, 0, v91
	v_add_f32_e32 v91, 0x358637bd, v91
	v_rsq_f32_e32 v94, v91
	v_mul_f32_e32 v91, 0.5, v91
	v_mul_f32_e32 v92, v94, v94
	v_fma_f32 v92, -v91, v92, 0.5
	v_fma_f32 v94, v94, v92, v94
	s_waitcnt vmcnt(14)
	v_sub_f32_e32 v98, v98, v93
	v_sub_f32_e32 v99, v99, v93
	v_sub_f32_e32 v100, v100, v93
	v_sub_f32_e32 v101, v101, v93
	v_sub_f32_e32 v102, v102, v93
	v_sub_f32_e32 v103, v103, v93
	v_sub_f32_e32 v104, v104, v93
	v_sub_f32_e32 v105, v105, v93
	v_sub_f32_e32 v106, v106, v93
	v_sub_f32_e32 v107, v107, v93
	v_sub_f32_e32 v108, v108, v93
	v_sub_f32_e32 v109, v109, v93
	v_sub_f32_e32 v110, v110, v93
	v_sub_f32_e32 v111, v111, v93
	v_sub_f32_e32 v112, v112, v93
	v_sub_f32_e32 v113, v113, v93
	v_add_f32_e32 v162, 1.0, v162
	v_add_f32_e32 v163, 1.0, v163
	v_add_f32_e32 v164, 1.0, v164
	v_add_f32_e32 v165, 1.0, v165
	v_add_f32_e32 v166, 1.0, v166
	v_add_f32_e32 v167, 1.0, v167
	v_add_f32_e32 v168, 1.0, v168
	v_add_f32_e32 v169, 1.0, v169
	v_add_f32_e32 v170, 1.0, v170
	v_add_f32_e32 v171, 1.0, v171
	v_add_f32_e32 v172, 1.0, v172
	v_add_f32_e32 v173, 1.0, v173
	v_add_f32_e32 v174, 1.0, v174
	v_add_f32_e32 v175, 1.0, v175
	v_add_f32_e32 v176, 1.0, v176
	v_add_f32_e32 v177, 1.0, v177
	v_mul_f32_e32 v98, v94, v98
	v_mul_f32_e32 v99, v94, v99
	v_mul_f32_e32 v100, v94, v100
	v_mul_f32_e32 v101, v94, v101
	v_mul_f32_e32 v102, v94, v102
	v_mul_f32_e32 v103, v94, v103
	v_mul_f32_e32 v104, v94, v104
	v_mul_f32_e32 v105, v94, v105
	v_mul_f32_e32 v106, v94, v106
	v_mul_f32_e32 v107, v94, v107
	v_mul_f32_e32 v108, v94, v108
	v_mul_f32_e32 v109, v94, v109
	v_mul_f32_e32 v110, v94, v110
	v_mul_f32_e32 v111, v94, v111
	v_mul_f32_e32 v112, v94, v112
	v_mul_f32_e32 v113, v94, v113
	v_fma_f32 v98, v98, v162, v146
	v_fma_f32 v99, v99, v163, v147
	v_fma_f32 v100, v100, v164, v148
	v_fma_f32 v101, v101, v165, v149
	v_fma_f32 v102, v102, v166, v150
	v_fma_f32 v103, v103, v167, v151
	v_fma_f32 v104, v104, v168, v152
	v_fma_f32 v105, v105, v169, v153
	v_fma_f32 v106, v106, v170, v154
	v_fma_f32 v107, v107, v171, v155
	v_fma_f32 v108, v108, v172, v156
	v_fma_f32 v109, v109, v173, v157
	v_fma_f32 v110, v110, v174, v158
	v_fma_f32 v111, v111, v175, v159
	v_fma_f32 v112, v112, v176, v160
	v_fma_f32 v113, v113, v177, v161
	v_cvt_pk_bf16_f32 v190, v98, v99
	v_cvt_pk_bf16_f32 v191, v100, v101
	v_cvt_pk_bf16_f32 v192, v102, v103
	v_cvt_pk_bf16_f32 v193, v104, v105
	v_cvt_pk_bf16_f32 v194, v106, v107
	v_cvt_pk_bf16_f32 v195, v108, v109
	v_cvt_pk_bf16_f32 v196, v110, v111
	v_cvt_pk_bf16_f32 v197, v112, v113
	s_add_u32 s2, s10, 0x1c00000
	s_addc_u32 s3, s11, 0
	global_store_dwordx2 v1, v[190:191], s[2:3]
	global_store_dwordx2 v1, v[192:193], s[2:3] offset:512
	global_store_dwordx2 v1, v[194:195], s[2:3] offset:1024
	global_store_dwordx2 v1, v[196:197], s[2:3] offset:1536
	s_cmp_eq_u32 s22, 3
	s_cbranch_scc1 .Lln_b_noctx
	s_add_u32 s2, s24, 0x0
	s_addc_u32 s3, s25, 0
	global_load_dwordx4 v[58:61], v0, s[2:3]
	global_load_dwordx4 v[62:65], v0, s[2:3] offset:1024
	global_load_dwordx4 v[66:69], v0, s[2:3] offset:2048
	global_load_dwordx4 v[70:73], v0, s[2:3] offset:3072
	s_add_u32 s2, s24, 0x800000
	s_addc_u32 s3, s25, 0
	global_load_dwordx4 v[74:77], v0, s[2:3]
	global_load_dwordx4 v[78:81], v0, s[2:3] offset:1024
	global_load_dwordx4 v[82:85], v0, s[2:3] offset:2048
	global_load_dwordx4 v[86:89], v0, s[2:3] offset:3072
	s_add_u32 s2, s24, 0x1000000
	s_addc_u32 s3, s25, 0
	global_load_dwordx4 v[98:101], v0, s[2:3]
	global_load_dwordx4 v[102:105], v0, s[2:3] offset:1024
	global_load_dwordx4 v[106:109], v0, s[2:3] offset:2048
	global_load_dwordx4 v[110:113], v0, s[2:3] offset:3072
	s_add_u32 s2, s24, 0x1800000
	s_addc_u32 s3, s25, 0
	global_load_dwordx4 v[146:149], v0, s[2:3]
	global_load_dwordx4 v[150:153], v0, s[2:3] offset:1024
	global_load_dwordx4 v[154:157], v0, s[2:3] offset:2048
	global_load_dwordx4 v[158:161], v0, s[2:3] offset:3072
	s_add_u32 s2, s24, 0x2000000
	s_addc_u32 s3, s25, 0
	global_load_dwordx4 v[162:165], v0, s[2:3]
	global_load_dwordx4 v[166:169], v0, s[2:3] offset:1024
	global_load_dwordx4 v[170:173], v0, s[2:3] offset:2048
	global_load_dwordx4 v[174:177], v0, s[2:3] offset:3072
	s_mov_b64 s[2:3], s[26:27]
	global_load_dwordx4 v[226:229], v0, s[2:3]
	global_load_dwordx4 v[230:233], v0, s[2:3] offset:1024
	global_load_dwordx4 v[234:237], v0, s[2:3] offset:2048
	global_load_dwordx4 v[238:241], v0, s[2:3] offset:3072
	s_waitcnt vmcnt(16)
	v_add_f32_e32 v58, v58, v74
	v_add_f32_e32 v59, v59, v75
	v_add_f32_e32 v60, v60, v76
	v_add_f32_e32 v61, v61, v77
	v_add_f32_e32 v62, v62, v78
	v_add_f32_e32 v63, v63, v79
	v_add_f32_e32 v64, v64, v80
	v_add_f32_e32 v65, v65, v81
	v_add_f32_e32 v66, v66, v82
	v_add_f32_e32 v67, v67, v83
	v_add_f32_e32 v68, v68, v84
	v_add_f32_e32 v69, v69, v85
	v_add_f32_e32 v70, v70, v86
	v_add_f32_e32 v71, v71, v87
	v_add_f32_e32 v72, v72, v88
	v_add_f32_e32 v73, v73, v89
	s_add_u32 s2, s24, 0x2800000
	s_addc_u32 s3, s25, 0
	global_load_dwordx4 v[74:77], v0, s[2:3]
	global_load_dwordx4 v[78:81], v0, s[2:3] offset:1024
	global_load_dwordx4 v[82:85], v0, s[2:3] offset:2048
	global_load_dwordx4 v[86:89], v0, s[2:3] offset:3072
	s_waitcnt vmcnt(16)
; DI void ln_row_v(const Frame& F, f32x4 (&v)[4], float* xout, const float* g, const float* b, const float* sh, const float* sc, bf16_t* hout, const float* slab, const float* gres, float* stat = nullptr) {
;     if (slab) {
; #pragma unroll
;         for (int j = 0; j < 4; ++j) { f32x4 a = ((const f32x4*)slab)[F.lane + 64 * j];
; #pragma unroll
;             for (int z = 1; z < 8; ++z) a += ((const f32x4*)(slab + (size_t)z * MC * 1024))[F.lane + 64 * j];
;             v[j] = v[j] * ALPHA + ((const f32x4*)gres)[F.lane + 64 * j] * a; }
;     }
;     if (g) {
;         float s = 0.f, s2 = 0.f;
; #pragma unroll
;         for (int j = 0; j < 4; ++j) { s += (v[j][0] + v[j][1]) + (v[j][2] + v[j][3]); s2 += (v[j][0] * v[j][0] + v[j][1] * v[j][1]) + (v[j][2] * v[j][2] + v[j][3] * v[j][3]); }
;         wave_sum2(s, s2, F.lane);
;         const float mean = s * (1.f / D); const float rstd = 1.f / sqrtf(fmaxf(s2 * (1.f / D) - mean * mean, 0.f) + EPS);
	v_add_f32_e32 v58, v58, v98
	v_add_f32_e32 v59, v59, v99
	v_add_f32_e32 v60, v60, v100
	v_add_f32_e32 v61, v61, v101
	v_add_f32_e32 v62, v62, v102
	v_add_f32_e32 v63, v63, v103
	v_add_f32_e32 v64, v64, v104
	v_add_f32_e32 v65, v65, v105
	v_add_f32_e32 v66, v66, v106
	v_add_f32_e32 v67, v67, v107
	v_add_f32_e32 v68, v68, v108
	v_add_f32_e32 v69, v69, v109
	v_add_f32_e32 v70, v70, v110
	v_add_f32_e32 v71, v71, v111
	v_add_f32_e32 v72, v72, v112
	v_add_f32_e32 v73, v73, v113
	s_add_u32 s2, s24, 0x3000000
	s_addc_u32 s3, s25, 0
	global_load_dwordx4 v[98:101], v0, s[2:3]
	global_load_dwordx4 v[102:105], v0, s[2:3] offset:1024
	global_load_dwordx4 v[106:109], v0, s[2:3] offset:2048
	global_load_dwordx4 v[110:113], v0, s[2:3] offset:3072
	s_waitcnt vmcnt(16)
	v_add_f32_e32 v58, v58, v146
	v_add_f32_e32 v59, v59, v147
	v_add_f32_e32 v60, v60, v148
	v_add_f32_e32 v61, v61, v149
	v_add_f32_e32 v62, v62, v150
	v_add_f32_e32 v63, v63, v151
	v_add_f32_e32 v64, v64, v152
	v_add_f32_e32 v65, v65, v153
	v_add_f32_e32 v66, v66, v154
	v_add_f32_e32 v67, v67, v155
	v_add_f32_e32 v68, v68, v156
	v_add_f32_e32 v69, v69, v157
	v_add_f32_e32 v70, v70, v158
	v_add_f32_e32 v71, v71, v159
	v_add_f32_e32 v72, v72, v160
	v_add_f32_e32 v73, v73, v161
	s_add_u32 s2, s24, 0x3800000
	s_addc_u32 s3, s25, 0
	global_load_dwordx4 v[146:149], v0, s[2:3]
	global_load_dwordx4 v[150:153], v0, s[2:3] offset:1024
	global_load_dwordx4 v[154:157], v0, s[2:3] offset:2048
	global_load_dwordx4 v[158:161], v0, s[2:3] offset:3072
	s_waitcnt vmcnt(16)
	v_add_f32_e32 v58, v58, v162
	v_add_f32_e32 v59, v59, v163
	v_add_f32_e32 v60, v60, v164
	v_add_f32_e32 v61, v61, v165
	v_add_f32_e32 v62, v62, v166
	v_add_f32_e32 v63, v63, v167
	v_add_f32_e32 v64, v64, v168
	v_add_f32_e32 v65, v65, v169
	v_add_f32_e32 v66, v66, v170
	v_add_f32_e32 v67, v67, v171
	v_add_f32_e32 v68, v68, v172
	v_add_f32_e32 v69, v69, v173
	v_add_f32_e32 v70, v70, v174
	v_add_f32_e32 v71, v71, v175
	v_add_f32_e32 v72, v72, v176
	v_add_f32_e32 v73, v73, v177
	s_waitcnt vmcnt(8)
	v_add_f32_e32 v58, v58, v74
	v_add_f32_e32 v59, v59, v75
	v_add_f32_e32 v60, v60, v76
	v_add_f32_e32 v61, v61, v77
	v_add_f32_e32 v62, v62, v78
	v_add_f32_e32 v63, v63, v79
	v_add_f32_e32 v64, v64, v80
	v_add_f32_e32 v65, v65, v81
	v_add_f32_e32 v66, v66, v82
	v_add_f32_e32 v67, v67, v83
	v_add_f32_e32 v68, v68, v84
	v_add_f32_e32 v69, v69, v85
	v_add_f32_e32 v70, v70, v86
	v_add_f32_e32 v71, v71, v87
	v_add_f32_e32 v72, v72, v88
	v_add_f32_e32 v73, v73, v89
	s_waitcnt vmcnt(4)
	v_add_f32_e32 v58, v58, v98
	v_add_f32_e32 v59, v59, v99
	v_add_f32_e32 v60, v60, v100
	v_add_f32_e32 v61, v61, v101
	v_add_f32_e32 v62, v62, v102
	v_add_f32_e32 v63, v63, v103
	v_add_f32_e32 v64, v64, v104
	v_add_f32_e32 v65, v65, v105
	v_add_f32_e32 v66, v66, v106
	v_add_f32_e32 v67, v67, v107
	v_add_f32_e32 v68, v68, v108
	v_add_f32_e32 v69, v69, v109
	v_add_f32_e32 v70, v70, v110
	v_add_f32_e32 v71, v71, v111
	v_add_f32_e32 v72, v72, v112
	v_add_f32_e32 v73, v73, v113
	s_waitcnt vmcnt(0)
	v_add_f32_e32 v58, v58, v146
	v_add_f32_e32 v59, v59, v147
	v_add_f32_e32 v60, v60, v148
	v_add_f32_e32 v61, v61, v149
	v_add_f32_e32 v62, v62, v150
	v_add_f32_e32 v63, v63, v151
	v_add_f32_e32 v64, v64, v152
	v_add_f32_e32 v65, v65, v153
	v_add_f32_e32 v66, v66, v154
	v_add_f32_e32 v67, v67, v155
	v_add_f32_e32 v68, v68, v156
	v_add_f32_e32 v69, v69, v157
	v_add_f32_e32 v70, v70, v158
	v_add_f32_e32 v71, v71, v159
	v_add_f32_e32 v72, v72, v160
	v_add_f32_e32 v73, v73, v161
	v_mul_f32_e32 v42, 0x3fd744fd, v42
	v_mul_f32_e32 v43, 0x3fd744fd, v43
	v_mul_f32_e32 v44, 0x3fd744fd, v44
	v_mul_f32_e32 v45, 0x3fd744fd, v45
	v_mul_f32_e32 v46, 0x3fd744fd, v46
	v_mul_f32_e32 v47, 0x3fd744fd, v47
	v_mul_f32_e32 v48, 0x3fd744fd, v48
	v_mul_f32_e32 v49, 0x3fd744fd, v49
	v_mul_f32_e32 v50, 0x3fd744fd, v50
	v_mul_f32_e32 v51, 0x3fd744fd, v51
	v_mul_f32_e32 v52, 0x3fd744fd, v52
	v_mul_f32_e32 v53, 0x3fd744fd, v53
	v_mul_f32_e32 v54, 0x3fd744fd, v54
	v_mul_f32_e32 v55, 0x3fd744fd, v55
	v_mul_f32_e32 v56, 0x3fd744fd, v56
	v_mul_f32_e32 v57, 0x3fd744fd, v57
	v_fmac_f32_e32 v42, v226, v58
	v_fmac_f32_e32 v43, v227, v59
	v_fmac_f32_e32 v44, v228, v60
	v_fmac_f32_e32 v45, v229, v61
	v_fmac_f32_e32 v46, v230, v62
	v_fmac_f32_e32 v47, v231, v63
	v_fmac_f32_e32 v48, v232, v64
	v_fmac_f32_e32 v49, v233, v65
	v_fmac_f32_e32 v50, v234, v66
	v_fmac_f32_e32 v51, v235, v67
	v_fmac_f32_e32 v52, v236, v68
	v_fmac_f32_e32 v53, v237, v69
	v_fmac_f32_e32 v54, v238, v70
	v_fmac_f32_e32 v55, v239, v71
	v_fmac_f32_e32 v56, v240, v72
	v_fmac_f32_e32 v57, v241, v73
	v_add_f32_e32 v9, v42, v43
	v_add_f32_e32 v91, v44, v45
	v_mul_f32_e32 v90, v42, v42
	v_mul_f32_e32 v92, v43, v43
	v_add_f32_e32 v9, v9, v46
	v_add_f32_e32 v91, v91, v47
	v_add_f32_e32 v9, v9, v48
	v_add_f32_e32 v91, v91, v49
	v_add_f32_e32 v9, v9, v50
	v_add_f32_e32 v91, v91, v51
	v_add_f32_e32 v9, v9, v52
	v_add_f32_e32 v91, v91, v53
	v_add_f32_e32 v9, v9, v54
	v_add_f32_e32 v91, v91, v55
	v_add_f32_e32 v9, v9, v56
	v_add_f32_e32 v91, v91, v57
	v_fmac_f32_e32 v90, v44, v44
	v_fmac_f32_e32 v92, v45, v45
	v_fmac_f32_e32 v90, v46, v46
	v_fmac_f32_e32 v92, v47, v47
	v_fmac_f32_e32 v90, v48, v48
	v_fmac_f32_e32 v92, v49, v49
	v_fmac_f32_e32 v90, v50, v50
	v_fmac_f32_e32 v92, v51, v51
	v_fmac_f32_e32 v90, v52, v52
	v_fmac_f32_e32 v92, v53, v53
	v_fmac_f32_e32 v90, v54, v54
	v_fmac_f32_e32 v92, v55, v55
	v_fmac_f32_e32 v90, v56, v56
	v_fmac_f32_e32 v92, v57, v57
	v_add_f32_e32 v9, v9, v91
	v_add_f32_e32 v90, v90, v92
	ds_bpermute_b32 v91, v3, v9
	ds_bpermute_b32 v92, v3, v90
	s_waitcnt lgkmcnt(0)
	v_add_f32_e32 v9, v9, v91
	v_add_f32_e32 v90, v90, v92
	ds_bpermute_b32 v91, v4, v9
	ds_bpermute_b32 v92, v4, v90
	s_waitcnt lgkmcnt(0)
; DI void ln_row_v(const Frame& F, f32x4 (&v)[4], float* xout, const float* g, const float* b, const float* sh, const float* sc, bf16_t* hout, const float* slab, const float* gres, float* stat = nullptr) {
;     ...
;     if (g) {
;         float s = 0.f, s2 = 0.f;
; #pragma unroll
;         for (int j = 0; j < 4; ++j) { s += (v[j][0] + v[j][1]) + (v[j][2] + v[j][3]); s2 += (v[j][0] * v[j][0] + v[j][1] * v[j][1]) + (v[j][2] * v[j][2] + v[j][3] * v[j][3]); }
;         wave_sum2(s, s2, F.lane);
;         const float mean = s * (1.f / D); const float rstd = 1.f / sqrtf(fmaxf(s2 * (1.f / D) - mean * mean, 0.f) + EPS);
;         if (stat && F.lane == 0) { f32x2 sv = {mean, rstd}; *(f32x2*)stat = sv; }
; #pragma unroll
;         for (int j = 0; j < 4; ++j) { const f32x4 gg = ((const f32x4*)g)[F.lane + 64 * j], bb = ((const f32x4*)b)[F.lane + 64 * j];
;             v[j] = (v[j] - mean) * rstd * gg + bb; if (xout) ((f32x4*)xout)[F.lane + 64 * j] = v[j]; }
	v_add_f32_e32 v9, v9, v91
	v_add_f32_e32 v90, v90, v92
	ds_bpermute_b32 v91, v5, v9
	ds_bpermute_b32 v92, v5, v90
	s_waitcnt lgkmcnt(0)
	v_add_f32_e32 v9, v9, v91
	v_add_f32_e32 v90, v90, v92
	ds_bpermute_b32 v91, v6, v9
	ds_bpermute_b32 v92, v6, v90
	s_waitcnt lgkmcnt(0)
	v_add_f32_e32 v9, v9, v91
	v_add_f32_e32 v90, v90, v92
	ds_bpermute_b32 v91, v7, v9
	ds_bpermute_b32 v92, v7, v90
	s_waitcnt lgkmcnt(0)
	v_add_f32_e32 v9, v9, v91
	v_add_f32_e32 v90, v90, v92
	ds_bpermute_b32 v91, v8, v9
	ds_bpermute_b32 v92, v8, v90
	s_waitcnt lgkmcnt(0)
	v_add_f32_e32 v9, v9, v91
	v_add_f32_e32 v90, v90, v92
	v_mul_f32_e32 v93, 0x3a800000, v9
	v_mul_f32_e32 v91, 0x3a800000, v90
	v_fma_f32 v91, -v93, v93, v91
	v_max_f32_e32 v91, 0, v91
	v_add_f32_e32 v91, 0x358637bd, v91
	v_rsq_f32_e32 v94, v91
	v_mul_f32_e32 v91, 0.5, v91
	v_mul_f32_e32 v92, v94, v94
	v_fma_f32 v92, -v91, v92, 0.5
	v_fma_f32 v94, v94, v92, v94
	v_sub_f32_e32 v42, v42, v93
	v_sub_f32_e32 v43, v43, v93
	v_sub_f32_e32 v44, v44, v93
	v_sub_f32_e32 v45, v45, v93
	v_sub_f32_e32 v46, v46, v93
	v_sub_f32_e32 v47, v47, v93
	v_sub_f32_e32 v48, v48, v93
	v_sub_f32_e32 v49, v49, v93
	v_sub_f32_e32 v50, v50, v93
	v_sub_f32_e32 v51, v51, v93
	v_sub_f32_e32 v52, v52, v93
	v_sub_f32_e32 v53, v53, v93
	v_sub_f32_e32 v54, v54, v93
	v_sub_f32_e32 v55, v55, v93
	v_sub_f32_e32 v56, v56, v93
	v_sub_f32_e32 v57, v57, v93
	v_mul_f32_e32 v42, v94, v42
	v_mul_f32_e32 v43, v94, v43
	v_mul_f32_e32 v44, v94, v44
	v_mul_f32_e32 v45, v94, v45
	v_mul_f32_e32 v46, v94, v46
	v_mul_f32_e32 v47, v94, v47
	v_mul_f32_e32 v48, v94, v48
	v_mul_f32_e32 v49, v94, v49
	v_mul_f32_e32 v50, v94, v50
	v_mul_f32_e32 v51, v94, v51
	v_mul_f32_e32 v52, v94, v52
	v_mul_f32_e32 v53, v94, v53
	v_mul_f32_e32 v54, v94, v54
	v_mul_f32_e32 v55, v94, v55
	v_mul_f32_e32 v56, v94, v56
	v_mul_f32_e32 v57, v94, v57
	v_fma_f32 v42, v42, v10, v26
	v_fma_f32 v43, v43, v11, v27
	v_fma_f32 v44, v44, v12, v28
	v_fma_f32 v45, v45, v13, v29
	v_fma_f32 v46, v46, v14, v30
	v_fma_f32 v47, v47, v15, v31
	v_fma_f32 v48, v48, v16, v32
	v_fma_f32 v49, v49, v17, v33
	v_fma_f32 v50, v50, v18, v34
	v_fma_f32 v51, v51, v19, v35
	v_fma_f32 v52, v52, v20, v36
	v_fma_f32 v53, v53, v21, v37
	v_fma_f32 v54, v54, v22, v38
	v_fma_f32 v55, v55, v23, v39
	v_fma_f32 v56, v56, v24, v40
	v_fma_f32 v57, v57, v25, v41
	s_mov_b64 s[2:3], s[20:21]
	global_store_dwordx4 v0, v[42:45], s[2:3]
	global_store_dwordx4 v0, v[46:49], s[2:3] offset:1024
	global_store_dwordx4 v0, v[50:53], s[2:3] offset:2048
	global_store_dwordx4 v0, v[54:57], s[2:3] offset:3072
	v_add_f32_e32 v9, v42, v43
	v_add_f32_e32 v91, v44, v45
	v_mul_f32_e32 v90, v42, v42
	v_mul_f32_e32 v92, v43, v43
	v_add_f32_e32 v9, v9, v46
	v_add_f32_e32 v91, v91, v47
	v_add_f32_e32 v9, v9, v48
	v_add_f32_e32 v91, v91, v49
	v_add_f32_e32 v9, v9, v50
	v_add_f32_e32 v91, v91, v51
	v_add_f32_e32 v9, v9, v52
	v_add_f32_e32 v91, v91, v53
	v_add_f32_e32 v9, v9, v54
	v_add_f32_e32 v91, v91, v55
	v_add_f32_e32 v9, v9, v56
	v_add_f32_e32 v91, v91, v57
	v_fmac_f32_e32 v90, v44, v44
	v_fmac_f32_e32 v92, v45, v45
	v_fmac_f32_e32 v90, v46, v46
	v_fmac_f32_e32 v92, v47, v47
	v_fmac_f32_e32 v90, v48, v48
	v_fmac_f32_e32 v92, v49, v49
	v_fmac_f32_e32 v90, v50, v50
	v_fmac_f32_e32 v92, v51, v51
	v_fmac_f32_e32 v90, v52, v52
	v_fmac_f32_e32 v92, v53, v53
	v_fmac_f32_e32 v90, v54, v54
	v_fmac_f32_e32 v92, v55, v55
	v_fmac_f32_e32 v90, v56, v56
	v_fmac_f32_e32 v92, v57, v57
	v_add_f32_e32 v9, v9, v91
	v_add_f32_e32 v90, v90, v92
	ds_bpermute_b32 v91, v3, v9
	ds_bpermute_b32 v92, v3, v90
	s_waitcnt lgkmcnt(0)
; DI unsigned pk2(float lo, float hi) { f32x2 v = {lo, hi}; bf16x2_t b = __builtin_convertvector(v, bf16x2_t); return __builtin_bit_cast(unsigned, b); }
; DI void ln_row_v(const Frame& F, f32x4 (&v)[4], float* xout, const float* g, const float* b, const float* sh, const float* sc, bf16_t* hout, const float* slab, const float* gres, float* stat = nullptr) {
;     ...
;     if (hout) {
;         float s = 0.f, s2 = 0.f;
; #pragma unroll
;         for (int j = 0; j < 4; ++j) { s += (v[j][0] + v[j][1]) + (v[j][2] + v[j][3]); s2 += (v[j][0] * v[j][0] + v[j][1] * v[j][1]) + (v[j][2] * v[j][2] + v[j][3] * v[j][3]); }
;         wave_sum2(s, s2, F.lane);
;         const float mean = s * (1.f / D); const float rstd = 1.f / sqrtf(fmaxf(s2 * (1.f / D) - mean * mean, 0.f) + EPS);
; #pragma unroll
;         for (int j = 0; j < 4; ++j) { const f32x4 hh = ((const f32x4*)sh)[F.lane + 64 * j], cc = ((const f32x4*)sc)[F.lane + 64 * j];
;             const f32x4 o = (v[j] - mean) * rstd * (cc + 1.f) + hh; u32x2 wv; wv.x = pk2(o[0], o[1]); wv.y = pk2(o[2], o[3]);
;             ((u32x2*)hout)[F.lane + 64 * j] = wv; }
;     }
	v_add_f32_e32 v9, v9, v91
	v_add_f32_e32 v90, v90, v92
	ds_bpermute_b32 v91, v4, v9
	ds_bpermute_b32 v92, v4, v90
	s_waitcnt lgkmcnt(0)
	v_add_f32_e32 v9, v9, v91
	v_add_f32_e32 v90, v90, v92
	ds_bpermute_b32 v91, v5, v9
	ds_bpermute_b32 v92, v5, v90
	s_waitcnt lgkmcnt(0)
	v_add_f32_e32 v9, v9, v91
	v_add_f32_e32 v90, v90, v92
	ds_bpermute_b32 v91, v6, v9
	ds_bpermute_b32 v92, v6, v90
	s_waitcnt lgkmcnt(0)
	v_add_f32_e32 v9, v9, v91
	v_add_f32_e32 v90, v90, v92
	ds_bpermute_b32 v91, v7, v9
	ds_bpermute_b32 v92, v7, v90
	s_waitcnt lgkmcnt(0)
	v_add_f32_e32 v9, v9, v91
	v_add_f32_e32 v90, v90, v92
	ds_bpermute_b32 v91, v8, v9
	ds_bpermute_b32 v92, v8, v90
	s_waitcnt lgkmcnt(0)
	v_add_f32_e32 v9, v9, v91
	v_add_f32_e32 v90, v90, v92
	v_mul_f32_e32 v93, 0x3a800000, v9
	v_mul_f32_e32 v91, 0x3a800000, v90
	v_fma_f32 v91, -v93, v93, v91
	v_max_f32_e32 v91, 0, v91
	v_add_f32_e32 v91, 0x358637bd, v91
	v_rsq_f32_e32 v94, v91
	v_mul_f32_e32 v91, 0.5, v91
	v_mul_f32_e32 v92, v94, v94
	v_fma_f32 v92, -v91, v92, 0.5
	v_fma_f32 v94, v94, v92, v94
	v_sub_f32_e32 v42, v42, v93
	v_sub_f32_e32 v43, v43, v93
	v_sub_f32_e32 v44, v44, v93
	v_sub_f32_e32 v45, v45, v93
	v_sub_f32_e32 v46, v46, v93
	v_sub_f32_e32 v47, v47, v93
	v_sub_f32_e32 v48, v48, v93
	v_sub_f32_e32 v49, v49, v93
	v_sub_f32_e32 v50, v50, v93
	v_sub_f32_e32 v51, v51, v93
	v_sub_f32_e32 v52, v52, v93
	v_sub_f32_e32 v53, v53, v93
	v_sub_f32_e32 v54, v54, v93
	v_sub_f32_e32 v55, v55, v93
	v_sub_f32_e32 v56, v56, v93
	v_sub_f32_e32 v57, v57, v93
	v_add_f32_e32 v130, 1.0, v130
	v_add_f32_e32 v131, 1.0, v131
	v_add_f32_e32 v132, 1.0, v132
	v_add_f32_e32 v133, 1.0, v133
	v_add_f32_e32 v134, 1.0, v134
	v_add_f32_e32 v135, 1.0, v135
	v_add_f32_e32 v136, 1.0, v136
	v_add_f32_e32 v137, 1.0, v137
	v_add_f32_e32 v138, 1.0, v138
	v_add_f32_e32 v139, 1.0, v139
	v_add_f32_e32 v140, 1.0, v140
	v_add_f32_e32 v141, 1.0, v141
	v_add_f32_e32 v142, 1.0, v142
	v_add_f32_e32 v143, 1.0, v143
	v_add_f32_e32 v144, 1.0, v144
	v_add_f32_e32 v145, 1.0, v145
	v_mul_f32_e32 v42, v94, v42
	v_mul_f32_e32 v43, v94, v43
	v_mul_f32_e32 v44, v94, v44
	v_mul_f32_e32 v45, v94, v45
	v_mul_f32_e32 v46, v94, v46
	v_mul_f32_e32 v47, v94, v47
	v_mul_f32_e32 v48, v94, v48
	v_mul_f32_e32 v49, v94, v49
	v_mul_f32_e32 v50, v94, v50
	v_mul_f32_e32 v51, v94, v51
	v_mul_f32_e32 v52, v94, v52
	v_mul_f32_e32 v53, v94, v53
	v_mul_f32_e32 v54, v94, v54
	v_mul_f32_e32 v55, v94, v55
	v_mul_f32_e32 v56, v94, v56
	v_mul_f32_e32 v57, v94, v57
	v_fma_f32 v42, v42, v130, v114
	v_fma_f32 v43, v43, v131, v115
	v_fma_f32 v44, v44, v132, v116
	v_fma_f32 v45, v45, v133, v117
	v_fma_f32 v46, v46, v134, v118
	v_fma_f32 v47, v47, v135, v119
	v_fma_f32 v48, v48, v136, v120
	v_fma_f32 v49, v49, v137, v121
	v_fma_f32 v50, v50, v138, v122
	v_fma_f32 v51, v51, v139, v123
	v_fma_f32 v52, v52, v140, v124
	v_fma_f32 v53, v53, v141, v125
	v_fma_f32 v54, v54, v142, v126
	v_fma_f32 v55, v55, v143, v127
	v_fma_f32 v56, v56, v144, v128
	v_fma_f32 v57, v57, v145, v129
	v_cvt_pk_bf16_f32 v190, v42, v43
	v_cvt_pk_bf16_f32 v191, v44, v45
	v_cvt_pk_bf16_f32 v192, v46, v47
	v_cvt_pk_bf16_f32 v193, v48, v49
	v_cvt_pk_bf16_f32 v194, v50, v51
	v_cvt_pk_bf16_f32 v195, v52, v53
	v_cvt_pk_bf16_f32 v196, v54, v55
	v_cvt_pk_bf16_f32 v197, v56, v57
	s_add_u32 s2, s10, 0x2000000
	s_addc_u32 s3, s11, 0
	global_store_dwordx2 v1, v[190:191], s[2:3]
	global_store_dwordx2 v1, v[192:193], s[2:3] offset:512
	global_store_dwordx2 v1, v[194:195], s[2:3] offset:1024
	global_store_dwordx2 v1, v[196:197], s[2:3] offset:1536
.Lln_b_noctx:
	s_waitcnt vmcnt(0)
	s_branch .Lln_b_done

; DI const float* modp(const Frame& F, int l, int mr, int which) { return (const float*)(F.ws + WS_MOD) + ((size_t)(l * 9 + mr) * 6 + which) * 1024; }
; DI void ln_phase(const Frame& F, int which) {
;     const int gw = F.vcu * 8 + F.wave, NGW = F.G * 8; const int l = F.l;
;     const int nrows = (l == NL - 1) ? ML : MT;
;     bf16_t* H = (bf16_t*)(F.ws + WS_HB);
;     const float* g = pin(F, which == 0 ? I_LN1G : I_LN2G) + l * 1024; const float* b = pin(F, which == 0 ? I_LN1B : I_LN2B) + l * 1024;
;     const bool wh = !(which == 1 && l == NL - 1);
;     f32x4 vc[4], vn[4];
;     if (gw < nrows) ln_load(F, xrow_ptr(F, gw), vc);
;     for (int row = gw; row < nrows; row += NGW) {
;         if (row + NGW < nrows) ln_load(F, xrow_ptr(F, row + NGW), vn);
;         const int mr = row < ML ? (row >> 11) : 8;
;         const float* sh = which == 0 ? modp(F, l, mr, 3) : modp(F, l + 1 < NL ? l + 1 : l, mr, 0);
;         const float* sc = which == 0 ? modp(F, l, mr, 4) : modp(F, l + 1 < NL ? l + 1 : l, mr, 1);
;         const bool sl = (which == 1 && row >= ML);
;         const bool st_only = row < ML && !(which == 1 && l == NL - 1);
.Lln_b_done:
	s_add_i32 s16, s16, 0x4800
	s_add_i32 s2, s70, 0xffe5
	s_and_b32 s2, s2, 0xff
	s_cmp_gt_u32 s2, 8
	s_cselect_b64 s[8:9], -1, 0
	s_cmp_lt_u32 s2, 9
	s_cselect_b64 s[12:13], -1, 0
	s_and_b64 s[2:3], s[12:13], exec
	s_movk_i32 s2, 0x4800
	s_cselect_b32 s28, 0x4000, s2
	s_cmp_ge_u32 s16, s28
	s_cbranch_scc1 .LBB0_536
	s_lshl_b64 s[2:3], s[44:45], 3
	s_add_u32 s2, s62, s2
	s_addc_u32 s3, s63, s3
	s_load_dwordx4 s[4:7], s[2:3], 0xb8
	v_readlane_b32 s18, v255, 35
	s_lshl_b32 s2, s18, 12
	v_mov_b32_e32 v0, s16
	v_sub_co_u32_e32 v1, vcc, s16, v217
	s_waitcnt lgkmcnt(0)
	s_add_u32 s10, s6, s2
	s_addc_u32 s11, s7, 0
	s_add_u32 s14, s4, s2
	s_addc_u32 s15, s5, 0
	s_add_u32 s29, s94, 0x3600000
	s_addc_u32 s30, s95, 0
	v_readlane_b32 s20, v255, 17
	v_cndmask_b32_e32 v0, v1, v0, vcc
	v_mov_b32_e32 v1, v97
	s_and_b64 s[2:3], vcc, exec
	v_readlane_b32 s21, v255, 18
	s_cselect_b32 s3, s21, s30
	s_cselect_b32 s2, s20, s29
	v_lshlrev_b64 v[0:1], 12, v[0:1]
	v_lshl_add_u64 v[0:1], s[2:3], 0, v[0:1]
	v_lshlrev_b32_e32 v12, 4, v186
	v_readfirstlane_b32 s2, v0
	v_readfirstlane_b32 s3, v1
	s_nop 4
	global_load_dwordx4 v[16:19], v12, s[2:3]
	global_load_dwordx4 v[8:11], v12, s[2:3] offset:1024
	global_load_dwordx4 v[4:7], v12, s[2:3] offset:2048
	global_load_dwordx4 v[0:3], v12, s[2:3] offset:3072
	v_readlane_b32 s2, v255, 34
	s_cmp_lt_u32 s2, 27
	s_cselect_b64 s[2:3], -1, 0
	s_cmp_lg_u64 s[2:3], 0
	v_mov_b32_e32 v13, v97
	s_addc_u32 s31, s18, 0
	s_cmp_lg_u64 s[4:5], 0
	v_lshl_add_u64 v[32:33], s[14:15], 0, v[12:13]
	v_lshl_add_u64 v[34:35], s[10:11], 0, v[12:13]
	v_lshl_add_u64 v[12:13], s[94:95], 0, v[12:13]
	s_mov_b64 s[4:5], 0x9100000
	v_lshl_add_u64 v[36:37], v[12:13], 0, s[4:5]
	s_mov_b64 s[4:5], 0x105000
	v_lshl_add_u64 v[38:39], v[12:13], 0, s[4:5]
	s_mov_b64 s[4:5], 0x100000
	v_lshl_add_u64 v[40:41], v[12:13], 0, s[4:5]
	s_mov_b64 s[4:5], 0x101000
	s_cselect_b64 s[6:7], -1, 0
	v_lshl_add_u64 v[42:43], v[12:13], 0, s[4:5]
	s_lshl_b32 s34, s93, 3
	s_lshl_b32 s4, s16, 3
	s_add_u32 s4, s4, s44
	s_addc_u32 s5, 0, s45
	v_readlane_b32 s10, v255, 16
	s_add_u32 s14, s10, s4
	v_readlane_b32 s4, v255, 21
	s_addc_u32 s15, s4, s5
	s_lshl_b32 s35, s93, 6
	s_lshl_b64 s[4:5], s[16:17], 11
	v_readlane_b32 s10, v255, 6
	s_add_u32 s10, s10, s44
	v_readlane_b32 s11, v255, 7
	s_addc_u32 s11, s11, s45
	s_add_u32 s4, s10, s4
	v_lshlrev_b32_e32 v12, 3, v186
	v_mov_b32_e32 v13, v97
	s_addc_u32 s5, s11, s5
	v_lshlrev_b32_e32 v14, 2, v186
	v_lshl_add_u64 v[44:45], s[4:5], 0, v[12:13]
	v_mov_b32_e32 v12, 0
	s_mul_i32 s31, s31, 9
	v_xor_b32_e32 v52, 4, v14
	v_xor_b32_e32 v53, 8, v14
	v_xor_b32_e32 v54, 16, v14
	v_xor_b32_e32 v55, 32, v14
	v_xor_b32_e32 v56, 64, v14
	v_xor_b32_e32 v57, 0x80, v14
	v_cmp_ne_u32_e64 s[2:3], 0, v186
	s_lshl_b32 s18, s93, 14
	s_mov_b32 s19, s17
	s_mov_b64 s[4:5], s[16:17]
	v_mov_b32_e32 v13, v12
	v_mov_b32_e32 v14, v12
	v_mov_b32_e32 v15, v12
	v_mov_b32_e32 v20, v12
	v_mov_b32_e32 v21, v12
	v_mov_b32_e32 v22, v12
	v_mov_b32_e32 v23, v12
	v_mov_b32_e32 v24, v12
	v_mov_b32_e32 v25, v12
	v_mov_b32_e32 v26, v12
	v_mov_b32_e32 v27, v12
	v_mov_b32_e32 v28, v12
	v_mov_b32_e32 v29, v12
	v_mov_b32_e32 v30, v12
	v_mov_b32_e32 v31, v12
	v_readlane_b32 s22, v255, 19
	v_readlane_b32 s23, v255, 20
	s_branch .LBB0_517

; DI const float* modp(const Frame& F, int l, int mr, int which) { return (const float*)(F.ws + WS_MOD) + ((size_t)(l * 9 + mr) * 6 + which) * 1024; }
; DI void ln_row_v(const Frame& F, f32x4 (&v)[4], float* xout, const float* g, const float* b, const float* sh, const float* sc, bf16_t* hout, const float* slab, const float* gres, float* stat = nullptr) {
;     ...
;     if (hout) {
;         float s = 0.f, s2 = 0.f;
; #pragma unroll
;         for (int j = 0; j < 4; ++j) { s += (v[j][0] + v[j][1]) + (v[j][2] + v[j][3]); s2 += (v[j][0] * v[j][0] + v[j][1] * v[j][1]) + (v[j][2] * v[j][2] + v[j][3] * v[j][3]); }
;         wave_sum2(s, s2, F.lane);
;         const float mean = s * (1.f / D); const float rstd = 1.f / sqrtf(fmaxf(s2 * (1.f / D) - mean * mean, 0.f) + EPS);
; DI void prologue_b(const Frame& F) {
;     const int gw = F.vcu * 8 + F.wave, NGW = F.G * 8;
;     bf16_t* H = (bf16_t*)(F.ws + WS_HB);
;     for (int row = gw; row < MT; row += NGW) {
;         const int mr = row < ML ? (row >> 11) : 8;
;         const float* xi = row < ML ? pin(F, I_X) + (size_t)row * D : pin(F, I_CTX) + (size_t)(row - ML) * D;
;         ln_row(F, xi, nullptr, nullptr, nullptr, modp(F, 0, mr, 0), modp(F, 0, mr, 1), H + (size_t)row * D);
.LBB0_663:
	s_and_b64 vcc, exec, s[2:3]
	s_cbranch_vccz .LBB0_671
	v_readlane_b32 s2, v255, 29
	s_lshl_b32 s2, s2, 3
	v_readlane_b32 s3, v255, 31
	s_add_i32 s16, s3, s2
	v_lshlrev_b32_e32 v0, 4, v186
	v_lshlrev_b32_e32 v1, 3, v186
	v_lshlrev_b32_e32 v96, 2, v186
	v_xor_b32_e32 v3, 4, v96
	v_xor_b32_e32 v4, 8, v96
	v_xor_b32_e32 v5, 16, v96
	v_xor_b32_e32 v6, 32, v96
	v_xor_b32_e32 v7, 64, v96
	v_xor_b32_e32 v8, 128, v96
	s_load_dwordx2 s[8:9], s[62:63], 0x0
	s_load_dwordx2 s[20:21], s[62:63], 0x10
	s_mov_b32 s22, 0
	s_lshl_b32 s2, s16, 12
	s_waitcnt lgkmcnt(0)
	s_add_u32 s8, s8, s2
	s_addc_u32 s9, s9, 0
	s_add_u32 s20, s20, s2
	s_addc_u32 s21, s21, 0
	s_lshl_b32 s2, s16, 11
	s_add_u32 s10, s94, s2
	s_addc_u32 s11, s95, 0
	s_add_u32 s10, s10, 0x3e00000
	s_addc_u32 s11, s11, 0
	s_lshl_b32 s2, s16, 3
	s_add_u32 s12, s94, s2
	s_addc_u32 s13, s95, 0
	s_add_u32 s12, s12, 0x4c0000
	s_addc_u32 s13, s13, 0
	s_mov_b32 s3, 0
	s_mul_i32 s3, s3, 0x36000
	s_add_u32 s14, s94, s3
	s_addc_u32 s15, s95, 0
	s_add_u32 s14, s14, 0x100000
	s_addc_u32 s15, s15, 0
	s_add_u32 s18, s14, 0x1000
	s_addc_u32 s19, s15, 0
	s_add_u32 s2, s8, 0x0
	s_addc_u32 s3, s9, 0
	global_load_dwordx4 v[42:45], v0, s[2:3]
	global_load_dwordx4 v[46:49], v0, s[2:3] offset:1024
	global_load_dwordx4 v[50:53], v0, s[2:3] offset:2048
	global_load_dwordx4 v[54:57], v0, s[2:3] offset:3072
	s_add_u32 s2, s14, 0x0
	s_addc_u32 s3, s15, 0
	global_load_dwordx4 v[114:117], v0, s[2:3]
	global_load_dwordx4 v[118:121], v0, s[2:3] offset:1024
	global_load_dwordx4 v[122:125], v0, s[2:3] offset:2048
	global_load_dwordx4 v[126:129], v0, s[2:3] offset:3072
	s_add_u32 s2, s18, 0x0
	s_addc_u32 s3, s19, 0
	global_load_dwordx4 v[130:133], v0, s[2:3]
	global_load_dwordx4 v[134:137], v0, s[2:3] offset:1024
	global_load_dwordx4 v[138:141], v0, s[2:3] offset:2048
	global_load_dwordx4 v[142:145], v0, s[2:3] offset:3072
	s_add_u32 s2, s8, 0x800000
	s_addc_u32 s3, s9, 0
	global_load_dwordx4 v[58:61], v0, s[2:3]
	global_load_dwordx4 v[62:65], v0, s[2:3] offset:1024
	global_load_dwordx4 v[66:69], v0, s[2:3] offset:2048
	global_load_dwordx4 v[70:73], v0, s[2:3] offset:3072
	s_add_u32 s2, s14, 0x6000
	s_addc_u32 s3, s15, 0
	global_load_dwordx4 v[146:149], v0, s[2:3]
	global_load_dwordx4 v[150:153], v0, s[2:3] offset:1024
	global_load_dwordx4 v[154:157], v0, s[2:3] offset:2048
	global_load_dwordx4 v[158:161], v0, s[2:3] offset:3072
	s_add_u32 s2, s18, 0x6000
	s_addc_u32 s3, s19, 0
	global_load_dwordx4 v[162:165], v0, s[2:3]
	global_load_dwordx4 v[166:169], v0, s[2:3] offset:1024
	global_load_dwordx4 v[170:173], v0, s[2:3] offset:2048
	global_load_dwordx4 v[174:177], v0, s[2:3] offset:3072
	s_add_u32 s2, s8, 0x1000000
	s_addc_u32 s3, s9, 0
	global_load_dwordx4 v[74:77], v0, s[2:3]
	global_load_dwordx4 v[78:81], v0, s[2:3] offset:1024
	global_load_dwordx4 v[82:85], v0, s[2:3] offset:2048
	global_load_dwordx4 v[86:89], v0, s[2:3] offset:3072
	s_add_u32 s2, s8, 0x1800000
	s_addc_u32 s3, s9, 0
	global_load_dwordx4 v[98:101], v0, s[2:3]
	global_load_dwordx4 v[102:105], v0, s[2:3] offset:1024
	global_load_dwordx4 v[106:109], v0, s[2:3] offset:2048
	global_load_dwordx4 v[110:113], v0, s[2:3] offset:3072
	s_waitcnt vmcnt(28)
	v_add_f32_e32 v9, v42, v43
	v_add_f32_e32 v91, v44, v45
	v_mul_f32_e32 v90, v42, v42
	v_mul_f32_e32 v92, v43, v43
	v_add_f32_e32 v9, v9, v46
	v_add_f32_e32 v91, v91, v47
	v_add_f32_e32 v9, v9, v48
	v_add_f32_e32 v91, v91, v49
	v_add_f32_e32 v9, v9, v50
	v_add_f32_e32 v91, v91, v51
	v_add_f32_e32 v9, v9, v52
	v_add_f32_e32 v91, v91, v53
	v_add_f32_e32 v9, v9, v54
	v_add_f32_e32 v91, v91, v55
	v_add_f32_e32 v9, v9, v56
	v_add_f32_e32 v91, v91, v57
	v_fmac_f32_e32 v90, v44, v44
	v_fmac_f32_e32 v92, v45, v45
	v_fmac_f32_e32 v90, v46, v46
	v_fmac_f32_e32 v92, v47, v47
	v_fmac_f32_e32 v90, v48, v48
	v_fmac_f32_e32 v92, v49, v49
	v_fmac_f32_e32 v90, v50, v50
	v_fmac_f32_e32 v92, v51, v51
	v_fmac_f32_e32 v90, v52, v52
	v_fmac_f32_e32 v92, v53, v53
	v_fmac_f32_e32 v90, v54, v54
	v_fmac_f32_e32 v92, v55, v55
	v_fmac_f32_e32 v90, v56, v56
	v_fmac_f32_e32 v92, v57, v57
	v_add_f32_e32 v9, v9, v91
	v_add_f32_e32 v90, v90, v92
	ds_bpermute_b32 v91, v3, v9
	ds_bpermute_b32 v92, v3, v90
	s_waitcnt lgkmcnt(0)
	v_add_f32_e32 v9, v9, v91
	v_add_f32_e32 v90, v90, v92
	ds_bpermute_b32 v91, v4, v9
	ds_bpermute_b32 v92, v4, v90
	s_waitcnt lgkmcnt(0)
	v_add_f32_e32 v9, v9, v91
	v_add_f32_e32 v90, v90, v92
	ds_bpermute_b32 v91, v5, v9
	ds_bpermute_b32 v92, v5, v90
	s_waitcnt lgkmcnt(0)
	v_add_f32_e32 v9, v9, v91
	v_add_f32_e32 v90, v90, v92
	ds_bpermute_b32 v91, v6, v9
	ds_bpermute_b32 v92, v6, v90
	s_waitcnt lgkmcnt(0)
	v_add_f32_e32 v9, v9, v91
	v_add_f32_e32 v90, v90, v92
	ds_bpermute_b32 v91, v7, v9
	ds_bpermute_b32 v92, v7, v90
	s_waitcnt lgkmcnt(0)
	v_add_f32_e32 v9, v9, v91
	v_add_f32_e32 v90, v90, v92
	ds_bpermute_b32 v91, v8, v9
	ds_bpermute_b32 v92, v8, v90
	s_waitcnt lgkmcnt(0)
	v_add_f32_e32 v9, v9, v91
	v_add_f32_e32 v90, v90, v92
	v_mul_f32_e32 v93, 0x3a800000, v9
	v_mul_f32_e32 v91, 0x3a800000, v90
	v_fma_f32 v91, -v93, v93, v91
	v_max_f32_e32 v91, 0, v91
	v_add_f32_e32 v91, 0x358637bd, v91
	v_rsq_f32_e32 v94, v91
	v_mul_f32_e32 v91, 0.5, v91
	v_mul_f32_e32 v92, v94, v94
	v_fma_f32 v92, -v91, v92, 0.5
	v_fma_f32 v94, v94, v92, v94
	s_waitcnt vmcnt(20)
; DI unsigned pk2(float lo, float hi) { f32x2 v = {lo, hi}; bf16x2_t b = __builtin_convertvector(v, bf16x2_t); return __builtin_bit_cast(unsigned, b); }
; DI const float* modp(const Frame& F, int l, int mr, int which) { return (const float*)(F.ws + WS_MOD) + ((size_t)(l * 9 + mr) * 6 + which) * 1024; }
; DI void ln_row_v(const Frame& F, f32x4 (&v)[4], float* xout, const float* g, const float* b, const float* sh, const float* sc, bf16_t* hout, const float* slab, const float* gres, float* stat = nullptr) {
;     ...
;     if (hout) {
;         float s = 0.f, s2 = 0.f;
; #pragma unroll
;         for (int j = 0; j < 4; ++j) { s += (v[j][0] + v[j][1]) + (v[j][2] + v[j][3]); s2 += (v[j][0] * v[j][0] + v[j][1] * v[j][1]) + (v[j][2] * v[j][2] + v[j][3] * v[j][3]); }
;         wave_sum2(s, s2, F.lane);
;         const float mean = s * (1.f / D); const float rstd = 1.f / sqrtf(fmaxf(s2 * (1.f / D) - mean * mean, 0.f) + EPS);
; #pragma unroll
;         for (int j = 0; j < 4; ++j) { const f32x4 hh = ((const f32x4*)sh)[F.lane + 64 * j], cc = ((const f32x4*)sc)[F.lane + 64 * j];
;             const f32x4 o = (v[j] - mean) * rstd * (cc + 1.f) + hh; u32x2 wv; wv.x = pk2(o[0], o[1]); wv.y = pk2(o[2], o[3]);
;             ((u32x2*)hout)[F.lane + 64 * j] = wv; }
;     }
; DI void prologue_b(const Frame& F) {
;     ...
;     for (int row = gw; row < MT; row += NGW) {
;         const int mr = row < ML ? (row >> 11) : 8;
;         const float* xi = row < ML ? pin(F, I_X) + (size_t)row * D : pin(F, I_CTX) + (size_t)(row - ML) * D;
;         ln_row(F, xi, nullptr, nullptr, nullptr, modp(F, 0, mr, 0), modp(F, 0, mr, 1), H + (size_t)row * D);
	v_sub_f32_e32 v42, v42, v93
	v_sub_f32_e32 v43, v43, v93
	v_sub_f32_e32 v44, v44, v93
	v_sub_f32_e32 v45, v45, v93
	v_sub_f32_e32 v46, v46, v93
	v_sub_f32_e32 v47, v47, v93
	v_sub_f32_e32 v48, v48, v93
	v_sub_f32_e32 v49, v49, v93
	v_sub_f32_e32 v50, v50, v93
	v_sub_f32_e32 v51, v51, v93
	v_sub_f32_e32 v52, v52, v93
	v_sub_f32_e32 v53, v53, v93
	v_sub_f32_e32 v54, v54, v93
	v_sub_f32_e32 v55, v55, v93
	v_sub_f32_e32 v56, v56, v93
	v_sub_f32_e32 v57, v57, v93
	v_add_f32_e32 v130, 1.0, v130
	v_add_f32_e32 v131, 1.0, v131
	v_add_f32_e32 v132, 1.0, v132
	v_add_f32_e32 v133, 1.0, v133
	v_add_f32_e32 v134, 1.0, v134
	v_add_f32_e32 v135, 1.0, v135
	v_add_f32_e32 v136, 1.0, v136
	v_add_f32_e32 v137, 1.0, v137
	v_add_f32_e32 v138, 1.0, v138
	v_add_f32_e32 v139, 1.0, v139
	v_add_f32_e32 v140, 1.0, v140
	v_add_f32_e32 v141, 1.0, v141
	v_add_f32_e32 v142, 1.0, v142
	v_add_f32_e32 v143, 1.0, v143
	v_add_f32_e32 v144, 1.0, v144
	v_add_f32_e32 v145, 1.0, v145
	v_mul_f32_e32 v42, v94, v42
	v_mul_f32_e32 v43, v94, v43
	v_mul_f32_e32 v44, v94, v44
	v_mul_f32_e32 v45, v94, v45
	v_mul_f32_e32 v46, v94, v46
	v_mul_f32_e32 v47, v94, v47
	v_mul_f32_e32 v48, v94, v48
	v_mul_f32_e32 v49, v94, v49
	v_mul_f32_e32 v50, v94, v50
	v_mul_f32_e32 v51, v94, v51
	v_mul_f32_e32 v52, v94, v52
	v_mul_f32_e32 v53, v94, v53
	v_mul_f32_e32 v54, v94, v54
	v_mul_f32_e32 v55, v94, v55
	v_mul_f32_e32 v56, v94, v56
	v_mul_f32_e32 v57, v94, v57
	v_fma_f32 v42, v42, v130, v114
	v_fma_f32 v43, v43, v131, v115
	v_fma_f32 v44, v44, v132, v116
	v_fma_f32 v45, v45, v133, v117
	v_fma_f32 v46, v46, v134, v118
	v_fma_f32 v47, v47, v135, v119
	v_fma_f32 v48, v48, v136, v120
	v_fma_f32 v49, v49, v137, v121
	v_fma_f32 v50, v50, v138, v122
	v_fma_f32 v51, v51, v139, v123
	v_fma_f32 v52, v52, v140, v124
	v_fma_f32 v53, v53, v141, v125
	v_fma_f32 v54, v54, v142, v126
	v_fma_f32 v55, v55, v143, v127
	v_fma_f32 v56, v56, v144, v128
	v_fma_f32 v57, v57, v145, v129
	v_cvt_pk_bf16_f32 v190, v42, v43
	v_cvt_pk_bf16_f32 v191, v44, v45
	v_cvt_pk_bf16_f32 v192, v46, v47
	v_cvt_pk_bf16_f32 v193, v48, v49
	v_cvt_pk_bf16_f32 v194, v50, v51
	v_cvt_pk_bf16_f32 v195, v52, v53
	v_cvt_pk_bf16_f32 v196, v54, v55
	v_cvt_pk_bf16_f32 v197, v56, v57
	s_add_u32 s2, s10, 0x0
	s_addc_u32 s3, s11, 0
	global_store_dwordx2 v1, v[190:191], s[2:3]
	global_store_dwordx2 v1, v[192:193], s[2:3] offset:512
	global_store_dwordx2 v1, v[194:195], s[2:3] offset:1024
	global_store_dwordx2 v1, v[196:197], s[2:3] offset:1536
	s_add_u32 s2, s8, 0x2000000
	s_addc_u32 s3, s9, 0
	global_load_dwordx4 v[42:45], v0, s[2:3]
	global_load_dwordx4 v[46:49], v0, s[2:3] offset:1024
	global_load_dwordx4 v[50:53], v0, s[2:3] offset:2048
	global_load_dwordx4 v[54:57], v0, s[2:3] offset:3072
	s_add_u32 s2, s14, 0xc000
	s_addc_u32 s3, s15, 0
	global_load_dwordx4 v[114:117], v0, s[2:3]
	global_load_dwordx4 v[118:121], v0, s[2:3] offset:1024
	global_load_dwordx4 v[122:125], v0, s[2:3] offset:2048
	global_load_dwordx4 v[126:129], v0, s[2:3] offset:3072
	s_add_u32 s2, s18, 0xc000
	s_addc_u32 s3, s19, 0
	global_load_dwordx4 v[130:133], v0, s[2:3]
	global_load_dwordx4 v[134:137], v0, s[2:3] offset:1024
	global_load_dwordx4 v[138:141], v0, s[2:3] offset:2048
	global_load_dwordx4 v[142:145], v0, s[2:3] offset:3072
	s_waitcnt vmcnt(32)
	v_add_f32_e32 v9, v58, v59
	v_add_f32_e32 v91, v60, v61
	v_mul_f32_e32 v90, v58, v58
	v_mul_f32_e32 v92, v59, v59
	v_add_f32_e32 v9, v9, v62
	v_add_f32_e32 v91, v91, v63
	v_add_f32_e32 v9, v9, v64
	v_add_f32_e32 v91, v91, v65
	v_add_f32_e32 v9, v9, v66
	v_add_f32_e32 v91, v91, v67
	v_add_f32_e32 v9, v9, v68
	v_add_f32_e32 v91, v91, v69
	v_add_f32_e32 v9, v9, v70
	v_add_f32_e32 v91, v91, v71
	v_add_f32_e32 v9, v9, v72
	v_add_f32_e32 v91, v91, v73
	v_fmac_f32_e32 v90, v60, v60
	v_fmac_f32_e32 v92, v61, v61
	v_fmac_f32_e32 v90, v62, v62
	v_fmac_f32_e32 v92, v63, v63
	v_fmac_f32_e32 v90, v64, v64
	v_fmac_f32_e32 v92, v65, v65
	v_fmac_f32_e32 v90, v66, v66
	v_fmac_f32_e32 v92, v67, v67
	v_fmac_f32_e32 v90, v68, v68
	v_fmac_f32_e32 v92, v69, v69
	v_fmac_f32_e32 v90, v70, v70
	v_fmac_f32_e32 v92, v71, v71
	v_fmac_f32_e32 v90, v72, v72
	v_fmac_f32_e32 v92, v73, v73
	v_add_f32_e32 v9, v9, v91
	v_add_f32_e32 v90, v90, v92
	ds_bpermute_b32 v91, v3, v9
	ds_bpermute_b32 v92, v3, v90
	s_waitcnt lgkmcnt(0)
	v_add_f32_e32 v9, v9, v91
	v_add_f32_e32 v90, v90, v92
	ds_bpermute_b32 v91, v4, v9
	ds_bpermute_b32 v92, v4, v90
	s_waitcnt lgkmcnt(0)
	v_add_f32_e32 v9, v9, v91
	v_add_f32_e32 v90, v90, v92
	ds_bpermute_b32 v91, v5, v9
	ds_bpermute_b32 v92, v5, v90
	s_waitcnt lgkmcnt(0)
	v_add_f32_e32 v9, v9, v91
	v_add_f32_e32 v90, v90, v92
	ds_bpermute_b32 v91, v6, v9
	ds_bpermute_b32 v92, v6, v90
	s_waitcnt lgkmcnt(0)
	v_add_f32_e32 v9, v9, v91
	v_add_f32_e32 v90, v90, v92
	ds_bpermute_b32 v91, v7, v9
	ds_bpermute_b32 v92, v7, v90
	s_waitcnt lgkmcnt(0)
	v_add_f32_e32 v9, v9, v91
	v_add_f32_e32 v90, v90, v92
	ds_bpermute_b32 v91, v8, v9
	ds_bpermute_b32 v92, v8, v90
	s_waitcnt lgkmcnt(0)
	v_add_f32_e32 v9, v9, v91
	v_add_f32_e32 v90, v90, v92
	v_mul_f32_e32 v93, 0x3a800000, v9
	v_mul_f32_e32 v91, 0x3a800000, v90
	v_fma_f32 v91, -v93, v93, v91
	v_max_f32_e32 v91, 0, v91
	v_add_f32_e32 v91, 0x358637bd, v91
	v_rsq_f32_e32 v94, v91
	v_mul_f32_e32 v91, 0.5, v91
	v_mul_f32_e32 v92, v94, v94
	v_fma_f32 v92, -v91, v92, 0.5
	v_fma_f32 v94, v94, v92, v94
	s_waitcnt vmcnt(24)
; DI unsigned pk2(float lo, float hi) { f32x2 v = {lo, hi}; bf16x2_t b = __builtin_convertvector(v, bf16x2_t); return __builtin_bit_cast(unsigned, b); }
; DI const float* modp(const Frame& F, int l, int mr, int which) { return (const float*)(F.ws + WS_MOD) + ((size_t)(l * 9 + mr) * 6 + which) * 1024; }
; DI void ln_row_v(const Frame& F, f32x4 (&v)[4], float* xout, const float* g, const float* b, const float* sh, const float* sc, bf16_t* hout, const float* slab, const float* gres, float* stat = nullptr) {
;     ...
;     if (hout) {
;         float s = 0.f, s2 = 0.f;
; #pragma unroll
;         for (int j = 0; j < 4; ++j) { s += (v[j][0] + v[j][1]) + (v[j][2] + v[j][3]); s2 += (v[j][0] * v[j][0] + v[j][1] * v[j][1]) + (v[j][2] * v[j][2] + v[j][3] * v[j][3]); }
;         wave_sum2(s, s2, F.lane);
;         const float mean = s * (1.f / D); const float rstd = 1.f / sqrtf(fmaxf(s2 * (1.f / D) - mean * mean, 0.f) + EPS);
; #pragma unroll
;         for (int j = 0; j < 4; ++j) { const f32x4 hh = ((const f32x4*)sh)[F.lane + 64 * j], cc = ((const f32x4*)sc)[F.lane + 64 * j];
;             const f32x4 o = (v[j] - mean) * rstd * (cc + 1.f) + hh; u32x2 wv; wv.x = pk2(o[0], o[1]); wv.y = pk2(o[2], o[3]);
;             ((u32x2*)hout)[F.lane + 64 * j] = wv; }
;     }
; DI void prologue_b(const Frame& F) {
;     ...
;     for (int row = gw; row < MT; row += NGW) {
;         const int mr = row < ML ? (row >> 11) : 8;
;         const float* xi = row < ML ? pin(F, I_X) + (size_t)row * D : pin(F, I_CTX) + (size_t)(row - ML) * D;
;         ln_row(F, xi, nullptr, nullptr, nullptr, modp(F, 0, mr, 0), modp(F, 0, mr, 1), H + (size_t)row * D);
	v_sub_f32_e32 v58, v58, v93
	v_sub_f32_e32 v59, v59, v93
	v_sub_f32_e32 v60, v60, v93
	v_sub_f32_e32 v61, v61, v93
	v_sub_f32_e32 v62, v62, v93
	v_sub_f32_e32 v63, v63, v93
	v_sub_f32_e32 v64, v64, v93
	v_sub_f32_e32 v65, v65, v93
	v_sub_f32_e32 v66, v66, v93
	v_sub_f32_e32 v67, v67, v93
	v_sub_f32_e32 v68, v68, v93
	v_sub_f32_e32 v69, v69, v93
	v_sub_f32_e32 v70, v70, v93
	v_sub_f32_e32 v71, v71, v93
	v_sub_f32_e32 v72, v72, v93
	v_sub_f32_e32 v73, v73, v93
	v_add_f32_e32 v162, 1.0, v162
	v_add_f32_e32 v163, 1.0, v163
	v_add_f32_e32 v164, 1.0, v164
	v_add_f32_e32 v165, 1.0, v165
	v_add_f32_e32 v166, 1.0, v166
	v_add_f32_e32 v167, 1.0, v167
	v_add_f32_e32 v168, 1.0, v168
	v_add_f32_e32 v169, 1.0, v169
	v_add_f32_e32 v170, 1.0, v170
	v_add_f32_e32 v171, 1.0, v171
	v_add_f32_e32 v172, 1.0, v172
	v_add_f32_e32 v173, 1.0, v173
	v_add_f32_e32 v174, 1.0, v174
	v_add_f32_e32 v175, 1.0, v175
	v_add_f32_e32 v176, 1.0, v176
	v_add_f32_e32 v177, 1.0, v177
	v_mul_f32_e32 v58, v94, v58
	v_mul_f32_e32 v59, v94, v59
	v_mul_f32_e32 v60, v94, v60
	v_mul_f32_e32 v61, v94, v61
	v_mul_f32_e32 v62, v94, v62
	v_mul_f32_e32 v63, v94, v63
	v_mul_f32_e32 v64, v94, v64
	v_mul_f32_e32 v65, v94, v65
	v_mul_f32_e32 v66, v94, v66
	v_mul_f32_e32 v67, v94, v67
	v_mul_f32_e32 v68, v94, v68
	v_mul_f32_e32 v69, v94, v69
	v_mul_f32_e32 v70, v94, v70
	v_mul_f32_e32 v71, v94, v71
	v_mul_f32_e32 v72, v94, v72
	v_mul_f32_e32 v73, v94, v73
	v_fma_f32 v58, v58, v162, v146
	v_fma_f32 v59, v59, v163, v147
	v_fma_f32 v60, v60, v164, v148
	v_fma_f32 v61, v61, v165, v149
	v_fma_f32 v62, v62, v166, v150
	v_fma_f32 v63, v63, v167, v151
	v_fma_f32 v64, v64, v168, v152
	v_fma_f32 v65, v65, v169, v153
	v_fma_f32 v66, v66, v170, v154
	v_fma_f32 v67, v67, v171, v155
	v_fma_f32 v68, v68, v172, v156
	v_fma_f32 v69, v69, v173, v157
	v_fma_f32 v70, v70, v174, v158
	v_fma_f32 v71, v71, v175, v159
	v_fma_f32 v72, v72, v176, v160
	v_fma_f32 v73, v73, v177, v161
	v_cvt_pk_bf16_f32 v190, v58, v59
	v_cvt_pk_bf16_f32 v191, v60, v61
	v_cvt_pk_bf16_f32 v192, v62, v63
	v_cvt_pk_bf16_f32 v193, v64, v65
	v_cvt_pk_bf16_f32 v194, v66, v67
	v_cvt_pk_bf16_f32 v195, v68, v69
	v_cvt_pk_bf16_f32 v196, v70, v71
	v_cvt_pk_bf16_f32 v197, v72, v73
	s_add_u32 s2, s10, 0x400000
	s_addc_u32 s3, s11, 0
	global_store_dwordx2 v1, v[190:191], s[2:3]
	global_store_dwordx2 v1, v[192:193], s[2:3] offset:512
	global_store_dwordx2 v1, v[194:195], s[2:3] offset:1024
	global_store_dwordx2 v1, v[196:197], s[2:3] offset:1536
	s_add_u32 s2, s8, 0x2800000
	s_addc_u32 s3, s9, 0
	global_load_dwordx4 v[58:61], v0, s[2:3]
	global_load_dwordx4 v[62:65], v0, s[2:3] offset:1024
	global_load_dwordx4 v[66:69], v0, s[2:3] offset:2048
	global_load_dwordx4 v[70:73], v0, s[2:3] offset:3072
	s_add_u32 s2, s14, 0x12000
	s_addc_u32 s3, s15, 0
	global_load_dwordx4 v[146:149], v0, s[2:3]
	global_load_dwordx4 v[150:153], v0, s[2:3] offset:1024
	global_load_dwordx4 v[154:157], v0, s[2:3] offset:2048
	global_load_dwordx4 v[158:161], v0, s[2:3] offset:3072
	s_add_u32 s2, s18, 0x12000
	s_addc_u32 s3, s19, 0
	global_load_dwordx4 v[162:165], v0, s[2:3]
	global_load_dwordx4 v[166:169], v0, s[2:3] offset:1024
	global_load_dwordx4 v[170:173], v0, s[2:3] offset:2048
	global_load_dwordx4 v[174:177], v0, s[2:3] offset:3072
	s_waitcnt vmcnt(36)
	v_add_f32_e32 v9, v74, v75
	v_add_f32_e32 v91, v76, v77
	v_mul_f32_e32 v90, v74, v74
	v_mul_f32_e32 v92, v75, v75
	v_add_f32_e32 v9, v9, v78
	v_add_f32_e32 v91, v91, v79
	v_add_f32_e32 v9, v9, v80
	v_add_f32_e32 v91, v91, v81
	v_add_f32_e32 v9, v9, v82
	v_add_f32_e32 v91, v91, v83
	v_add_f32_e32 v9, v9, v84
	v_add_f32_e32 v91, v91, v85
	v_add_f32_e32 v9, v9, v86
	v_add_f32_e32 v91, v91, v87
	v_add_f32_e32 v9, v9, v88
	v_add_f32_e32 v91, v91, v89
	v_fmac_f32_e32 v90, v76, v76
	v_fmac_f32_e32 v92, v77, v77
	v_fmac_f32_e32 v90, v78, v78
	v_fmac_f32_e32 v92, v79, v79
	v_fmac_f32_e32 v90, v80, v80
	v_fmac_f32_e32 v92, v81, v81
	v_fmac_f32_e32 v90, v82, v82
	v_fmac_f32_e32 v92, v83, v83
	v_fmac_f32_e32 v90, v84, v84
	v_fmac_f32_e32 v92, v85, v85
	v_fmac_f32_e32 v90, v86, v86
	v_fmac_f32_e32 v92, v87, v87
	v_fmac_f32_e32 v90, v88, v88
	v_fmac_f32_e32 v92, v89, v89
	v_add_f32_e32 v9, v9, v91
	v_add_f32_e32 v90, v90, v92
	ds_bpermute_b32 v91, v3, v9
	ds_bpermute_b32 v92, v3, v90
	s_waitcnt lgkmcnt(0)
	v_add_f32_e32 v9, v9, v91
	v_add_f32_e32 v90, v90, v92
	ds_bpermute_b32 v91, v4, v9
	ds_bpermute_b32 v92, v4, v90
	s_waitcnt lgkmcnt(0)
	v_add_f32_e32 v9, v9, v91
	v_add_f32_e32 v90, v90, v92
	ds_bpermute_b32 v91, v5, v9
	ds_bpermute_b32 v92, v5, v90
	s_waitcnt lgkmcnt(0)
	v_add_f32_e32 v9, v9, v91
	v_add_f32_e32 v90, v90, v92
	ds_bpermute_b32 v91, v6, v9
	ds_bpermute_b32 v92, v6, v90
	s_waitcnt lgkmcnt(0)
	v_add_f32_e32 v9, v9, v91
	v_add_f32_e32 v90, v90, v92
	ds_bpermute_b32 v91, v7, v9
	ds_bpermute_b32 v92, v7, v90
	s_waitcnt lgkmcnt(0)
	v_add_f32_e32 v9, v9, v91
	v_add_f32_e32 v90, v90, v92
	ds_bpermute_b32 v91, v8, v9
	ds_bpermute_b32 v92, v8, v90
	s_waitcnt lgkmcnt(0)
	v_add_f32_e32 v9, v9, v91
	v_add_f32_e32 v90, v90, v92
	v_mul_f32_e32 v93, 0x3a800000, v9
	v_mul_f32_e32 v91, 0x3a800000, v90
	v_fma_f32 v91, -v93, v93, v91
	v_max_f32_e32 v91, 0, v91
	v_add_f32_e32 v91, 0x358637bd, v91
	v_rsq_f32_e32 v94, v91
	v_mul_f32_e32 v91, 0.5, v91
	v_mul_f32_e32 v92, v94, v94
	v_fma_f32 v92, -v91, v92, 0.5
	v_fma_f32 v94, v94, v92, v94
	s_waitcnt vmcnt(16)
; DI unsigned pk2(float lo, float hi) { f32x2 v = {lo, hi}; bf16x2_t b = __builtin_convertvector(v, bf16x2_t); return __builtin_bit_cast(unsigned, b); }
; DI const float* modp(const Frame& F, int l, int mr, int which) { return (const float*)(F.ws + WS_MOD) + ((size_t)(l * 9 + mr) * 6 + which) * 1024; }
; DI void ln_row_v(const Frame& F, f32x4 (&v)[4], float* xout, const float* g, const float* b, const float* sh, const float* sc, bf16_t* hout, const float* slab, const float* gres, float* stat = nullptr) {
;     ...
;     if (hout) {
;         float s = 0.f, s2 = 0.f;
; #pragma unroll
;         for (int j = 0; j < 4; ++j) { s += (v[j][0] + v[j][1]) + (v[j][2] + v[j][3]); s2 += (v[j][0] * v[j][0] + v[j][1] * v[j][1]) + (v[j][2] * v[j][2] + v[j][3] * v[j][3]); }
;         wave_sum2(s, s2, F.lane);
;         const float mean = s * (1.f / D); const float rstd = 1.f / sqrtf(fmaxf(s2 * (1.f / D) - mean * mean, 0.f) + EPS);
; #pragma unroll
;         for (int j = 0; j < 4; ++j) { const f32x4 hh = ((const f32x4*)sh)[F.lane + 64 * j], cc = ((const f32x4*)sc)[F.lane + 64 * j];
;             const f32x4 o = (v[j] - mean) * rstd * (cc + 1.f) + hh; u32x2 wv; wv.x = pk2(o[0], o[1]); wv.y = pk2(o[2], o[3]);
;             ((u32x2*)hout)[F.lane + 64 * j] = wv; }
;     }
; DI void prologue_b(const Frame& F) {
;     ...
;     for (int row = gw; row < MT; row += NGW) {
;         const int mr = row < ML ? (row >> 11) : 8;
;         const float* xi = row < ML ? pin(F, I_X) + (size_t)row * D : pin(F, I_CTX) + (size_t)(row - ML) * D;
;         ln_row(F, xi, nullptr, nullptr, nullptr, modp(F, 0, mr, 0), modp(F, 0, mr, 1), H + (size_t)row * D);
	v_sub_f32_e32 v74, v74, v93
	v_sub_f32_e32 v75, v75, v93
	v_sub_f32_e32 v76, v76, v93
	v_sub_f32_e32 v77, v77, v93
	v_sub_f32_e32 v78, v78, v93
	v_sub_f32_e32 v79, v79, v93
	v_sub_f32_e32 v80, v80, v93
	v_sub_f32_e32 v81, v81, v93
	v_sub_f32_e32 v82, v82, v93
	v_sub_f32_e32 v83, v83, v93
	v_sub_f32_e32 v84, v84, v93
	v_sub_f32_e32 v85, v85, v93
	v_sub_f32_e32 v86, v86, v93
	v_sub_f32_e32 v87, v87, v93
	v_sub_f32_e32 v88, v88, v93
	v_sub_f32_e32 v89, v89, v93
	v_add_f32_e32 v130, 1.0, v130
	v_add_f32_e32 v131, 1.0, v131
	v_add_f32_e32 v132, 1.0, v132
	v_add_f32_e32 v133, 1.0, v133
	v_add_f32_e32 v134, 1.0, v134
	v_add_f32_e32 v135, 1.0, v135
	v_add_f32_e32 v136, 1.0, v136
	v_add_f32_e32 v137, 1.0, v137
	v_add_f32_e32 v138, 1.0, v138
	v_add_f32_e32 v139, 1.0, v139
	v_add_f32_e32 v140, 1.0, v140
	v_add_f32_e32 v141, 1.0, v141
	v_add_f32_e32 v142, 1.0, v142
	v_add_f32_e32 v143, 1.0, v143
	v_add_f32_e32 v144, 1.0, v144
	v_add_f32_e32 v145, 1.0, v145
	v_mul_f32_e32 v74, v94, v74
	v_mul_f32_e32 v75, v94, v75
	v_mul_f32_e32 v76, v94, v76
	v_mul_f32_e32 v77, v94, v77
	v_mul_f32_e32 v78, v94, v78
	v_mul_f32_e32 v79, v94, v79
	v_mul_f32_e32 v80, v94, v80
	v_mul_f32_e32 v81, v94, v81
	v_mul_f32_e32 v82, v94, v82
	v_mul_f32_e32 v83, v94, v83
	v_mul_f32_e32 v84, v94, v84
	v_mul_f32_e32 v85, v94, v85
	v_mul_f32_e32 v86, v94, v86
	v_mul_f32_e32 v87, v94, v87
	v_mul_f32_e32 v88, v94, v88
	v_mul_f32_e32 v89, v94, v89
	v_fma_f32 v74, v74, v130, v114
	v_fma_f32 v75, v75, v131, v115
	v_fma_f32 v76, v76, v132, v116
	v_fma_f32 v77, v77, v133, v117
	v_fma_f32 v78, v78, v134, v118
	v_fma_f32 v79, v79, v135, v119
	v_fma_f32 v80, v80, v136, v120
	v_fma_f32 v81, v81, v137, v121
	v_fma_f32 v82, v82, v138, v122
	v_fma_f32 v83, v83, v139, v123
	v_fma_f32 v84, v84, v140, v124
	v_fma_f32 v85, v85, v141, v125
	v_fma_f32 v86, v86, v142, v126
	v_fma_f32 v87, v87, v143, v127
	v_fma_f32 v88, v88, v144, v128
	v_fma_f32 v89, v89, v145, v129
	v_cvt_pk_bf16_f32 v190, v74, v75
	v_cvt_pk_bf16_f32 v191, v76, v77
	v_cvt_pk_bf16_f32 v192, v78, v79
	v_cvt_pk_bf16_f32 v193, v80, v81
	v_cvt_pk_bf16_f32 v194, v82, v83
	v_cvt_pk_bf16_f32 v195, v84, v85
	v_cvt_pk_bf16_f32 v196, v86, v87
	v_cvt_pk_bf16_f32 v197, v88, v89
	s_add_u32 s2, s10, 0x800000
	s_addc_u32 s3, s11, 0
	global_store_dwordx2 v1, v[190:191], s[2:3]
	global_store_dwordx2 v1, v[192:193], s[2:3] offset:512
	global_store_dwordx2 v1, v[194:195], s[2:3] offset:1024
	global_store_dwordx2 v1, v[196:197], s[2:3] offset:1536
	s_add_u32 s2, s8, 0x3000000
	s_addc_u32 s3, s9, 0
	global_load_dwordx4 v[74:77], v0, s[2:3]
	global_load_dwordx4 v[78:81], v0, s[2:3] offset:1024
	global_load_dwordx4 v[82:85], v0, s[2:3] offset:2048
	global_load_dwordx4 v[86:89], v0, s[2:3] offset:3072
	s_add_u32 s2, s14, 0x18000
	s_addc_u32 s3, s15, 0
	global_load_dwordx4 v[114:117], v0, s[2:3]
	global_load_dwordx4 v[118:121], v0, s[2:3] offset:1024
	global_load_dwordx4 v[122:125], v0, s[2:3] offset:2048
	global_load_dwordx4 v[126:129], v0, s[2:3] offset:3072
	s_add_u32 s2, s18, 0x18000
	s_addc_u32 s3, s19, 0
	global_load_dwordx4 v[130:133], v0, s[2:3]
	global_load_dwordx4 v[134:137], v0, s[2:3] offset:1024
	global_load_dwordx4 v[138:141], v0, s[2:3] offset:2048
	global_load_dwordx4 v[142:145], v0, s[2:3] offset:3072
	v_add_f32_e32 v9, v98, v99
	v_add_f32_e32 v91, v100, v101
	v_mul_f32_e32 v90, v98, v98
	v_mul_f32_e32 v92, v99, v99
	v_add_f32_e32 v9, v9, v102
	v_add_f32_e32 v91, v91, v103
	v_add_f32_e32 v9, v9, v104
	v_add_f32_e32 v91, v91, v105
	v_add_f32_e32 v9, v9, v106
	v_add_f32_e32 v91, v91, v107
	v_add_f32_e32 v9, v9, v108
	v_add_f32_e32 v91, v91, v109
	v_add_f32_e32 v9, v9, v110
	v_add_f32_e32 v91, v91, v111
	v_add_f32_e32 v9, v9, v112
	v_add_f32_e32 v91, v91, v113
	v_fmac_f32_e32 v90, v100, v100
	v_fmac_f32_e32 v92, v101, v101
	v_fmac_f32_e32 v90, v102, v102
	v_fmac_f32_e32 v92, v103, v103
	v_fmac_f32_e32 v90, v104, v104
	v_fmac_f32_e32 v92, v105, v105
	v_fmac_f32_e32 v90, v106, v106
	v_fmac_f32_e32 v92, v107, v107
	v_fmac_f32_e32 v90, v108, v108
	v_fmac_f32_e32 v92, v109, v109
	v_fmac_f32_e32 v90, v110, v110
	v_fmac_f32_e32 v92, v111, v111
	v_fmac_f32_e32 v90, v112, v112
	v_fmac_f32_e32 v92, v113, v113
	v_add_f32_e32 v9, v9, v91
	v_add_f32_e32 v90, v90, v92
	ds_bpermute_b32 v91, v3, v9
	ds_bpermute_b32 v92, v3, v90
	s_waitcnt lgkmcnt(0)
	v_add_f32_e32 v9, v9, v91
	v_add_f32_e32 v90, v90, v92
	ds_bpermute_b32 v91, v4, v9
	ds_bpermute_b32 v92, v4, v90
	s_waitcnt lgkmcnt(0)
	v_add_f32_e32 v9, v9, v91
	v_add_f32_e32 v90, v90, v92
	ds_bpermute_b32 v91, v5, v9
	ds_bpermute_b32 v92, v5, v90
	s_waitcnt lgkmcnt(0)
	v_add_f32_e32 v9, v9, v91
	v_add_f32_e32 v90, v90, v92
	ds_bpermute_b32 v91, v6, v9
	ds_bpermute_b32 v92, v6, v90
	s_waitcnt lgkmcnt(0)
	v_add_f32_e32 v9, v9, v91
	v_add_f32_e32 v90, v90, v92
	ds_bpermute_b32 v91, v7, v9
	ds_bpermute_b32 v92, v7, v90
	s_waitcnt lgkmcnt(0)
	v_add_f32_e32 v9, v9, v91
	v_add_f32_e32 v90, v90, v92
	ds_bpermute_b32 v91, v8, v9
	ds_bpermute_b32 v92, v8, v90
	s_waitcnt lgkmcnt(0)
	v_add_f32_e32 v9, v9, v91
	v_add_f32_e32 v90, v90, v92
	v_mul_f32_e32 v93, 0x3a800000, v9
	v_mul_f32_e32 v91, 0x3a800000, v90
	v_fma_f32 v91, -v93, v93, v91
	v_max_f32_e32 v91, 0, v91
	v_add_f32_e32 v91, 0x358637bd, v91
	v_rsq_f32_e32 v94, v91
	v_mul_f32_e32 v91, 0.5, v91
	v_mul_f32_e32 v92, v94, v94
	v_fma_f32 v92, -v91, v92, 0.5
	v_fma_f32 v94, v94, v92, v94
	s_waitcnt vmcnt(16)
; DI unsigned pk2(float lo, float hi) { f32x2 v = {lo, hi}; bf16x2_t b = __builtin_convertvector(v, bf16x2_t); return __builtin_bit_cast(unsigned, b); }
; DI const float* modp(const Frame& F, int l, int mr, int which) { return (const float*)(F.ws + WS_MOD) + ((size_t)(l * 9 + mr) * 6 + which) * 1024; }
; DI void ln_row_v(const Frame& F, f32x4 (&v)[4], float* xout, const float* g, const float* b, const float* sh, const float* sc, bf16_t* hout, const float* slab, const float* gres, float* stat = nullptr) {
;     ...
;     if (hout) {
;         float s = 0.f, s2 = 0.f;
; #pragma unroll
;         for (int j = 0; j < 4; ++j) { s += (v[j][0] + v[j][1]) + (v[j][2] + v[j][3]); s2 += (v[j][0] * v[j][0] + v[j][1] * v[j][1]) + (v[j][2] * v[j][2] + v[j][3] * v[j][3]); }
;         wave_sum2(s, s2, F.lane);
;         const float mean = s * (1.f / D); const float rstd = 1.f / sqrtf(fmaxf(s2 * (1.f / D) - mean * mean, 0.f) + EPS);
; #pragma unroll
;         for (int j = 0; j < 4; ++j) { const f32x4 hh = ((const f32x4*)sh)[F.lane + 64 * j], cc = ((const f32x4*)sc)[F.lane + 64 * j];
;             const f32x4 o = (v[j] - mean) * rstd * (cc + 1.f) + hh; u32x2 wv; wv.x = pk2(o[0], o[1]); wv.y = pk2(o[2], o[3]);
;             ((u32x2*)hout)[F.lane + 64 * j] = wv; }
;     }
; DI void prologue_b(const Frame& F) {
;     ...
;     for (int row = gw; row < MT; row += NGW) {
;         const int mr = row < ML ? (row >> 11) : 8;
;         const float* xi = row < ML ? pin(F, I_X) + (size_t)row * D : pin(F, I_CTX) + (size_t)(row - ML) * D;
;         ln_row(F, xi, nullptr, nullptr, nullptr, modp(F, 0, mr, 0), modp(F, 0, mr, 1), H + (size_t)row * D);
	v_sub_f32_e32 v98, v98, v93
	v_sub_f32_e32 v99, v99, v93
	v_sub_f32_e32 v100, v100, v93
	v_sub_f32_e32 v101, v101, v93
	v_sub_f32_e32 v102, v102, v93
	v_sub_f32_e32 v103, v103, v93
	v_sub_f32_e32 v104, v104, v93
	v_sub_f32_e32 v105, v105, v93
	v_sub_f32_e32 v106, v106, v93
	v_sub_f32_e32 v107, v107, v93
	v_sub_f32_e32 v108, v108, v93
	v_sub_f32_e32 v109, v109, v93
	v_sub_f32_e32 v110, v110, v93
	v_sub_f32_e32 v111, v111, v93
	v_sub_f32_e32 v112, v112, v93
	v_sub_f32_e32 v113, v113, v93
	v_add_f32_e32 v162, 1.0, v162
	v_add_f32_e32 v163, 1.0, v163
	v_add_f32_e32 v164, 1.0, v164
	v_add_f32_e32 v165, 1.0, v165
	v_add_f32_e32 v166, 1.0, v166
	v_add_f32_e32 v167, 1.0, v167
	v_add_f32_e32 v168, 1.0, v168
	v_add_f32_e32 v169, 1.0, v169
	v_add_f32_e32 v170, 1.0, v170
	v_add_f32_e32 v171, 1.0, v171
	v_add_f32_e32 v172, 1.0, v172
	v_add_f32_e32 v173, 1.0, v173
	v_add_f32_e32 v174, 1.0, v174
	v_add_f32_e32 v175, 1.0, v175
	v_add_f32_e32 v176, 1.0, v176
	v_add_f32_e32 v177, 1.0, v177
	v_mul_f32_e32 v98, v94, v98
	v_mul_f32_e32 v99, v94, v99
	v_mul_f32_e32 v100, v94, v100
	v_mul_f32_e32 v101, v94, v101
	v_mul_f32_e32 v102, v94, v102
	v_mul_f32_e32 v103, v94, v103
	v_mul_f32_e32 v104, v94, v104
	v_mul_f32_e32 v105, v94, v105
	v_mul_f32_e32 v106, v94, v106
	v_mul_f32_e32 v107, v94, v107
	v_mul_f32_e32 v108, v94, v108
	v_mul_f32_e32 v109, v94, v109
	v_mul_f32_e32 v110, v94, v110
	v_mul_f32_e32 v111, v94, v111
	v_mul_f32_e32 v112, v94, v112
	v_mul_f32_e32 v113, v94, v113
	v_fma_f32 v98, v98, v162, v146
	v_fma_f32 v99, v99, v163, v147
	v_fma_f32 v100, v100, v164, v148
	v_fma_f32 v101, v101, v165, v149
	v_fma_f32 v102, v102, v166, v150
	v_fma_f32 v103, v103, v167, v151
	v_fma_f32 v104, v104, v168, v152
	v_fma_f32 v105, v105, v169, v153
	v_fma_f32 v106, v106, v170, v154
	v_fma_f32 v107, v107, v171, v155
	v_fma_f32 v108, v108, v172, v156
	v_fma_f32 v109, v109, v173, v157
	v_fma_f32 v110, v110, v174, v158
	v_fma_f32 v111, v111, v175, v159
	v_fma_f32 v112, v112, v176, v160
	v_fma_f32 v113, v113, v177, v161
	v_cvt_pk_bf16_f32 v190, v98, v99
	v_cvt_pk_bf16_f32 v191, v100, v101
	v_cvt_pk_bf16_f32 v192, v102, v103
	v_cvt_pk_bf16_f32 v193, v104, v105
	v_cvt_pk_bf16_f32 v194, v106, v107
	v_cvt_pk_bf16_f32 v195, v108, v109
	v_cvt_pk_bf16_f32 v196, v110, v111
	v_cvt_pk_bf16_f32 v197, v112, v113
	s_add_u32 s2, s10, 0xc00000
	s_addc_u32 s3, s11, 0
	global_store_dwordx2 v1, v[190:191], s[2:3]
	global_store_dwordx2 v1, v[192:193], s[2:3] offset:512
	global_store_dwordx2 v1, v[194:195], s[2:3] offset:1024
	global_store_dwordx2 v1, v[196:197], s[2:3] offset:1536
	s_add_u32 s2, s8, 0x3800000
	s_addc_u32 s3, s9, 0
	global_load_dwordx4 v[98:101], v0, s[2:3]
	global_load_dwordx4 v[102:105], v0, s[2:3] offset:1024
	global_load_dwordx4 v[106:109], v0, s[2:3] offset:2048
	global_load_dwordx4 v[110:113], v0, s[2:3] offset:3072
	s_add_u32 s2, s14, 0x1e000
	s_addc_u32 s3, s15, 0
	global_load_dwordx4 v[146:149], v0, s[2:3]
	global_load_dwordx4 v[150:153], v0, s[2:3] offset:1024
	global_load_dwordx4 v[154:157], v0, s[2:3] offset:2048
	global_load_dwordx4 v[158:161], v0, s[2:3] offset:3072
	s_add_u32 s2, s18, 0x1e000
	s_addc_u32 s3, s19, 0
	global_load_dwordx4 v[162:165], v0, s[2:3]
	global_load_dwordx4 v[166:169], v0, s[2:3] offset:1024
	global_load_dwordx4 v[170:173], v0, s[2:3] offset:2048
	global_load_dwordx4 v[174:177], v0, s[2:3] offset:3072
	v_add_f32_e32 v9, v42, v43
	v_add_f32_e32 v91, v44, v45
	v_mul_f32_e32 v90, v42, v42
	v_mul_f32_e32 v92, v43, v43
	v_add_f32_e32 v9, v9, v46
	v_add_f32_e32 v91, v91, v47
	v_add_f32_e32 v9, v9, v48
	v_add_f32_e32 v91, v91, v49
	v_add_f32_e32 v9, v9, v50
	v_add_f32_e32 v91, v91, v51
	v_add_f32_e32 v9, v9, v52
	v_add_f32_e32 v91, v91, v53
	v_add_f32_e32 v9, v9, v54
	v_add_f32_e32 v91, v91, v55
	v_add_f32_e32 v9, v9, v56
	v_add_f32_e32 v91, v91, v57
	v_fmac_f32_e32 v90, v44, v44
	v_fmac_f32_e32 v92, v45, v45
	v_fmac_f32_e32 v90, v46, v46
	v_fmac_f32_e32 v92, v47, v47
	v_fmac_f32_e32 v90, v48, v48
	v_fmac_f32_e32 v92, v49, v49
	v_fmac_f32_e32 v90, v50, v50
	v_fmac_f32_e32 v92, v51, v51
	v_fmac_f32_e32 v90, v52, v52
	v_fmac_f32_e32 v92, v53, v53
	v_fmac_f32_e32 v90, v54, v54
	v_fmac_f32_e32 v92, v55, v55
	v_fmac_f32_e32 v90, v56, v56
	v_fmac_f32_e32 v92, v57, v57
	v_add_f32_e32 v9, v9, v91
	v_add_f32_e32 v90, v90, v92
	ds_bpermute_b32 v91, v3, v9
	ds_bpermute_b32 v92, v3, v90
	s_waitcnt lgkmcnt(0)
	v_add_f32_e32 v9, v9, v91
	v_add_f32_e32 v90, v90, v92
	ds_bpermute_b32 v91, v4, v9
	ds_bpermute_b32 v92, v4, v90
	s_waitcnt lgkmcnt(0)
	v_add_f32_e32 v9, v9, v91
	v_add_f32_e32 v90, v90, v92
	ds_bpermute_b32 v91, v5, v9
	ds_bpermute_b32 v92, v5, v90
	s_waitcnt lgkmcnt(0)
	v_add_f32_e32 v9, v9, v91
	v_add_f32_e32 v90, v90, v92
	ds_bpermute_b32 v91, v6, v9
	ds_bpermute_b32 v92, v6, v90
	s_waitcnt lgkmcnt(0)
	v_add_f32_e32 v9, v9, v91
	v_add_f32_e32 v90, v90, v92
	ds_bpermute_b32 v91, v7, v9
	ds_bpermute_b32 v92, v7, v90
	s_waitcnt lgkmcnt(0)
	v_add_f32_e32 v9, v9, v91
	v_add_f32_e32 v90, v90, v92
	ds_bpermute_b32 v91, v8, v9
	ds_bpermute_b32 v92, v8, v90
	s_waitcnt lgkmcnt(0)
	v_add_f32_e32 v9, v9, v91
	v_add_f32_e32 v90, v90, v92
	v_mul_f32_e32 v93, 0x3a800000, v9
	v_mul_f32_e32 v91, 0x3a800000, v90
	v_fma_f32 v91, -v93, v93, v91
	v_max_f32_e32 v91, 0, v91
	v_add_f32_e32 v91, 0x358637bd, v91
	v_rsq_f32_e32 v94, v91
	v_mul_f32_e32 v91, 0.5, v91
	v_mul_f32_e32 v92, v94, v94
	v_fma_f32 v92, -v91, v92, 0.5
	v_fma_f32 v94, v94, v92, v94
	s_waitcnt vmcnt(16)
; DI unsigned pk2(float lo, float hi) { f32x2 v = {lo, hi}; bf16x2_t b = __builtin_convertvector(v, bf16x2_t); return __builtin_bit_cast(unsigned, b); }
; DI const float* modp(const Frame& F, int l, int mr, int which) { return (const float*)(F.ws + WS_MOD) + ((size_t)(l * 9 + mr) * 6 + which) * 1024; }
; DI void ln_row_v(const Frame& F, f32x4 (&v)[4], float* xout, const float* g, const float* b, const float* sh, const float* sc, bf16_t* hout, const float* slab, const float* gres, float* stat = nullptr) {
;     ...
;     if (hout) {
;         float s = 0.f, s2 = 0.f;
; #pragma unroll
;         for (int j = 0; j < 4; ++j) { s += (v[j][0] + v[j][1]) + (v[j][2] + v[j][3]); s2 += (v[j][0] * v[j][0] + v[j][1] * v[j][1]) + (v[j][2] * v[j][2] + v[j][3] * v[j][3]); }
;         wave_sum2(s, s2, F.lane);
;         const float mean = s * (1.f / D); const float rstd = 1.f / sqrtf(fmaxf(s2 * (1.f / D) - mean * mean, 0.f) + EPS);
; #pragma unroll
;         for (int j = 0; j < 4; ++j) { const f32x4 hh = ((const f32x4*)sh)[F.lane + 64 * j], cc = ((const f32x4*)sc)[F.lane + 64 * j];
;             const f32x4 o = (v[j] - mean) * rstd * (cc + 1.f) + hh; u32x2 wv; wv.x = pk2(o[0], o[1]); wv.y = pk2(o[2], o[3]);
;             ((u32x2*)hout)[F.lane + 64 * j] = wv; }
;     }
; DI void prologue_b(const Frame& F) {
;     ...
;     for (int row = gw; row < MT; row += NGW) {
;         const int mr = row < ML ? (row >> 11) : 8;
;         const float* xi = row < ML ? pin(F, I_X) + (size_t)row * D : pin(F, I_CTX) + (size_t)(row - ML) * D;
;         ln_row(F, xi, nullptr, nullptr, nullptr, modp(F, 0, mr, 0), modp(F, 0, mr, 1), H + (size_t)row * D);
	v_sub_f32_e32 v42, v42, v93
	v_sub_f32_e32 v43, v43, v93
	v_sub_f32_e32 v44, v44, v93
	v_sub_f32_e32 v45, v45, v93
	v_sub_f32_e32 v46, v46, v93
	v_sub_f32_e32 v47, v47, v93
	v_sub_f32_e32 v48, v48, v93
	v_sub_f32_e32 v49, v49, v93
	v_sub_f32_e32 v50, v50, v93
	v_sub_f32_e32 v51, v51, v93
	v_sub_f32_e32 v52, v52, v93
	v_sub_f32_e32 v53, v53, v93
	v_sub_f32_e32 v54, v54, v93
	v_sub_f32_e32 v55, v55, v93
	v_sub_f32_e32 v56, v56, v93
	v_sub_f32_e32 v57, v57, v93
	v_add_f32_e32 v130, 1.0, v130
	v_add_f32_e32 v131, 1.0, v131
	v_add_f32_e32 v132, 1.0, v132
	v_add_f32_e32 v133, 1.0, v133
	v_add_f32_e32 v134, 1.0, v134
	v_add_f32_e32 v135, 1.0, v135
	v_add_f32_e32 v136, 1.0, v136
	v_add_f32_e32 v137, 1.0, v137
	v_add_f32_e32 v138, 1.0, v138
	v_add_f32_e32 v139, 1.0, v139
	v_add_f32_e32 v140, 1.0, v140
	v_add_f32_e32 v141, 1.0, v141
	v_add_f32_e32 v142, 1.0, v142
	v_add_f32_e32 v143, 1.0, v143
	v_add_f32_e32 v144, 1.0, v144
	v_add_f32_e32 v145, 1.0, v145
	v_mul_f32_e32 v42, v94, v42
	v_mul_f32_e32 v43, v94, v43
	v_mul_f32_e32 v44, v94, v44
	v_mul_f32_e32 v45, v94, v45
	v_mul_f32_e32 v46, v94, v46
	v_mul_f32_e32 v47, v94, v47
	v_mul_f32_e32 v48, v94, v48
	v_mul_f32_e32 v49, v94, v49
	v_mul_f32_e32 v50, v94, v50
	v_mul_f32_e32 v51, v94, v51
	v_mul_f32_e32 v52, v94, v52
	v_mul_f32_e32 v53, v94, v53
	v_mul_f32_e32 v54, v94, v54
	v_mul_f32_e32 v55, v94, v55
	v_mul_f32_e32 v56, v94, v56
	v_mul_f32_e32 v57, v94, v57
	v_fma_f32 v42, v42, v130, v114
	v_fma_f32 v43, v43, v131, v115
	v_fma_f32 v44, v44, v132, v116
	v_fma_f32 v45, v45, v133, v117
	v_fma_f32 v46, v46, v134, v118
	v_fma_f32 v47, v47, v135, v119
	v_fma_f32 v48, v48, v136, v120
	v_fma_f32 v49, v49, v137, v121
	v_fma_f32 v50, v50, v138, v122
	v_fma_f32 v51, v51, v139, v123
	v_fma_f32 v52, v52, v140, v124
	v_fma_f32 v53, v53, v141, v125
	v_fma_f32 v54, v54, v142, v126
	v_fma_f32 v55, v55, v143, v127
	v_fma_f32 v56, v56, v144, v128
	v_fma_f32 v57, v57, v145, v129
	v_cvt_pk_bf16_f32 v190, v42, v43
	v_cvt_pk_bf16_f32 v191, v44, v45
	v_cvt_pk_bf16_f32 v192, v46, v47
	v_cvt_pk_bf16_f32 v193, v48, v49
	v_cvt_pk_bf16_f32 v194, v50, v51
	v_cvt_pk_bf16_f32 v195, v52, v53
	v_cvt_pk_bf16_f32 v196, v54, v55
	v_cvt_pk_bf16_f32 v197, v56, v57
	s_add_u32 s2, s10, 0x1000000
	s_addc_u32 s3, s11, 0
	global_store_dwordx2 v1, v[190:191], s[2:3]
	global_store_dwordx2 v1, v[192:193], s[2:3] offset:512
	global_store_dwordx2 v1, v[194:195], s[2:3] offset:1024
	global_store_dwordx2 v1, v[196:197], s[2:3] offset:1536
	s_mov_b64 s[2:3], s[20:21]
	global_load_dwordx4 v[42:45], v0, s[2:3]
	global_load_dwordx4 v[46:49], v0, s[2:3] offset:1024
	global_load_dwordx4 v[50:53], v0, s[2:3] offset:2048
	global_load_dwordx4 v[54:57], v0, s[2:3] offset:3072
	s_add_u32 s2, s14, 0x24000
	s_addc_u32 s3, s15, 0
	global_load_dwordx4 v[114:117], v0, s[2:3]
	global_load_dwordx4 v[118:121], v0, s[2:3] offset:1024
	global_load_dwordx4 v[122:125], v0, s[2:3] offset:2048
	global_load_dwordx4 v[126:129], v0, s[2:3] offset:3072
	s_add_u32 s2, s18, 0x24000
	s_addc_u32 s3, s19, 0
	global_load_dwordx4 v[130:133], v0, s[2:3]
	global_load_dwordx4 v[134:137], v0, s[2:3] offset:1024
	global_load_dwordx4 v[138:141], v0, s[2:3] offset:2048
	global_load_dwordx4 v[142:145], v0, s[2:3] offset:3072
	v_add_f32_e32 v9, v58, v59
	v_add_f32_e32 v91, v60, v61
	v_mul_f32_e32 v90, v58, v58
	v_mul_f32_e32 v92, v59, v59
	v_add_f32_e32 v9, v9, v62
	v_add_f32_e32 v91, v91, v63
	v_add_f32_e32 v9, v9, v64
	v_add_f32_e32 v91, v91, v65
	v_add_f32_e32 v9, v9, v66
	v_add_f32_e32 v91, v91, v67
	v_add_f32_e32 v9, v9, v68
	v_add_f32_e32 v91, v91, v69
	v_add_f32_e32 v9, v9, v70
	v_add_f32_e32 v91, v91, v71
	v_add_f32_e32 v9, v9, v72
	v_add_f32_e32 v91, v91, v73
	v_fmac_f32_e32 v90, v60, v60
	v_fmac_f32_e32 v92, v61, v61
	v_fmac_f32_e32 v90, v62, v62
	v_fmac_f32_e32 v92, v63, v63
	v_fmac_f32_e32 v90, v64, v64
	v_fmac_f32_e32 v92, v65, v65
	v_fmac_f32_e32 v90, v66, v66
	v_fmac_f32_e32 v92, v67, v67
	v_fmac_f32_e32 v90, v68, v68
	v_fmac_f32_e32 v92, v69, v69
	v_fmac_f32_e32 v90, v70, v70
	v_fmac_f32_e32 v92, v71, v71
	v_fmac_f32_e32 v90, v72, v72
	v_fmac_f32_e32 v92, v73, v73
	v_add_f32_e32 v9, v9, v91
	v_add_f32_e32 v90, v90, v92
	ds_bpermute_b32 v91, v3, v9
	ds_bpermute_b32 v92, v3, v90
	s_waitcnt lgkmcnt(0)
	v_add_f32_e32 v9, v9, v91
	v_add_f32_e32 v90, v90, v92
	ds_bpermute_b32 v91, v4, v9
	ds_bpermute_b32 v92, v4, v90
	s_waitcnt lgkmcnt(0)
	v_add_f32_e32 v9, v9, v91
	v_add_f32_e32 v90, v90, v92
	ds_bpermute_b32 v91, v5, v9
	ds_bpermute_b32 v92, v5, v90
	s_waitcnt lgkmcnt(0)
	v_add_f32_e32 v9, v9, v91
	v_add_f32_e32 v90, v90, v92
	ds_bpermute_b32 v91, v6, v9
	ds_bpermute_b32 v92, v6, v90
	s_waitcnt lgkmcnt(0)
	v_add_f32_e32 v9, v9, v91
	v_add_f32_e32 v90, v90, v92
	ds_bpermute_b32 v91, v7, v9
	ds_bpermute_b32 v92, v7, v90
	s_waitcnt lgkmcnt(0)
	v_add_f32_e32 v9, v9, v91
	v_add_f32_e32 v90, v90, v92
	ds_bpermute_b32 v91, v8, v9
	ds_bpermute_b32 v92, v8, v90
	s_waitcnt lgkmcnt(0)
	v_add_f32_e32 v9, v9, v91
	v_add_f32_e32 v90, v90, v92
	v_mul_f32_e32 v93, 0x3a800000, v9
	v_mul_f32_e32 v91, 0x3a800000, v90
	v_fma_f32 v91, -v93, v93, v91
	v_max_f32_e32 v91, 0, v91
	v_add_f32_e32 v91, 0x358637bd, v91
	v_rsq_f32_e32 v94, v91
	v_mul_f32_e32 v91, 0.5, v91
	v_mul_f32_e32 v92, v94, v94
	v_fma_f32 v92, -v91, v92, 0.5
	v_fma_f32 v94, v94, v92, v94
	s_waitcnt vmcnt(16)
; DI unsigned pk2(float lo, float hi) { f32x2 v = {lo, hi}; bf16x2_t b = __builtin_convertvector(v, bf16x2_t); return __builtin_bit_cast(unsigned, b); }
; DI const float* modp(const Frame& F, int l, int mr, int which) { return (const float*)(F.ws + WS_MOD) + ((size_t)(l * 9 + mr) * 6 + which) * 1024; }
; DI void ln_row_v(const Frame& F, f32x4 (&v)[4], float* xout, const float* g, const float* b, const float* sh, const float* sc, bf16_t* hout, const float* slab, const float* gres, float* stat = nullptr) {
;     ...
;     if (hout) {
;         float s = 0.f, s2 = 0.f;
; #pragma unroll
;         for (int j = 0; j < 4; ++j) { s += (v[j][0] + v[j][1]) + (v[j][2] + v[j][3]); s2 += (v[j][0] * v[j][0] + v[j][1] * v[j][1]) + (v[j][2] * v[j][2] + v[j][3] * v[j][3]); }
;         wave_sum2(s, s2, F.lane);
;         const float mean = s * (1.f / D); const float rstd = 1.f / sqrtf(fmaxf(s2 * (1.f / D) - mean * mean, 0.f) + EPS);
; #pragma unroll
;         for (int j = 0; j < 4; ++j) { const f32x4 hh = ((const f32x4*)sh)[F.lane + 64 * j], cc = ((const f32x4*)sc)[F.lane + 64 * j];
;             const f32x4 o = (v[j] - mean) * rstd * (cc + 1.f) + hh; u32x2 wv; wv.x = pk2(o[0], o[1]); wv.y = pk2(o[2], o[3]);
;             ((u32x2*)hout)[F.lane + 64 * j] = wv; }
;     }
; DI void prologue_b(const Frame& F) {
;     ...
;     for (int row = gw; row < MT; row += NGW) {
;         const int mr = row < ML ? (row >> 11) : 8;
;         const float* xi = row < ML ? pin(F, I_X) + (size_t)row * D : pin(F, I_CTX) + (size_t)(row - ML) * D;
;         ln_row(F, xi, nullptr, nullptr, nullptr, modp(F, 0, mr, 0), modp(F, 0, mr, 1), H + (size_t)row * D);
	v_sub_f32_e32 v58, v58, v93
	v_sub_f32_e32 v59, v59, v93
	v_sub_f32_e32 v60, v60, v93
	v_sub_f32_e32 v61, v61, v93
	v_sub_f32_e32 v62, v62, v93
	v_sub_f32_e32 v63, v63, v93
	v_sub_f32_e32 v64, v64, v93
	v_sub_f32_e32 v65, v65, v93
	v_sub_f32_e32 v66, v66, v93
	v_sub_f32_e32 v67, v67, v93
	v_sub_f32_e32 v68, v68, v93
	v_sub_f32_e32 v69, v69, v93
	v_sub_f32_e32 v70, v70, v93
	v_sub_f32_e32 v71, v71, v93
	v_sub_f32_e32 v72, v72, v93
	v_sub_f32_e32 v73, v73, v93
	v_add_f32_e32 v162, 1.0, v162
	v_add_f32_e32 v163, 1.0, v163
	v_add_f32_e32 v164, 1.0, v164
	v_add_f32_e32 v165, 1.0, v165
	v_add_f32_e32 v166, 1.0, v166
	v_add_f32_e32 v167, 1.0, v167
	v_add_f32_e32 v168, 1.0, v168
	v_add_f32_e32 v169, 1.0, v169
	v_add_f32_e32 v170, 1.0, v170
	v_add_f32_e32 v171, 1.0, v171
	v_add_f32_e32 v172, 1.0, v172
	v_add_f32_e32 v173, 1.0, v173
	v_add_f32_e32 v174, 1.0, v174
	v_add_f32_e32 v175, 1.0, v175
	v_add_f32_e32 v176, 1.0, v176
	v_add_f32_e32 v177, 1.0, v177
	v_mul_f32_e32 v58, v94, v58
	v_mul_f32_e32 v59, v94, v59
	v_mul_f32_e32 v60, v94, v60
	v_mul_f32_e32 v61, v94, v61
	v_mul_f32_e32 v62, v94, v62
	v_mul_f32_e32 v63, v94, v63
	v_mul_f32_e32 v64, v94, v64
	v_mul_f32_e32 v65, v94, v65
	v_mul_f32_e32 v66, v94, v66
	v_mul_f32_e32 v67, v94, v67
	v_mul_f32_e32 v68, v94, v68
	v_mul_f32_e32 v69, v94, v69
	v_mul_f32_e32 v70, v94, v70
	v_mul_f32_e32 v71, v94, v71
	v_mul_f32_e32 v72, v94, v72
	v_mul_f32_e32 v73, v94, v73
	v_fma_f32 v58, v58, v162, v146
	v_fma_f32 v59, v59, v163, v147
	v_fma_f32 v60, v60, v164, v148
	v_fma_f32 v61, v61, v165, v149
	v_fma_f32 v62, v62, v166, v150
	v_fma_f32 v63, v63, v167, v151
	v_fma_f32 v64, v64, v168, v152
	v_fma_f32 v65, v65, v169, v153
	v_fma_f32 v66, v66, v170, v154
	v_fma_f32 v67, v67, v171, v155
	v_fma_f32 v68, v68, v172, v156
	v_fma_f32 v69, v69, v173, v157
	v_fma_f32 v70, v70, v174, v158
	v_fma_f32 v71, v71, v175, v159
	v_fma_f32 v72, v72, v176, v160
	v_fma_f32 v73, v73, v177, v161
	v_cvt_pk_bf16_f32 v190, v58, v59
	v_cvt_pk_bf16_f32 v191, v60, v61
	v_cvt_pk_bf16_f32 v192, v62, v63
	v_cvt_pk_bf16_f32 v193, v64, v65
	v_cvt_pk_bf16_f32 v194, v66, v67
	v_cvt_pk_bf16_f32 v195, v68, v69
	v_cvt_pk_bf16_f32 v196, v70, v71
	v_cvt_pk_bf16_f32 v197, v72, v73
	s_add_u32 s2, s10, 0x1400000
	s_addc_u32 s3, s11, 0
	global_store_dwordx2 v1, v[190:191], s[2:3]
	global_store_dwordx2 v1, v[192:193], s[2:3] offset:512
	global_store_dwordx2 v1, v[194:195], s[2:3] offset:1024
	global_store_dwordx2 v1, v[196:197], s[2:3] offset:1536
	s_add_u32 s2, s14, 0x2a000
	s_addc_u32 s3, s15, 0
	global_load_dwordx4 v[146:149], v0, s[2:3]
	global_load_dwordx4 v[150:153], v0, s[2:3] offset:1024
	global_load_dwordx4 v[154:157], v0, s[2:3] offset:2048
	global_load_dwordx4 v[158:161], v0, s[2:3] offset:3072
	s_add_u32 s2, s18, 0x2a000
	s_addc_u32 s3, s19, 0
	global_load_dwordx4 v[162:165], v0, s[2:3]
	global_load_dwordx4 v[166:169], v0, s[2:3] offset:1024
	global_load_dwordx4 v[170:173], v0, s[2:3] offset:2048
	global_load_dwordx4 v[174:177], v0, s[2:3] offset:3072
	v_add_f32_e32 v9, v74, v75
	v_add_f32_e32 v91, v76, v77
	v_mul_f32_e32 v90, v74, v74
	v_mul_f32_e32 v92, v75, v75
	v_add_f32_e32 v9, v9, v78
	v_add_f32_e32 v91, v91, v79
	v_add_f32_e32 v9, v9, v80
	v_add_f32_e32 v91, v91, v81
	v_add_f32_e32 v9, v9, v82
	v_add_f32_e32 v91, v91, v83
	v_add_f32_e32 v9, v9, v84
	v_add_f32_e32 v91, v91, v85
	v_add_f32_e32 v9, v9, v86
	v_add_f32_e32 v91, v91, v87
	v_add_f32_e32 v9, v9, v88
	v_add_f32_e32 v91, v91, v89
	v_fmac_f32_e32 v90, v76, v76
	v_fmac_f32_e32 v92, v77, v77
	v_fmac_f32_e32 v90, v78, v78
	v_fmac_f32_e32 v92, v79, v79
	v_fmac_f32_e32 v90, v80, v80
	v_fmac_f32_e32 v92, v81, v81
	v_fmac_f32_e32 v90, v82, v82
	v_fmac_f32_e32 v92, v83, v83
	v_fmac_f32_e32 v90, v84, v84
	v_fmac_f32_e32 v92, v85, v85
	v_fmac_f32_e32 v90, v86, v86
	v_fmac_f32_e32 v92, v87, v87
	v_fmac_f32_e32 v90, v88, v88
	v_fmac_f32_e32 v92, v89, v89
	v_add_f32_e32 v9, v9, v91
	v_add_f32_e32 v90, v90, v92
	ds_bpermute_b32 v91, v3, v9
	ds_bpermute_b32 v92, v3, v90
	s_waitcnt lgkmcnt(0)
	v_add_f32_e32 v9, v9, v91
	v_add_f32_e32 v90, v90, v92
	ds_bpermute_b32 v91, v4, v9
	ds_bpermute_b32 v92, v4, v90
	s_waitcnt lgkmcnt(0)
	v_add_f32_e32 v9, v9, v91
	v_add_f32_e32 v90, v90, v92
	ds_bpermute_b32 v91, v5, v9
	ds_bpermute_b32 v92, v5, v90
	s_waitcnt lgkmcnt(0)
	v_add_f32_e32 v9, v9, v91
	v_add_f32_e32 v90, v90, v92
	ds_bpermute_b32 v91, v6, v9
	ds_bpermute_b32 v92, v6, v90
	s_waitcnt lgkmcnt(0)
	v_add_f32_e32 v9, v9, v91
	v_add_f32_e32 v90, v90, v92
	ds_bpermute_b32 v91, v7, v9
	ds_bpermute_b32 v92, v7, v90
	s_waitcnt lgkmcnt(0)
	v_add_f32_e32 v9, v9, v91
	v_add_f32_e32 v90, v90, v92
	ds_bpermute_b32 v91, v8, v9
	ds_bpermute_b32 v92, v8, v90
	s_waitcnt lgkmcnt(0)
	v_add_f32_e32 v9, v9, v91
	v_add_f32_e32 v90, v90, v92
	v_mul_f32_e32 v93, 0x3a800000, v9
	v_mul_f32_e32 v91, 0x3a800000, v90
	v_fma_f32 v91, -v93, v93, v91
	v_max_f32_e32 v91, 0, v91
	v_add_f32_e32 v91, 0x358637bd, v91
	v_rsq_f32_e32 v94, v91
	v_mul_f32_e32 v91, 0.5, v91
	v_mul_f32_e32 v92, v94, v94
	v_fma_f32 v92, -v91, v92, 0.5
	v_fma_f32 v94, v94, v92, v94
	s_waitcnt vmcnt(12)
; DI unsigned pk2(float lo, float hi) { f32x2 v = {lo, hi}; bf16x2_t b = __builtin_convertvector(v, bf16x2_t); return __builtin_bit_cast(unsigned, b); }
; DI void ln_row_v(const Frame& F, f32x4 (&v)[4], float* xout, const float* g, const float* b, const float* sh, const float* sc, bf16_t* hout, const float* slab, const float* gres, float* stat = nullptr) {
;     ...
;         float s = 0.f, s2 = 0.f;
; #pragma unroll
;         for (int j = 0; j < 4; ++j) { s += (v[j][0] + v[j][1]) + (v[j][2] + v[j][3]); s2 += (v[j][0] * v[j][0] + v[j][1] * v[j][1]) + (v[j][2] * v[j][2] + v[j][3] * v[j][3]); }
;         wave_sum2(s, s2, F.lane);
;         const float mean = s * (1.f / D); const float rstd = 1.f / sqrtf(fmaxf(s2 * (1.f / D) - mean * mean, 0.f) + EPS);
; #pragma unroll
;         for (int j = 0; j < 4; ++j) { const f32x4 hh = ((const f32x4*)sh)[F.lane + 64 * j], cc = ((const f32x4*)sc)[F.lane + 64 * j];
;             const f32x4 o = (v[j] - mean) * rstd * (cc + 1.f) + hh; u32x2 wv; wv.x = pk2(o[0], o[1]); wv.y = pk2(o[2], o[3]);
;             ((u32x2*)hout)[F.lane + 64 * j] = wv; }
	v_sub_f32_e32 v74, v74, v93
	v_sub_f32_e32 v75, v75, v93
	v_sub_f32_e32 v76, v76, v93
	v_sub_f32_e32 v77, v77, v93
	v_sub_f32_e32 v78, v78, v93
	v_sub_f32_e32 v79, v79, v93
	v_sub_f32_e32 v80, v80, v93
	v_sub_f32_e32 v81, v81, v93
	v_sub_f32_e32 v82, v82, v93
	v_sub_f32_e32 v83, v83, v93
	v_sub_f32_e32 v84, v84, v93
	v_sub_f32_e32 v85, v85, v93
	v_sub_f32_e32 v86, v86, v93
	v_sub_f32_e32 v87, v87, v93
	v_sub_f32_e32 v88, v88, v93
	v_sub_f32_e32 v89, v89, v93
	v_add_f32_e32 v130, 1.0, v130
	v_add_f32_e32 v131, 1.0, v131
	v_add_f32_e32 v132, 1.0, v132
	v_add_f32_e32 v133, 1.0, v133
	v_add_f32_e32 v134, 1.0, v134
	v_add_f32_e32 v135, 1.0, v135
	v_add_f32_e32 v136, 1.0, v136
	v_add_f32_e32 v137, 1.0, v137
	v_add_f32_e32 v138, 1.0, v138
	v_add_f32_e32 v139, 1.0, v139
	v_add_f32_e32 v140, 1.0, v140
	v_add_f32_e32 v141, 1.0, v141
	v_add_f32_e32 v142, 1.0, v142
	v_add_f32_e32 v143, 1.0, v143
	v_add_f32_e32 v144, 1.0, v144
	v_add_f32_e32 v145, 1.0, v145
	v_mul_f32_e32 v74, v94, v74
	v_mul_f32_e32 v75, v94, v75
	v_mul_f32_e32 v76, v94, v76
	v_mul_f32_e32 v77, v94, v77
	v_mul_f32_e32 v78, v94, v78
	v_mul_f32_e32 v79, v94, v79
	v_mul_f32_e32 v80, v94, v80
	v_mul_f32_e32 v81, v94, v81
	v_mul_f32_e32 v82, v94, v82
	v_mul_f32_e32 v83, v94, v83
	v_mul_f32_e32 v84, v94, v84
	v_mul_f32_e32 v85, v94, v85
	v_mul_f32_e32 v86, v94, v86
	v_mul_f32_e32 v87, v94, v87
	v_mul_f32_e32 v88, v94, v88
	v_mul_f32_e32 v89, v94, v89
	v_fma_f32 v74, v74, v130, v114
	v_fma_f32 v75, v75, v131, v115
	v_fma_f32 v76, v76, v132, v116
	v_fma_f32 v77, v77, v133, v117
	v_fma_f32 v78, v78, v134, v118
	v_fma_f32 v79, v79, v135, v119
	v_fma_f32 v80, v80, v136, v120
	v_fma_f32 v81, v81, v137, v121
	v_fma_f32 v82, v82, v138, v122
	v_fma_f32 v83, v83, v139, v123
	v_fma_f32 v84, v84, v140, v124
	v_fma_f32 v85, v85, v141, v125
	v_fma_f32 v86, v86, v142, v126
	v_fma_f32 v87, v87, v143, v127
	v_fma_f32 v88, v88, v144, v128
	v_fma_f32 v89, v89, v145, v129
	v_cvt_pk_bf16_f32 v190, v74, v75
	v_cvt_pk_bf16_f32 v191, v76, v77
	v_cvt_pk_bf16_f32 v192, v78, v79
	v_cvt_pk_bf16_f32 v193, v80, v81
	v_cvt_pk_bf16_f32 v194, v82, v83
	v_cvt_pk_bf16_f32 v195, v84, v85
	v_cvt_pk_bf16_f32 v196, v86, v87
	v_cvt_pk_bf16_f32 v197, v88, v89
	s_add_u32 s2, s10, 0x1800000
	s_addc_u32 s3, s11, 0
	global_store_dwordx2 v1, v[190:191], s[2:3]
	global_store_dwordx2 v1, v[192:193], s[2:3] offset:512
	global_store_dwordx2 v1, v[194:195], s[2:3] offset:1024
	global_store_dwordx2 v1, v[196:197], s[2:3] offset:1536
	s_add_u32 s2, s14, 0x30000
	s_addc_u32 s3, s15, 0
	global_load_dwordx4 v[114:117], v0, s[2:3]
	global_load_dwordx4 v[118:121], v0, s[2:3] offset:1024
	global_load_dwordx4 v[122:125], v0, s[2:3] offset:2048
	global_load_dwordx4 v[126:129], v0, s[2:3] offset:3072
	s_add_u32 s2, s18, 0x30000
	s_addc_u32 s3, s19, 0
	global_load_dwordx4 v[130:133], v0, s[2:3]
	global_load_dwordx4 v[134:137], v0, s[2:3] offset:1024
	global_load_dwordx4 v[138:141], v0, s[2:3] offset:2048
	global_load_dwordx4 v[142:145], v0, s[2:3] offset:3072
	v_add_f32_e32 v9, v98, v99
	v_add_f32_e32 v91, v100, v101
	v_mul_f32_e32 v90, v98, v98
	v_mul_f32_e32 v92, v99, v99
	v_add_f32_e32 v9, v9, v102
	v_add_f32_e32 v91, v91, v103
	v_add_f32_e32 v9, v9, v104
	v_add_f32_e32 v91, v91, v105
	v_add_f32_e32 v9, v9, v106
	v_add_f32_e32 v91, v91, v107
	v_add_f32_e32 v9, v9, v108
	v_add_f32_e32 v91, v91, v109
	v_add_f32_e32 v9, v9, v110
	v_add_f32_e32 v91, v91, v111
	v_add_f32_e32 v9, v9, v112
	v_add_f32_e32 v91, v91, v113
	v_fmac_f32_e32 v90, v100, v100
	v_fmac_f32_e32 v92, v101, v101
	v_fmac_f32_e32 v90, v102, v102
	v_fmac_f32_e32 v92, v103, v103
	v_fmac_f32_e32 v90, v104, v104
	v_fmac_f32_e32 v92, v105, v105
	v_fmac_f32_e32 v90, v106, v106
	v_fmac_f32_e32 v92, v107, v107
	v_fmac_f32_e32 v90, v108, v108
	v_fmac_f32_e32 v92, v109, v109
	v_fmac_f32_e32 v90, v110, v110
	v_fmac_f32_e32 v92, v111, v111
	v_fmac_f32_e32 v90, v112, v112
	v_fmac_f32_e32 v92, v113, v113
	v_add_f32_e32 v9, v9, v91
	v_add_f32_e32 v90, v90, v92
	ds_bpermute_b32 v91, v3, v9
	ds_bpermute_b32 v92, v3, v90
	s_waitcnt lgkmcnt(0)
	v_add_f32_e32 v9, v9, v91
	v_add_f32_e32 v90, v90, v92
	ds_bpermute_b32 v91, v4, v9
	ds_bpermute_b32 v92, v4, v90
	s_waitcnt lgkmcnt(0)
	v_add_f32_e32 v9, v9, v91
	v_add_f32_e32 v90, v90, v92
	ds_bpermute_b32 v91, v5, v9
	ds_bpermute_b32 v92, v5, v90
	s_waitcnt lgkmcnt(0)
	v_add_f32_e32 v9, v9, v91
	v_add_f32_e32 v90, v90, v92
	ds_bpermute_b32 v91, v6, v9
	ds_bpermute_b32 v92, v6, v90
	s_waitcnt lgkmcnt(0)
	v_add_f32_e32 v9, v9, v91
	v_add_f32_e32 v90, v90, v92
	ds_bpermute_b32 v91, v7, v9
	ds_bpermute_b32 v92, v7, v90
	s_waitcnt lgkmcnt(0)
	v_add_f32_e32 v9, v9, v91
	v_add_f32_e32 v90, v90, v92
	ds_bpermute_b32 v91, v8, v9
	ds_bpermute_b32 v92, v8, v90
	s_waitcnt lgkmcnt(0)
	v_add_f32_e32 v9, v9, v91
	v_add_f32_e32 v90, v90, v92
	v_mul_f32_e32 v93, 0x3a800000, v9
	v_mul_f32_e32 v91, 0x3a800000, v90
	v_fma_f32 v91, -v93, v93, v91
	v_max_f32_e32 v91, 0, v91
	v_add_f32_e32 v91, 0x358637bd, v91
	v_rsq_f32_e32 v94, v91
	v_mul_f32_e32 v91, 0.5, v91
	v_mul_f32_e32 v92, v94, v94
	v_fma_f32 v92, -v91, v92, 0.5
	v_fma_f32 v94, v94, v92, v94
	s_waitcnt vmcnt(12)
; DI unsigned pk2(float lo, float hi) { f32x2 v = {lo, hi}; bf16x2_t b = __builtin_convertvector(v, bf16x2_t); return __builtin_bit_cast(unsigned, b); }
; DI void ln_row_v(const Frame& F, f32x4 (&v)[4], float* xout, const float* g, const float* b, const float* sh, const float* sc, bf16_t* hout, const float* slab, const float* gres, float* stat = nullptr) {
;     ...
;         float s = 0.f, s2 = 0.f;
; #pragma unroll
;         for (int j = 0; j < 4; ++j) { s += (v[j][0] + v[j][1]) + (v[j][2] + v[j][3]); s2 += (v[j][0] * v[j][0] + v[j][1] * v[j][1]) + (v[j][2] * v[j][2] + v[j][3] * v[j][3]); }
;         wave_sum2(s, s2, F.lane);
;         const float mean = s * (1.f / D); const float rstd = 1.f / sqrtf(fmaxf(s2 * (1.f / D) - mean * mean, 0.f) + EPS);
; #pragma unroll
;         for (int j = 0; j < 4; ++j) { const f32x4 hh = ((const f32x4*)sh)[F.lane + 64 * j], cc = ((const f32x4*)sc)[F.lane + 64 * j];
;             const f32x4 o = (v[j] - mean) * rstd * (cc + 1.f) + hh; u32x2 wv; wv.x = pk2(o[0], o[1]); wv.y = pk2(o[2], o[3]);
;             ((u32x2*)hout)[F.lane + 64 * j] = wv; }
	v_sub_f32_e32 v98, v98, v93
	v_sub_f32_e32 v99, v99, v93
	v_sub_f32_e32 v100, v100, v93
	v_sub_f32_e32 v101, v101, v93
	v_sub_f32_e32 v102, v102, v93
	v_sub_f32_e32 v103, v103, v93
	v_sub_f32_e32 v104, v104, v93
	v_sub_f32_e32 v105, v105, v93
	v_sub_f32_e32 v106, v106, v93
	v_sub_f32_e32 v107, v107, v93
	v_sub_f32_e32 v108, v108, v93
	v_sub_f32_e32 v109, v109, v93
	v_sub_f32_e32 v110, v110, v93
	v_sub_f32_e32 v111, v111, v93
	v_sub_f32_e32 v112, v112, v93
	v_sub_f32_e32 v113, v113, v93
	v_add_f32_e32 v162, 1.0, v162
	v_add_f32_e32 v163, 1.0, v163
	v_add_f32_e32 v164, 1.0, v164
	v_add_f32_e32 v165, 1.0, v165
	v_add_f32_e32 v166, 1.0, v166
	v_add_f32_e32 v167, 1.0, v167
	v_add_f32_e32 v168, 1.0, v168
	v_add_f32_e32 v169, 1.0, v169
	v_add_f32_e32 v170, 1.0, v170
	v_add_f32_e32 v171, 1.0, v171
	v_add_f32_e32 v172, 1.0, v172
	v_add_f32_e32 v173, 1.0, v173
	v_add_f32_e32 v174, 1.0, v174
	v_add_f32_e32 v175, 1.0, v175
	v_add_f32_e32 v176, 1.0, v176
	v_add_f32_e32 v177, 1.0, v177
	v_mul_f32_e32 v98, v94, v98
	v_mul_f32_e32 v99, v94, v99
	v_mul_f32_e32 v100, v94, v100
	v_mul_f32_e32 v101, v94, v101
	v_mul_f32_e32 v102, v94, v102
	v_mul_f32_e32 v103, v94, v103
	v_mul_f32_e32 v104, v94, v104
	v_mul_f32_e32 v105, v94, v105
	v_mul_f32_e32 v106, v94, v106
	v_mul_f32_e32 v107, v94, v107
	v_mul_f32_e32 v108, v94, v108
	v_mul_f32_e32 v109, v94, v109
	v_mul_f32_e32 v110, v94, v110
	v_mul_f32_e32 v111, v94, v111
	v_mul_f32_e32 v112, v94, v112
	v_mul_f32_e32 v113, v94, v113
	v_fma_f32 v98, v98, v162, v146
	v_fma_f32 v99, v99, v163, v147
	v_fma_f32 v100, v100, v164, v148
	v_fma_f32 v101, v101, v165, v149
	v_fma_f32 v102, v102, v166, v150
	v_fma_f32 v103, v103, v167, v151
	v_fma_f32 v104, v104, v168, v152
	v_fma_f32 v105, v105, v169, v153
	v_fma_f32 v106, v106, v170, v154
	v_fma_f32 v107, v107, v171, v155
	v_fma_f32 v108, v108, v172, v156
	v_fma_f32 v109, v109, v173, v157
	v_fma_f32 v110, v110, v174, v158
	v_fma_f32 v111, v111, v175, v159
	v_fma_f32 v112, v112, v176, v160
	v_fma_f32 v113, v113, v177, v161
	v_cvt_pk_bf16_f32 v190, v98, v99
	v_cvt_pk_bf16_f32 v191, v100, v101
	v_cvt_pk_bf16_f32 v192, v102, v103
	v_cvt_pk_bf16_f32 v193, v104, v105
	v_cvt_pk_bf16_f32 v194, v106, v107
	v_cvt_pk_bf16_f32 v195, v108, v109
	v_cvt_pk_bf16_f32 v196, v110, v111
	v_cvt_pk_bf16_f32 v197, v112, v113
	s_add_u32 s2, s10, 0x1c00000
	s_addc_u32 s3, s11, 0
	global_store_dwordx2 v1, v[190:191], s[2:3]
	global_store_dwordx2 v1, v[192:193], s[2:3] offset:512
	global_store_dwordx2 v1, v[194:195], s[2:3] offset:1024
	global_store_dwordx2 v1, v[196:197], s[2:3] offset:1536
	v_add_f32_e32 v9, v42, v43
	v_add_f32_e32 v91, v44, v45
	v_mul_f32_e32 v90, v42, v42
	v_mul_f32_e32 v92, v43, v43
	v_add_f32_e32 v9, v9, v46
	v_add_f32_e32 v91, v91, v47
	v_add_f32_e32 v9, v9, v48
	v_add_f32_e32 v91, v91, v49
	v_add_f32_e32 v9, v9, v50
	v_add_f32_e32 v91, v91, v51
	v_add_f32_e32 v9, v9, v52
	v_add_f32_e32 v91, v91, v53
	v_add_f32_e32 v9, v9, v54
	v_add_f32_e32 v91, v91, v55
	v_add_f32_e32 v9, v9, v56
	v_add_f32_e32 v91, v91, v57
	v_fmac_f32_e32 v90, v44, v44
	v_fmac_f32_e32 v92, v45, v45
	v_fmac_f32_e32 v90, v46, v46
	v_fmac_f32_e32 v92, v47, v47
	v_fmac_f32_e32 v90, v48, v48
	v_fmac_f32_e32 v92, v49, v49
	v_fmac_f32_e32 v90, v50, v50
	v_fmac_f32_e32 v92, v51, v51
	v_fmac_f32_e32 v90, v52, v52
	v_fmac_f32_e32 v92, v53, v53
	v_fmac_f32_e32 v90, v54, v54
	v_fmac_f32_e32 v92, v55, v55
	v_fmac_f32_e32 v90, v56, v56
	v_fmac_f32_e32 v92, v57, v57
	v_add_f32_e32 v9, v9, v91
	v_add_f32_e32 v90, v90, v92
	ds_bpermute_b32 v91, v3, v9
	ds_bpermute_b32 v92, v3, v90
	s_waitcnt lgkmcnt(0)
	v_add_f32_e32 v9, v9, v91
	v_add_f32_e32 v90, v90, v92
	ds_bpermute_b32 v91, v4, v9
	ds_bpermute_b32 v92, v4, v90
	s_waitcnt lgkmcnt(0)
	v_add_f32_e32 v9, v9, v91
	v_add_f32_e32 v90, v90, v92
	ds_bpermute_b32 v91, v5, v9
	ds_bpermute_b32 v92, v5, v90
	s_waitcnt lgkmcnt(0)
	v_add_f32_e32 v9, v9, v91
	v_add_f32_e32 v90, v90, v92
	ds_bpermute_b32 v91, v6, v9
	ds_bpermute_b32 v92, v6, v90
	s_waitcnt lgkmcnt(0)
; DI unsigned pk2(float lo, float hi) { f32x2 v = {lo, hi}; bf16x2_t b = __builtin_convertvector(v, bf16x2_t); return __builtin_bit_cast(unsigned, b); }
; DI const float* modp(const Frame& F, int l, int mr, int which) { return (const float*)(F.ws + WS_MOD) + ((size_t)(l * 9 + mr) * 6 + which) * 1024; }
; DI void ln_row_v(const Frame& F, f32x4 (&v)[4], float* xout, const float* g, const float* b, const float* sh, const float* sc, bf16_t* hout, const float* slab, const float* gres, float* stat = nullptr) {
;     ...
;         float s = 0.f, s2 = 0.f;
; #pragma unroll
;         for (int j = 0; j < 4; ++j) { s += (v[j][0] + v[j][1]) + (v[j][2] + v[j][3]); s2 += (v[j][0] * v[j][0] + v[j][1] * v[j][1]) + (v[j][2] * v[j][2] + v[j][3] * v[j][3]); }
;         wave_sum2(s, s2, F.lane);
;         const float mean = s * (1.f / D); const float rstd = 1.f / sqrtf(fmaxf(s2 * (1.f / D) - mean * mean, 0.f) + EPS);
; #pragma unroll
;         for (int j = 0; j < 4; ++j) { const f32x4 hh = ((const f32x4*)sh)[F.lane + 64 * j], cc = ((const f32x4*)sc)[F.lane + 64 * j];
;             const f32x4 o = (v[j] - mean) * rstd * (cc + 1.f) + hh; u32x2 wv; wv.x = pk2(o[0], o[1]); wv.y = pk2(o[2], o[3]);
;             ((u32x2*)hout)[F.lane + 64 * j] = wv; }
; DI void prologue_b(const Frame& F) {
;     ...
;     for (int row = gw; row < MT; row += NGW) {
;         const int mr = row < ML ? (row >> 11) : 8;
;         const float* xi = row < ML ? pin(F, I_X) + (size_t)row * D : pin(F, I_CTX) + (size_t)(row - ML) * D;
;         ln_row(F, xi, nullptr, nullptr, nullptr, modp(F, 0, mr, 0), modp(F, 0, mr, 1), H + (size_t)row * D);
;     }
	v_add_f32_e32 v9, v9, v91
	v_add_f32_e32 v90, v90, v92
	ds_bpermute_b32 v91, v7, v9
	ds_bpermute_b32 v92, v7, v90
	s_waitcnt lgkmcnt(0)
	v_add_f32_e32 v9, v9, v91
	v_add_f32_e32 v90, v90, v92
	ds_bpermute_b32 v91, v8, v9
	ds_bpermute_b32 v92, v8, v90
	s_waitcnt lgkmcnt(0)
	v_add_f32_e32 v9, v9, v91
	v_add_f32_e32 v90, v90, v92
	v_mul_f32_e32 v93, 0x3a800000, v9
	v_mul_f32_e32 v91, 0x3a800000, v90
	v_fma_f32 v91, -v93, v93, v91
	v_max_f32_e32 v91, 0, v91
	v_add_f32_e32 v91, 0x358637bd, v91
	v_rsq_f32_e32 v94, v91
	v_mul_f32_e32 v91, 0.5, v91
	v_mul_f32_e32 v92, v94, v94
	v_fma_f32 v92, -v91, v92, 0.5
	v_fma_f32 v94, v94, v92, v94
	s_waitcnt vmcnt(4)
	v_sub_f32_e32 v42, v42, v93
	v_sub_f32_e32 v43, v43, v93
	v_sub_f32_e32 v44, v44, v93
	v_sub_f32_e32 v45, v45, v93
	v_sub_f32_e32 v46, v46, v93
	v_sub_f32_e32 v47, v47, v93
	v_sub_f32_e32 v48, v48, v93
	v_sub_f32_e32 v49, v49, v93
	v_sub_f32_e32 v50, v50, v93
	v_sub_f32_e32 v51, v51, v93
	v_sub_f32_e32 v52, v52, v93
	v_sub_f32_e32 v53, v53, v93
	v_sub_f32_e32 v54, v54, v93
	v_sub_f32_e32 v55, v55, v93
	v_sub_f32_e32 v56, v56, v93
	v_sub_f32_e32 v57, v57, v93
	v_add_f32_e32 v130, 1.0, v130
	v_add_f32_e32 v131, 1.0, v131
	v_add_f32_e32 v132, 1.0, v132
	v_add_f32_e32 v133, 1.0, v133
	v_add_f32_e32 v134, 1.0, v134
	v_add_f32_e32 v135, 1.0, v135
	v_add_f32_e32 v136, 1.0, v136
	v_add_f32_e32 v137, 1.0, v137
	v_add_f32_e32 v138, 1.0, v138
	v_add_f32_e32 v139, 1.0, v139
	v_add_f32_e32 v140, 1.0, v140
	v_add_f32_e32 v141, 1.0, v141
	v_add_f32_e32 v142, 1.0, v142
	v_add_f32_e32 v143, 1.0, v143
	v_add_f32_e32 v144, 1.0, v144
	v_add_f32_e32 v145, 1.0, v145
	v_mul_f32_e32 v42, v94, v42
	v_mul_f32_e32 v43, v94, v43
	v_mul_f32_e32 v44, v94, v44
	v_mul_f32_e32 v45, v94, v45
	v_mul_f32_e32 v46, v94, v46
	v_mul_f32_e32 v47, v94, v47
	v_mul_f32_e32 v48, v94, v48
	v_mul_f32_e32 v49, v94, v49
	v_mul_f32_e32 v50, v94, v50
	v_mul_f32_e32 v51, v94, v51
	v_mul_f32_e32 v52, v94, v52
	v_mul_f32_e32 v53, v94, v53
	v_mul_f32_e32 v54, v94, v54
	v_mul_f32_e32 v55, v94, v55
	v_mul_f32_e32 v56, v94, v56
	v_mul_f32_e32 v57, v94, v57
	v_fma_f32 v42, v42, v130, v114
	v_fma_f32 v43, v43, v131, v115
	v_fma_f32 v44, v44, v132, v116
	v_fma_f32 v45, v45, v133, v117
	v_fma_f32 v46, v46, v134, v118
	v_fma_f32 v47, v47, v135, v119
	v_fma_f32 v48, v48, v136, v120
	v_fma_f32 v49, v49, v137, v121
	v_fma_f32 v50, v50, v138, v122
	v_fma_f32 v51, v51, v139, v123
	v_fma_f32 v52, v52, v140, v124
	v_fma_f32 v53, v53, v141, v125
	v_fma_f32 v54, v54, v142, v126
	v_fma_f32 v55, v55, v143, v127
	v_fma_f32 v56, v56, v144, v128
	v_fma_f32 v57, v57, v145, v129
	v_cvt_pk_bf16_f32 v190, v42, v43
	v_cvt_pk_bf16_f32 v191, v44, v45
	v_cvt_pk_bf16_f32 v192, v46, v47
	v_cvt_pk_bf16_f32 v193, v48, v49
	v_cvt_pk_bf16_f32 v194, v50, v51
	v_cvt_pk_bf16_f32 v195, v52, v53
	v_cvt_pk_bf16_f32 v196, v54, v55
	v_cvt_pk_bf16_f32 v197, v56, v57
	s_add_u32 s2, s10, 0x2000000
	s_addc_u32 s3, s11, 0
	global_store_dwordx2 v1, v[190:191], s[2:3]
	global_store_dwordx2 v1, v[192:193], s[2:3] offset:512
	global_store_dwordx2 v1, v[194:195], s[2:3] offset:1024
	global_store_dwordx2 v1, v[196:197], s[2:3] offset:1536
	s_waitcnt vmcnt(0)
	s_add_i32 s16, s16, 0x4800
	s_cmpk_gt_u32 s16, 0x47ff
	s_cbranch_scc1 .LBB0_671
	s_lshl_b64 s[2:3], s[44:45], 3
	s_add_u32 s4, s62, s2
	s_addc_u32 s5, s63, s3
	v_lshlrev_b32_e32 v0, 2, v186
	v_lshlrev_b32_e32 v96, 3, v186
	s_add_u32 s18, s94, 0x100000
	v_xor_b32_e32 v18, 4, v0
	v_xor_b32_e32 v19, 8, v0
	v_xor_b32_e32 v20, 16, v0
	v_xor_b32_e32 v21, 32, v0
	v_xor_b32_e32 v22, 64, v0
	v_xor_b32_e32 v23, 0x80, v0
	v_or_b32_e32 v0, 64, v186
	v_or_b32_e32 v2, 0x80, v186
	v_or_b32_e32 v4, 0xc0, v186
	v_lshl_add_u64 v[6:7], s[94:95], 0, v[96:97]
	s_mov_b64 s[2:3], 0x3e00000
	s_addc_u32 s19, s95, 0
	v_lshl_add_u64 v[16:17], v[6:7], 0, s[2:3]
	s_lshl_b32 s20, s93, 3
	s_lshl_b64 s[6:7], s[16:17], 12
	s_lshl_b32 s21, s93, 15
	v_lshlrev_b32_e32 v24, 4, v186
	v_lshlrev_b32_e32 v25, 4, v0
	v_lshlrev_b32_e32 v26, 4, v2
	v_lshlrev_b32_e32 v27, 4, v4
	s_mov_b64 s[8:9], s[16:17]
	s_branch .LBB0_668
